# adds: all flat_load/flat_store on workspace pointers become global_* (no lgkmcnt coupling / LDS path use), -log2e folded into rstd for gate tiles
# speedup vs baseline: 1.0390x; 1.0085x over previous
; __device__ __forceinline__ unsigned cvt_pk_bf16(float lo, float hi) { typedef float f2 __attribute__((ext_vector_type(2))); typedef __bf16 b2 __attribute__((ext_vector_type(2))); f2 v = {lo, hi}; b2 b = __builtin_convertvector(v, b2); return __builtin_bit_cast(unsigned, b); }
; __device__ __forceinline__ void transpose_item(const float* W, int K, int N, bf16_t* WT, int n0d, int n0s, float scale, int k0, float* scr, int lane, bool gperm = false, const float* kgain = nullptr) {
;     ...
;         for (int i = 0; i < 32; ++i) { const int kk = 2 * i + (lane >> 5); scr[kk * 33 + (lane & 31)] = W[(size_t)(k0 + kk) * N + src] * kgain[k0 + kk]; }
;     } else if (n0s >= 0) {
; #pragma unroll
;         for (int i = 0; i < 32; ++i) { const int kk = 2 * i + (lane >> 5); scr[kk * 33 + (lane & 31)] = W[(size_t)(k0 + kk) * N + n0s + (lane & 31)] * (kgain ? scale * kgain[k0 + kk] : scale); }
;     } else {
; #pragma unroll
;         for (int i = 0; i < 32; ++i) { const int kk = 2 * i + (lane >> 5); scr[kk * 33 + (lane & 31)] = 0.f; }
;     }
;     __builtin_amdgcn_wave_barrier(); asm volatile("s_waitcnt lgkmcnt(0)" ::: "memory");
;     const int c = lane & 7;
; #pragma unroll
;     for (int j = 0; j < 4; ++j) { const int n = (lane >> 3) + 8 * j; const float* s = scr + (8 * c) * 33 + n;
;         u32x4 o; o.x = cvt_pk_bf16(s[0 * 33], s[1 * 33]); o.y = cvt_pk_bf16(s[2 * 33], s[3 * 33]); o.z = cvt_pk_bf16(s[4 * 33], s[5 * 33]); o.w = cvt_pk_bf16(s[6 * 33], s[7 * 33]);
;         *(u32x4*)(WT + (size_t)(n0d + n) * K + k0 + 8 * c) = o; }
;     __builtin_amdgcn_wave_barrier(); asm volatile("s_waitcnt lgkmcnt(0)" ::: "memory");
.LBB0_9:
	v_lshl_add_u32 v10, v10, 2, s24
	s_mul_i32 s1, s14, 0xd00000
	ds_write_b32 v10, v6
	s_waitcnt lgkmcnt(0)
	s_mul_hi_i32 s0, s14, 0xd00000
	s_add_u32 s12, s39, s1
	ds_read_b32 v10, v67
	ds_read_b32 v11, v67 offset:132
	ds_read_b32 v12, v67 offset:264
	ds_read_b32 v13, v67 offset:396
	ds_read_b32 v90, v67 offset:528
	ds_read_b32 v91, v67 offset:660
	ds_read_b32 v92, v67 offset:792
	ds_read_b32 v93, v67 offset:924
	s_addc_u32 s14, s40, s0
	s_ashr_i32 s17, s16, 31
	s_lshl_b64 s[0:1], s[16:17], 1
	s_add_u32 s0, s12, s0
	s_waitcnt lgkmcnt(0)
	v_cvt_pk_bf16_f32 v10, v10, v11
	v_cvt_pk_bf16_f32 v11, v12, v13
	v_cvt_pk_bf16_f32 v12, v90, v91
	v_or_b32_e32 v90, s15, v66
	s_addc_u32 s1, s14, s1
	v_lshlrev_b32_e32 v6, 1, v8
	v_ashrrev_i32_e32 v91, 31, v90
	v_lshl_add_u64 v[88:89], s[0:1], 0, v[6:7]
	v_lshlrev_b64 v[90:91], 11, v[90:91]
	v_cvt_pk_bf16_f32 v13, v92, v93
	v_lshl_add_u64 v[90:91], v[88:89], 0, v[90:91]
	global_store_dwordx4 v[90:91], v[10:13], off
	ds_read_b32 v6, v67 offset:32
	ds_read_b32 v10, v67 offset:164
	ds_read_b32 v11, v67 offset:296
	ds_read_b32 v12, v67 offset:428
	ds_read_b32 v13, v67 offset:560
	ds_read_b32 v90, v67 offset:692
	ds_read_b32 v91, v67 offset:824
	ds_read_b32 v92, v67 offset:956
	s_waitcnt lgkmcnt(0)
	v_cvt_pk_bf16_f32 v11, v11, v12
	v_cvt_pk_bf16_f32 v10, v6, v10
	v_cvt_pk_bf16_f32 v12, v13, v90
	v_or_b32_e32 v90, s15, v81
	v_cvt_pk_bf16_f32 v13, v91, v92
	v_ashrrev_i32_e32 v91, 31, v90
	v_lshlrev_b64 v[90:91], 11, v[90:91]
	v_lshl_add_u64 v[90:91], v[88:89], 0, v[90:91]
	global_store_dwordx4 v[90:91], v[10:13], off
	ds_read_b32 v6, v67 offset:64
	ds_read_b32 v10, v67 offset:196
	ds_read_b32 v11, v67 offset:328
	ds_read_b32 v12, v67 offset:460
	ds_read_b32 v13, v67 offset:592
	ds_read_b32 v90, v67 offset:724
	ds_read_b32 v91, v67 offset:856
	ds_read_b32 v92, v67 offset:988
	s_waitcnt lgkmcnt(0)
	v_cvt_pk_bf16_f32 v11, v11, v12
	v_cvt_pk_bf16_f32 v10, v6, v10
	v_cvt_pk_bf16_f32 v12, v13, v90
	v_or_b32_e32 v90, s15, v82
	v_cvt_pk_bf16_f32 v13, v91, v92
	v_ashrrev_i32_e32 v91, 31, v90
	v_lshlrev_b64 v[90:91], 11, v[90:91]
	v_lshl_add_u64 v[90:91], v[88:89], 0, v[90:91]
	global_store_dwordx4 v[90:91], v[10:13], off
	ds_read_b32 v6, v67 offset:96
	ds_read_b32 v10, v67 offset:228
	ds_read_b32 v11, v67 offset:360
	ds_read_b32 v12, v67 offset:492
	ds_read_b32 v13, v67 offset:624
	ds_read_b32 v90, v67 offset:756
	ds_read_b32 v91, v67 offset:888
	ds_read_b32 v92, v67 offset:1020
	s_waitcnt lgkmcnt(0)
	v_cvt_pk_bf16_f32 v11, v11, v12
	v_cvt_pk_bf16_f32 v10, v6, v10
	v_cvt_pk_bf16_f32 v12, v13, v90
	v_or_b32_e32 v90, s15, v83
	v_cvt_pk_bf16_f32 v13, v91, v92
	v_ashrrev_i32_e32 v91, 31, v90
	v_lshlrev_b64 v[90:91], 11, v[90:91]
	v_lshl_add_u64 v[88:89], v[88:89], 0, v[90:91]
	global_store_dwordx4 v[88:89], v[10:13], off
	s_waitcnt lgkmcnt(0)

; __device__ __forceinline__ void transpose_item(const float* W, int K, int N, bf16_t* WT, int n0d, int n0s, float scale, int k0, float* scr, int lane, bool gperm = false, const float* kgain = nullptr) {
;     ...
;     } else if (n0s >= 0) {
; #pragma unroll
;         for (int i = 0; i < 32; ++i) { const int kk = 2 * i + (lane >> 5); scr[kk * 33 + (lane & 31)] = W[(size_t)(k0 + kk) * N + n0s + (lane & 31)] * (kgain ? scale * kgain[k0 + kk] : scale); }
;     } else {
; __device__ __forceinline__ void prologue(const Args& a, unsigned char* ws, char* lds, int gw, int NGW, int wave, int lane) {
;     ...
;         { const int nb = r % 16, kb = r / 16;
;             transpose_item(a.in[13] + (size_t)l * 128 * 512, 128, 512, (bf16_t*)(ws + WS_WUKV) + (size_t)l * 512 * 128, nb * 32, nb * 32, 1.f, kb * 64, scr, lane); }
.LBB0_11:
	s_mul_hi_i32 s0, s48, 0x794e8a9b
	s_lshr_b32 s1, s0, 31
	s_ashr_i32 s0, s0, 12
	s_add_i32 s14, s0, s1
	s_mul_i32 s0, s14, 0xffffde3c
	s_add_i32 s18, s48, s0
	s_cmpk_gt_i32 s18, 0xcff
	s_mov_b64 s[0:1], -1
	s_cbranch_scc0 .LBB0_97
	s_cmpk_gt_u32 s18, 0xeff
	s_cbranch_scc0 .LBB0_94
	s_cmpk_gt_u32 s18, 0x10ff
	s_cbranch_scc0 .LBB0_91
	s_cmpk_gt_u32 s18, 0x1bff
	s_cbranch_scc0 .LBB0_24
	s_cmpk_gt_u32 s18, 0x217f
	s_cbranch_scc0 .LBB0_21
	s_cmpk_gt_u32 s18, 0x21a3
	s_cbranch_scc0 .LBB0_18
	s_ashr_i32 s15, s14, 31
	v_readlane_b32 s52, v253, 16
	s_lshl_b64 s[0:1], s[14:15], 18
	v_readlane_b32 s62, v253, 26
	v_readlane_b32 s63, v253, 27
	s_add_u32 s19, s62, s0
	s_addc_u32 s21, s63, s1
	s_lshl_b64 s[16:17], s[14:15], 17
	s_add_u32 s1, s2, s16
	s_addc_u32 s12, s27, s17
	s_lshl_b32 s0, s14, 7
	s_sub_i32 s0, s43, s0
	s_add_i32 s0, s0, 0xfffbcb80
	s_mul_i32 s15, s14, 0xffff78f0
	s_and_b32 s0, s0, 0x1e0
	s_add_i32 s16, s45, s15
	s_and_b32 s15, s16, 0x7fffffc0
	s_lshl_b32 s17, s0, 2
	s_add_u32 s20, s19, s17
	s_addc_u32 s21, s21, 0
	v_lshlrev_b32_e32 v6, 2, v4
	v_lshl_add_u64 v[10:11], s[20:21], 0, v[6:7]
	v_or_b32_e32 v6, s15, v2
	v_lshlrev_b64 v[12:13], 11, v[6:7]
	v_or_b32_e32 v6, s15, v14
	v_lshlrev_b64 v[88:89], 11, v[6:7]
	v_or_b32_e32 v6, s15, v16
	v_lshlrev_b64 v[90:91], 11, v[6:7]
	v_or_b32_e32 v6, s15, v18
	v_lshlrev_b64 v[92:93], 11, v[6:7]
	v_or_b32_e32 v6, s15, v20
	v_lshlrev_b64 v[94:95], 11, v[6:7]
	v_or_b32_e32 v6, s15, v22
	v_lshlrev_b64 v[96:97], 11, v[6:7]
	v_or_b32_e32 v6, s15, v24
	v_lshlrev_b64 v[98:99], 11, v[6:7]
	v_or_b32_e32 v6, s15, v26
	v_lshl_add_u64 v[12:13], v[10:11], 0, v[12:13]
	v_lshlrev_b64 v[100:101], 11, v[6:7]
	v_or_b32_e32 v6, s15, v28
	v_lshl_add_u64 v[88:89], v[10:11], 0, v[88:89]
	v_lshl_add_u64 v[90:91], v[10:11], 0, v[90:91]
	v_lshl_add_u64 v[92:93], v[10:11], 0, v[92:93]
	v_lshl_add_u64 v[94:95], v[10:11], 0, v[94:95]
	v_lshl_add_u64 v[96:97], v[10:11], 0, v[96:97]
	v_lshl_add_u64 v[98:99], v[10:11], 0, v[98:99]
	v_lshl_add_u64 v[100:101], v[10:11], 0, v[100:101]
	global_load_dword v102, v[12:13], off
	global_load_dword v103, v[88:89], off
	global_load_dword v104, v[90:91], off
	global_load_dword v105, v[92:93], off
	global_load_dword v106, v[94:95], off
	global_load_dword v107, v[96:97], off
	global_load_dword v108, v[98:99], off
	global_load_dword v109, v[100:101], off
	v_lshlrev_b64 v[12:13], 11, v[6:7]
	v_or_b32_e32 v6, s15, v30
	v_lshlrev_b64 v[88:89], 11, v[6:7]
	v_or_b32_e32 v6, s15, v32
	v_lshlrev_b64 v[90:91], 11, v[6:7]
	v_or_b32_e32 v6, s15, v34
	v_lshlrev_b64 v[92:93], 11, v[6:7]
	v_or_b32_e32 v6, s15, v36
	v_lshlrev_b64 v[94:95], 11, v[6:7]
	v_or_b32_e32 v6, s15, v38
	v_lshlrev_b64 v[96:97], 11, v[6:7]
	v_or_b32_e32 v6, s15, v40
	v_lshlrev_b64 v[98:99], 11, v[6:7]
	v_or_b32_e32 v6, s15, v42
	v_lshl_add_u64 v[12:13], v[10:11], 0, v[12:13]
	v_lshlrev_b64 v[100:101], 11, v[6:7]
	v_or_b32_e32 v6, s15, v44
	v_lshl_add_u64 v[88:89], v[10:11], 0, v[88:89]
	v_lshl_add_u64 v[90:91], v[10:11], 0, v[90:91]
	v_lshl_add_u64 v[92:93], v[10:11], 0, v[92:93]
	v_lshl_add_u64 v[94:95], v[10:11], 0, v[94:95]
	v_lshl_add_u64 v[96:97], v[10:11], 0, v[96:97]
	v_lshl_add_u64 v[98:99], v[10:11], 0, v[98:99]
	v_lshl_add_u64 v[100:101], v[10:11], 0, v[100:101]
	global_load_dword v110, v[12:13], off
	global_load_dword v111, v[88:89], off
	global_load_dword v112, v[90:91], off
	global_load_dword v113, v[92:93], off
	global_load_dword v114, v[94:95], off
	global_load_dword v115, v[96:97], off
	global_load_dword v116, v[98:99], off
	global_load_dword v117, v[100:101], off
	v_lshlrev_b64 v[12:13], 11, v[6:7]
	v_or_b32_e32 v6, s15, v46
	v_lshlrev_b64 v[88:89], 11, v[6:7]
	v_or_b32_e32 v6, s15, v48
	v_lshlrev_b64 v[90:91], 11, v[6:7]
	v_or_b32_e32 v6, s15, v50
	v_lshlrev_b64 v[92:93], 11, v[6:7]
	v_or_b32_e32 v6, s15, v52
	v_lshlrev_b64 v[94:95], 11, v[6:7]
	v_or_b32_e32 v6, s15, v54
	v_lshlrev_b64 v[96:97], 11, v[6:7]
	v_or_b32_e32 v6, s15, v56
	v_lshlrev_b64 v[98:99], 11, v[6:7]
	v_or_b32_e32 v6, s15, v58
	v_lshl_add_u64 v[12:13], v[10:11], 0, v[12:13]
	v_lshlrev_b64 v[100:101], 11, v[6:7]
	v_or_b32_e32 v6, s15, v60
	v_lshl_add_u64 v[88:89], v[10:11], 0, v[88:89]
	v_lshl_add_u64 v[90:91], v[10:11], 0, v[90:91]
	v_lshl_add_u64 v[92:93], v[10:11], 0, v[92:93]
	v_lshl_add_u64 v[94:95], v[10:11], 0, v[94:95]
	v_lshl_add_u64 v[96:97], v[10:11], 0, v[96:97]
	v_lshl_add_u64 v[98:99], v[10:11], 0, v[98:99]
	v_lshl_add_u64 v[100:101], v[10:11], 0, v[100:101]
	global_load_dword v118, v[12:13], off
	global_load_dword v119, v[88:89], off
	global_load_dword v120, v[90:91], off
	global_load_dword v121, v[92:93], off
	global_load_dword v122, v[94:95], off
	global_load_dword v123, v[96:97], off
	global_load_dword v124, v[98:99], off
	global_load_dword v125, v[100:101], off
	v_lshlrev_b64 v[12:13], 11, v[6:7]
	v_or_b32_e32 v6, s15, v62
	v_lshlrev_b64 v[88:89], 11, v[6:7]
	v_or_b32_e32 v6, s15, v64
	v_lshlrev_b64 v[90:91], 11, v[6:7]
	v_or_b32_e32 v6, s15, v71
	v_lshlrev_b64 v[92:93], 11, v[6:7]
	v_or_b32_e32 v6, s15, v73
	v_lshlrev_b64 v[94:95], 11, v[6:7]
	v_or_b32_e32 v6, s15, v75
	v_lshlrev_b64 v[96:97], 11, v[6:7]
	v_or_b32_e32 v6, s16, v77
	v_lshlrev_b64 v[98:99], 11, v[6:7]
	v_or_b32_e32 v6, s16, v79
	v_lshlrev_b64 v[100:101], 11, v[6:7]
	v_lshl_add_u64 v[12:13], v[10:11], 0, v[12:13]
	v_lshl_add_u64 v[88:89], v[10:11], 0, v[88:89]
	v_lshl_add_u64 v[90:91], v[10:11], 0, v[90:91]
	v_lshl_add_u64 v[92:93], v[10:11], 0, v[92:93]
	v_lshl_add_u64 v[94:95], v[10:11], 0, v[94:95]
	v_lshl_add_u64 v[96:97], v[10:11], 0, v[96:97]
	v_lshl_add_u64 v[98:99], v[10:11], 0, v[98:99]
	v_lshl_add_u64 v[10:11], v[10:11], 0, v[100:101]
	global_load_dword v6, v[12:13], off
	s_nop 0
	global_load_dword v12, v[88:89], off
	global_load_dword v13, v[90:91], off
	s_nop 0
	global_load_dword v88, v[92:93], off
	global_load_dword v89, v[94:95], off
	global_load_dword v90, v[96:97], off
	global_load_dword v91, v[98:99], off
	s_nop 0
	global_load_dword v10, v[10:11], off
	s_lshl_b32 s15, s15, 1
	s_add_u32 s16, s1, s15
	s_addc_u32 s17, s12, 0
	v_readlane_b32 s53, v253, 17
	s_waitcnt vmcnt(0)
; __device__ __forceinline__ unsigned cvt_pk_bf16(float lo, float hi) { typedef float f2 __attribute__((ext_vector_type(2))); typedef __bf16 b2 __attribute__((ext_vector_type(2))); f2 v = {lo, hi}; b2 b = __builtin_convertvector(v, b2); return __builtin_bit_cast(unsigned, b); }
; __device__ __forceinline__ void transpose_item(const float* W, int K, int N, bf16_t* WT, int n0d, int n0s, float scale, int k0, float* scr, int lane, bool gperm = false, const float* kgain = nullptr) {
;     ...
;     __builtin_amdgcn_wave_barrier(); asm volatile("s_waitcnt lgkmcnt(0)" ::: "memory");
;     const int c = lane & 7;
; #pragma unroll
;     for (int j = 0; j < 4; ++j) { const int n = (lane >> 3) + 8 * j; const float* s = scr + (8 * c) * 33 + n;
;         u32x4 o; o.x = cvt_pk_bf16(s[0 * 33], s[1 * 33]); o.y = cvt_pk_bf16(s[2 * 33], s[3 * 33]); o.z = cvt_pk_bf16(s[4 * 33], s[5 * 33]); o.w = cvt_pk_bf16(s[6 * 33], s[7 * 33]);
;         *(u32x4*)(WT + (size_t)(n0d + n) * K + k0 + 8 * c) = o; }
;     __builtin_amdgcn_wave_barrier(); asm volatile("s_waitcnt lgkmcnt(0)" ::: "memory");
	ds_write_b32 v9, v102
	s_waitcnt vmcnt(30)
	ds_write_b32 v15, v103
	s_waitcnt vmcnt(29)
	ds_write_b32 v17, v104
	s_waitcnt vmcnt(28)
	ds_write_b32 v19, v105
	s_waitcnt vmcnt(27)
	ds_write_b32 v21, v106
	s_waitcnt vmcnt(26)
	ds_write_b32 v23, v107
	s_waitcnt vmcnt(25)
	ds_write_b32 v25, v108
	s_waitcnt vmcnt(24)
	ds_write_b32 v27, v109
	s_waitcnt vmcnt(23)
	ds_write_b32 v29, v110
	s_waitcnt vmcnt(22)
	ds_write_b32 v31, v111
	s_waitcnt vmcnt(21)
	ds_write_b32 v33, v112
	s_waitcnt vmcnt(20)
	ds_write_b32 v35, v113
	s_waitcnt vmcnt(19)
	ds_write_b32 v37, v114
	s_waitcnt vmcnt(18)
	ds_write_b32 v39, v115
	s_waitcnt vmcnt(17)
	ds_write_b32 v41, v116
	s_waitcnt vmcnt(16)
	ds_write_b32 v43, v117
	s_waitcnt vmcnt(15)
	ds_write_b32 v45, v118
	s_waitcnt vmcnt(14)
	ds_write_b32 v47, v119
	s_waitcnt vmcnt(13)
	ds_write_b32 v49, v120
	s_waitcnt vmcnt(12)
	ds_write_b32 v51, v121
	s_waitcnt vmcnt(11)
	ds_write_b32 v53, v122
	s_waitcnt vmcnt(10)
	ds_write_b32 v55, v123
	s_waitcnt vmcnt(9)
	ds_write_b32 v57, v124
	s_waitcnt vmcnt(8)
	ds_write_b32 v59, v125
	s_waitcnt vmcnt(7)
	ds_write_b32 v61, v6
	s_waitcnt vmcnt(6)
	ds_write_b32 v63, v12
	s_waitcnt vmcnt(5)
	ds_write_b32 v65, v13
	s_waitcnt vmcnt(4)
	ds_write_b32 v72, v88
	s_waitcnt vmcnt(3)
	ds_write_b32 v74, v89
	s_waitcnt vmcnt(2)
	ds_write_b32 v76, v90
	s_waitcnt vmcnt(1)
	ds_write_b32 v78, v91
	s_waitcnt vmcnt(0)
	ds_write_b32 v80, v10
	s_waitcnt lgkmcnt(0)
	ds_read_b32 v10, v67
	ds_read_b32 v11, v67 offset:132
	ds_read_b32 v12, v67 offset:264
	ds_read_b32 v13, v67 offset:396
	ds_read_b32 v90, v67 offset:528
	ds_read_b32 v91, v67 offset:660
	ds_read_b32 v92, v67 offset:792
	ds_read_b32 v93, v67 offset:924
	v_lshlrev_b32_e32 v6, 1, v8
	v_lshl_add_u64 v[88:89], s[16:17], 0, v[6:7]
	v_or_b32_e32 v6, s0, v66
	v_lshlrev_b32_e32 v6, 8, v6
	s_waitcnt lgkmcnt(6)
	v_cvt_pk_bf16_f32 v10, v10, v11
	s_waitcnt lgkmcnt(4)
	v_cvt_pk_bf16_f32 v11, v12, v13
	s_waitcnt lgkmcnt(2)
	v_cvt_pk_bf16_f32 v12, v90, v91
	s_waitcnt lgkmcnt(0)
	v_cvt_pk_bf16_f32 v13, v92, v93
	v_lshl_add_u64 v[90:91], v[88:89], 0, v[6:7]
	global_store_dwordx4 v[90:91], v[10:13], off
	ds_read_b32 v6, v67 offset:32
	ds_read_b32 v10, v67 offset:164
	ds_read_b32 v11, v67 offset:296
	ds_read_b32 v12, v67 offset:428
	ds_read_b32 v13, v67 offset:560
	ds_read_b32 v90, v67 offset:692
	ds_read_b32 v91, v67 offset:824
	ds_read_b32 v92, v67 offset:956
	s_waitcnt lgkmcnt(0)
	v_cvt_pk_bf16_f32 v10, v6, v10
	v_or_b32_e32 v6, s0, v81
	v_lshlrev_b32_e32 v6, 8, v6
	v_cvt_pk_bf16_f32 v11, v11, v12
	v_cvt_pk_bf16_f32 v12, v13, v90
	v_cvt_pk_bf16_f32 v13, v91, v92
	v_lshl_add_u64 v[90:91], v[88:89], 0, v[6:7]
	global_store_dwordx4 v[90:91], v[10:13], off
	ds_read_b32 v6, v67 offset:64
	ds_read_b32 v10, v67 offset:196
	ds_read_b32 v11, v67 offset:328
	ds_read_b32 v12, v67 offset:460
	ds_read_b32 v13, v67 offset:592
	ds_read_b32 v90, v67 offset:724
	ds_read_b32 v91, v67 offset:856
	ds_read_b32 v92, v67 offset:988
	s_waitcnt lgkmcnt(0)
	v_cvt_pk_bf16_f32 v10, v6, v10
	v_or_b32_e32 v6, s0, v82
	v_lshlrev_b32_e32 v6, 8, v6
	v_cvt_pk_bf16_f32 v11, v11, v12
	v_cvt_pk_bf16_f32 v12, v13, v90
	v_cvt_pk_bf16_f32 v13, v91, v92
	v_lshl_add_u64 v[90:91], v[88:89], 0, v[6:7]
	global_store_dwordx4 v[90:91], v[10:13], off
	ds_read_b32 v6, v67 offset:96
	ds_read_b32 v10, v67 offset:228
	ds_read_b32 v11, v67 offset:360
	ds_read_b32 v12, v67 offset:492
	ds_read_b32 v13, v67 offset:624
	ds_read_b32 v90, v67 offset:756
	ds_read_b32 v91, v67 offset:888
	ds_read_b32 v92, v67 offset:1020
	s_waitcnt lgkmcnt(0)
	v_cvt_pk_bf16_f32 v10, v6, v10
	v_or_b32_e32 v6, s0, v83
	v_lshlrev_b32_e32 v6, 8, v6
	v_cvt_pk_bf16_f32 v11, v11, v12
	v_cvt_pk_bf16_f32 v12, v13, v90
	v_cvt_pk_bf16_f32 v13, v91, v92
	v_lshl_add_u64 v[88:89], v[88:89], 0, v[6:7]
	global_store_dwordx4 v[88:89], v[10:13], off
	s_waitcnt lgkmcnt(0)
	v_readlane_b32 s54, v253, 18
	v_readlane_b32 s55, v253, 19
	v_readlane_b32 s56, v253, 20
	v_readlane_b32 s57, v253, 21
	v_readlane_b32 s58, v253, 22
	v_readlane_b32 s59, v253, 23
	v_readlane_b32 s60, v253, 24
	v_readlane_b32 s61, v253, 25
	v_readlane_b32 s64, v253, 28
	v_readlane_b32 s65, v253, 29
	v_readlane_b32 s66, v253, 30
	v_readlane_b32 s67, v253, 31
	s_mov_b64 s[0:1], 0
.LBB0_18:
	s_andn2_b64 vcc, exec, s[0:1]
	s_cbranch_vccnz .LBB0_20
; __device__ __forceinline__ void transpose_item(const float* W, int K, int N, bf16_t* WT, int n0d, int n0s, float scale, int k0, float* scr, int lane, bool gperm = false, const float* kgain = nullptr) {
;     ...
;     } else if (n0s >= 0) {
; #pragma unroll
;         for (int i = 0; i < 32; ++i) { const int kk = 2 * i + (lane >> 5); scr[kk * 33 + (lane & 31)] = W[(size_t)(k0 + kk) * N + n0s + (lane & 31)] * (kgain ? scale * kgain[k0 + kk] : scale); }
;     } else {
; __device__ __forceinline__ void prologue(const Args& a, unsigned char* ws, char* lds, int gw, int NGW, int wave, int lane) {
;     ...
;         if (r < I_UQ) { const int nb = r % 12, kb = r / 12;
;             transpose_item(a.in[12] + (size_t)l * 192 * 384, 192, 384, (bf16_t*)(ws + WS_WUQ) + (size_t)l * 384 * 192, nb * 32, nb * 32, 1.f, kb * 64, scr, lane); continue; }
	s_xor_b32 s0, s18, 0xff80
	s_and_b32 s1, s0, 0xff
	s_mulk_i32 s1, 0xab
	s_bfe_u32 s1, s1, 0x5000b
	s_mul_i32 s12, s1, 12
	s_sub_i32 s0, s0, s12
	v_readlane_b32 s52, v253, 16
	s_and_b32 s17, s0, 0xff
	s_mul_i32 s12, s14, 0x48000
	v_readlane_b32 s60, v253, 24
	s_mul_hi_i32 s0, s14, 0x48000
	v_readlane_b32 s61, v253, 25
	s_add_u32 s19, s60, s12
	s_addc_u32 s21, s61, s0
	s_mul_i32 s12, s14, 0x24000
	s_mul_hi_i32 s0, s14, 0x24000
	s_add_u32 s12, s28, s12
	s_addc_u32 s15, s29, s0
	s_lshl_b32 s0, s17, 5
	s_lshl_b32 s16, s1, 6
	s_lshl_b32 s17, s17, 7
	s_add_u32 s20, s19, s17
	s_addc_u32 s21, s21, 0
	v_lshlrev_b32_e32 v6, 2, v4
	v_lshl_add_u64 v[10:11], s[20:21], 0, v[6:7]
	v_or_b32_e32 v6, s16, v2
	v_mul_u32_u24_e32 v6, 0x180, v6
	v_lshlrev_b32_e32 v6, 2, v6
	v_lshl_add_u64 v[12:13], v[10:11], 0, v[6:7]
	v_or_b32_e32 v6, s16, v14
	v_mul_u32_u24_e32 v6, 0x180, v6
	v_lshlrev_b32_e32 v6, 2, v6
	v_lshl_add_u64 v[88:89], v[10:11], 0, v[6:7]
	v_or_b32_e32 v6, s16, v16
	v_mul_u32_u24_e32 v6, 0x180, v6
	v_lshlrev_b32_e32 v6, 2, v6
	v_lshl_add_u64 v[90:91], v[10:11], 0, v[6:7]
	v_or_b32_e32 v6, s16, v18
	v_mul_u32_u24_e32 v6, 0x180, v6
	v_lshlrev_b32_e32 v6, 2, v6
	v_lshl_add_u64 v[92:93], v[10:11], 0, v[6:7]
	v_or_b32_e32 v6, s16, v20
	v_mul_u32_u24_e32 v6, 0x180, v6
	v_lshlrev_b32_e32 v6, 2, v6
	v_lshl_add_u64 v[94:95], v[10:11], 0, v[6:7]
	v_or_b32_e32 v6, s16, v22
	v_mul_u32_u24_e32 v6, 0x180, v6
	v_lshlrev_b32_e32 v6, 2, v6
	v_lshl_add_u64 v[96:97], v[10:11], 0, v[6:7]
	v_or_b32_e32 v6, s16, v24
	v_mul_u32_u24_e32 v6, 0x180, v6
	v_lshlrev_b32_e32 v6, 2, v6
	v_lshl_add_u64 v[98:99], v[10:11], 0, v[6:7]
	v_or_b32_e32 v6, s16, v26
	v_mul_u32_u24_e32 v6, 0x180, v6
	v_lshlrev_b32_e32 v6, 2, v6
	v_lshl_add_u64 v[100:101], v[10:11], 0, v[6:7]
	v_or_b32_e32 v6, s16, v28
	v_mul_u32_u24_e32 v6, 0x180, v6
	v_lshlrev_b32_e32 v6, 2, v6
	global_load_dword v102, v[12:13], off
	global_load_dword v103, v[88:89], off
	global_load_dword v104, v[90:91], off
	global_load_dword v105, v[92:93], off
	global_load_dword v106, v[94:95], off
	global_load_dword v107, v[96:97], off
	global_load_dword v108, v[98:99], off
	global_load_dword v109, v[100:101], off
	v_lshl_add_u64 v[12:13], v[10:11], 0, v[6:7]
	v_or_b32_e32 v6, s16, v30
	v_mul_u32_u24_e32 v6, 0x180, v6
	v_lshlrev_b32_e32 v6, 2, v6
	v_lshl_add_u64 v[88:89], v[10:11], 0, v[6:7]
	v_or_b32_e32 v6, s16, v32
	v_mul_u32_u24_e32 v6, 0x180, v6
	v_lshlrev_b32_e32 v6, 2, v6
	v_lshl_add_u64 v[90:91], v[10:11], 0, v[6:7]
	v_or_b32_e32 v6, s16, v34
	v_mul_u32_u24_e32 v6, 0x180, v6
	v_lshlrev_b32_e32 v6, 2, v6
	v_lshl_add_u64 v[92:93], v[10:11], 0, v[6:7]
	v_or_b32_e32 v6, s16, v36
	v_mul_u32_u24_e32 v6, 0x180, v6
	v_lshlrev_b32_e32 v6, 2, v6
	v_lshl_add_u64 v[94:95], v[10:11], 0, v[6:7]
	v_or_b32_e32 v6, s16, v38
	v_mul_u32_u24_e32 v6, 0x180, v6
	v_lshlrev_b32_e32 v6, 2, v6
	v_lshl_add_u64 v[96:97], v[10:11], 0, v[6:7]
	v_or_b32_e32 v6, s16, v40
	v_mul_u32_u24_e32 v6, 0x180, v6
	v_lshlrev_b32_e32 v6, 2, v6
	v_lshl_add_u64 v[98:99], v[10:11], 0, v[6:7]
	v_or_b32_e32 v6, s16, v42
	v_mul_u32_u24_e32 v6, 0x180, v6
	v_lshlrev_b32_e32 v6, 2, v6
	v_lshl_add_u64 v[100:101], v[10:11], 0, v[6:7]
	v_or_b32_e32 v6, s16, v44
	v_mul_u32_u24_e32 v6, 0x180, v6
	v_lshlrev_b32_e32 v6, 2, v6
	global_load_dword v110, v[12:13], off
	global_load_dword v111, v[88:89], off
	global_load_dword v112, v[90:91], off
	global_load_dword v113, v[92:93], off
	global_load_dword v114, v[94:95], off
	global_load_dword v115, v[96:97], off
	global_load_dword v116, v[98:99], off
	global_load_dword v117, v[100:101], off
	v_lshl_add_u64 v[12:13], v[10:11], 0, v[6:7]
	v_or_b32_e32 v6, s16, v46
	v_mul_u32_u24_e32 v6, 0x180, v6
	v_lshlrev_b32_e32 v6, 2, v6
	v_lshl_add_u64 v[88:89], v[10:11], 0, v[6:7]
	v_or_b32_e32 v6, s16, v48
	v_mul_u32_u24_e32 v6, 0x180, v6
	v_lshlrev_b32_e32 v6, 2, v6
	v_lshl_add_u64 v[90:91], v[10:11], 0, v[6:7]
	v_or_b32_e32 v6, s16, v50
	v_mul_u32_u24_e32 v6, 0x180, v6
	v_lshlrev_b32_e32 v6, 2, v6
	v_lshl_add_u64 v[92:93], v[10:11], 0, v[6:7]
	v_or_b32_e32 v6, s16, v52
	v_mul_u32_u24_e32 v6, 0x180, v6
	v_lshlrev_b32_e32 v6, 2, v6
	v_lshl_add_u64 v[94:95], v[10:11], 0, v[6:7]
	v_or_b32_e32 v6, s16, v54
	v_mul_u32_u24_e32 v6, 0x180, v6
	v_lshlrev_b32_e32 v6, 2, v6
	v_lshl_add_u64 v[96:97], v[10:11], 0, v[6:7]
	v_or_b32_e32 v6, s16, v56
	v_mul_u32_u24_e32 v6, 0x180, v6
	v_lshlrev_b32_e32 v6, 2, v6
	v_lshl_add_u64 v[98:99], v[10:11], 0, v[6:7]
	v_or_b32_e32 v6, s16, v58
	v_mul_u32_u24_e32 v6, 0x180, v6
	v_lshlrev_b32_e32 v6, 2, v6
	v_lshl_add_u64 v[100:101], v[10:11], 0, v[6:7]
	v_or_b32_e32 v6, s16, v60
	v_mul_u32_u24_e32 v6, 0x180, v6
	v_lshlrev_b32_e32 v6, 2, v6
	global_load_dword v118, v[12:13], off
	global_load_dword v119, v[88:89], off
	global_load_dword v120, v[90:91], off
	global_load_dword v121, v[92:93], off
	global_load_dword v122, v[94:95], off
	global_load_dword v123, v[96:97], off
	global_load_dword v124, v[98:99], off
	s_nop 0
	global_load_dword v100, v[100:101], off
	v_lshl_add_u64 v[12:13], v[10:11], 0, v[6:7]
	v_or_b32_e32 v6, s16, v62
	v_mul_u32_u24_e32 v6, 0x180, v6
	v_lshlrev_b32_e32 v6, 2, v6
	v_lshl_add_u64 v[88:89], v[10:11], 0, v[6:7]
	v_or_b32_e32 v6, s16, v64
	v_mul_u32_u24_e32 v6, 0x180, v6
	v_lshlrev_b32_e32 v6, 2, v6
	v_lshl_add_u64 v[90:91], v[10:11], 0, v[6:7]
	v_or_b32_e32 v6, s16, v71
	v_mul_u32_u24_e32 v6, 0x180, v6
	v_lshlrev_b32_e32 v6, 2, v6
	v_lshl_add_u64 v[92:93], v[10:11], 0, v[6:7]
	v_or_b32_e32 v6, s16, v73
	v_mul_u32_u24_e32 v6, 0x180, v6
	v_lshlrev_b32_e32 v6, 2, v6
	v_lshl_add_u64 v[94:95], v[10:11], 0, v[6:7]
	v_or_b32_e32 v6, s16, v75
	v_mul_u32_u24_e32 v6, 0x180, v6
	v_lshlrev_b32_e32 v6, 2, v6
	v_lshl_add_u64 v[96:97], v[10:11], 0, v[6:7]
	v_or_b32_e32 v6, s16, v77
	v_mul_u32_u24_e32 v6, 0x180, v6
	v_lshlrev_b32_e32 v6, 2, v6
	v_lshl_add_u64 v[98:99], v[10:11], 0, v[6:7]
	v_or_b32_e32 v6, s16, v79
	v_mul_u32_u24_e32 v6, 0x180, v6
	v_lshlrev_b32_e32 v6, 2, v6
	v_lshl_add_u64 v[10:11], v[10:11], 0, v[6:7]
	global_load_dword v6, v[12:13], off
	s_nop 0
	global_load_dword v12, v[88:89], off
	global_load_dword v13, v[90:91], off
	s_nop 0
	global_load_dword v88, v[92:93], off
	global_load_dword v89, v[94:95], off
	global_load_dword v90, v[96:97], off
	global_load_dword v91, v[98:99], off
	s_nop 0
	global_load_dword v10, v[10:11], off
	s_lshl_b32 s1, s1, 7
	s_add_u32 s16, s12, s1
	s_addc_u32 s17, s15, 0
	v_readlane_b32 s53, v253, 17
	v_readlane_b32 s54, v253, 18
	v_readlane_b32 s55, v253, 19
	v_readlane_b32 s56, v253, 20
	v_readlane_b32 s57, v253, 21
	v_readlane_b32 s58, v253, 22
	v_readlane_b32 s59, v253, 23
	v_readlane_b32 s62, v253, 26
	v_readlane_b32 s63, v253, 27
	v_readlane_b32 s64, v253, 28
	v_readlane_b32 s65, v253, 29
	v_readlane_b32 s66, v253, 30
	v_readlane_b32 s67, v253, 31
	s_waitcnt vmcnt(0)
; __device__ __forceinline__ unsigned cvt_pk_bf16(float lo, float hi) { typedef float f2 __attribute__((ext_vector_type(2))); typedef __bf16 b2 __attribute__((ext_vector_type(2))); f2 v = {lo, hi}; b2 b = __builtin_convertvector(v, b2); return __builtin_bit_cast(unsigned, b); }
; __device__ __forceinline__ void transpose_item(const float* W, int K, int N, bf16_t* WT, int n0d, int n0s, float scale, int k0, float* scr, int lane, bool gperm = false, const float* kgain = nullptr) {
;     ...
;     __builtin_amdgcn_wave_barrier(); asm volatile("s_waitcnt lgkmcnt(0)" ::: "memory");
;     const int c = lane & 7;
; #pragma unroll
;     for (int j = 0; j < 4; ++j) { const int n = (lane >> 3) + 8 * j; const float* s = scr + (8 * c) * 33 + n;
;         u32x4 o; o.x = cvt_pk_bf16(s[0 * 33], s[1 * 33]); o.y = cvt_pk_bf16(s[2 * 33], s[3 * 33]); o.z = cvt_pk_bf16(s[4 * 33], s[5 * 33]); o.w = cvt_pk_bf16(s[6 * 33], s[7 * 33]);
;         *(u32x4*)(WT + (size_t)(n0d + n) * K + k0 + 8 * c) = o; }
;     __builtin_amdgcn_wave_barrier(); asm volatile("s_waitcnt lgkmcnt(0)" ::: "memory");
	ds_write_b32 v9, v102
	ds_write_b32 v15, v103
	ds_write_b32 v17, v104
	ds_write_b32 v19, v105
	ds_write_b32 v21, v106
	ds_write_b32 v23, v107
	ds_write_b32 v25, v108
	ds_write_b32 v27, v109
	ds_write_b32 v29, v110
	ds_write_b32 v31, v111
	ds_write_b32 v33, v112
	ds_write_b32 v35, v113
	ds_write_b32 v37, v114
	ds_write_b32 v39, v115
	ds_write_b32 v41, v116
	ds_write_b32 v43, v117
	ds_write_b32 v45, v118
	ds_write_b32 v47, v119
	ds_write_b32 v49, v120
	ds_write_b32 v51, v121
	ds_write_b32 v53, v122
	ds_write_b32 v55, v123
	ds_write_b32 v57, v124
	ds_write_b32 v59, v100
	ds_write_b32 v61, v6
	ds_write_b32 v63, v12
	ds_write_b32 v65, v13
	ds_write_b32 v72, v88
	ds_write_b32 v74, v89
	ds_write_b32 v76, v90
	ds_write_b32 v78, v91
	ds_write_b32 v80, v10
	s_waitcnt lgkmcnt(0)
	ds_read_b32 v10, v67
	ds_read_b32 v11, v67 offset:132
	ds_read_b32 v12, v67 offset:264
	ds_read_b32 v13, v67 offset:396
	ds_read_b32 v90, v67 offset:528
	ds_read_b32 v91, v67 offset:660
	ds_read_b32 v92, v67 offset:792
	ds_read_b32 v93, v67 offset:924
	v_lshlrev_b32_e32 v6, 1, v8
	v_lshl_add_u64 v[88:89], s[16:17], 0, v[6:7]
	v_or_b32_e32 v6, s0, v66
	v_mul_u32_u24_e32 v6, 0xc0, v6
	v_lshlrev_b32_e32 v6, 1, v6
	s_waitcnt lgkmcnt(0)
	v_cvt_pk_bf16_f32 v10, v10, v11
	v_cvt_pk_bf16_f32 v11, v12, v13
	v_cvt_pk_bf16_f32 v12, v90, v91
	v_cvt_pk_bf16_f32 v13, v92, v93
	v_lshl_add_u64 v[90:91], v[88:89], 0, v[6:7]
	global_store_dwordx4 v[90:91], v[10:13], off
	ds_read_b32 v6, v67 offset:32
	ds_read_b32 v10, v67 offset:164
	ds_read_b32 v11, v67 offset:296
	ds_read_b32 v12, v67 offset:428
	ds_read_b32 v13, v67 offset:560
	ds_read_b32 v90, v67 offset:692
	ds_read_b32 v91, v67 offset:824
	ds_read_b32 v92, v67 offset:956
	s_waitcnt lgkmcnt(0)
	v_cvt_pk_bf16_f32 v10, v6, v10
	v_or_b32_e32 v6, s0, v81
	v_mul_u32_u24_e32 v6, 0xc0, v6
	v_lshlrev_b32_e32 v6, 1, v6
	v_cvt_pk_bf16_f32 v11, v11, v12
	v_cvt_pk_bf16_f32 v12, v13, v90
	v_cvt_pk_bf16_f32 v13, v91, v92
	v_lshl_add_u64 v[90:91], v[88:89], 0, v[6:7]
	global_store_dwordx4 v[90:91], v[10:13], off
	ds_read_b32 v6, v67 offset:64
	ds_read_b32 v10, v67 offset:196
	ds_read_b32 v11, v67 offset:328
	ds_read_b32 v12, v67 offset:460
	ds_read_b32 v13, v67 offset:592
	ds_read_b32 v90, v67 offset:724
	ds_read_b32 v91, v67 offset:856
	ds_read_b32 v92, v67 offset:988
	s_waitcnt lgkmcnt(0)
	v_cvt_pk_bf16_f32 v10, v6, v10
	v_or_b32_e32 v6, s0, v82
	v_mul_u32_u24_e32 v6, 0xc0, v6
	v_lshlrev_b32_e32 v6, 1, v6
	v_cvt_pk_bf16_f32 v11, v11, v12
	v_cvt_pk_bf16_f32 v12, v13, v90
	v_cvt_pk_bf16_f32 v13, v91, v92
	v_lshl_add_u64 v[90:91], v[88:89], 0, v[6:7]
	global_store_dwordx4 v[90:91], v[10:13], off
	ds_read_b32 v6, v67 offset:96
	ds_read_b32 v10, v67 offset:228
	ds_read_b32 v11, v67 offset:360
	ds_read_b32 v12, v67 offset:492
	ds_read_b32 v13, v67 offset:624
	ds_read_b32 v90, v67 offset:756
	ds_read_b32 v91, v67 offset:888
	ds_read_b32 v92, v67 offset:1020
	s_waitcnt lgkmcnt(0)
	v_cvt_pk_bf16_f32 v10, v6, v10
	v_or_b32_e32 v6, s0, v83
	v_mul_u32_u24_e32 v6, 0xc0, v6
	v_lshlrev_b32_e32 v6, 1, v6
	v_cvt_pk_bf16_f32 v11, v11, v12
	v_cvt_pk_bf16_f32 v12, v13, v90
	v_cvt_pk_bf16_f32 v13, v91, v92
	v_lshl_add_u64 v[88:89], v[88:89], 0, v[6:7]
	global_store_dwordx4 v[88:89], v[10:13], off
	s_waitcnt lgkmcnt(0)

; __device__ __forceinline__ void transpose_item(const float* W, int K, int N, bf16_t* WT, int n0d, int n0s, float scale, int k0, float* scr, int lane, bool gperm = false, const float* kgain = nullptr) {
;     ...
;     } else if (n0s >= 0) {
; #pragma unroll
;         for (int i = 0; i < 32; ++i) { const int kk = 2 * i + (lane >> 5); scr[kk * 33 + (lane & 31)] = W[(size_t)(k0 + kk) * N + n0s + (lane & 31)] * (kgain ? scale * kgain[k0 + kk] : scale); }
;     } else {
; __device__ __forceinline__ void prologue(const Args& a, unsigned char* ws, char* lds, int gw, int NGW, int wave, int lane) {
;     ...
;         if (r < I_FO) { const int nb = r % 32, kb = r / 32;
;             transpose_item(a.in[22] + (size_t)l * FF * DM, FF, DM, (bf16_t*)(ws + WS_WFO) + (size_t)l * DM * FF, nb * 32, nb * 32, 1.f, kb * 64, scr, lane); continue; }
.LBB0_21:
	s_andn2_b64 vcc, exec, s[0:1]
	s_cbranch_vccnz .LBB0_23
	v_readlane_b32 s52, v253, 32
	s_mul_i32 s1, s14, 0xb00000
	v_readlane_b32 s64, v253, 44
	s_mul_hi_i32 s0, s14, 0xb00000
	v_readlane_b32 s65, v253, 45
	s_add_u32 s16, s64, s1
	s_addc_u32 s17, s65, s0
	s_mul_i32 s1, s14, 0x580000
	s_mul_hi_i32 s0, s14, 0x580000
	s_add_u32 s1, s30, s1
	s_addc_u32 s15, s31, s0
	s_lshl_b32 s0, s14, 7
	s_mul_i32 s12, s14, 0xffffbc78
	s_sub_i32 s0, s43, s0
	s_add_i32 s12, s41, s12
	s_and_b32 s0, s0, 0x3e0
	s_and_b32 s12, s12, 0x7fc0
	s_addk_i32 s12, 0xc800
	s_lshl_b32 s19, s0, 2
	s_add_u32 s16, s16, s19
	s_addc_u32 s17, s17, 0
	v_lshlrev_b32_e32 v6, 2, v4
	v_lshl_add_u64 v[10:11], s[16:17], 0, v[6:7]
	v_or_b32_e32 v6, s12, v2
	v_lshlrev_b64 v[12:13], 12, v[6:7]
	v_or_b32_e32 v6, s12, v14
	v_lshlrev_b64 v[88:89], 12, v[6:7]
	v_or_b32_e32 v6, s12, v16
	v_lshlrev_b64 v[90:91], 12, v[6:7]
	v_or_b32_e32 v6, s12, v18
	v_lshlrev_b64 v[92:93], 12, v[6:7]
	v_or_b32_e32 v6, s12, v20
	v_lshlrev_b64 v[94:95], 12, v[6:7]
	v_or_b32_e32 v6, s12, v22
	v_lshlrev_b64 v[96:97], 12, v[6:7]
	v_or_b32_e32 v6, s12, v24
	v_lshlrev_b64 v[98:99], 12, v[6:7]
	v_or_b32_e32 v6, s12, v26
	v_lshl_add_u64 v[12:13], v[10:11], 0, v[12:13]
	v_lshlrev_b64 v[100:101], 12, v[6:7]
	v_or_b32_e32 v6, s12, v28
	v_lshl_add_u64 v[88:89], v[10:11], 0, v[88:89]
	v_lshl_add_u64 v[90:91], v[10:11], 0, v[90:91]
	v_lshl_add_u64 v[92:93], v[10:11], 0, v[92:93]
	v_lshl_add_u64 v[94:95], v[10:11], 0, v[94:95]
	v_lshl_add_u64 v[96:97], v[10:11], 0, v[96:97]
	v_lshl_add_u64 v[98:99], v[10:11], 0, v[98:99]
	v_lshl_add_u64 v[100:101], v[10:11], 0, v[100:101]
	global_load_dword v102, v[12:13], off
	global_load_dword v103, v[88:89], off
	global_load_dword v104, v[90:91], off
	global_load_dword v105, v[92:93], off
	global_load_dword v106, v[94:95], off
	global_load_dword v107, v[96:97], off
	global_load_dword v108, v[98:99], off
	global_load_dword v109, v[100:101], off
	v_lshlrev_b64 v[12:13], 12, v[6:7]
	v_or_b32_e32 v6, s12, v30
	v_lshlrev_b64 v[88:89], 12, v[6:7]
	v_or_b32_e32 v6, s12, v32
	v_lshlrev_b64 v[90:91], 12, v[6:7]
	v_or_b32_e32 v6, s12, v34
	v_lshlrev_b64 v[92:93], 12, v[6:7]
	v_or_b32_e32 v6, s12, v36
	v_lshlrev_b64 v[94:95], 12, v[6:7]
	v_or_b32_e32 v6, s12, v38
	v_lshlrev_b64 v[96:97], 12, v[6:7]
	v_or_b32_e32 v6, s12, v40
	v_lshlrev_b64 v[98:99], 12, v[6:7]
	v_or_b32_e32 v6, s12, v42
	v_lshl_add_u64 v[12:13], v[10:11], 0, v[12:13]
	v_lshlrev_b64 v[100:101], 12, v[6:7]
	v_or_b32_e32 v6, s12, v44
	v_lshl_add_u64 v[88:89], v[10:11], 0, v[88:89]
	v_lshl_add_u64 v[90:91], v[10:11], 0, v[90:91]
	v_lshl_add_u64 v[92:93], v[10:11], 0, v[92:93]
	v_lshl_add_u64 v[94:95], v[10:11], 0, v[94:95]
	v_lshl_add_u64 v[96:97], v[10:11], 0, v[96:97]
	v_lshl_add_u64 v[98:99], v[10:11], 0, v[98:99]
	v_lshl_add_u64 v[100:101], v[10:11], 0, v[100:101]
	global_load_dword v110, v[12:13], off
	global_load_dword v111, v[88:89], off
	global_load_dword v112, v[90:91], off
	global_load_dword v113, v[92:93], off
	global_load_dword v114, v[94:95], off
	global_load_dword v115, v[96:97], off
	global_load_dword v116, v[98:99], off
	global_load_dword v117, v[100:101], off
	v_lshlrev_b64 v[12:13], 12, v[6:7]
	v_or_b32_e32 v6, s12, v46
	v_lshlrev_b64 v[88:89], 12, v[6:7]
	v_or_b32_e32 v6, s12, v48
	v_lshlrev_b64 v[90:91], 12, v[6:7]
	v_or_b32_e32 v6, s12, v50
	v_lshlrev_b64 v[92:93], 12, v[6:7]
	v_or_b32_e32 v6, s12, v52
	v_lshlrev_b64 v[94:95], 12, v[6:7]
	v_or_b32_e32 v6, s12, v54
	v_lshlrev_b64 v[96:97], 12, v[6:7]
	v_or_b32_e32 v6, s12, v56
	v_lshlrev_b64 v[98:99], 12, v[6:7]
	v_or_b32_e32 v6, s12, v58
	v_lshl_add_u64 v[12:13], v[10:11], 0, v[12:13]
	v_lshlrev_b64 v[100:101], 12, v[6:7]
	v_or_b32_e32 v6, s12, v60
	v_lshl_add_u64 v[88:89], v[10:11], 0, v[88:89]
	v_lshl_add_u64 v[90:91], v[10:11], 0, v[90:91]
	v_lshl_add_u64 v[92:93], v[10:11], 0, v[92:93]
	v_lshl_add_u64 v[94:95], v[10:11], 0, v[94:95]
	v_lshl_add_u64 v[96:97], v[10:11], 0, v[96:97]
	v_lshl_add_u64 v[98:99], v[10:11], 0, v[98:99]
	v_lshl_add_u64 v[100:101], v[10:11], 0, v[100:101]
	global_load_dword v118, v[12:13], off
	global_load_dword v119, v[88:89], off
	global_load_dword v120, v[90:91], off
	global_load_dword v121, v[92:93], off
	global_load_dword v122, v[94:95], off
	global_load_dword v123, v[96:97], off
	global_load_dword v124, v[98:99], off
	global_load_dword v125, v[100:101], off
	v_lshlrev_b64 v[12:13], 12, v[6:7]
	v_or_b32_e32 v6, s12, v62
	v_lshlrev_b64 v[88:89], 12, v[6:7]
	v_or_b32_e32 v6, s12, v64
	v_lshlrev_b64 v[90:91], 12, v[6:7]
	v_or_b32_e32 v6, s12, v71
	v_lshlrev_b64 v[92:93], 12, v[6:7]
	v_or_b32_e32 v6, s12, v73
	v_lshlrev_b64 v[94:95], 12, v[6:7]
	v_or_b32_e32 v6, s12, v75
	v_lshlrev_b64 v[96:97], 12, v[6:7]
	v_or_b32_e32 v6, s12, v77
	v_lshlrev_b64 v[98:99], 12, v[6:7]
	v_or_b32_e32 v6, s12, v79
	v_lshlrev_b64 v[100:101], 12, v[6:7]
	v_lshl_add_u64 v[12:13], v[10:11], 0, v[12:13]
	v_lshl_add_u64 v[88:89], v[10:11], 0, v[88:89]
	v_lshl_add_u64 v[90:91], v[10:11], 0, v[90:91]
	v_lshl_add_u64 v[92:93], v[10:11], 0, v[92:93]
	v_lshl_add_u64 v[94:95], v[10:11], 0, v[94:95]
	v_lshl_add_u64 v[96:97], v[10:11], 0, v[96:97]
	v_lshl_add_u64 v[98:99], v[10:11], 0, v[98:99]
	v_lshl_add_u64 v[10:11], v[10:11], 0, v[100:101]
	global_load_dword v6, v[12:13], off
	s_nop 0
	global_load_dword v12, v[88:89], off
	global_load_dword v13, v[90:91], off
	s_nop 0
	global_load_dword v88, v[92:93], off
	global_load_dword v89, v[94:95], off
	global_load_dword v90, v[96:97], off
	global_load_dword v91, v[98:99], off
	s_nop 0
	global_load_dword v10, v[10:11], off
	s_lshl_b64 s[16:17], s[12:13], 1
	s_add_u32 s16, s1, s16
	s_waitcnt vmcnt(0)
; __device__ __forceinline__ unsigned cvt_pk_bf16(float lo, float hi) { typedef float f2 __attribute__((ext_vector_type(2))); typedef __bf16 b2 __attribute__((ext_vector_type(2))); f2 v = {lo, hi}; b2 b = __builtin_convertvector(v, b2); return __builtin_bit_cast(unsigned, b); }
; __device__ __forceinline__ void transpose_item(const float* W, int K, int N, bf16_t* WT, int n0d, int n0s, float scale, int k0, float* scr, int lane, bool gperm = false, const float* kgain = nullptr) {
;     ...
;     __builtin_amdgcn_wave_barrier(); asm volatile("s_waitcnt lgkmcnt(0)" ::: "memory");
;     const int c = lane & 7;
; #pragma unroll
;     for (int j = 0; j < 4; ++j) { const int n = (lane >> 3) + 8 * j; const float* s = scr + (8 * c) * 33 + n;
;         u32x4 o; o.x = cvt_pk_bf16(s[0 * 33], s[1 * 33]); o.y = cvt_pk_bf16(s[2 * 33], s[3 * 33]); o.z = cvt_pk_bf16(s[4 * 33], s[5 * 33]); o.w = cvt_pk_bf16(s[6 * 33], s[7 * 33]);
;         *(u32x4*)(WT + (size_t)(n0d + n) * K + k0 + 8 * c) = o; }
;     __builtin_amdgcn_wave_barrier(); asm volatile("s_waitcnt lgkmcnt(0)" ::: "memory");
	ds_write_b32 v9, v102
	ds_write_b32 v15, v103
	ds_write_b32 v17, v104
	ds_write_b32 v19, v105
	ds_write_b32 v21, v106
	ds_write_b32 v23, v107
	ds_write_b32 v25, v108
	ds_write_b32 v27, v109
	ds_write_b32 v29, v110
	ds_write_b32 v31, v111
	ds_write_b32 v33, v112
	ds_write_b32 v35, v113
	ds_write_b32 v37, v114
	ds_write_b32 v39, v115
	ds_write_b32 v41, v116
	ds_write_b32 v43, v117
	ds_write_b32 v45, v118
	ds_write_b32 v47, v119
	ds_write_b32 v49, v120
	ds_write_b32 v51, v121
	ds_write_b32 v53, v122
	ds_write_b32 v55, v123
	ds_write_b32 v57, v124
	ds_write_b32 v59, v125
	ds_write_b32 v61, v6
	ds_write_b32 v63, v12
	ds_write_b32 v65, v13
	ds_write_b32 v72, v88
	ds_write_b32 v74, v89
	ds_write_b32 v76, v90
	ds_write_b32 v78, v91
	ds_write_b32 v80, v10
	s_waitcnt lgkmcnt(0)
	ds_read_b32 v10, v67
	ds_read_b32 v11, v67 offset:132
	ds_read_b32 v12, v67 offset:264
	ds_read_b32 v13, v67 offset:396
	ds_read_b32 v90, v67 offset:528
	ds_read_b32 v91, v67 offset:660
	ds_read_b32 v92, v67 offset:792
	ds_read_b32 v93, v67 offset:924
	s_addc_u32 s17, s15, s17
	v_lshlrev_b32_e32 v6, 1, v8
	v_lshl_add_u64 v[88:89], s[16:17], 0, v[6:7]
	v_or_b32_e32 v6, s0, v66
	v_mul_u32_u24_e32 v6, 0xb00, v6
	v_lshlrev_b32_e32 v6, 1, v6
	s_waitcnt lgkmcnt(0)
	v_cvt_pk_bf16_f32 v10, v10, v11
	v_cvt_pk_bf16_f32 v11, v12, v13
	v_cvt_pk_bf16_f32 v12, v90, v91
	v_cvt_pk_bf16_f32 v13, v92, v93
	v_lshl_add_u64 v[90:91], v[88:89], 0, v[6:7]
	global_store_dwordx4 v[90:91], v[10:13], off
	ds_read_b32 v6, v67 offset:32
	ds_read_b32 v10, v67 offset:164
	ds_read_b32 v11, v67 offset:296
	ds_read_b32 v12, v67 offset:428
	ds_read_b32 v13, v67 offset:560
	ds_read_b32 v90, v67 offset:692
	ds_read_b32 v91, v67 offset:824
	ds_read_b32 v92, v67 offset:956
	s_waitcnt lgkmcnt(0)
	v_cvt_pk_bf16_f32 v10, v6, v10
	v_or_b32_e32 v6, s0, v81
	v_mul_u32_u24_e32 v6, 0xb00, v6
	v_lshlrev_b32_e32 v6, 1, v6
	v_cvt_pk_bf16_f32 v11, v11, v12
	v_cvt_pk_bf16_f32 v12, v13, v90
	v_cvt_pk_bf16_f32 v13, v91, v92
	v_lshl_add_u64 v[90:91], v[88:89], 0, v[6:7]
	global_store_dwordx4 v[90:91], v[10:13], off
	ds_read_b32 v6, v67 offset:64
	ds_read_b32 v10, v67 offset:196
	ds_read_b32 v11, v67 offset:328
	ds_read_b32 v12, v67 offset:460
	ds_read_b32 v13, v67 offset:592
	ds_read_b32 v90, v67 offset:724
	ds_read_b32 v91, v67 offset:856
	ds_read_b32 v92, v67 offset:988
	s_waitcnt lgkmcnt(0)
	v_cvt_pk_bf16_f32 v10, v6, v10
	v_or_b32_e32 v6, s0, v82
	v_mul_u32_u24_e32 v6, 0xb00, v6
	v_lshlrev_b32_e32 v6, 1, v6
	v_cvt_pk_bf16_f32 v11, v11, v12
	v_cvt_pk_bf16_f32 v12, v13, v90
	v_cvt_pk_bf16_f32 v13, v91, v92
	v_lshl_add_u64 v[90:91], v[88:89], 0, v[6:7]
	global_store_dwordx4 v[90:91], v[10:13], off
	ds_read_b32 v6, v67 offset:96
	ds_read_b32 v10, v67 offset:228
	ds_read_b32 v11, v67 offset:360
	ds_read_b32 v12, v67 offset:492
	ds_read_b32 v13, v67 offset:624
	ds_read_b32 v90, v67 offset:756
	ds_read_b32 v91, v67 offset:888
	ds_read_b32 v92, v67 offset:1020
	s_waitcnt lgkmcnt(0)
	v_cvt_pk_bf16_f32 v10, v6, v10
	v_or_b32_e32 v6, s0, v83
	v_mul_u32_u24_e32 v6, 0xb00, v6
	v_lshlrev_b32_e32 v6, 1, v6
	v_cvt_pk_bf16_f32 v11, v11, v12
	v_cvt_pk_bf16_f32 v12, v13, v90
	v_cvt_pk_bf16_f32 v13, v91, v92
	v_lshl_add_u64 v[88:89], v[88:89], 0, v[6:7]
	global_store_dwordx4 v[88:89], v[10:13], off
	s_waitcnt lgkmcnt(0)
	v_readlane_b32 s53, v253, 33
	v_readlane_b32 s54, v253, 34
	v_readlane_b32 s55, v253, 35
	v_readlane_b32 s56, v253, 36
	v_readlane_b32 s57, v253, 37
	v_readlane_b32 s58, v253, 38
	v_readlane_b32 s59, v253, 39
	v_readlane_b32 s60, v253, 40
	v_readlane_b32 s61, v253, 41
	v_readlane_b32 s62, v253, 42
	v_readlane_b32 s63, v253, 43
	v_readlane_b32 s66, v253, 46
	v_readlane_b32 s67, v253, 47

; __device__ __forceinline__ unsigned cvt_pk_bf16(float lo, float hi) { typedef float f2 __attribute__((ext_vector_type(2))); typedef __bf16 b2 __attribute__((ext_vector_type(2))); f2 v = {lo, hi}; b2 b = __builtin_convertvector(v, b2); return __builtin_bit_cast(unsigned, b); }
; __device__ __forceinline__ void transpose_item(const float* W, int K, int N, bf16_t* WT, int n0d, int n0s, float scale, int k0, float* scr, int lane, bool gperm = false, const float* kgain = nullptr) {
;     ...
;         for (int i = 0; i < 32; ++i) { const int kk = 2 * i + (lane >> 5); scr[kk * 33 + (lane & 31)] = W[(size_t)(k0 + kk) * N + n0s + (lane & 31)] * (kgain ? scale * kgain[k0 + kk] : scale); }
;     } else {
; #pragma unroll
;         for (int i = 0; i < 32; ++i) { const int kk = 2 * i + (lane >> 5); scr[kk * 33 + (lane & 31)] = 0.f; }
;     }
;     __builtin_amdgcn_wave_barrier(); asm volatile("s_waitcnt lgkmcnt(0)" ::: "memory");
;     const int c = lane & 7;
; #pragma unroll
;     for (int j = 0; j < 4; ++j) { const int n = (lane >> 3) + 8 * j; const float* s = scr + (8 * c) * 33 + n;
;         u32x4 o; o.x = cvt_pk_bf16(s[0 * 33], s[1 * 33]); o.y = cvt_pk_bf16(s[2 * 33], s[3 * 33]); o.z = cvt_pk_bf16(s[4 * 33], s[5 * 33]); o.w = cvt_pk_bf16(s[6 * 33], s[7 * 33]);
;         *(u32x4*)(WT + (size_t)(n0d + n) * K + k0 + 8 * c) = o; }
;     __builtin_amdgcn_wave_barrier(); asm volatile("s_waitcnt lgkmcnt(0)" ::: "memory");
; __device__ __forceinline__ void prologue(const Args& a, unsigned char* ws, char* lds, int gw, int NGW, int wave, int lane) {
;     ...
;         if (r < I_FI) { const int nb = r % (NUG / 32), kb = r / (NUG / 32);
;             const int n0d = nb * 32, src0 = ((n0d >> 7) & 1) * FF + (n0d >> 8) * 128 + (n0d & 127);
;             transpose_item(a.in[19] + (size_t)l * DM * NUG, DM, NUG, (bf16_t*)(ws + WS_WFI) + (size_t)l * NUG * DM, n0d, src0, 1.f, kb * 64, scr, lane, false, a.in[18] + l * DM); continue; }
.Lpro1_nokg:
	s_waitcnt vmcnt(0)
	v_mul_f32_e32 v126, v126, v194
	ds_write_b32 v9, v126
	v_mul_f32_e32 v127, v127, v195
	ds_write_b32 v15, v127
	v_mul_f32_e32 v128, v128, v196
	ds_write_b32 v17, v128
	v_mul_f32_e32 v129, v129, v197
	ds_write_b32 v19, v129
	v_mul_f32_e32 v130, v130, v198
	ds_write_b32 v21, v130
	v_mul_f32_e32 v131, v131, v199
	ds_write_b32 v23, v131
	v_mul_f32_e32 v132, v132, v200
	ds_write_b32 v25, v132
	v_mul_f32_e32 v133, v133, v201
	ds_write_b32 v27, v133
	v_mul_f32_e32 v134, v134, v202
	ds_write_b32 v29, v134
	v_mul_f32_e32 v135, v135, v203
	ds_write_b32 v31, v135
	v_mul_f32_e32 v136, v136, v204
	ds_write_b32 v33, v136
	v_mul_f32_e32 v137, v137, v205
	ds_write_b32 v35, v137
	v_mul_f32_e32 v138, v138, v206
	ds_write_b32 v37, v138
	v_mul_f32_e32 v139, v139, v207
	ds_write_b32 v39, v139
	v_mul_f32_e32 v140, v140, v208
	ds_write_b32 v41, v140
	v_mul_f32_e32 v141, v141, v209
	ds_write_b32 v43, v141
	v_mul_f32_e32 v142, v142, v210
	ds_write_b32 v45, v142
	v_mul_f32_e32 v143, v143, v211
	ds_write_b32 v47, v143
	v_mul_f32_e32 v144, v144, v212
	ds_write_b32 v49, v144
	v_mul_f32_e32 v145, v145, v213
	ds_write_b32 v51, v145
	v_mul_f32_e32 v146, v146, v214
	ds_write_b32 v53, v146
	v_mul_f32_e32 v147, v147, v215
	ds_write_b32 v55, v147
	v_mul_f32_e32 v148, v148, v216
	ds_write_b32 v57, v148
	v_mul_f32_e32 v149, v149, v217
	ds_write_b32 v59, v149
	v_mul_f32_e32 v150, v150, v218
	ds_write_b32 v61, v150
	v_mul_f32_e32 v151, v151, v219
	ds_write_b32 v63, v151
	v_mul_f32_e32 v152, v152, v220
	ds_write_b32 v65, v152
	v_mul_f32_e32 v153, v153, v221
	ds_write_b32 v72, v153
	v_mul_f32_e32 v154, v154, v222
	ds_write_b32 v74, v154
	v_mul_f32_e32 v155, v155, v223
	ds_write_b32 v76, v155
	v_mul_f32_e32 v156, v156, v224
	ds_write_b32 v78, v156
	v_mul_f32_e32 v157, v157, v225
	ds_write_b32 v80, v157
	s_mul_i32 s1, s14, 0xb00000
	s_mul_hi_i32 s0, s14, 0xb00000
	s_add_u32 s1, s33, s1
	s_waitcnt lgkmcnt(0)
	s_addc_u32 s16, s34, s0
	s_lshl_b32 s0, s15, 1
	ds_read_b32 v10, v67
	ds_read_b32 v11, v67 offset:132
	ds_read_b32 v12, v67 offset:264
	ds_read_b32 v13, v67 offset:396
	ds_read_b32 v90, v67 offset:528
	ds_read_b32 v91, v67 offset:660
	ds_read_b32 v92, v67 offset:792
	ds_read_b32 v93, v67 offset:924
	s_add_u32 s0, s1, s0
	s_addc_u32 s1, s16, 0
	v_lshlrev_b32_e32 v6, 1, v8
	v_lshl_add_u64 v[88:89], s[0:1], 0, v[6:7]
	v_or_b32_e32 v6, s12, v66
	v_lshlrev_b32_e32 v6, 11, v6
	s_waitcnt lgkmcnt(0)
	v_cvt_pk_bf16_f32 v10, v10, v11
	v_cvt_pk_bf16_f32 v11, v12, v13
	v_cvt_pk_bf16_f32 v12, v90, v91
	v_cvt_pk_bf16_f32 v13, v92, v93
	v_lshl_add_u64 v[90:91], v[88:89], 0, v[6:7]
	global_store_dwordx4 v[90:91], v[10:13], off
	ds_read_b32 v6, v67 offset:32
	ds_read_b32 v10, v67 offset:164
	ds_read_b32 v11, v67 offset:296
	ds_read_b32 v12, v67 offset:428
	ds_read_b32 v13, v67 offset:560
	ds_read_b32 v90, v67 offset:692
	ds_read_b32 v91, v67 offset:824
	ds_read_b32 v92, v67 offset:956
	s_waitcnt lgkmcnt(0)
	v_cvt_pk_bf16_f32 v10, v6, v10
	v_or_b32_e32 v6, s12, v81
	v_lshlrev_b32_e32 v6, 11, v6
	v_cvt_pk_bf16_f32 v11, v11, v12
	v_cvt_pk_bf16_f32 v12, v13, v90
	v_cvt_pk_bf16_f32 v13, v91, v92
	v_lshl_add_u64 v[90:91], v[88:89], 0, v[6:7]
	global_store_dwordx4 v[90:91], v[10:13], off
	ds_read_b32 v6, v67 offset:64
	ds_read_b32 v10, v67 offset:196
	ds_read_b32 v11, v67 offset:328
	ds_read_b32 v12, v67 offset:460
	ds_read_b32 v13, v67 offset:592
	ds_read_b32 v90, v67 offset:724
	ds_read_b32 v91, v67 offset:856
	ds_read_b32 v92, v67 offset:988
	s_waitcnt lgkmcnt(0)
	v_cvt_pk_bf16_f32 v10, v6, v10
	v_or_b32_e32 v6, s12, v82
	v_lshlrev_b32_e32 v6, 11, v6
	v_cvt_pk_bf16_f32 v11, v11, v12
	v_cvt_pk_bf16_f32 v12, v13, v90
	v_cvt_pk_bf16_f32 v13, v91, v92
	v_lshl_add_u64 v[90:91], v[88:89], 0, v[6:7]
	global_store_dwordx4 v[90:91], v[10:13], off
	ds_read_b32 v6, v67 offset:96
	ds_read_b32 v10, v67 offset:228
	ds_read_b32 v11, v67 offset:360
	ds_read_b32 v12, v67 offset:492
	ds_read_b32 v13, v67 offset:624
	ds_read_b32 v90, v67 offset:756
	ds_read_b32 v91, v67 offset:888
	ds_read_b32 v92, v67 offset:1020
	s_waitcnt lgkmcnt(0)
	v_cvt_pk_bf16_f32 v10, v6, v10
	v_or_b32_e32 v6, s12, v83
	v_lshlrev_b32_e32 v6, 11, v6
	v_cvt_pk_bf16_f32 v11, v11, v12
	v_cvt_pk_bf16_f32 v12, v13, v90
	v_cvt_pk_bf16_f32 v13, v91, v92
	v_lshl_add_u64 v[88:89], v[88:89], 0, v[6:7]
	global_store_dwordx4 v[88:89], v[10:13], off
	s_waitcnt lgkmcnt(0)

; __device__ __forceinline__ void transpose_item(const float* W, int K, int N, bf16_t* WT, int n0d, int n0s, float scale, int k0, float* scr, int lane, bool gperm = false, const float* kgain = nullptr) {
;     ...
;     } else if (n0s >= 0) {
; #pragma unroll
;         for (int i = 0; i < 32; ++i) { const int kk = 2 * i + (lane >> 5); scr[kk * 33 + (lane & 31)] = W[(size_t)(k0 + kk) * N + n0s + (lane & 31)] * (kgain ? scale * kgain[k0 + kk] : scale); }
;     } else {
; __device__ __forceinline__ void prologue(const Args& a, unsigned char* ws, char* lds, int gw, int NGW, int wave, int lane) {
;     ...
;         if (r < I_OUT) { const int nb = r % 32, kb = r / 32;
;             transpose_item(a.in[17] + (size_t)l * DM * DM, DM, DM, (bf16_t*)(ws + WS_WOUT) + (size_t)l * DM * DM, nb * 32, nb * 32, 1.f, kb * 64, scr, lane); continue; }
.LBB0_91:
	s_andn2_b64 vcc, exec, s[0:1]
	s_cbranch_vccnz .LBB0_93
	s_ashr_i32 s15, s14, 31
	v_readlane_b32 s52, v253, 32
	s_lshl_b64 s[0:1], s[14:15], 22
	v_readlane_b32 s54, v253, 34
	v_readlane_b32 s55, v253, 35
	s_add_u32 s19, s54, s0
	s_addc_u32 s20, s55, s1
	s_lshl_b64 s[16:17], s[14:15], 21
	s_add_u32 s1, s35, s16
	s_addc_u32 s15, s36, s17
	s_lshl_b32 s0, s14, 7
	s_mul_i32 s12, s14, 0xffffbc78
	s_sub_i32 s0, s43, s0
	s_add_i32 s12, s41, s12
	s_and_b32 s0, s0, 0x3e0
	s_and_b32 s12, s12, 0x3fc0
	s_addk_i32 s12, 0xe200
	s_lshl_b32 s16, s0, 2
	s_add_u32 s16, s19, s16
	s_addc_u32 s17, s20, 0
	v_lshlrev_b32_e32 v6, 2, v4
	v_lshl_add_u64 v[10:11], s[16:17], 0, v[6:7]
	v_or_b32_e32 v6, s12, v2
	v_lshlrev_b64 v[12:13], 12, v[6:7]
	v_or_b32_e32 v6, s12, v14
	v_lshlrev_b64 v[88:89], 12, v[6:7]
	v_or_b32_e32 v6, s12, v16
	v_lshlrev_b64 v[90:91], 12, v[6:7]
	v_or_b32_e32 v6, s12, v18
	v_lshlrev_b64 v[92:93], 12, v[6:7]
	v_or_b32_e32 v6, s12, v20
	v_lshlrev_b64 v[94:95], 12, v[6:7]
	v_or_b32_e32 v6, s12, v22
	v_lshlrev_b64 v[96:97], 12, v[6:7]
	v_or_b32_e32 v6, s12, v24
	v_lshlrev_b64 v[98:99], 12, v[6:7]
	v_or_b32_e32 v6, s12, v26
	v_lshl_add_u64 v[12:13], v[10:11], 0, v[12:13]
	v_lshlrev_b64 v[100:101], 12, v[6:7]
	v_or_b32_e32 v6, s12, v28
	v_lshl_add_u64 v[88:89], v[10:11], 0, v[88:89]
	v_lshl_add_u64 v[90:91], v[10:11], 0, v[90:91]
	v_lshl_add_u64 v[92:93], v[10:11], 0, v[92:93]
	v_lshl_add_u64 v[94:95], v[10:11], 0, v[94:95]
	v_lshl_add_u64 v[96:97], v[10:11], 0, v[96:97]
	v_lshl_add_u64 v[98:99], v[10:11], 0, v[98:99]
	v_lshl_add_u64 v[100:101], v[10:11], 0, v[100:101]
	global_load_dword v102, v[12:13], off
	global_load_dword v103, v[88:89], off
	global_load_dword v104, v[90:91], off
	global_load_dword v105, v[92:93], off
	global_load_dword v106, v[94:95], off
	global_load_dword v107, v[96:97], off
	global_load_dword v108, v[98:99], off
	global_load_dword v109, v[100:101], off
	v_lshlrev_b64 v[12:13], 12, v[6:7]
	v_or_b32_e32 v6, s12, v30
	v_lshlrev_b64 v[88:89], 12, v[6:7]
	v_or_b32_e32 v6, s12, v32
	v_lshlrev_b64 v[90:91], 12, v[6:7]
	v_or_b32_e32 v6, s12, v34
	v_lshlrev_b64 v[92:93], 12, v[6:7]
	v_or_b32_e32 v6, s12, v36
	v_lshlrev_b64 v[94:95], 12, v[6:7]
	v_or_b32_e32 v6, s12, v38
	v_lshlrev_b64 v[96:97], 12, v[6:7]
	v_or_b32_e32 v6, s12, v40
	v_lshlrev_b64 v[98:99], 12, v[6:7]
	v_or_b32_e32 v6, s12, v42
	v_lshl_add_u64 v[12:13], v[10:11], 0, v[12:13]
	v_lshlrev_b64 v[100:101], 12, v[6:7]
	v_or_b32_e32 v6, s12, v44
	v_lshl_add_u64 v[88:89], v[10:11], 0, v[88:89]
	v_lshl_add_u64 v[90:91], v[10:11], 0, v[90:91]
	v_lshl_add_u64 v[92:93], v[10:11], 0, v[92:93]
	v_lshl_add_u64 v[94:95], v[10:11], 0, v[94:95]
	v_lshl_add_u64 v[96:97], v[10:11], 0, v[96:97]
	v_lshl_add_u64 v[98:99], v[10:11], 0, v[98:99]
	v_lshl_add_u64 v[100:101], v[10:11], 0, v[100:101]
	global_load_dword v110, v[12:13], off
	global_load_dword v111, v[88:89], off
	global_load_dword v112, v[90:91], off
	global_load_dword v113, v[92:93], off
	global_load_dword v114, v[94:95], off
	global_load_dword v115, v[96:97], off
	global_load_dword v116, v[98:99], off
	global_load_dword v117, v[100:101], off
	v_lshlrev_b64 v[12:13], 12, v[6:7]
	v_or_b32_e32 v6, s12, v46
	v_lshlrev_b64 v[88:89], 12, v[6:7]
	v_or_b32_e32 v6, s12, v48
	v_lshlrev_b64 v[90:91], 12, v[6:7]
	v_or_b32_e32 v6, s12, v50
	v_lshlrev_b64 v[92:93], 12, v[6:7]
	v_or_b32_e32 v6, s12, v52
	v_lshlrev_b64 v[94:95], 12, v[6:7]
	v_or_b32_e32 v6, s12, v54
	v_lshlrev_b64 v[96:97], 12, v[6:7]
	v_or_b32_e32 v6, s12, v56
	v_lshlrev_b64 v[98:99], 12, v[6:7]
	v_or_b32_e32 v6, s12, v58
	v_lshl_add_u64 v[12:13], v[10:11], 0, v[12:13]
	v_lshlrev_b64 v[100:101], 12, v[6:7]
	v_or_b32_e32 v6, s12, v60
	v_lshl_add_u64 v[88:89], v[10:11], 0, v[88:89]
	v_lshl_add_u64 v[90:91], v[10:11], 0, v[90:91]
	v_lshl_add_u64 v[92:93], v[10:11], 0, v[92:93]
	v_lshl_add_u64 v[94:95], v[10:11], 0, v[94:95]
	v_lshl_add_u64 v[96:97], v[10:11], 0, v[96:97]
	v_lshl_add_u64 v[98:99], v[10:11], 0, v[98:99]
	v_lshl_add_u64 v[100:101], v[10:11], 0, v[100:101]
	global_load_dword v118, v[12:13], off
	global_load_dword v119, v[88:89], off
	global_load_dword v120, v[90:91], off
	global_load_dword v121, v[92:93], off
	global_load_dword v122, v[94:95], off
	global_load_dword v123, v[96:97], off
	global_load_dword v124, v[98:99], off
	global_load_dword v125, v[100:101], off
	v_lshlrev_b64 v[12:13], 12, v[6:7]
	v_or_b32_e32 v6, s12, v62
	v_lshlrev_b64 v[88:89], 12, v[6:7]
	v_or_b32_e32 v6, s12, v64
	v_lshlrev_b64 v[90:91], 12, v[6:7]
	v_or_b32_e32 v6, s12, v71
	v_lshlrev_b64 v[92:93], 12, v[6:7]
	v_or_b32_e32 v6, s12, v73
	v_lshlrev_b64 v[94:95], 12, v[6:7]
	v_or_b32_e32 v6, s12, v75
	v_lshlrev_b64 v[96:97], 12, v[6:7]
	v_or_b32_e32 v6, s12, v77
	v_lshlrev_b64 v[98:99], 12, v[6:7]
	v_or_b32_e32 v6, s12, v79
	v_lshlrev_b64 v[100:101], 12, v[6:7]
	v_lshl_add_u64 v[12:13], v[10:11], 0, v[12:13]
	v_lshl_add_u64 v[88:89], v[10:11], 0, v[88:89]
	v_lshl_add_u64 v[90:91], v[10:11], 0, v[90:91]
	v_lshl_add_u64 v[92:93], v[10:11], 0, v[92:93]
	v_lshl_add_u64 v[94:95], v[10:11], 0, v[94:95]
	v_lshl_add_u64 v[96:97], v[10:11], 0, v[96:97]
	v_lshl_add_u64 v[98:99], v[10:11], 0, v[98:99]
	v_lshl_add_u64 v[10:11], v[10:11], 0, v[100:101]
	global_load_dword v6, v[12:13], off
	s_nop 0
	global_load_dword v12, v[88:89], off
	global_load_dword v13, v[90:91], off
	s_nop 0
	global_load_dword v88, v[92:93], off
	global_load_dword v89, v[94:95], off
	global_load_dword v90, v[96:97], off
	global_load_dword v91, v[98:99], off
	s_nop 0
	global_load_dword v10, v[10:11], off
	s_lshl_b64 s[16:17], s[12:13], 1
	s_add_u32 s16, s1, s16
	s_addc_u32 s17, s15, s17
	s_waitcnt vmcnt(0)
; __device__ __forceinline__ unsigned cvt_pk_bf16(float lo, float hi) { typedef float f2 __attribute__((ext_vector_type(2))); typedef __bf16 b2 __attribute__((ext_vector_type(2))); f2 v = {lo, hi}; b2 b = __builtin_convertvector(v, b2); return __builtin_bit_cast(unsigned, b); }
; __device__ __forceinline__ void transpose_item(const float* W, int K, int N, bf16_t* WT, int n0d, int n0s, float scale, int k0, float* scr, int lane, bool gperm = false, const float* kgain = nullptr) {
;     ...
;     __builtin_amdgcn_wave_barrier(); asm volatile("s_waitcnt lgkmcnt(0)" ::: "memory");
;     const int c = lane & 7;
; #pragma unroll
;     for (int j = 0; j < 4; ++j) { const int n = (lane >> 3) + 8 * j; const float* s = scr + (8 * c) * 33 + n;
;         u32x4 o; o.x = cvt_pk_bf16(s[0 * 33], s[1 * 33]); o.y = cvt_pk_bf16(s[2 * 33], s[3 * 33]); o.z = cvt_pk_bf16(s[4 * 33], s[5 * 33]); o.w = cvt_pk_bf16(s[6 * 33], s[7 * 33]);
;         *(u32x4*)(WT + (size_t)(n0d + n) * K + k0 + 8 * c) = o; }
;     __builtin_amdgcn_wave_barrier(); asm volatile("s_waitcnt lgkmcnt(0)" ::: "memory");
	ds_write_b32 v9, v102
	ds_write_b32 v15, v103
	ds_write_b32 v17, v104
	ds_write_b32 v19, v105
	ds_write_b32 v21, v106
	ds_write_b32 v23, v107
	ds_write_b32 v25, v108
	ds_write_b32 v27, v109
	ds_write_b32 v29, v110
	ds_write_b32 v31, v111
	ds_write_b32 v33, v112
	ds_write_b32 v35, v113
	ds_write_b32 v37, v114
	ds_write_b32 v39, v115
	ds_write_b32 v41, v116
	ds_write_b32 v43, v117
	ds_write_b32 v45, v118
	ds_write_b32 v47, v119
	ds_write_b32 v49, v120
	ds_write_b32 v51, v121
	ds_write_b32 v53, v122
	ds_write_b32 v55, v123
	ds_write_b32 v57, v124
	ds_write_b32 v59, v125
	ds_write_b32 v61, v6
	ds_write_b32 v63, v12
	ds_write_b32 v65, v13
	ds_write_b32 v72, v88
	ds_write_b32 v74, v89
	ds_write_b32 v76, v90
	ds_write_b32 v78, v91
	ds_write_b32 v80, v10
	s_waitcnt lgkmcnt(0)
	ds_read_b32 v10, v67
	ds_read_b32 v11, v67 offset:132
	ds_read_b32 v12, v67 offset:264
	ds_read_b32 v13, v67 offset:396
	ds_read_b32 v90, v67 offset:528
	ds_read_b32 v91, v67 offset:660
	ds_read_b32 v92, v67 offset:792
	ds_read_b32 v93, v67 offset:924
	v_lshlrev_b32_e32 v6, 1, v8
	v_lshl_add_u64 v[88:89], s[16:17], 0, v[6:7]
	v_or_b32_e32 v6, s0, v66
	v_lshlrev_b32_e32 v6, 11, v6
	s_waitcnt lgkmcnt(0)
	v_cvt_pk_bf16_f32 v10, v10, v11
	v_cvt_pk_bf16_f32 v11, v12, v13
	v_cvt_pk_bf16_f32 v12, v90, v91
	v_cvt_pk_bf16_f32 v13, v92, v93
	v_lshl_add_u64 v[90:91], v[88:89], 0, v[6:7]
	global_store_dwordx4 v[90:91], v[10:13], off
	ds_read_b32 v6, v67 offset:32
	ds_read_b32 v10, v67 offset:164
	ds_read_b32 v11, v67 offset:296
	ds_read_b32 v12, v67 offset:428
	ds_read_b32 v13, v67 offset:560
	ds_read_b32 v90, v67 offset:692
	ds_read_b32 v91, v67 offset:824
	ds_read_b32 v92, v67 offset:956
	s_waitcnt lgkmcnt(0)
	v_cvt_pk_bf16_f32 v10, v6, v10
	v_or_b32_e32 v6, s0, v81
	v_lshlrev_b32_e32 v6, 11, v6
	v_cvt_pk_bf16_f32 v11, v11, v12
	v_cvt_pk_bf16_f32 v12, v13, v90
	v_cvt_pk_bf16_f32 v13, v91, v92
	v_lshl_add_u64 v[90:91], v[88:89], 0, v[6:7]
	global_store_dwordx4 v[90:91], v[10:13], off
	ds_read_b32 v6, v67 offset:64
	ds_read_b32 v10, v67 offset:196
	ds_read_b32 v11, v67 offset:328
	ds_read_b32 v12, v67 offset:460
	ds_read_b32 v13, v67 offset:592
	ds_read_b32 v90, v67 offset:724
	ds_read_b32 v91, v67 offset:856
	ds_read_b32 v92, v67 offset:988
	s_waitcnt lgkmcnt(0)
	v_cvt_pk_bf16_f32 v10, v6, v10
	v_or_b32_e32 v6, s0, v82
	v_lshlrev_b32_e32 v6, 11, v6
	v_cvt_pk_bf16_f32 v11, v11, v12
	v_cvt_pk_bf16_f32 v12, v13, v90
	v_cvt_pk_bf16_f32 v13, v91, v92
	v_lshl_add_u64 v[90:91], v[88:89], 0, v[6:7]
	global_store_dwordx4 v[90:91], v[10:13], off
	ds_read_b32 v6, v67 offset:96
	ds_read_b32 v10, v67 offset:228
	ds_read_b32 v11, v67 offset:360
	ds_read_b32 v12, v67 offset:492
	ds_read_b32 v13, v67 offset:624
	ds_read_b32 v90, v67 offset:756
	ds_read_b32 v91, v67 offset:888
	ds_read_b32 v92, v67 offset:1020
	s_waitcnt lgkmcnt(0)
	v_cvt_pk_bf16_f32 v10, v6, v10
	v_or_b32_e32 v6, s0, v83
	v_lshlrev_b32_e32 v6, 11, v6
	v_cvt_pk_bf16_f32 v11, v11, v12
	v_cvt_pk_bf16_f32 v12, v13, v90
	v_cvt_pk_bf16_f32 v13, v91, v92
	v_lshl_add_u64 v[88:89], v[88:89], 0, v[6:7]
	global_store_dwordx4 v[88:89], v[10:13], off
	s_waitcnt lgkmcnt(0)
	v_readlane_b32 s53, v253, 33
	v_readlane_b32 s56, v253, 36
	v_readlane_b32 s57, v253, 37
	v_readlane_b32 s58, v253, 38
	v_readlane_b32 s59, v253, 39
	v_readlane_b32 s60, v253, 40
	v_readlane_b32 s61, v253, 41
	v_readlane_b32 s62, v253, 42
	v_readlane_b32 s63, v253, 43
	v_readlane_b32 s64, v253, 44
	v_readlane_b32 s65, v253, 45
	v_readlane_b32 s66, v253, 46
	v_readlane_b32 s67, v253, 47

; __device__ __forceinline__ void transpose_item(const float* W, int K, int N, bf16_t* WT, int n0d, int n0s, float scale, int k0, float* scr, int lane, bool gperm = false, const float* kgain = nullptr) {
;     ...
;     } else if (n0s >= 0) {
; #pragma unroll
;         for (int i = 0; i < 32; ++i) { const int kk = 2 * i + (lane >> 5); scr[kk * 33 + (lane & 31)] = W[(size_t)(k0 + kk) * N + n0s + (lane & 31)] * (kgain ? scale * kgain[k0 + kk] : scale); }
;     } else {
; __device__ __forceinline__ void prologue(const Args& a, unsigned char* ws, char* lds, int gw, int NGW, int wave, int lane) {
;     ...
;         if (r < I_BR) { const int i = r / 128, rr = r % 128, nb = rr % 32, kb = rr / 32;
;             transpose_item(a.in[16] + ((size_t)l * 4 + i) * 256 * 1024, 256, 1024, (bf16_t*)(ws + WS_WBR) + ((size_t)l * 4 + i) * 1024 * 256, nb * 32, nb * 32, 1.f, kb * 64, scr, lane); continue; }
.LBB0_94:
	s_andn2_b64 vcc, exec, s[0:1]
	s_cbranch_vccnz .LBB0_96
	s_add_i32 s0, s18, 0xfffff300
	s_ashr_i32 s15, s14, 31
	s_lshr_b32 s12, s0, 7
	s_lshl_b64 s[0:1], s[14:15], 2
	s_add_u32 s0, s0, s12
	s_addc_u32 s1, s1, 0
	s_lshl_b64 s[16:17], s[0:1], 20
	v_readlane_b32 s52, v253, 32
	v_readlane_b32 s53, v253, 33
	s_add_u32 s19, s52, s16
	s_addc_u32 s20, s53, s17
	s_lshl_b64 s[16:17], s[0:1], 19
	s_add_u32 s1, s37, s16
	s_addc_u32 s12, s38, s17
	s_lshl_b32 s0, s14, 7
	s_sub_i32 s0, s43, s0
	s_mul_i32 s15, s14, 0xffffbc78
	s_and_b32 s0, s0, 0x3e0
	s_add_i32 s15, s41, s15
	s_and_b32 s15, s15, 0xc0
	s_lshl_b32 s16, s0, 2
	s_add_u32 s16, s19, s16
	s_addc_u32 s17, s20, 0
	v_lshlrev_b32_e32 v6, 2, v4
	v_lshl_add_u64 v[10:11], s[16:17], 0, v[6:7]
	v_or_b32_e32 v6, s15, v2
	v_lshlrev_b32_e32 v6, 12, v6
	v_lshl_add_u64 v[12:13], v[10:11], 0, v[6:7]
	v_or_b32_e32 v6, s15, v14
	v_lshlrev_b32_e32 v6, 12, v6
	v_lshl_add_u64 v[88:89], v[10:11], 0, v[6:7]
	v_or_b32_e32 v6, s15, v16
	v_lshlrev_b32_e32 v6, 12, v6
	global_load_dword v98, v[12:13], off
	global_load_dword v99, v[88:89], off
	v_lshl_add_u64 v[12:13], v[10:11], 0, v[6:7]
	v_or_b32_e32 v6, s15, v18
	v_lshlrev_b32_e32 v6, 12, v6
	v_lshl_add_u64 v[88:89], v[10:11], 0, v[6:7]
	v_or_b32_e32 v6, s15, v20
	v_lshlrev_b32_e32 v6, 12, v6
	v_lshl_add_u64 v[90:91], v[10:11], 0, v[6:7]
	v_or_b32_e32 v6, s15, v22
	v_lshlrev_b32_e32 v6, 12, v6
	v_lshl_add_u64 v[92:93], v[10:11], 0, v[6:7]
	v_or_b32_e32 v6, s15, v24
	v_lshlrev_b32_e32 v6, 12, v6
	v_lshl_add_u64 v[94:95], v[10:11], 0, v[6:7]
	v_or_b32_e32 v6, s15, v26
	v_lshlrev_b32_e32 v6, 12, v6
	v_lshl_add_u64 v[96:97], v[10:11], 0, v[6:7]
	v_or_b32_e32 v6, s15, v28
	v_lshlrev_b32_e32 v6, 12, v6
	global_load_dword v100, v[12:13], off
	global_load_dword v101, v[88:89], off
	s_nop 0
	global_load_dword v90, v[90:91], off
	s_nop 0
	global_load_dword v91, v[92:93], off
	s_nop 0
	global_load_dword v92, v[94:95], off
	global_load_dword v93, v[96:97], off
	v_lshl_add_u64 v[12:13], v[10:11], 0, v[6:7]
	v_or_b32_e32 v6, s15, v30
	v_lshlrev_b32_e32 v6, 12, v6
	v_lshl_add_u64 v[88:89], v[10:11], 0, v[6:7]
	v_or_b32_e32 v6, s15, v32
	v_lshlrev_b32_e32 v6, 12, v6
	global_load_dword v94, v[12:13], off
	global_load_dword v95, v[88:89], off
	v_lshl_add_u64 v[12:13], v[10:11], 0, v[6:7]
	v_or_b32_e32 v6, s15, v34
	v_lshlrev_b32_e32 v6, 12, v6
	v_lshl_add_u64 v[88:89], v[10:11], 0, v[6:7]
	v_or_b32_e32 v6, s15, v36
	v_lshlrev_b32_e32 v6, 12, v6
	global_load_dword v96, v[12:13], off
	s_nop 0
	global_load_dword v88, v[88:89], off
	v_lshl_add_u64 v[12:13], v[10:11], 0, v[6:7]
	v_or_b32_e32 v6, s15, v38
	v_lshlrev_b32_e32 v6, 12, v6
	global_load_dword v89, v[12:13], off
	v_lshl_add_u64 v[12:13], v[10:11], 0, v[6:7]
	v_or_b32_e32 v6, s15, v40
	v_lshlrev_b32_e32 v6, 12, v6
	global_load_dword v97, v[12:13], off
	v_lshl_add_u64 v[12:13], v[10:11], 0, v[6:7]
	v_or_b32_e32 v6, s15, v42
	v_lshlrev_b32_e32 v6, 12, v6
	global_load_dword v102, v[12:13], off
	v_lshl_add_u64 v[12:13], v[10:11], 0, v[6:7]
	v_or_b32_e32 v6, s15, v44
	v_lshlrev_b32_e32 v6, 12, v6
	global_load_dword v103, v[12:13], off
	v_lshl_add_u64 v[12:13], v[10:11], 0, v[6:7]
	v_or_b32_e32 v6, s15, v46
	v_lshlrev_b32_e32 v6, 12, v6
	global_load_dword v104, v[12:13], off
	v_lshl_add_u64 v[12:13], v[10:11], 0, v[6:7]
	v_or_b32_e32 v6, s15, v48
	v_lshlrev_b32_e32 v6, 12, v6
	global_load_dword v105, v[12:13], off
	v_lshl_add_u64 v[12:13], v[10:11], 0, v[6:7]
	v_or_b32_e32 v6, s15, v50
	v_lshlrev_b32_e32 v6, 12, v6
	global_load_dword v106, v[12:13], off
	v_lshl_add_u64 v[12:13], v[10:11], 0, v[6:7]
	v_or_b32_e32 v6, s15, v52
	v_lshlrev_b32_e32 v6, 12, v6
	global_load_dword v107, v[12:13], off
	v_lshl_add_u64 v[12:13], v[10:11], 0, v[6:7]
	v_or_b32_e32 v6, s15, v54
	v_lshlrev_b32_e32 v6, 12, v6
	global_load_dword v108, v[12:13], off
	v_lshl_add_u64 v[12:13], v[10:11], 0, v[6:7]
	v_or_b32_e32 v6, s15, v56
	v_lshlrev_b32_e32 v6, 12, v6
	global_load_dword v109, v[12:13], off
	v_lshl_add_u64 v[12:13], v[10:11], 0, v[6:7]
	v_or_b32_e32 v6, s15, v58
	v_lshlrev_b32_e32 v6, 12, v6
	global_load_dword v110, v[12:13], off
	v_lshl_add_u64 v[12:13], v[10:11], 0, v[6:7]
	v_or_b32_e32 v6, s15, v60
	v_lshlrev_b32_e32 v6, 12, v6
	global_load_dword v111, v[12:13], off
	v_lshl_add_u64 v[12:13], v[10:11], 0, v[6:7]
	v_or_b32_e32 v6, s15, v62
	v_lshlrev_b32_e32 v6, 12, v6
	global_load_dword v112, v[12:13], off
	v_lshl_add_u64 v[12:13], v[10:11], 0, v[6:7]
	v_or_b32_e32 v6, s15, v64
	v_lshlrev_b32_e32 v6, 12, v6
	global_load_dword v113, v[12:13], off
	v_lshl_add_u64 v[12:13], v[10:11], 0, v[6:7]
	v_or_b32_e32 v6, s15, v71
	v_lshlrev_b32_e32 v6, 12, v6
	global_load_dword v114, v[12:13], off
	v_lshl_add_u64 v[12:13], v[10:11], 0, v[6:7]
	v_or_b32_e32 v6, s15, v73
	v_lshlrev_b32_e32 v6, 12, v6
	global_load_dword v115, v[12:13], off
	v_lshl_add_u64 v[12:13], v[10:11], 0, v[6:7]
	v_or_b32_e32 v6, s15, v75
	v_lshlrev_b32_e32 v6, 12, v6
	global_load_dword v116, v[12:13], off
	v_lshl_add_u64 v[12:13], v[10:11], 0, v[6:7]
	v_or_b32_e32 v6, s15, v77
	v_lshlrev_b32_e32 v6, 12, v6
	global_load_dword v117, v[12:13], off
	v_lshl_add_u64 v[12:13], v[10:11], 0, v[6:7]
	v_or_b32_e32 v6, s15, v79
	v_lshlrev_b32_e32 v6, 12, v6
	global_load_dword v12, v[12:13], off
	v_lshl_add_u64 v[10:11], v[10:11], 0, v[6:7]
	global_load_dword v6, v[10:11], off
	s_waitcnt vmcnt(0)
; __device__ __forceinline__ unsigned cvt_pk_bf16(float lo, float hi) { typedef float f2 __attribute__((ext_vector_type(2))); typedef __bf16 b2 __attribute__((ext_vector_type(2))); f2 v = {lo, hi}; b2 b = __builtin_convertvector(v, b2); return __builtin_bit_cast(unsigned, b); }
; __device__ __forceinline__ void transpose_item(const float* W, int K, int N, bf16_t* WT, int n0d, int n0s, float scale, int k0, float* scr, int lane, bool gperm = false, const float* kgain = nullptr) {
;     ...
;     __builtin_amdgcn_wave_barrier(); asm volatile("s_waitcnt lgkmcnt(0)" ::: "memory");
;     const int c = lane & 7;
; #pragma unroll
;     for (int j = 0; j < 4; ++j) { const int n = (lane >> 3) + 8 * j; const float* s = scr + (8 * c) * 33 + n;
;         u32x4 o; o.x = cvt_pk_bf16(s[0 * 33], s[1 * 33]); o.y = cvt_pk_bf16(s[2 * 33], s[3 * 33]); o.z = cvt_pk_bf16(s[4 * 33], s[5 * 33]); o.w = cvt_pk_bf16(s[6 * 33], s[7 * 33]);
;         *(u32x4*)(WT + (size_t)(n0d + n) * K + k0 + 8 * c) = o; }
;     __builtin_amdgcn_wave_barrier(); asm volatile("s_waitcnt lgkmcnt(0)" ::: "memory");
	ds_write_b32 v9, v98
	ds_write_b32 v15, v99
	ds_write_b32 v17, v100
	ds_write_b32 v19, v101
	ds_write_b32 v21, v90
	ds_write_b32 v23, v91
	ds_write_b32 v25, v92
	ds_write_b32 v27, v93
	ds_write_b32 v29, v94
	ds_write_b32 v31, v95
	ds_write_b32 v33, v96
	ds_write_b32 v35, v88
	ds_write_b32 v37, v89
	ds_write_b32 v39, v97
	ds_write_b32 v41, v102
	ds_write_b32 v43, v103
	ds_write_b32 v45, v104
	ds_write_b32 v47, v105
	ds_write_b32 v49, v106
	ds_write_b32 v51, v107
	ds_write_b32 v53, v108
	ds_write_b32 v55, v109
	ds_write_b32 v57, v110
	ds_write_b32 v59, v111
	ds_write_b32 v61, v112
	ds_write_b32 v63, v113
	ds_write_b32 v65, v114
	ds_write_b32 v72, v115
	ds_write_b32 v74, v116
	ds_write_b32 v76, v117
	ds_write_b32 v78, v12
	ds_write_b32 v80, v6
	s_waitcnt lgkmcnt(0)
	s_lshl_b32 s15, s15, 1
	ds_read_b32 v10, v67
	ds_read_b32 v11, v67 offset:132
	ds_read_b32 v12, v67 offset:264
	ds_read_b32 v13, v67 offset:396
	ds_read_b32 v90, v67 offset:528
	ds_read_b32 v91, v67 offset:660
	ds_read_b32 v92, v67 offset:792
	ds_read_b32 v93, v67 offset:924
	s_add_u32 s16, s1, s15
	s_addc_u32 s17, s12, 0
	v_lshlrev_b32_e32 v6, 1, v8
	v_lshl_add_u64 v[88:89], s[16:17], 0, v[6:7]
	v_or_b32_e32 v6, s0, v66
	v_lshlrev_b32_e32 v6, 9, v6
	s_waitcnt lgkmcnt(0)
	v_cvt_pk_bf16_f32 v10, v10, v11
	v_cvt_pk_bf16_f32 v11, v12, v13
	v_cvt_pk_bf16_f32 v12, v90, v91
	v_cvt_pk_bf16_f32 v13, v92, v93
	v_lshl_add_u64 v[90:91], v[88:89], 0, v[6:7]
	global_store_dwordx4 v[90:91], v[10:13], off
	ds_read_b32 v6, v67 offset:32
	ds_read_b32 v10, v67 offset:164
	ds_read_b32 v11, v67 offset:296
	ds_read_b32 v12, v67 offset:428
	ds_read_b32 v13, v67 offset:560
	ds_read_b32 v90, v67 offset:692
	ds_read_b32 v91, v67 offset:824
	ds_read_b32 v92, v67 offset:956
	s_waitcnt lgkmcnt(0)
	v_cvt_pk_bf16_f32 v10, v6, v10
	v_or_b32_e32 v6, s0, v81
	v_lshlrev_b32_e32 v6, 9, v6
	v_cvt_pk_bf16_f32 v11, v11, v12
	v_cvt_pk_bf16_f32 v12, v13, v90
	v_cvt_pk_bf16_f32 v13, v91, v92
	v_lshl_add_u64 v[90:91], v[88:89], 0, v[6:7]
	global_store_dwordx4 v[90:91], v[10:13], off
	ds_read_b32 v6, v67 offset:64
	ds_read_b32 v10, v67 offset:196
	ds_read_b32 v11, v67 offset:328
	ds_read_b32 v12, v67 offset:460
	ds_read_b32 v13, v67 offset:592
	ds_read_b32 v90, v67 offset:724
	ds_read_b32 v91, v67 offset:856
	ds_read_b32 v92, v67 offset:988
	s_waitcnt lgkmcnt(0)
	v_cvt_pk_bf16_f32 v10, v6, v10
	v_or_b32_e32 v6, s0, v82
	v_lshlrev_b32_e32 v6, 9, v6
	v_cvt_pk_bf16_f32 v11, v11, v12
	v_cvt_pk_bf16_f32 v12, v13, v90
	v_cvt_pk_bf16_f32 v13, v91, v92
	v_lshl_add_u64 v[90:91], v[88:89], 0, v[6:7]
	global_store_dwordx4 v[90:91], v[10:13], off
	ds_read_b32 v6, v67 offset:96
	ds_read_b32 v10, v67 offset:228
	ds_read_b32 v11, v67 offset:360
	ds_read_b32 v12, v67 offset:492
	ds_read_b32 v13, v67 offset:624
	ds_read_b32 v90, v67 offset:756
	ds_read_b32 v91, v67 offset:888
	ds_read_b32 v92, v67 offset:1020
	s_waitcnt lgkmcnt(0)
	v_cvt_pk_bf16_f32 v10, v6, v10
	v_or_b32_e32 v6, s0, v83
	v_lshlrev_b32_e32 v6, 9, v6
	v_cvt_pk_bf16_f32 v11, v11, v12
	v_cvt_pk_bf16_f32 v12, v13, v90
	v_cvt_pk_bf16_f32 v13, v91, v92
	v_lshl_add_u64 v[88:89], v[88:89], 0, v[6:7]
	global_store_dwordx4 v[88:89], v[10:13], off
	s_waitcnt lgkmcnt(0)
	v_readlane_b32 s54, v253, 34
	v_readlane_b32 s55, v253, 35
	v_readlane_b32 s56, v253, 36
	v_readlane_b32 s57, v253, 37
	v_readlane_b32 s58, v253, 38
	v_readlane_b32 s59, v253, 39
	v_readlane_b32 s60, v253, 40
	v_readlane_b32 s61, v253, 41
	v_readlane_b32 s62, v253, 42
	v_readlane_b32 s63, v253, 43
	v_readlane_b32 s64, v253, 44
	v_readlane_b32 s65, v253, 45
	v_readlane_b32 s66, v253, 46
	v_readlane_b32 s67, v253, 47

; __device__ __forceinline__ void prologue(const Args& a, unsigned char* ws, char* lds, int gw, int NGW, int wave, int lane) {
;     ...
;     float2* rope = (float2*)(ws + WS_ROPE);
;     for (int e = gw * 64 + lane; e < 2048 * 16; e += NGW * 64) {
;         const int pos = e >> 4, i = e & 15;
;         const float inv = exp2f(-(float)i * (13.287712379549449f / 16.0f));
;         const float ang = (float)pos * inv;
;         const double rev = (double)ang * 0.15915494309189535; const double fr = rev - __builtin_rint(rev);
;         rope[e] = make_float2(__builtin_amdgcn_cosf((float)fr), __builtin_amdgcn_sinf((float)fr));
;     }
.LBB0_184:
	v_ashrrev_i32_e32 v3, 4, v2
	v_cvt_f32_i32_e32 v3, v3
	v_add_co_u32_e32 v6, vcc, -4, v4
	v_add_u32_e32 v2, s54, v2
	v_mul_f32_e32 v3, v1, v3
	v_cvt_f64_f32_e32 v[8:9], v3
	v_mul_f64 v[10:11], v[8:9], s[10:11]
	v_rndne_f64_e32 v[10:11], v[10:11]
	v_fma_f64 v[8:9], v[8:9], s[10:11], -v[10:11]
	v_cvt_f32_f64_e32 v3, v[8:9]
	v_cos_f32_e32 v8, v3
	v_sin_f32_e32 v9, v3
	v_addc_co_u32_e32 v7, vcc, -1, v5, vcc
	v_cmp_lt_i32_e32 vcc, s12, v2
	v_lshl_add_u64 v[4:5], v[4:5], 0, s[6:7]
	s_or_b64 s[8:9], vcc, s[8:9]
	global_store_dwordx2 v[6:7], v[8:9], off
	s_andn2_b64 exec, exec, s[8:9]
	s_cbranch_execnz .LBB0_184

; __device__ __forceinline__ unsigned cvt_pk_bf16(float lo, float hi) { typedef float f2 __attribute__((ext_vector_type(2))); typedef __bf16 b2 __attribute__((ext_vector_type(2))); f2 v = {lo, hi}; b2 b = __builtin_convertvector(v, b2); return __builtin_bit_cast(unsigned, b); }
; __device__ __forceinline__ void convert_phase(const float* xa, const float* xb, int row_g0, int T, bf16_t* XR, float* S0, int gw, int NGW, int lane) {
; #pragma unroll 1
;     for (int m0 = gw; m0 < T; m0 += 2 * NGW) { const int m1 = (m0 + NGW < T) ? m0 + NGW : m0;
;         f32x4 v[2][4];
; #pragma unroll
;         for (int k = 0; k < 2; ++k) { const int R = row_g0 + (k ? m1 : m0); const float* xr = (R < NTOK_P) ? xa + (size_t)R * DM : xb + (size_t)(R - NTOK_P) * DM;
; #pragma unroll
;             for (int j = 0; j < 4; ++j) v[k][j] = __builtin_nontemporal_load(((const f32x4*)xr) + lane + 64 * j); }
; #pragma unroll
;         for (int k = 0; k < 2; ++k) { const int m = k ? m1 : m0; float s = 0.f;
; #pragma unroll
;             for (int j = 0; j < 4; ++j) s += (v[k][j].x * v[k][j].x + v[k][j].y * v[k][j].y) + (v[k][j].z * v[k][j].z + v[k][j].w * v[k][j].w);
;             s = wave_sum(s);
;             u32x2* o8 = (u32x2*)(XR + (size_t)m * DM);
; #pragma unroll
;             for (int j = 0; j < 4; ++j) { u32x2 w; w.x = cvt_pk_bf16(v[k][j].x, v[k][j].y); w.y = cvt_pk_bf16(v[k][j].z, v[k][j].w); o8[lane + 64 * j] = w; }
;             if (lane < 16) S0[(size_t)m * 16 + lane] = (lane == 0) ? s : 0.f; }
;     }
; }
.LBB0_205:
	s_add_i32 s1, s6, s25
	s_cmp_lt_i32 s1, s0
	s_cselect_b32 s4, s1, s6
	s_add_i32 s5, s94, s6
	s_add_i32 s7, s5, 0xffff0000
	s_ashr_i32 s8, s5, 31
	s_cmp_lt_i32 s5, 0x10000
	v_readlane_b32 s68, v253, 0
	s_cselect_b32 s9, s8, 0
	s_cselect_b32 s8, s5, s7
	v_readlane_b32 s69, v253, 1
	v_readlane_b32 s70, v253, 2
	v_readlane_b32 s71, v253, 3
	s_cselect_b32 s5, s69, s71
	s_cselect_b32 s7, s68, s70
	s_lshl_b64 s[8:9], s[8:9], 12
	s_add_u32 s8, s7, s8
	s_addc_u32 s9, s5, s9
	global_load_dwordx4 v[28:31], v26, s[8:9] nt
	global_load_dwordx4 v[32:35], v26, s[8:9] offset:1024 nt
	global_load_dwordx4 v[36:39], v26, s[8:9] offset:2048 nt
	global_load_dwordx4 v[40:43], v26, s[8:9] offset:3072 nt
	s_add_i32 s5, s4, s94
	s_ashr_i32 s7, s5, 31
	s_add_i32 s8, s5, 0xffff0000
	s_cmp_lt_i32 s5, 0x10000
	s_cselect_b32 s9, s7, 0
	s_cselect_b32 s8, s5, s8
	s_cselect_b32 s5, s69, s71
	s_cselect_b32 s7, s68, s70
	s_lshl_b64 s[8:9], s[8:9], 12
	s_add_u32 s8, s7, s8
	s_addc_u32 s9, s5, s9
	s_waitcnt lgkmcnt(0)
	global_load_dwordx4 v[12:15], v26, s[8:9] nt
	global_load_dwordx4 v[8:11], v26, s[8:9] offset:1024 nt
	global_load_dwordx4 v[4:7], v26, s[8:9] offset:2048 nt
	global_load_dwordx4 v[0:3], v26, s[8:9] offset:3072 nt
	s_ashr_i32 s7, s6, 31
	s_lshl_b64 s[8:9], s[6:7], 11
	v_readlane_b32 s72, v253, 4
	v_readlane_b32 s73, v253, 5
	v_readlane_b32 s74, v253, 6
	v_readlane_b32 s75, v253, 7
	v_readlane_b32 s76, v253, 8
	v_readlane_b32 s77, v253, 9
	v_readlane_b32 s78, v253, 10
	v_readlane_b32 s79, v253, 11
	v_readlane_b32 s80, v253, 12
	v_readlane_b32 s81, v253, 13
	v_readlane_b32 s82, v253, 14
	v_readlane_b32 s83, v253, 15
	s_waitcnt vmcnt(0)
	v_mul_f32_e32 v27, v29, v29
	v_mul_f32_e32 v44, v31, v31
	v_mul_f32_e32 v45, v33, v33
	v_mul_f32_e32 v46, v35, v35
	v_mul_f32_e32 v47, v37, v37
	v_mul_f32_e32 v48, v39, v39
	v_fmac_f32_e32 v27, v28, v28
	v_fmac_f32_e32 v44, v30, v30
	v_fmac_f32_e32 v45, v32, v32
	v_fmac_f32_e32 v46, v34, v34
	v_mul_f32_e32 v49, v41, v41
	v_mul_f32_e32 v50, v43, v43
	v_fmac_f32_e32 v47, v36, v36
	v_fmac_f32_e32 v48, v38, v38
	v_add_f32_e32 v27, v27, v44
	v_add_f32_e32 v44, v45, v46
	v_fmac_f32_e32 v49, v40, v40
	v_fmac_f32_e32 v50, v42, v42
	v_add_f32_e32 v45, v47, v48
	v_add_f32_e32 v27, v27, v44
	v_add_f32_e32 v46, v49, v50
	v_add_f32_e32 v27, v27, v45
	v_add_f32_e32 v27, v27, v46
	ds_bpermute_b32 v44, v20, v27
	v_cvt_pk_bf16_f32 v28, v28, v29
	v_cvt_pk_bf16_f32 v29, v30, v31
	v_cvt_pk_bf16_f32 v30, v32, v33
	v_cvt_pk_bf16_f32 v31, v34, v35
	s_waitcnt lgkmcnt(0)
	v_add_f32_e32 v27, v27, v44
	ds_bpermute_b32 v44, v21, v27
	v_cvt_pk_bf16_f32 v32, v36, v37
	s_waitcnt lgkmcnt(0)
	v_add_f32_e32 v27, v27, v44
	ds_bpermute_b32 v44, v22, v27
	s_waitcnt lgkmcnt(0)
	v_add_f32_e32 v27, v27, v44
	ds_bpermute_b32 v46, v23, v27
	v_lshl_add_u64 v[44:45], v[18:19], 0, s[8:9]
	global_store_dwordx2 v[44:45], v[28:29], off
	global_store_dwordx2 v[44:45], v[30:31], off offset:512
	v_cvt_pk_bf16_f32 v30, v40, v41
	v_cvt_pk_bf16_f32 v31, v42, v43
	s_waitcnt lgkmcnt(0)
	v_add_f32_e32 v27, v27, v46
	ds_bpermute_b32 v33, v24, v27
	global_store_dwordx2 v[44:45], v[30:31], off offset:1536
	s_waitcnt lgkmcnt(0)
	v_add_f32_e32 v27, v27, v33
	ds_bpermute_b32 v28, v25, v27
	v_cvt_pk_bf16_f32 v33, v38, v39
	global_store_dwordx2 v[44:45], v[32:33], off offset:1024
	s_and_saveexec_b64 s[8:9], vcc
	s_cbranch_execz .LBB0_207
	s_waitcnt lgkmcnt(0)
	v_add_f32_e32 v27, v27, v28
	s_lshl_b64 s[6:7], s[6:7], 6
	v_cndmask_b32_e64 v27, 0, v27, s[38:39]
	v_lshl_add_u64 v[28:29], v[16:17], 0, s[6:7]
	global_store_dword v[28:29], v27, off
.LBB0_207:
	s_or_b64 exec, exec, s[8:9]
	v_mul_f32_e32 v27, v13, v13
	s_waitcnt lgkmcnt(0)
	v_mul_f32_e32 v28, v15, v15
	v_fmac_f32_e32 v27, v12, v12
	v_fmac_f32_e32 v28, v14, v14
	v_add_f32_e32 v27, v27, v28
	v_mul_f32_e32 v28, v9, v9
	v_mul_f32_e32 v29, v11, v11
	v_fmac_f32_e32 v28, v8, v8
	v_fmac_f32_e32 v29, v10, v10
	v_add_f32_e32 v28, v28, v29
	v_add_f32_e32 v27, v27, v28
	v_mul_f32_e32 v28, v5, v5
	v_mul_f32_e32 v29, v7, v7
	v_fmac_f32_e32 v28, v4, v4
	v_fmac_f32_e32 v29, v6, v6
	v_add_f32_e32 v28, v28, v29
	v_add_f32_e32 v27, v27, v28
	v_mul_f32_e32 v28, v1, v1
	v_mul_f32_e32 v29, v3, v3
	v_fmac_f32_e32 v28, v0, v0
	v_fmac_f32_e32 v29, v2, v2
	v_add_f32_e32 v28, v28, v29
	v_add_f32_e32 v27, v27, v28
	ds_bpermute_b32 v28, v20, v27
	s_ashr_i32 s5, s4, 31
	s_lshl_b64 s[6:7], s[4:5], 11
	v_cvt_pk_bf16_f32 v8, v8, v9
	v_cvt_pk_bf16_f32 v9, v10, v11
	s_waitcnt lgkmcnt(0)
	v_add_f32_e32 v27, v27, v28
	ds_bpermute_b32 v28, v21, v27
	v_cvt_pk_bf16_f32 v4, v4, v5
	v_cvt_pk_bf16_f32 v5, v6, v7
	v_cvt_pk_bf16_f32 v0, v0, v1
	v_cvt_pk_bf16_f32 v1, v2, v3
	s_waitcnt lgkmcnt(0)
	v_add_f32_e32 v27, v27, v28
	ds_bpermute_b32 v28, v22, v27
	s_waitcnt lgkmcnt(0)
	v_add_f32_e32 v27, v27, v28
	ds_bpermute_b32 v28, v23, v27
	s_waitcnt lgkmcnt(0)
	v_add_f32_e32 v27, v27, v28
	ds_bpermute_b32 v29, v24, v27
	v_cvt_pk_bf16_f32 v28, v12, v13
	s_waitcnt lgkmcnt(0)
	v_add_f32_e32 v12, v27, v29
	ds_bpermute_b32 v13, v25, v12
	v_cvt_pk_bf16_f32 v29, v14, v15
	v_lshl_add_u64 v[14:15], v[18:19], 0, s[6:7]
	global_store_dwordx2 v[14:15], v[28:29], off
	global_store_dwordx2 v[14:15], v[8:9], off offset:512
	global_store_dwordx2 v[14:15], v[4:5], off offset:1024
	global_store_dwordx2 v[14:15], v[0:1], off offset:1536
	s_and_saveexec_b64 s[6:7], vcc
	s_cbranch_execz .LBB0_204
	s_waitcnt lgkmcnt(0)
	v_add_f32_e32 v0, v12, v13
	s_lshl_b64 s[4:5], s[4:5], 6
	v_cndmask_b32_e64 v2, 0, v0, s[38:39]
	v_lshl_add_u64 v[0:1], v[16:17], 0, s[4:5]
	global_store_dword v[0:1], v2, off
	s_branch .LBB0_204

; __device__ __forceinline__ void rows_rstd8(const float* ssq, int row0, int fq, float (&rs)[2][4]) {
;     f32x4 p[2][4];
; #pragma unroll
;     for (int ai = 0; ai < 2; ++ai)
; #pragma unroll
;         for (int m = 0; m < 4; ++m) p[ai][m] = ((const f32x4*)(ssq + (size_t)(row0 + ai * HALF + m * 16) * 16))[fq];
; #pragma unroll
;     for (int ai = 0; ai < 2; ++ai)
; #pragma unroll
;         for (int m = 0; m < 4; ++m) { float v = (p[ai][m][0] + p[ai][m][1]) + (p[ai][m][2] + p[ai][m][3]); v += __shfl_xor(v, 16); v += __shfl_xor(v, 32); rs[ai][m] = __builtin_amdgcn_rsqf(v * (1.0f / 1024.0f) + 1e-6f); }
; }
;     __device__ __forceinline__ void operator()(const f32x4 (&acc)[2][2][4][2], const Unit& u, int wr, int wc, int fr, int fq) const {
;         const int row0 = u.pm * BM + wr * 64 + fr; const int col0 = u.pn * BM + wc * 32 + 8 * fq;
;         const bool sg = u.pn >= sig_pn0;
;         float rs8[2][4]; rows_rstd8(ssq, row0, fq, rs8);
; #pragma unroll
;         for (int ai = 0; ai < 2; ++ai)
; #pragma unroll
;             for (int m = 0; m < 4; ++m) { bf16_t* rowp = O + (size_t)(row0 + ai * HALF + m * 16) * ldc + col0;
;                 const float rs_ = rs8[ai][m];
;                 f32x4 g0 = acc[ai][0][m][0] * rs_, g1 = acc[ai][0][m][1] * rs_, g2 = acc[ai][1][m][0] * rs_, g3 = acc[ai][1][m][1] * rs_;
;                 if (sg) {
; #pragma unroll
;                     for (int j = 0; j < 4; ++j) {
;                         const float e0 = fminf(1.0f + __builtin_amdgcn_exp2f(-1.4426950408889634f * g0[j]), 1e6f), e1 = fminf(1.0f + __builtin_amdgcn_exp2f(-1.4426950408889634f * g1[j]), 1e6f);
;                         const float e2 = fminf(1.0f + __builtin_amdgcn_exp2f(-1.4426950408889634f * g2[j]), 1e6f), e3 = fminf(1.0f + __builtin_amdgcn_exp2f(-1.4426950408889634f * g3[j]), 1e6f);
;                         g0[j] = e1 * __builtin_amdgcn_rcpf(e0); g1[j] = e2 * __builtin_amdgcn_rcpf(e1); g2[j] = e3 * __builtin_amdgcn_rcpf(e2); g3[j] = __builtin_amdgcn_rcpf(e3); }
.LBB0_281:
	v_lshl_add_u32 v158, s40, 8, v137
	v_or_b32_e32 v156, 16, v158
	v_ashrrev_i32_e32 v159, 31, v158
	v_ashrrev_i32_e32 v157, 31, v156
	v_lshlrev_b64 v[144:145], 6, v[158:159]
	v_lshlrev_b64 v[146:147], 6, v[156:157]
	v_or_b32_e32 v154, 32, v158
	v_or_b32_e32 v152, 48, v158
	v_lshl_add_u64 v[144:145], v[138:139], 0, v[144:145]
	v_lshl_add_u64 v[146:147], v[138:139], 0, v[146:147]
	v_ashrrev_i32_e32 v155, 31, v154
	v_ashrrev_i32_e32 v153, 31, v152
	global_load_dwordx4 v[160:163], v[144:145], off
	global_load_dwordx4 v[164:167], v[146:147], off
	v_lshlrev_b64 v[144:145], 6, v[154:155]
	v_lshlrev_b64 v[146:147], 6, v[152:153]
	v_add_u32_e32 v150, 0x80, v158
	v_add_u32_e32 v148, 0x90, v158
	v_lshl_add_u64 v[144:145], v[138:139], 0, v[144:145]
	v_lshl_add_u64 v[146:147], v[138:139], 0, v[146:147]
	v_ashrrev_i32_e32 v151, 31, v150
	v_ashrrev_i32_e32 v149, 31, v148
	global_load_dwordx4 v[168:171], v[144:145], off
	global_load_dwordx4 v[172:175], v[146:147], off
	v_lshlrev_b64 v[144:145], 6, v[150:151]
	v_lshlrev_b64 v[146:147], 6, v[148:149]
	v_lshl_add_u64 v[144:145], v[138:139], 0, v[144:145]
	v_lshl_add_u64 v[146:147], v[138:139], 0, v[146:147]
	global_load_dwordx4 v[180:183], v[144:145], off
	global_load_dwordx4 v[184:187], v[146:147], off
	v_add_u32_e32 v146, 0xa0, v158
	v_ashrrev_i32_e32 v147, 31, v146
	v_lshlrev_b64 v[144:145], 6, v[146:147]
	v_lshl_add_u64 v[144:145], v[138:139], 0, v[144:145]
	global_load_dwordx4 v[188:191], v[144:145], off
	v_add_u32_e32 v144, 0xb0, v158
	v_ashrrev_i32_e32 v145, 31, v144
	v_lshlrev_b64 v[194:195], 6, v[144:145]
	v_lshl_add_u64 v[194:195], v[138:139], 0, v[194:195]
	global_load_dwordx4 v[194:197], v[194:195], off
	v_cmp_lt_i32_e32 vcc, v247, v245
	s_cmp_gt_i32 s6, 9
	s_cselect_b64 s[46:47], -1, 0
	s_cselect_b32 s99, 0xbfb8aa3b, 1.0
	v_cndmask_b32_e32 v179, v244, v247, vcc
	v_lshlrev_b32_e32 v179, 2, v179
	v_cmp_lt_i32_e32 vcc, v250, v245
	s_mov_b64 s[40:41], -1
	s_waitcnt vmcnt(0) lgkmcnt(0)
	v_mov_b32_e32 v198, v161
	v_mov_b32_e32 v199, v162
	v_mov_b32_e32 v161, v163
	v_pk_add_f32 v[160:161], v[198:199], v[160:161]
	v_add_f32_e32 v162, v164, v165
	v_add_f32_e32 v163, v166, v167
	v_add_f32_e32 v160, v160, v161
	v_add_f32_e32 v161, v162, v163
	v_cndmask_b32_e32 v192, v244, v250, vcc
	v_add_f32_e32 v164, v168, v169
	v_add_f32_e32 v165, v170, v171
	v_add_f32_e32 v162, v164, v165
	v_lshlrev_b32_e32 v192, 2, v192
	v_add_f32_e32 v166, v172, v173
	v_add_f32_e32 v168, v180, v181
	v_add_f32_e32 v169, v182, v183
	v_add_f32_e32 v164, v168, v169
	ds_bpermute_b32 v168, v179, v160
	ds_bpermute_b32 v169, v179, v161
	v_add_f32_e32 v167, v174, v175
	v_add_f32_e32 v170, v184, v185
	v_add_f32_e32 v171, v186, v187
	v_add_f32_e32 v172, v188, v189
	v_add_f32_e32 v173, v190, v191
	s_waitcnt lgkmcnt(1)
	v_add_f32_e32 v160, v160, v168
	v_add_f32_e32 v174, v194, v195
	v_add_f32_e32 v175, v196, v197
	v_add_f32_e32 v163, v166, v167
	v_add_f32_e32 v165, v170, v171
	v_add_f32_e32 v166, v172, v173
	v_add_f32_e32 v167, v174, v175
	s_waitcnt lgkmcnt(0)
	v_add_f32_e32 v191, v161, v169
	ds_bpermute_b32 v161, v192, v160
	ds_bpermute_b32 v170, v179, v162
	ds_bpermute_b32 v171, v179, v163
	ds_bpermute_b32 v172, v179, v164
	ds_bpermute_b32 v173, v179, v165
	ds_bpermute_b32 v174, v179, v166
	ds_bpermute_b32 v175, v179, v167
	s_waitcnt lgkmcnt(6)
	v_add_f32_e32 v160, v160, v161
	s_waitcnt lgkmcnt(5)
	v_add_f32_e32 v189, v162, v170
	s_waitcnt lgkmcnt(4)
	v_add_f32_e32 v187, v163, v171
	s_waitcnt lgkmcnt(3)
	v_add_f32_e32 v185, v164, v172
	s_waitcnt lgkmcnt(2)
	v_add_f32_e32 v183, v165, v173
	s_waitcnt lgkmcnt(1)
	v_add_f32_e32 v181, v166, v174
	s_waitcnt lgkmcnt(0)
	v_add_f32_e32 v179, v167, v175
	v_fmamk_f32 v160, v160, 0x3a800000, v242
	ds_bpermute_b32 v194, v192, v191
	ds_bpermute_b32 v190, v192, v189
	ds_bpermute_b32 v188, v192, v187
	ds_bpermute_b32 v186, v192, v185
	v_rsq_f32_e32 v164, v160
	ds_bpermute_b32 v184, v192, v183
	ds_bpermute_b32 v182, v192, v181
	ds_bpermute_b32 v180, v192, v179
	v_mul_f32_e32 v164, s99, v164
	v_pk_mul_f32 v[126:127], v[126:127], v[164:165] op_sel_hi:[1,0]
	v_pk_mul_f32 v[124:125], v[124:125], v[164:165] op_sel_hi:[1,0]
	v_pk_mul_f32 v[122:123], v[122:123], v[164:165] op_sel_hi:[1,0]
	v_pk_mul_f32 v[120:121], v[120:121], v[164:165] op_sel_hi:[1,0]
	v_pk_mul_f32 v[160:161], v[118:119], v[164:165] op_sel_hi:[1,0]
	v_pk_mul_f32 v[162:163], v[116:117], v[164:165] op_sel_hi:[1,0]
	v_pk_mul_f32 v[114:115], v[114:115], v[164:165] op_sel_hi:[1,0]
	v_pk_mul_f32 v[112:113], v[112:113], v[164:165] op_sel_hi:[1,0]
	s_and_b64 vcc, exec, s[46:47]
	s_cbranch_vccz .LBB0_283
	v_exp_f32_e32 v116, v124
	v_exp_f32_e32 v117, v120
	v_exp_f32_e32 v118, v162
	v_exp_f32_e32 v119, v112
	v_add_f32_e32 v116, 1.0, v116
	v_add_f32_e32 v117, 1.0, v117
	v_min_f32_e32 v116, 0x49742400, v116
	v_min_f32_e32 v164, 0x49742400, v117
	v_add_f32_e32 v117, 1.0, v118
	v_min_f32_e32 v168, 0x49742400, v117
	v_add_f32_e32 v117, 1.0, v119
	v_rcp_f32_e32 v166, v116
	v_min_f32_e32 v172, 0x49742400, v117
	v_exp_f32_e32 v117, v125
	v_exp_f32_e32 v118, v121
	v_exp_f32_e32 v119, v163
	v_exp_f32_e32 v167, v113
	v_add_f32_e32 v117, 1.0, v117
	v_add_f32_e32 v118, 1.0, v118
	v_min_f32_e32 v117, 0x49742400, v117
	v_min_f32_e32 v165, 0x49742400, v118
	v_add_f32_e32 v118, 1.0, v119
	v_min_f32_e32 v169, 0x49742400, v118
	v_add_f32_e32 v118, 1.0, v167
	v_rcp_f32_e32 v167, v117
	v_min_f32_e32 v173, 0x49742400, v118
	v_exp_f32_e32 v118, v126
	v_exp_f32_e32 v119, v122
	v_exp_f32_e32 v192, v160
	v_exp_f32_e32 v195, v114
	v_add_f32_e32 v118, 1.0, v118
	v_add_f32_e32 v119, 1.0, v119
	v_min_f32_e32 v118, 0x49742400, v118
	v_min_f32_e32 v196, 0x49742400, v119
	v_add_f32_e32 v119, 1.0, v192
	v_min_f32_e32 v198, 0x49742400, v119
	v_add_f32_e32 v119, 1.0, v195
	v_rcp_f32_e32 v202, v118
	v_min_f32_e32 v200, 0x49742400, v119
	v_exp_f32_e32 v119, v127
	v_exp_f32_e32 v192, v123
	v_exp_f32_e32 v195, v161
	v_add_f32_e32 v192, 1.0, v192
	v_add_f32_e32 v119, 1.0, v119
	v_exp_f32_e32 v201, v115
	v_min_f32_e32 v197, 0x49742400, v192
	v_add_f32_e32 v192, 1.0, v195
	v_min_f32_e32 v119, 0x49742400, v119
	v_min_f32_e32 v199, 0x49742400, v192
	v_rcp_f32_e32 v170, v164
	v_rcp_f32_e32 v174, v168
	v_rcp_f32_e32 v171, v165
	v_rcp_f32_e32 v175, v169
	v_rcp_f32_e32 v204, v196
	v_rcp_f32_e32 v206, v198
	v_rcp_f32_e32 v203, v119
	v_rcp_f32_e32 v205, v197
	v_rcp_f32_e32 v207, v199
	v_add_f32_e32 v192, 1.0, v201
	v_min_f32_e32 v201, 0x49742400, v192
	v_rcp_f32_e32 v116, v172
	v_rcp_f32_e32 v117, v173
	v_rcp_f32_e32 v118, v200
	v_pk_mul_f32 v[164:165], v[164:165], v[166:167]
	v_pk_mul_f32 v[166:167], v[196:197], v[202:203]
	v_pk_mul_f32 v[168:169], v[168:169], v[170:171]
	v_pk_mul_f32 v[170:171], v[198:199], v[204:205]
	v_rcp_f32_e32 v119, v201
	v_pk_mul_f32 v[172:173], v[172:173], v[174:175]
	v_pk_mul_f32 v[174:175], v[200:201], v[206:207]
	s_mov_b64 s[40:41], 0

;     __device__ __forceinline__ void operator()(const f32x4 (&acc)[2][2][4][2], const Unit& u, int wr, int wc, int fr, int fq) const {
;     ...
;             for (int m = 0; m < 4; ++m) { bf16_t* rowp = O + (size_t)(row0 + ai * HALF + m * 16) * ldc + col0;
;                 const float rs_ = rs8[ai][m];
;                 f32x4 g0 = acc[ai][0][m][0] * rs_, g1 = acc[ai][0][m][1] * rs_, g2 = acc[ai][1][m][0] * rs_, g3 = acc[ai][1][m][1] * rs_;
;                 if (sg) {
; #pragma unroll
;                     for (int j = 0; j < 4; ++j) {
;                         const float e0 = fminf(1.0f + __builtin_amdgcn_exp2f(-1.4426950408889634f * g0[j]), 1e6f), e1 = fminf(1.0f + __builtin_amdgcn_exp2f(-1.4426950408889634f * g1[j]), 1e6f);
;                         const float e2 = fminf(1.0f + __builtin_amdgcn_exp2f(-1.4426950408889634f * g2[j]), 1e6f), e3 = fminf(1.0f + __builtin_amdgcn_exp2f(-1.4426950408889634f * g3[j]), 1e6f);
;                         g0[j] = e1 * __builtin_amdgcn_rcpf(e0); g1[j] = e2 * __builtin_amdgcn_rcpf(e1); g2[j] = e3 * __builtin_amdgcn_rcpf(e2); g3[j] = __builtin_amdgcn_rcpf(e3); }
;                 }
;                 if (sg) { typedef unsigned u32x2 __attribute__((ext_vector_type(2)));
;                     bf16_t* rp = rat + (size_t)(row0 + ai * HALF + m * 16) * 1024 + (u.pn - sig_pn0) * 64 + 16 * wc + 4 * fq; const size_t pl = (size_t)Trows * 1024;
;                     { u32x2 w; w.x = cvt_pk_bf16(g0[0], g0[1]); w.y = cvt_pk_bf16(g0[2], g0[3]); *(u32x2*)rp = w; }
;                     { u32x2 w; w.x = cvt_pk_bf16(g1[0], g1[1]); w.y = cvt_pk_bf16(g1[2], g1[3]); *(u32x2*)(rp + pl) = w; }
;                     { u32x2 w; w.x = cvt_pk_bf16(g2[0], g2[1]); w.y = cvt_pk_bf16(g2[2], g2[3]); *(u32x2*)(rp + 2 * pl) = w; }
;                     { u32x2 w; w.x = cvt_pk_bf16(g3[0], g3[1]); w.y = cvt_pk_bf16(g3[2], g3[3]); *(u32x2*)(rp + 3 * pl) = w; } }
;                 else {
;                 { u32x4 w; w.x = cvt_pk_bf16(g0[0], g0[1]); w.y = cvt_pk_bf16(g0[2], g0[3]); w.z = cvt_pk_bf16(g1[0], g1[1]); w.w = cvt_pk_bf16(g1[2], g1[3]); *(u32x4*)rowp = w; }
;                 { u32x4 w; w.x = cvt_pk_bf16(g2[0], g2[1]); w.y = cvt_pk_bf16(g2[2], g2[3]); w.z = cvt_pk_bf16(g3[0], g3[1]); w.w = cvt_pk_bf16(g3[2], g3[3]); *(u32x4*)(rowp + HALF) = w; } } }
.LBB0_285:
	v_cndmask_b32_e64 v112, 0, 1, s[46:47]
	v_readlane_b32 s80, v254, 47
	v_readlane_b32 s82, v254, 49
	s_mov_b64 s[8:9], -1
	v_cmp_ne_u32_e64 s[40:41], 1, v112
	s_andn2_b64 vcc, exec, s[46:47]
	v_lshlrev_b32_e32 v192, 1, v136
	v_cvt_pk_bf16_f32 v120, v164, v165
	v_cvt_pk_bf16_f32 v121, v166, v167
	v_cvt_pk_bf16_f32 v122, v168, v169
	v_cvt_pk_bf16_f32 v123, v170, v171
	v_cvt_pk_bf16_f32 v112, v172, v173
	v_cvt_pk_bf16_f32 v113, v174, v175
	v_cvt_pk_bf16_f32 v114, v116, v117
	v_cvt_pk_bf16_f32 v115, v118, v119
	v_readlane_b32 s81, v254, 48
	v_readlane_b32 s83, v254, 50
	s_cbranch_vccnz .LBB0_287
	v_lshlrev_b64 v[116:117], 11, v[158:159]
	v_lshl_add_u64 v[116:117], s[20:21], 0, v[116:117]
	s_lshl_b32 s16, s6, 7
	v_lshl_add_u64 v[116:117], v[116:117], 0, s[16:17]
	s_lshl_b32 s16, s75, 1
	v_lshl_add_u64 v[116:117], v[116:117], 0, s[16:17]
	v_lshl_add_u64 v[116:117], v[116:117], 0, v[192:193]
	v_lshl_add_u64 v[118:119], v[116:117], 0, s[90:91]
	v_add_co_u32_e32 v116, vcc, s30, v116
	s_mov_b64 s[8:9], 0
	s_nop 0
	v_addc_co_u32_e32 v117, vcc, -1, v117, vcc
	global_store_dwordx2 v[116:117], v[120:121], off
	v_lshl_add_u64 v[116:117], v[118:119], 0, s[12:13]
	global_store_dwordx2 v[116:117], v[122:123], off
	v_lshl_add_u64 v[116:117], v[116:117], 0, s[12:13]
	global_store_dwordx2 v[116:117], v[112:113], off
	v_lshl_add_u64 v[116:117], v[116:117], 0, s[12:13]
	global_store_dwordx2 v[116:117], v[114:115], off
.LBB0_287:
	v_lshl_or_b32 v116, s6, 8, v177
	s_andn2_b64 vcc, exec, s[8:9]
	v_ashrrev_i32_e32 v117, 31, v116
	s_cbranch_vccnz .LBB0_289
	v_mov_b64_e32 v[118:119], s[14:15]
	v_mad_i64_i32 v[118:119], s[8:9], v158, s56, v[118:119]
	v_lshl_add_u64 v[118:119], v[116:117], 1, v[118:119]
	global_store_dwordx4 v[118:119], v[120:123], off
	global_store_dwordx4 v[118:119], v[112:115], off offset:256
.LBB0_289:
	s_waitcnt lgkmcnt(0)
	s_nop 0
	v_add_f32_e32 v112, v191, v194
	v_fmamk_f32 v112, v112, 0x3a800000, v242
	v_rsq_f32_e32 v118, v112
	s_mov_b64 s[48:49], -1
	s_and_b64 vcc, exec, s[46:47]
	v_mul_f32_e32 v118, s99, v118
	v_pk_mul_f32 v[110:111], v[110:111], v[118:119] op_sel_hi:[1,0]
	v_pk_mul_f32 v[108:109], v[108:109], v[118:119] op_sel_hi:[1,0]
	v_pk_mul_f32 v[106:107], v[106:107], v[118:119] op_sel_hi:[1,0]
	v_pk_mul_f32 v[104:105], v[104:105], v[118:119] op_sel_hi:[1,0]
	v_pk_mul_f32 v[112:113], v[102:103], v[118:119] op_sel_hi:[1,0]
	v_pk_mul_f32 v[114:115], v[100:101], v[118:119] op_sel_hi:[1,0]
	v_pk_mul_f32 v[98:99], v[98:99], v[118:119] op_sel_hi:[1,0]
	v_pk_mul_f32 v[96:97], v[96:97], v[118:119] op_sel_hi:[1,0]
	s_cbranch_vccz .LBB0_291
	v_exp_f32_e32 v100, v108
	v_exp_f32_e32 v101, v104
	v_exp_f32_e32 v102, v114
	v_exp_f32_e32 v103, v96
	v_add_f32_e32 v100, 1.0, v100
	v_add_f32_e32 v101, 1.0, v101
	v_min_f32_e32 v100, 0x49742400, v100
	v_min_f32_e32 v118, 0x49742400, v101
	v_add_f32_e32 v101, 1.0, v102
	v_min_f32_e32 v122, 0x49742400, v101
	v_add_f32_e32 v101, 1.0, v103
	v_rcp_f32_e32 v120, v100
	v_min_f32_e32 v126, 0x49742400, v101
	v_exp_f32_e32 v101, v109
	v_exp_f32_e32 v102, v105
	v_exp_f32_e32 v103, v115
	v_exp_f32_e32 v121, v97
	v_add_f32_e32 v101, 1.0, v101
	v_add_f32_e32 v102, 1.0, v102
	v_min_f32_e32 v101, 0x49742400, v101
	v_min_f32_e32 v119, 0x49742400, v102
	v_add_f32_e32 v102, 1.0, v103
	v_min_f32_e32 v123, 0x49742400, v102
	v_add_f32_e32 v102, 1.0, v121
	v_rcp_f32_e32 v121, v101
	v_min_f32_e32 v127, 0x49742400, v102
	v_exp_f32_e32 v102, v110
	v_exp_f32_e32 v103, v106
	v_exp_f32_e32 v161, v112
	v_exp_f32_e32 v163, v98
	v_add_f32_e32 v102, 1.0, v102
	v_add_f32_e32 v103, 1.0, v103
	v_min_f32_e32 v102, 0x49742400, v102
	v_min_f32_e32 v160, 0x49742400, v103
	v_add_f32_e32 v103, 1.0, v161
	v_min_f32_e32 v162, 0x49742400, v103
	v_add_f32_e32 v103, 1.0, v163
	v_rcp_f32_e32 v166, v102
	v_min_f32_e32 v164, 0x49742400, v103
	v_exp_f32_e32 v103, v111
	v_exp_f32_e32 v161, v107
	v_exp_f32_e32 v163, v113
	v_add_f32_e32 v103, 1.0, v103
	v_add_f32_e32 v161, 1.0, v161
	v_exp_f32_e32 v165, v99
	v_add_f32_e32 v163, 1.0, v163
	v_min_f32_e32 v103, 0x49742400, v103
	v_min_f32_e32 v161, 0x49742400, v161
	v_min_f32_e32 v163, 0x49742400, v163
	v_rcp_f32_e32 v124, v118
	v_rcp_f32_e32 v158, v122
	v_rcp_f32_e32 v125, v119
	v_rcp_f32_e32 v159, v123
	v_rcp_f32_e32 v168, v160
	v_rcp_f32_e32 v170, v162
	v_rcp_f32_e32 v167, v103
	v_rcp_f32_e32 v169, v161
	v_rcp_f32_e32 v171, v163
	v_add_f32_e32 v165, 1.0, v165
	v_min_f32_e32 v165, 0x49742400, v165
	v_rcp_f32_e32 v100, v126
	v_rcp_f32_e32 v101, v127
	v_rcp_f32_e32 v102, v164
	v_pk_mul_f32 v[118:119], v[118:119], v[120:121]
	v_pk_mul_f32 v[120:121], v[160:161], v[166:167]
	v_pk_mul_f32 v[122:123], v[122:123], v[124:125]
	v_pk_mul_f32 v[124:125], v[162:163], v[168:169]
	v_rcp_f32_e32 v103, v165
	v_pk_mul_f32 v[126:127], v[126:127], v[158:159]
	v_pk_mul_f32 v[158:159], v[164:165], v[170:171]
	s_mov_b64 s[48:49], 0

;     __device__ __forceinline__ void operator()(const f32x4 (&acc)[2][2][4][2], const Unit& u, int wr, int wc, int fr, int fq) const {
;     ...
;             for (int m = 0; m < 4; ++m) { bf16_t* rowp = O + (size_t)(row0 + ai * HALF + m * 16) * ldc + col0;
;                 const float rs_ = rs8[ai][m];
;                 f32x4 g0 = acc[ai][0][m][0] * rs_, g1 = acc[ai][0][m][1] * rs_, g2 = acc[ai][1][m][0] * rs_, g3 = acc[ai][1][m][1] * rs_;
;                 if (sg) {
; #pragma unroll
;                     for (int j = 0; j < 4; ++j) {
;                         const float e0 = fminf(1.0f + __builtin_amdgcn_exp2f(-1.4426950408889634f * g0[j]), 1e6f), e1 = fminf(1.0f + __builtin_amdgcn_exp2f(-1.4426950408889634f * g1[j]), 1e6f);
;                         const float e2 = fminf(1.0f + __builtin_amdgcn_exp2f(-1.4426950408889634f * g2[j]), 1e6f), e3 = fminf(1.0f + __builtin_amdgcn_exp2f(-1.4426950408889634f * g3[j]), 1e6f);
;                         g0[j] = e1 * __builtin_amdgcn_rcpf(e0); g1[j] = e2 * __builtin_amdgcn_rcpf(e1); g2[j] = e3 * __builtin_amdgcn_rcpf(e2); g3[j] = __builtin_amdgcn_rcpf(e3); }
;                 }
;                 if (sg) { typedef unsigned u32x2 __attribute__((ext_vector_type(2)));
;                     bf16_t* rp = rat + (size_t)(row0 + ai * HALF + m * 16) * 1024 + (u.pn - sig_pn0) * 64 + 16 * wc + 4 * fq; const size_t pl = (size_t)Trows * 1024;
;                     { u32x2 w; w.x = cvt_pk_bf16(g0[0], g0[1]); w.y = cvt_pk_bf16(g0[2], g0[3]); *(u32x2*)rp = w; }
;                     { u32x2 w; w.x = cvt_pk_bf16(g1[0], g1[1]); w.y = cvt_pk_bf16(g1[2], g1[3]); *(u32x2*)(rp + pl) = w; }
;                     { u32x2 w; w.x = cvt_pk_bf16(g2[0], g2[1]); w.y = cvt_pk_bf16(g2[2], g2[3]); *(u32x2*)(rp + 2 * pl) = w; }
;                     { u32x2 w; w.x = cvt_pk_bf16(g3[0], g3[1]); w.y = cvt_pk_bf16(g3[2], g3[3]); *(u32x2*)(rp + 3 * pl) = w; } }
;                 else {
;                 { u32x4 w; w.x = cvt_pk_bf16(g0[0], g0[1]); w.y = cvt_pk_bf16(g0[2], g0[3]); w.z = cvt_pk_bf16(g1[0], g1[1]); w.w = cvt_pk_bf16(g1[2], g1[3]); *(u32x4*)rowp = w; }
;                 { u32x4 w; w.x = cvt_pk_bf16(g2[0], g2[1]); w.y = cvt_pk_bf16(g2[2], g2[3]); w.z = cvt_pk_bf16(g3[0], g3[1]); w.w = cvt_pk_bf16(g3[2], g3[3]); *(u32x4*)(rowp + HALF) = w; } } }
.LBB0_293:
	s_mov_b64 s[8:9], -1
	s_and_b64 vcc, exec, s[40:41]
	v_cvt_pk_bf16_f32 v104, v118, v119
	v_cvt_pk_bf16_f32 v105, v120, v121
	v_cvt_pk_bf16_f32 v106, v122, v123
	v_cvt_pk_bf16_f32 v107, v124, v125
	v_cvt_pk_bf16_f32 v96, v126, v127
	v_cvt_pk_bf16_f32 v97, v158, v159
	v_cvt_pk_bf16_f32 v98, v100, v101
	v_cvt_pk_bf16_f32 v99, v102, v103
	s_cbranch_vccnz .LBB0_295
	v_lshlrev_b64 v[100:101], 11, v[156:157]
	v_lshl_add_u64 v[100:101], s[20:21], 0, v[100:101]
	s_lshl_b32 s16, s6, 7
	v_lshl_add_u64 v[100:101], v[100:101], 0, s[16:17]
	s_lshl_b32 s16, s75, 1
	v_lshl_add_u64 v[100:101], v[100:101], 0, s[16:17]
	v_lshl_add_u64 v[100:101], v[100:101], 0, v[192:193]
	v_lshl_add_u64 v[102:103], v[100:101], 0, s[90:91]
	v_add_co_u32_e32 v100, vcc, s30, v100
	s_mov_b64 s[8:9], 0
	s_nop 0
	v_addc_co_u32_e32 v101, vcc, -1, v101, vcc
	global_store_dwordx2 v[100:101], v[104:105], off
	v_lshl_add_u64 v[100:101], v[102:103], 0, s[12:13]
	global_store_dwordx2 v[100:101], v[106:107], off
	v_lshl_add_u64 v[100:101], v[100:101], 0, s[12:13]
	global_store_dwordx2 v[100:101], v[96:97], off
	v_lshl_add_u64 v[100:101], v[100:101], 0, s[12:13]
	global_store_dwordx2 v[100:101], v[98:99], off
.LBB0_295:
	s_andn2_b64 vcc, exec, s[8:9]
	s_cbranch_vccnz .LBB0_297
	v_mov_b64_e32 v[100:101], s[14:15]
	v_mad_i64_i32 v[100:101], s[8:9], v156, s56, v[100:101]
	v_lshl_add_u64 v[100:101], v[116:117], 1, v[100:101]
	global_store_dwordx4 v[100:101], v[104:107], off
	global_store_dwordx4 v[100:101], v[96:99], off offset:256
.LBB0_297:
	s_nop 1
	v_add_f32_e32 v96, v189, v190
	v_fmamk_f32 v96, v96, 0x3a800000, v242
	v_rsq_f32_e32 v100, v96
	s_mov_b64 s[48:49], -1
	s_and_b64 vcc, exec, s[46:47]
	v_mul_f32_e32 v100, s99, v100
	v_pk_mul_f32 v[94:95], v[94:95], v[100:101] op_sel_hi:[1,0]
	v_pk_mul_f32 v[92:93], v[92:93], v[100:101] op_sel_hi:[1,0]
	v_pk_mul_f32 v[90:91], v[90:91], v[100:101] op_sel_hi:[1,0]
	v_pk_mul_f32 v[88:89], v[88:89], v[100:101] op_sel_hi:[1,0]
	v_pk_mul_f32 v[96:97], v[86:87], v[100:101] op_sel_hi:[1,0]
	v_pk_mul_f32 v[98:99], v[84:85], v[100:101] op_sel_hi:[1,0]
	v_pk_mul_f32 v[82:83], v[82:83], v[100:101] op_sel_hi:[1,0]
	v_pk_mul_f32 v[80:81], v[80:81], v[100:101] op_sel_hi:[1,0]
	s_cbranch_vccz .LBB0_299
	v_exp_f32_e32 v84, v92
	v_exp_f32_e32 v85, v88
	v_exp_f32_e32 v86, v98
	v_exp_f32_e32 v87, v80
	v_add_f32_e32 v84, 1.0, v84
	v_add_f32_e32 v85, 1.0, v85
	v_min_f32_e32 v84, 0x49742400, v84
	v_min_f32_e32 v100, 0x49742400, v85
	v_add_f32_e32 v85, 1.0, v86
	v_min_f32_e32 v104, 0x49742400, v85
	v_add_f32_e32 v85, 1.0, v87
	v_rcp_f32_e32 v102, v84
	v_min_f32_e32 v108, 0x49742400, v85
	v_exp_f32_e32 v85, v93
	v_exp_f32_e32 v86, v89
	v_exp_f32_e32 v87, v99
	v_exp_f32_e32 v103, v81
	v_add_f32_e32 v85, 1.0, v85
	v_add_f32_e32 v86, 1.0, v86
	v_min_f32_e32 v85, 0x49742400, v85
	v_min_f32_e32 v101, 0x49742400, v86
	v_add_f32_e32 v86, 1.0, v87
	v_min_f32_e32 v105, 0x49742400, v86
	v_add_f32_e32 v86, 1.0, v103
	v_rcp_f32_e32 v103, v85
	v_min_f32_e32 v109, 0x49742400, v86
	v_exp_f32_e32 v86, v94
	v_exp_f32_e32 v87, v90
	v_exp_f32_e32 v113, v96
	v_exp_f32_e32 v115, v82
	v_add_f32_e32 v86, 1.0, v86
	v_add_f32_e32 v87, 1.0, v87
	v_min_f32_e32 v86, 0x49742400, v86
	v_min_f32_e32 v112, 0x49742400, v87
	v_add_f32_e32 v87, 1.0, v113
	v_min_f32_e32 v114, 0x49742400, v87
	v_add_f32_e32 v87, 1.0, v115
	v_rcp_f32_e32 v120, v86
	v_min_f32_e32 v118, 0x49742400, v87
	v_exp_f32_e32 v87, v95
	v_exp_f32_e32 v113, v91
	v_exp_f32_e32 v115, v97
	v_add_f32_e32 v87, 1.0, v87
	v_add_f32_e32 v113, 1.0, v113
	v_exp_f32_e32 v119, v83
	v_add_f32_e32 v115, 1.0, v115
	v_min_f32_e32 v87, 0x49742400, v87
	v_min_f32_e32 v113, 0x49742400, v113
	v_min_f32_e32 v115, 0x49742400, v115
	v_rcp_f32_e32 v106, v100
	v_rcp_f32_e32 v110, v104
	v_rcp_f32_e32 v107, v101
	v_rcp_f32_e32 v111, v105
	v_rcp_f32_e32 v122, v112
	v_rcp_f32_e32 v124, v114
	v_rcp_f32_e32 v121, v87
	v_rcp_f32_e32 v123, v113
	v_rcp_f32_e32 v125, v115
	v_add_f32_e32 v119, 1.0, v119
	v_min_f32_e32 v119, 0x49742400, v119
	v_rcp_f32_e32 v84, v108
	v_rcp_f32_e32 v85, v109
	v_rcp_f32_e32 v86, v118
	v_pk_mul_f32 v[100:101], v[100:101], v[102:103]
	v_pk_mul_f32 v[102:103], v[112:113], v[120:121]
	v_pk_mul_f32 v[104:105], v[104:105], v[106:107]
	v_pk_mul_f32 v[106:107], v[114:115], v[122:123]
	v_rcp_f32_e32 v87, v119
	v_pk_mul_f32 v[108:109], v[108:109], v[110:111]
	v_pk_mul_f32 v[110:111], v[118:119], v[124:125]
	s_mov_b64 s[48:49], 0

;     __device__ __forceinline__ void operator()(const f32x4 (&acc)[2][2][4][2], const Unit& u, int wr, int wc, int fr, int fq) const {
;     ...
;             for (int m = 0; m < 4; ++m) { bf16_t* rowp = O + (size_t)(row0 + ai * HALF + m * 16) * ldc + col0;
;                 const float rs_ = rs8[ai][m];
;                 f32x4 g0 = acc[ai][0][m][0] * rs_, g1 = acc[ai][0][m][1] * rs_, g2 = acc[ai][1][m][0] * rs_, g3 = acc[ai][1][m][1] * rs_;
;                 if (sg) {
; #pragma unroll
;                     for (int j = 0; j < 4; ++j) {
;                         const float e0 = fminf(1.0f + __builtin_amdgcn_exp2f(-1.4426950408889634f * g0[j]), 1e6f), e1 = fminf(1.0f + __builtin_amdgcn_exp2f(-1.4426950408889634f * g1[j]), 1e6f);
;                         const float e2 = fminf(1.0f + __builtin_amdgcn_exp2f(-1.4426950408889634f * g2[j]), 1e6f), e3 = fminf(1.0f + __builtin_amdgcn_exp2f(-1.4426950408889634f * g3[j]), 1e6f);
;                         g0[j] = e1 * __builtin_amdgcn_rcpf(e0); g1[j] = e2 * __builtin_amdgcn_rcpf(e1); g2[j] = e3 * __builtin_amdgcn_rcpf(e2); g3[j] = __builtin_amdgcn_rcpf(e3); }
;                 }
;                 if (sg) { typedef unsigned u32x2 __attribute__((ext_vector_type(2)));
;                     bf16_t* rp = rat + (size_t)(row0 + ai * HALF + m * 16) * 1024 + (u.pn - sig_pn0) * 64 + 16 * wc + 4 * fq; const size_t pl = (size_t)Trows * 1024;
;                     { u32x2 w; w.x = cvt_pk_bf16(g0[0], g0[1]); w.y = cvt_pk_bf16(g0[2], g0[3]); *(u32x2*)rp = w; }
;                     { u32x2 w; w.x = cvt_pk_bf16(g1[0], g1[1]); w.y = cvt_pk_bf16(g1[2], g1[3]); *(u32x2*)(rp + pl) = w; }
;                     { u32x2 w; w.x = cvt_pk_bf16(g2[0], g2[1]); w.y = cvt_pk_bf16(g2[2], g2[3]); *(u32x2*)(rp + 2 * pl) = w; }
;                     { u32x2 w; w.x = cvt_pk_bf16(g3[0], g3[1]); w.y = cvt_pk_bf16(g3[2], g3[3]); *(u32x2*)(rp + 3 * pl) = w; } }
;                 else {
;                 { u32x4 w; w.x = cvt_pk_bf16(g0[0], g0[1]); w.y = cvt_pk_bf16(g0[2], g0[3]); w.z = cvt_pk_bf16(g1[0], g1[1]); w.w = cvt_pk_bf16(g1[2], g1[3]); *(u32x4*)rowp = w; }
;                 { u32x4 w; w.x = cvt_pk_bf16(g2[0], g2[1]); w.y = cvt_pk_bf16(g2[2], g2[3]); w.z = cvt_pk_bf16(g3[0], g3[1]); w.w = cvt_pk_bf16(g3[2], g3[3]); *(u32x4*)(rowp + HALF) = w; } } }
.LBB0_301:
	s_mov_b64 s[8:9], -1
	s_and_b64 vcc, exec, s[40:41]
	v_cvt_pk_bf16_f32 v88, v100, v101
	v_cvt_pk_bf16_f32 v89, v102, v103
	v_cvt_pk_bf16_f32 v90, v104, v105
	v_cvt_pk_bf16_f32 v91, v106, v107
	v_cvt_pk_bf16_f32 v80, v108, v109
	v_cvt_pk_bf16_f32 v81, v110, v111
	v_cvt_pk_bf16_f32 v82, v84, v85
	v_cvt_pk_bf16_f32 v83, v86, v87
	s_cbranch_vccnz .LBB0_303
	v_lshlrev_b64 v[84:85], 11, v[154:155]
	v_lshl_add_u64 v[84:85], s[20:21], 0, v[84:85]
	s_lshl_b32 s16, s6, 7
	v_lshl_add_u64 v[84:85], v[84:85], 0, s[16:17]
	s_lshl_b32 s16, s75, 1
	v_lshl_add_u64 v[84:85], v[84:85], 0, s[16:17]
	v_lshl_add_u64 v[84:85], v[84:85], 0, v[192:193]
	v_lshl_add_u64 v[86:87], v[84:85], 0, s[90:91]
	v_add_co_u32_e32 v84, vcc, s30, v84
	s_mov_b64 s[8:9], 0
	s_nop 0
	v_addc_co_u32_e32 v85, vcc, -1, v85, vcc
	global_store_dwordx2 v[84:85], v[88:89], off
	v_lshl_add_u64 v[84:85], v[86:87], 0, s[12:13]
	global_store_dwordx2 v[84:85], v[90:91], off
	v_lshl_add_u64 v[84:85], v[84:85], 0, s[12:13]
	global_store_dwordx2 v[84:85], v[80:81], off
	v_lshl_add_u64 v[84:85], v[84:85], 0, s[12:13]
	global_store_dwordx2 v[84:85], v[82:83], off
.LBB0_303:
	s_andn2_b64 vcc, exec, s[8:9]
	s_cbranch_vccnz .LBB0_305
	v_mov_b64_e32 v[84:85], s[14:15]
	v_mad_i64_i32 v[84:85], s[8:9], v154, s56, v[84:85]
	v_lshl_add_u64 v[84:85], v[116:117], 1, v[84:85]
	global_store_dwordx4 v[84:85], v[88:91], off
	global_store_dwordx4 v[84:85], v[80:83], off offset:256
.LBB0_305:
	s_nop 1
	v_add_f32_e32 v80, v187, v188
	v_fmamk_f32 v80, v80, 0x3a800000, v242
	v_rsq_f32_e32 v84, v80
	s_mov_b64 s[48:49], -1
	s_and_b64 vcc, exec, s[46:47]
	v_mul_f32_e32 v84, s99, v84
	v_pk_mul_f32 v[78:79], v[78:79], v[84:85] op_sel_hi:[1,0]
	v_pk_mul_f32 v[76:77], v[76:77], v[84:85] op_sel_hi:[1,0]
	v_pk_mul_f32 v[74:75], v[74:75], v[84:85] op_sel_hi:[1,0]
	v_pk_mul_f32 v[72:73], v[72:73], v[84:85] op_sel_hi:[1,0]
	v_pk_mul_f32 v[80:81], v[70:71], v[84:85] op_sel_hi:[1,0]
	v_pk_mul_f32 v[82:83], v[68:69], v[84:85] op_sel_hi:[1,0]
	v_pk_mul_f32 v[66:67], v[66:67], v[84:85] op_sel_hi:[1,0]
	v_pk_mul_f32 v[64:65], v[64:65], v[84:85] op_sel_hi:[1,0]
	s_cbranch_vccz .LBB0_307
	v_exp_f32_e32 v68, v76
	v_exp_f32_e32 v69, v72
	v_exp_f32_e32 v70, v82
	v_exp_f32_e32 v71, v64
	v_add_f32_e32 v68, 1.0, v68
	v_add_f32_e32 v69, 1.0, v69
	v_min_f32_e32 v68, 0x49742400, v68
	v_min_f32_e32 v84, 0x49742400, v69
	v_add_f32_e32 v69, 1.0, v70
	v_min_f32_e32 v88, 0x49742400, v69
	v_add_f32_e32 v69, 1.0, v71
	v_rcp_f32_e32 v86, v68
	v_min_f32_e32 v92, 0x49742400, v69
	v_exp_f32_e32 v69, v77
	v_exp_f32_e32 v70, v73
	v_exp_f32_e32 v71, v83
	v_exp_f32_e32 v87, v65
	v_add_f32_e32 v69, 1.0, v69
	v_add_f32_e32 v70, 1.0, v70
	v_min_f32_e32 v69, 0x49742400, v69
	v_min_f32_e32 v85, 0x49742400, v70
	v_add_f32_e32 v70, 1.0, v71
	v_min_f32_e32 v89, 0x49742400, v70
	v_add_f32_e32 v70, 1.0, v87
	v_rcp_f32_e32 v87, v69
	v_min_f32_e32 v93, 0x49742400, v70
	v_exp_f32_e32 v70, v78
	v_exp_f32_e32 v71, v74
	v_exp_f32_e32 v97, v80
	v_exp_f32_e32 v99, v66
	v_add_f32_e32 v70, 1.0, v70
	v_add_f32_e32 v71, 1.0, v71
	v_min_f32_e32 v70, 0x49742400, v70
	v_min_f32_e32 v96, 0x49742400, v71
	v_add_f32_e32 v71, 1.0, v97
	v_min_f32_e32 v98, 0x49742400, v71
	v_add_f32_e32 v71, 1.0, v99
	v_rcp_f32_e32 v102, v70
	v_min_f32_e32 v100, 0x49742400, v71
	v_exp_f32_e32 v71, v79
	v_exp_f32_e32 v97, v75
	v_exp_f32_e32 v99, v81
	v_add_f32_e32 v71, 1.0, v71
	v_add_f32_e32 v97, 1.0, v97
	v_exp_f32_e32 v101, v67
	v_add_f32_e32 v99, 1.0, v99
	v_min_f32_e32 v71, 0x49742400, v71
	v_min_f32_e32 v97, 0x49742400, v97
	v_min_f32_e32 v99, 0x49742400, v99
	v_rcp_f32_e32 v90, v84
	v_rcp_f32_e32 v94, v88
	v_rcp_f32_e32 v91, v85
	v_rcp_f32_e32 v95, v89
	v_rcp_f32_e32 v104, v96
	v_rcp_f32_e32 v106, v98
	v_rcp_f32_e32 v103, v71
	v_rcp_f32_e32 v105, v97
	v_rcp_f32_e32 v107, v99
	v_add_f32_e32 v101, 1.0, v101
	v_min_f32_e32 v101, 0x49742400, v101
	v_rcp_f32_e32 v68, v92
	v_rcp_f32_e32 v69, v93
	v_rcp_f32_e32 v70, v100
	v_pk_mul_f32 v[84:85], v[84:85], v[86:87]
	v_pk_mul_f32 v[86:87], v[96:97], v[102:103]
	v_pk_mul_f32 v[88:89], v[88:89], v[90:91]
	v_pk_mul_f32 v[90:91], v[98:99], v[104:105]
	v_rcp_f32_e32 v71, v101
	v_pk_mul_f32 v[92:93], v[92:93], v[94:95]
	v_pk_mul_f32 v[94:95], v[100:101], v[106:107]
	s_mov_b64 s[48:49], 0

;     __device__ __forceinline__ void operator()(const f32x4 (&acc)[2][2][4][2], const Unit& u, int wr, int wc, int fr, int fq) const {
;     ...
;             for (int m = 0; m < 4; ++m) { bf16_t* rowp = O + (size_t)(row0 + ai * HALF + m * 16) * ldc + col0;
;                 const float rs_ = rs8[ai][m];
;                 f32x4 g0 = acc[ai][0][m][0] * rs_, g1 = acc[ai][0][m][1] * rs_, g2 = acc[ai][1][m][0] * rs_, g3 = acc[ai][1][m][1] * rs_;
;                 if (sg) {
; #pragma unroll
;                     for (int j = 0; j < 4; ++j) {
;                         const float e0 = fminf(1.0f + __builtin_amdgcn_exp2f(-1.4426950408889634f * g0[j]), 1e6f), e1 = fminf(1.0f + __builtin_amdgcn_exp2f(-1.4426950408889634f * g1[j]), 1e6f);
;                         const float e2 = fminf(1.0f + __builtin_amdgcn_exp2f(-1.4426950408889634f * g2[j]), 1e6f), e3 = fminf(1.0f + __builtin_amdgcn_exp2f(-1.4426950408889634f * g3[j]), 1e6f);
;                         g0[j] = e1 * __builtin_amdgcn_rcpf(e0); g1[j] = e2 * __builtin_amdgcn_rcpf(e1); g2[j] = e3 * __builtin_amdgcn_rcpf(e2); g3[j] = __builtin_amdgcn_rcpf(e3); }
;                 }
;                 if (sg) { typedef unsigned u32x2 __attribute__((ext_vector_type(2)));
;                     bf16_t* rp = rat + (size_t)(row0 + ai * HALF + m * 16) * 1024 + (u.pn - sig_pn0) * 64 + 16 * wc + 4 * fq; const size_t pl = (size_t)Trows * 1024;
;                     { u32x2 w; w.x = cvt_pk_bf16(g0[0], g0[1]); w.y = cvt_pk_bf16(g0[2], g0[3]); *(u32x2*)rp = w; }
;                     { u32x2 w; w.x = cvt_pk_bf16(g1[0], g1[1]); w.y = cvt_pk_bf16(g1[2], g1[3]); *(u32x2*)(rp + pl) = w; }
;                     { u32x2 w; w.x = cvt_pk_bf16(g2[0], g2[1]); w.y = cvt_pk_bf16(g2[2], g2[3]); *(u32x2*)(rp + 2 * pl) = w; }
;                     { u32x2 w; w.x = cvt_pk_bf16(g3[0], g3[1]); w.y = cvt_pk_bf16(g3[2], g3[3]); *(u32x2*)(rp + 3 * pl) = w; } }
;                 else {
;                 { u32x4 w; w.x = cvt_pk_bf16(g0[0], g0[1]); w.y = cvt_pk_bf16(g0[2], g0[3]); w.z = cvt_pk_bf16(g1[0], g1[1]); w.w = cvt_pk_bf16(g1[2], g1[3]); *(u32x4*)rowp = w; }
;                 { u32x4 w; w.x = cvt_pk_bf16(g2[0], g2[1]); w.y = cvt_pk_bf16(g2[2], g2[3]); w.z = cvt_pk_bf16(g3[0], g3[1]); w.w = cvt_pk_bf16(g3[2], g3[3]); *(u32x4*)(rowp + HALF) = w; } } }
.LBB0_309:
	s_mov_b64 s[8:9], -1
	s_and_b64 vcc, exec, s[40:41]
	v_cvt_pk_bf16_f32 v72, v84, v85
	v_cvt_pk_bf16_f32 v73, v86, v87
	v_cvt_pk_bf16_f32 v74, v88, v89
	v_cvt_pk_bf16_f32 v75, v90, v91
	v_cvt_pk_bf16_f32 v64, v92, v93
	v_cvt_pk_bf16_f32 v65, v94, v95
	v_cvt_pk_bf16_f32 v66, v68, v69
	v_cvt_pk_bf16_f32 v67, v70, v71
	s_cbranch_vccnz .LBB0_311
	v_lshlrev_b64 v[68:69], 11, v[152:153]
	v_lshl_add_u64 v[68:69], s[20:21], 0, v[68:69]
	s_lshl_b32 s16, s6, 7
	v_lshl_add_u64 v[68:69], v[68:69], 0, s[16:17]
	s_lshl_b32 s16, s75, 1
	v_lshl_add_u64 v[68:69], v[68:69], 0, s[16:17]
	v_lshl_add_u64 v[68:69], v[68:69], 0, v[192:193]
	v_lshl_add_u64 v[70:71], v[68:69], 0, s[90:91]
	v_add_co_u32_e32 v68, vcc, s30, v68
	s_mov_b64 s[8:9], 0
	s_nop 0
	v_addc_co_u32_e32 v69, vcc, -1, v69, vcc
	global_store_dwordx2 v[68:69], v[72:73], off
	v_lshl_add_u64 v[68:69], v[70:71], 0, s[12:13]
	global_store_dwordx2 v[68:69], v[74:75], off
	v_lshl_add_u64 v[68:69], v[68:69], 0, s[12:13]
	global_store_dwordx2 v[68:69], v[64:65], off
	v_lshl_add_u64 v[68:69], v[68:69], 0, s[12:13]
	global_store_dwordx2 v[68:69], v[66:67], off
.LBB0_311:
	s_andn2_b64 vcc, exec, s[8:9]
	s_cbranch_vccnz .LBB0_313
	v_mov_b64_e32 v[68:69], s[14:15]
	v_mad_i64_i32 v[68:69], s[8:9], v152, s56, v[68:69]
	v_lshl_add_u64 v[68:69], v[116:117], 1, v[68:69]
	global_store_dwordx4 v[68:69], v[72:75], off
	global_store_dwordx4 v[68:69], v[64:67], off offset:256
.LBB0_313:
	s_nop 1
	v_add_f32_e32 v64, v185, v186
	v_fmamk_f32 v64, v64, 0x3a800000, v242
	v_rsq_f32_e32 v68, v64
	s_mov_b64 s[48:49], -1
	s_and_b64 vcc, exec, s[46:47]
	v_mul_f32_e32 v68, s99, v68
	v_pk_mul_f32 v[62:63], v[62:63], v[68:69] op_sel_hi:[1,0]
	v_pk_mul_f32 v[60:61], v[60:61], v[68:69] op_sel_hi:[1,0]
	v_pk_mul_f32 v[58:59], v[58:59], v[68:69] op_sel_hi:[1,0]
	v_pk_mul_f32 v[56:57], v[56:57], v[68:69] op_sel_hi:[1,0]
	v_pk_mul_f32 v[64:65], v[54:55], v[68:69] op_sel_hi:[1,0]
	v_pk_mul_f32 v[66:67], v[52:53], v[68:69] op_sel_hi:[1,0]
	v_pk_mul_f32 v[50:51], v[50:51], v[68:69] op_sel_hi:[1,0]
	v_pk_mul_f32 v[48:49], v[48:49], v[68:69] op_sel_hi:[1,0]
	s_cbranch_vccz .LBB0_315
	v_exp_f32_e32 v52, v60
	v_exp_f32_e32 v53, v56
	v_exp_f32_e32 v54, v66
	v_exp_f32_e32 v55, v48
	v_add_f32_e32 v52, 1.0, v52
	v_add_f32_e32 v53, 1.0, v53
	v_min_f32_e32 v52, 0x49742400, v52
	v_min_f32_e32 v68, 0x49742400, v53
	v_add_f32_e32 v53, 1.0, v54
	v_min_f32_e32 v72, 0x49742400, v53
	v_add_f32_e32 v53, 1.0, v55
	v_rcp_f32_e32 v70, v52
	v_min_f32_e32 v76, 0x49742400, v53
	v_exp_f32_e32 v53, v61
	v_exp_f32_e32 v54, v57
	v_exp_f32_e32 v55, v67
	v_exp_f32_e32 v71, v49
	v_add_f32_e32 v53, 1.0, v53
	v_add_f32_e32 v54, 1.0, v54
	v_min_f32_e32 v53, 0x49742400, v53
	v_min_f32_e32 v69, 0x49742400, v54
	v_add_f32_e32 v54, 1.0, v55
	v_min_f32_e32 v73, 0x49742400, v54
	v_add_f32_e32 v54, 1.0, v71
	v_rcp_f32_e32 v71, v53
	v_min_f32_e32 v77, 0x49742400, v54
	v_exp_f32_e32 v54, v62
	v_exp_f32_e32 v55, v58
	v_exp_f32_e32 v81, v64
	v_exp_f32_e32 v83, v50
	v_add_f32_e32 v54, 1.0, v54
	v_add_f32_e32 v55, 1.0, v55
	v_min_f32_e32 v54, 0x49742400, v54
	v_min_f32_e32 v80, 0x49742400, v55
	v_add_f32_e32 v55, 1.0, v81
	v_min_f32_e32 v82, 0x49742400, v55
	v_add_f32_e32 v55, 1.0, v83
	v_rcp_f32_e32 v86, v54
	v_min_f32_e32 v84, 0x49742400, v55
	v_exp_f32_e32 v55, v63
	v_exp_f32_e32 v81, v59
	v_exp_f32_e32 v83, v65
	v_add_f32_e32 v55, 1.0, v55
	v_add_f32_e32 v81, 1.0, v81
	v_exp_f32_e32 v85, v51
	v_add_f32_e32 v83, 1.0, v83
	v_min_f32_e32 v55, 0x49742400, v55
	v_min_f32_e32 v81, 0x49742400, v81
	v_min_f32_e32 v83, 0x49742400, v83
	v_rcp_f32_e32 v74, v68
	v_rcp_f32_e32 v78, v72
	v_rcp_f32_e32 v75, v69
	v_rcp_f32_e32 v79, v73
	v_rcp_f32_e32 v88, v80
	v_rcp_f32_e32 v90, v82
	v_rcp_f32_e32 v87, v55
	v_rcp_f32_e32 v89, v81
	v_rcp_f32_e32 v91, v83
	v_add_f32_e32 v85, 1.0, v85
	v_min_f32_e32 v85, 0x49742400, v85
	v_rcp_f32_e32 v52, v76
	v_rcp_f32_e32 v53, v77
	v_rcp_f32_e32 v54, v84
	v_pk_mul_f32 v[68:69], v[68:69], v[70:71]
	v_pk_mul_f32 v[70:71], v[80:81], v[86:87]
	v_pk_mul_f32 v[72:73], v[72:73], v[74:75]
	v_pk_mul_f32 v[74:75], v[82:83], v[88:89]
	v_rcp_f32_e32 v55, v85
	v_pk_mul_f32 v[76:77], v[76:77], v[78:79]
	v_pk_mul_f32 v[78:79], v[84:85], v[90:91]
	s_mov_b64 s[48:49], 0

;     __device__ __forceinline__ void operator()(const f32x4 (&acc)[2][2][4][2], const Unit& u, int wr, int wc, int fr, int fq) const {
;     ...
;             for (int m = 0; m < 4; ++m) { bf16_t* rowp = O + (size_t)(row0 + ai * HALF + m * 16) * ldc + col0;
;                 const float rs_ = rs8[ai][m];
;                 f32x4 g0 = acc[ai][0][m][0] * rs_, g1 = acc[ai][0][m][1] * rs_, g2 = acc[ai][1][m][0] * rs_, g3 = acc[ai][1][m][1] * rs_;
;                 if (sg) {
; #pragma unroll
;                     for (int j = 0; j < 4; ++j) {
;                         const float e0 = fminf(1.0f + __builtin_amdgcn_exp2f(-1.4426950408889634f * g0[j]), 1e6f), e1 = fminf(1.0f + __builtin_amdgcn_exp2f(-1.4426950408889634f * g1[j]), 1e6f);
;                         const float e2 = fminf(1.0f + __builtin_amdgcn_exp2f(-1.4426950408889634f * g2[j]), 1e6f), e3 = fminf(1.0f + __builtin_amdgcn_exp2f(-1.4426950408889634f * g3[j]), 1e6f);
;                         g0[j] = e1 * __builtin_amdgcn_rcpf(e0); g1[j] = e2 * __builtin_amdgcn_rcpf(e1); g2[j] = e3 * __builtin_amdgcn_rcpf(e2); g3[j] = __builtin_amdgcn_rcpf(e3); }
;                 }
;                 if (sg) { typedef unsigned u32x2 __attribute__((ext_vector_type(2)));
;                     bf16_t* rp = rat + (size_t)(row0 + ai * HALF + m * 16) * 1024 + (u.pn - sig_pn0) * 64 + 16 * wc + 4 * fq; const size_t pl = (size_t)Trows * 1024;
;                     { u32x2 w; w.x = cvt_pk_bf16(g0[0], g0[1]); w.y = cvt_pk_bf16(g0[2], g0[3]); *(u32x2*)rp = w; }
;                     { u32x2 w; w.x = cvt_pk_bf16(g1[0], g1[1]); w.y = cvt_pk_bf16(g1[2], g1[3]); *(u32x2*)(rp + pl) = w; }
;                     { u32x2 w; w.x = cvt_pk_bf16(g2[0], g2[1]); w.y = cvt_pk_bf16(g2[2], g2[3]); *(u32x2*)(rp + 2 * pl) = w; }
;                     { u32x2 w; w.x = cvt_pk_bf16(g3[0], g3[1]); w.y = cvt_pk_bf16(g3[2], g3[3]); *(u32x2*)(rp + 3 * pl) = w; } }
;                 else {
;                 { u32x4 w; w.x = cvt_pk_bf16(g0[0], g0[1]); w.y = cvt_pk_bf16(g0[2], g0[3]); w.z = cvt_pk_bf16(g1[0], g1[1]); w.w = cvt_pk_bf16(g1[2], g1[3]); *(u32x4*)rowp = w; }
;                 { u32x4 w; w.x = cvt_pk_bf16(g2[0], g2[1]); w.y = cvt_pk_bf16(g2[2], g2[3]); w.z = cvt_pk_bf16(g3[0], g3[1]); w.w = cvt_pk_bf16(g3[2], g3[3]); *(u32x4*)(rowp + HALF) = w; } } }
.LBB0_317:
	s_mov_b64 s[8:9], -1
	s_and_b64 vcc, exec, s[40:41]
	v_cvt_pk_bf16_f32 v56, v68, v69
	v_cvt_pk_bf16_f32 v57, v70, v71
	v_cvt_pk_bf16_f32 v58, v72, v73
	v_cvt_pk_bf16_f32 v59, v74, v75
	v_cvt_pk_bf16_f32 v48, v76, v77
	v_cvt_pk_bf16_f32 v49, v78, v79
	v_cvt_pk_bf16_f32 v50, v52, v53
	v_cvt_pk_bf16_f32 v51, v54, v55
	s_cbranch_vccnz .LBB0_319
	v_lshlrev_b64 v[52:53], 11, v[150:151]
	v_lshl_add_u64 v[52:53], s[20:21], 0, v[52:53]
	s_lshl_b32 s16, s6, 7
	v_lshl_add_u64 v[52:53], v[52:53], 0, s[16:17]
	s_lshl_b32 s16, s75, 1
	v_lshl_add_u64 v[52:53], v[52:53], 0, s[16:17]
	v_lshl_add_u64 v[52:53], v[52:53], 0, v[192:193]
	v_lshl_add_u64 v[54:55], v[52:53], 0, s[90:91]
	v_add_co_u32_e32 v52, vcc, s30, v52
	s_mov_b64 s[8:9], 0
	s_nop 0
	v_addc_co_u32_e32 v53, vcc, -1, v53, vcc
	global_store_dwordx2 v[52:53], v[56:57], off
	v_lshl_add_u64 v[52:53], v[54:55], 0, s[12:13]
	global_store_dwordx2 v[52:53], v[58:59], off
	v_lshl_add_u64 v[52:53], v[52:53], 0, s[12:13]
	global_store_dwordx2 v[52:53], v[48:49], off
	v_lshl_add_u64 v[52:53], v[52:53], 0, s[12:13]
	global_store_dwordx2 v[52:53], v[50:51], off
.LBB0_319:
	s_andn2_b64 vcc, exec, s[8:9]
	s_cbranch_vccnz .LBB0_321
	v_mov_b64_e32 v[52:53], s[14:15]
	v_mad_i64_i32 v[52:53], s[8:9], v150, s56, v[52:53]
	v_lshl_add_u64 v[52:53], v[116:117], 1, v[52:53]
	global_store_dwordx4 v[52:53], v[56:59], off
	global_store_dwordx4 v[52:53], v[48:51], off offset:256
.LBB0_321:
	s_nop 1
	v_add_f32_e32 v48, v183, v184
	v_fmamk_f32 v48, v48, 0x3a800000, v242
	v_rsq_f32_e32 v52, v48
	s_mov_b64 s[48:49], -1
	s_and_b64 vcc, exec, s[46:47]
	v_mul_f32_e32 v52, s99, v52
	v_pk_mul_f32 v[46:47], v[46:47], v[52:53] op_sel_hi:[1,0]
	v_pk_mul_f32 v[44:45], v[44:45], v[52:53] op_sel_hi:[1,0]
	v_pk_mul_f32 v[42:43], v[42:43], v[52:53] op_sel_hi:[1,0]
	v_pk_mul_f32 v[40:41], v[40:41], v[52:53] op_sel_hi:[1,0]
	v_pk_mul_f32 v[48:49], v[38:39], v[52:53] op_sel_hi:[1,0]
	v_pk_mul_f32 v[50:51], v[36:37], v[52:53] op_sel_hi:[1,0]
	v_pk_mul_f32 v[34:35], v[34:35], v[52:53] op_sel_hi:[1,0]
	v_pk_mul_f32 v[32:33], v[32:33], v[52:53] op_sel_hi:[1,0]
	s_cbranch_vccz .LBB0_323
	v_exp_f32_e32 v36, v44
	v_exp_f32_e32 v37, v40
	v_exp_f32_e32 v38, v50
	v_exp_f32_e32 v39, v32
	v_add_f32_e32 v36, 1.0, v36
	v_add_f32_e32 v37, 1.0, v37
	v_min_f32_e32 v36, 0x49742400, v36
	v_min_f32_e32 v52, 0x49742400, v37
	v_add_f32_e32 v37, 1.0, v38
	v_min_f32_e32 v56, 0x49742400, v37
	v_add_f32_e32 v37, 1.0, v39
	v_rcp_f32_e32 v54, v36
	v_min_f32_e32 v60, 0x49742400, v37
	v_exp_f32_e32 v37, v45
	v_exp_f32_e32 v38, v41
	v_exp_f32_e32 v39, v51
	v_exp_f32_e32 v55, v33
	v_add_f32_e32 v37, 1.0, v37
	v_add_f32_e32 v38, 1.0, v38
	v_min_f32_e32 v37, 0x49742400, v37
	v_min_f32_e32 v53, 0x49742400, v38
	v_add_f32_e32 v38, 1.0, v39
	v_min_f32_e32 v57, 0x49742400, v38
	v_add_f32_e32 v38, 1.0, v55
	v_rcp_f32_e32 v55, v37
	v_min_f32_e32 v61, 0x49742400, v38
	v_exp_f32_e32 v38, v46
	v_exp_f32_e32 v39, v42
	v_exp_f32_e32 v65, v48
	v_exp_f32_e32 v67, v34
	v_add_f32_e32 v38, 1.0, v38
	v_add_f32_e32 v39, 1.0, v39
	v_min_f32_e32 v38, 0x49742400, v38
	v_min_f32_e32 v64, 0x49742400, v39
	v_add_f32_e32 v39, 1.0, v65
	v_min_f32_e32 v66, 0x49742400, v39
	v_add_f32_e32 v39, 1.0, v67
	v_rcp_f32_e32 v70, v38
	v_min_f32_e32 v68, 0x49742400, v39
	v_exp_f32_e32 v39, v47
	v_exp_f32_e32 v65, v43
	v_exp_f32_e32 v67, v49
	v_add_f32_e32 v39, 1.0, v39
	v_add_f32_e32 v65, 1.0, v65
	v_exp_f32_e32 v69, v35
	v_add_f32_e32 v67, 1.0, v67
	v_min_f32_e32 v39, 0x49742400, v39
	v_min_f32_e32 v65, 0x49742400, v65
	v_min_f32_e32 v67, 0x49742400, v67
	v_rcp_f32_e32 v58, v52
	v_rcp_f32_e32 v62, v56
	v_rcp_f32_e32 v59, v53
	v_rcp_f32_e32 v63, v57
	v_rcp_f32_e32 v72, v64
	v_rcp_f32_e32 v74, v66
	v_rcp_f32_e32 v71, v39
	v_rcp_f32_e32 v73, v65
	v_rcp_f32_e32 v75, v67
	v_add_f32_e32 v69, 1.0, v69
	v_min_f32_e32 v69, 0x49742400, v69
	v_rcp_f32_e32 v36, v60
	v_rcp_f32_e32 v37, v61
	v_rcp_f32_e32 v38, v68
	v_pk_mul_f32 v[52:53], v[52:53], v[54:55]
	v_pk_mul_f32 v[54:55], v[64:65], v[70:71]
	v_pk_mul_f32 v[56:57], v[56:57], v[58:59]
	v_pk_mul_f32 v[58:59], v[66:67], v[72:73]
	v_rcp_f32_e32 v39, v69
	v_pk_mul_f32 v[60:61], v[60:61], v[62:63]
	v_pk_mul_f32 v[62:63], v[68:69], v[74:75]
	s_mov_b64 s[48:49], 0

;     __device__ __forceinline__ void operator()(const f32x4 (&acc)[2][2][4][2], const Unit& u, int wr, int wc, int fr, int fq) const {
;     ...
;                 f32x4 g0 = acc[ai][0][m][0] * rs_, g1 = acc[ai][0][m][1] * rs_, g2 = acc[ai][1][m][0] * rs_, g3 = acc[ai][1][m][1] * rs_;
;                 if (sg) {
; #pragma unroll
;                     for (int j = 0; j < 4; ++j) {
;                         const float e0 = fminf(1.0f + __builtin_amdgcn_exp2f(-1.4426950408889634f * g0[j]), 1e6f), e1 = fminf(1.0f + __builtin_amdgcn_exp2f(-1.4426950408889634f * g1[j]), 1e6f);
;                         const float e2 = fminf(1.0f + __builtin_amdgcn_exp2f(-1.4426950408889634f * g2[j]), 1e6f), e3 = fminf(1.0f + __builtin_amdgcn_exp2f(-1.4426950408889634f * g3[j]), 1e6f);
;                         g0[j] = e1 * __builtin_amdgcn_rcpf(e0); g1[j] = e2 * __builtin_amdgcn_rcpf(e1); g2[j] = e3 * __builtin_amdgcn_rcpf(e2); g3[j] = __builtin_amdgcn_rcpf(e3); }
;                 }
;                 if (sg) { typedef unsigned u32x2 __attribute__((ext_vector_type(2)));
;                     bf16_t* rp = rat + (size_t)(row0 + ai * HALF + m * 16) * 1024 + (u.pn - sig_pn0) * 64 + 16 * wc + 4 * fq; const size_t pl = (size_t)Trows * 1024;
;                     { u32x2 w; w.x = cvt_pk_bf16(g0[0], g0[1]); w.y = cvt_pk_bf16(g0[2], g0[3]); *(u32x2*)rp = w; }
;                     { u32x2 w; w.x = cvt_pk_bf16(g1[0], g1[1]); w.y = cvt_pk_bf16(g1[2], g1[3]); *(u32x2*)(rp + pl) = w; }
;                     { u32x2 w; w.x = cvt_pk_bf16(g2[0], g2[1]); w.y = cvt_pk_bf16(g2[2], g2[3]); *(u32x2*)(rp + 2 * pl) = w; }
;                     { u32x2 w; w.x = cvt_pk_bf16(g3[0], g3[1]); w.y = cvt_pk_bf16(g3[2], g3[3]); *(u32x2*)(rp + 3 * pl) = w; } }
;                 else {
;                 { u32x4 w; w.x = cvt_pk_bf16(g0[0], g0[1]); w.y = cvt_pk_bf16(g0[2], g0[3]); w.z = cvt_pk_bf16(g1[0], g1[1]); w.w = cvt_pk_bf16(g1[2], g1[3]); *(u32x4*)rowp = w; }
;                 { u32x4 w; w.x = cvt_pk_bf16(g2[0], g2[1]); w.y = cvt_pk_bf16(g2[2], g2[3]); w.z = cvt_pk_bf16(g3[0], g3[1]); w.w = cvt_pk_bf16(g3[2], g3[3]); *(u32x4*)(rowp + HALF) = w; } } }
.LBB0_325:
	s_mov_b64 s[8:9], -1
	s_and_b64 vcc, exec, s[40:41]
	v_cvt_pk_bf16_f32 v40, v52, v53
	v_cvt_pk_bf16_f32 v41, v54, v55
	v_cvt_pk_bf16_f32 v42, v56, v57
	v_cvt_pk_bf16_f32 v43, v58, v59
	v_cvt_pk_bf16_f32 v32, v60, v61
	v_cvt_pk_bf16_f32 v33, v62, v63
	v_cvt_pk_bf16_f32 v34, v36, v37
	v_cvt_pk_bf16_f32 v35, v38, v39
	s_cbranch_vccnz .LBB0_327
	v_lshlrev_b64 v[36:37], 11, v[148:149]
	v_lshl_add_u64 v[36:37], s[20:21], 0, v[36:37]
	s_lshl_b32 s16, s6, 7
	v_lshl_add_u64 v[36:37], v[36:37], 0, s[16:17]
	s_lshl_b32 s16, s75, 1
	v_lshl_add_u64 v[36:37], v[36:37], 0, s[16:17]
	v_lshl_add_u64 v[36:37], v[36:37], 0, v[192:193]
	v_lshl_add_u64 v[38:39], v[36:37], 0, s[90:91]
	v_add_co_u32_e32 v36, vcc, s30, v36
	s_mov_b64 s[8:9], 0
	s_nop 0
	v_addc_co_u32_e32 v37, vcc, -1, v37, vcc
	global_store_dwordx2 v[36:37], v[40:41], off
	v_lshl_add_u64 v[36:37], v[38:39], 0, s[12:13]
	global_store_dwordx2 v[36:37], v[42:43], off
	v_lshl_add_u64 v[36:37], v[36:37], 0, s[12:13]
	global_store_dwordx2 v[36:37], v[32:33], off
	v_lshl_add_u64 v[36:37], v[36:37], 0, s[12:13]
	global_store_dwordx2 v[36:37], v[34:35], off
.LBB0_327:
	s_andn2_b64 vcc, exec, s[8:9]
	s_cbranch_vccnz .LBB0_329
	v_mov_b64_e32 v[36:37], s[14:15]
	v_mad_i64_i32 v[36:37], s[8:9], v148, s56, v[36:37]
	v_lshl_add_u64 v[36:37], v[116:117], 1, v[36:37]
	global_store_dwordx4 v[36:37], v[40:43], off
	global_store_dwordx4 v[36:37], v[32:35], off offset:256
.LBB0_329:
	s_nop 1
	v_add_f32_e32 v32, v181, v182
	v_fmamk_f32 v32, v32, 0x3a800000, v242
	v_rsq_f32_e32 v36, v32
	s_mov_b64 s[48:49], -1
	s_and_b64 vcc, exec, s[46:47]
	v_mul_f32_e32 v36, s99, v36
	v_pk_mul_f32 v[30:31], v[30:31], v[36:37] op_sel_hi:[1,0]
	v_pk_mul_f32 v[28:29], v[28:29], v[36:37] op_sel_hi:[1,0]
	v_pk_mul_f32 v[26:27], v[26:27], v[36:37] op_sel_hi:[1,0]
	v_pk_mul_f32 v[24:25], v[24:25], v[36:37] op_sel_hi:[1,0]
	v_pk_mul_f32 v[32:33], v[22:23], v[36:37] op_sel_hi:[1,0]
	v_pk_mul_f32 v[34:35], v[20:21], v[36:37] op_sel_hi:[1,0]
	v_pk_mul_f32 v[18:19], v[18:19], v[36:37] op_sel_hi:[1,0]
	v_pk_mul_f32 v[16:17], v[16:17], v[36:37] op_sel_hi:[1,0]
	s_cbranch_vccz .LBB0_331
	v_exp_f32_e32 v20, v28
	v_exp_f32_e32 v21, v24
	v_exp_f32_e32 v22, v34
	v_exp_f32_e32 v23, v16
	v_add_f32_e32 v20, 1.0, v20
	v_add_f32_e32 v21, 1.0, v21
	v_min_f32_e32 v20, 0x49742400, v20
	v_min_f32_e32 v36, 0x49742400, v21
	v_add_f32_e32 v21, 1.0, v22
	v_min_f32_e32 v40, 0x49742400, v21
	v_add_f32_e32 v21, 1.0, v23
	v_rcp_f32_e32 v38, v20
	v_min_f32_e32 v44, 0x49742400, v21
	v_exp_f32_e32 v21, v29
	v_exp_f32_e32 v22, v25
	v_exp_f32_e32 v23, v35
	v_exp_f32_e32 v39, v17
	v_add_f32_e32 v21, 1.0, v21
	v_add_f32_e32 v22, 1.0, v22
	v_min_f32_e32 v21, 0x49742400, v21
	v_min_f32_e32 v37, 0x49742400, v22
	v_add_f32_e32 v22, 1.0, v23
	v_min_f32_e32 v41, 0x49742400, v22
	v_add_f32_e32 v22, 1.0, v39
	v_rcp_f32_e32 v39, v21
	v_min_f32_e32 v45, 0x49742400, v22
	v_exp_f32_e32 v22, v30
	v_exp_f32_e32 v23, v26
	v_exp_f32_e32 v49, v32
	v_exp_f32_e32 v51, v18
	v_add_f32_e32 v22, 1.0, v22
	v_add_f32_e32 v23, 1.0, v23
	v_min_f32_e32 v22, 0x49742400, v22
	v_min_f32_e32 v48, 0x49742400, v23
	v_add_f32_e32 v23, 1.0, v49
	v_min_f32_e32 v50, 0x49742400, v23
	v_add_f32_e32 v23, 1.0, v51
	v_rcp_f32_e32 v54, v22
	v_min_f32_e32 v52, 0x49742400, v23
	v_exp_f32_e32 v23, v31
	v_exp_f32_e32 v49, v27
	v_exp_f32_e32 v51, v33
	v_add_f32_e32 v23, 1.0, v23
	v_add_f32_e32 v49, 1.0, v49
	v_exp_f32_e32 v53, v19
	v_add_f32_e32 v51, 1.0, v51
	v_min_f32_e32 v23, 0x49742400, v23
	v_min_f32_e32 v49, 0x49742400, v49
	v_min_f32_e32 v51, 0x49742400, v51
	v_rcp_f32_e32 v42, v36
	v_rcp_f32_e32 v46, v40
	v_rcp_f32_e32 v43, v37
	v_rcp_f32_e32 v47, v41
	v_rcp_f32_e32 v56, v48
	v_rcp_f32_e32 v58, v50
	v_rcp_f32_e32 v55, v23
	v_rcp_f32_e32 v57, v49
	v_rcp_f32_e32 v59, v51
	v_add_f32_e32 v53, 1.0, v53
	v_min_f32_e32 v53, 0x49742400, v53
	v_rcp_f32_e32 v20, v44
	v_rcp_f32_e32 v21, v45
	v_rcp_f32_e32 v22, v52
	v_pk_mul_f32 v[36:37], v[36:37], v[38:39]
	v_pk_mul_f32 v[38:39], v[48:49], v[54:55]
	v_pk_mul_f32 v[40:41], v[40:41], v[42:43]
	v_pk_mul_f32 v[42:43], v[50:51], v[56:57]
	v_rcp_f32_e32 v23, v53
	v_pk_mul_f32 v[44:45], v[44:45], v[46:47]
	v_pk_mul_f32 v[46:47], v[52:53], v[58:59]
	s_mov_b64 s[48:49], 0

;     __device__ __forceinline__ void operator()(const f32x4 (&acc)[2][2][4][2], const Unit& u, int wr, int wc, int fr, int fq) const {
;     ...
;                 f32x4 g0 = acc[ai][0][m][0] * rs_, g1 = acc[ai][0][m][1] * rs_, g2 = acc[ai][1][m][0] * rs_, g3 = acc[ai][1][m][1] * rs_;
;                 if (sg) {
; #pragma unroll
;                     for (int j = 0; j < 4; ++j) {
;                         const float e0 = fminf(1.0f + __builtin_amdgcn_exp2f(-1.4426950408889634f * g0[j]), 1e6f), e1 = fminf(1.0f + __builtin_amdgcn_exp2f(-1.4426950408889634f * g1[j]), 1e6f);
;                         const float e2 = fminf(1.0f + __builtin_amdgcn_exp2f(-1.4426950408889634f * g2[j]), 1e6f), e3 = fminf(1.0f + __builtin_amdgcn_exp2f(-1.4426950408889634f * g3[j]), 1e6f);
;                         g0[j] = e1 * __builtin_amdgcn_rcpf(e0); g1[j] = e2 * __builtin_amdgcn_rcpf(e1); g2[j] = e3 * __builtin_amdgcn_rcpf(e2); g3[j] = __builtin_amdgcn_rcpf(e3); }
;                 }
;                 if (sg) { typedef unsigned u32x2 __attribute__((ext_vector_type(2)));
;                     bf16_t* rp = rat + (size_t)(row0 + ai * HALF + m * 16) * 1024 + (u.pn - sig_pn0) * 64 + 16 * wc + 4 * fq; const size_t pl = (size_t)Trows * 1024;
;                     { u32x2 w; w.x = cvt_pk_bf16(g0[0], g0[1]); w.y = cvt_pk_bf16(g0[2], g0[3]); *(u32x2*)rp = w; }
;                     { u32x2 w; w.x = cvt_pk_bf16(g1[0], g1[1]); w.y = cvt_pk_bf16(g1[2], g1[3]); *(u32x2*)(rp + pl) = w; }
;                     { u32x2 w; w.x = cvt_pk_bf16(g2[0], g2[1]); w.y = cvt_pk_bf16(g2[2], g2[3]); *(u32x2*)(rp + 2 * pl) = w; }
;                     { u32x2 w; w.x = cvt_pk_bf16(g3[0], g3[1]); w.y = cvt_pk_bf16(g3[2], g3[3]); *(u32x2*)(rp + 3 * pl) = w; } }
;                 else {
;                 { u32x4 w; w.x = cvt_pk_bf16(g0[0], g0[1]); w.y = cvt_pk_bf16(g0[2], g0[3]); w.z = cvt_pk_bf16(g1[0], g1[1]); w.w = cvt_pk_bf16(g1[2], g1[3]); *(u32x4*)rowp = w; }
;                 { u32x4 w; w.x = cvt_pk_bf16(g2[0], g2[1]); w.y = cvt_pk_bf16(g2[2], g2[3]); w.z = cvt_pk_bf16(g3[0], g3[1]); w.w = cvt_pk_bf16(g3[2], g3[3]); *(u32x4*)(rowp + HALF) = w; } } }
.LBB0_333:
	s_mov_b64 s[8:9], -1
	s_and_b64 vcc, exec, s[40:41]
	v_cvt_pk_bf16_f32 v24, v36, v37
	v_cvt_pk_bf16_f32 v25, v38, v39
	v_cvt_pk_bf16_f32 v26, v40, v41
	v_cvt_pk_bf16_f32 v27, v42, v43
	v_cvt_pk_bf16_f32 v16, v44, v45
	v_cvt_pk_bf16_f32 v17, v46, v47
	v_cvt_pk_bf16_f32 v18, v20, v21
	v_cvt_pk_bf16_f32 v19, v22, v23
	s_cbranch_vccnz .LBB0_335
	v_lshlrev_b64 v[20:21], 11, v[146:147]
	v_lshl_add_u64 v[20:21], s[20:21], 0, v[20:21]
	s_lshl_b32 s16, s6, 7
	v_lshl_add_u64 v[20:21], v[20:21], 0, s[16:17]
	s_lshl_b32 s16, s75, 1
	v_lshl_add_u64 v[20:21], v[20:21], 0, s[16:17]
	v_lshl_add_u64 v[20:21], v[20:21], 0, v[192:193]
	v_lshl_add_u64 v[22:23], v[20:21], 0, s[90:91]
	v_add_co_u32_e32 v20, vcc, s30, v20
	s_mov_b64 s[8:9], 0
	s_nop 0
	v_addc_co_u32_e32 v21, vcc, -1, v21, vcc
	global_store_dwordx2 v[20:21], v[24:25], off
	v_lshl_add_u64 v[20:21], v[22:23], 0, s[12:13]
	global_store_dwordx2 v[20:21], v[26:27], off
	v_lshl_add_u64 v[20:21], v[20:21], 0, s[12:13]
	global_store_dwordx2 v[20:21], v[16:17], off
	v_lshl_add_u64 v[20:21], v[20:21], 0, s[12:13]
	global_store_dwordx2 v[20:21], v[18:19], off
.LBB0_335:
	s_andn2_b64 vcc, exec, s[8:9]
	s_cbranch_vccnz .LBB0_337
	v_mov_b64_e32 v[20:21], s[14:15]
	v_mad_i64_i32 v[20:21], s[8:9], v146, s56, v[20:21]
	v_lshl_add_u64 v[20:21], v[116:117], 1, v[20:21]
	global_store_dwordx4 v[20:21], v[24:27], off
	global_store_dwordx4 v[20:21], v[16:19], off offset:256
.LBB0_337:
	s_nop 1
	v_add_f32_e32 v16, v179, v180
	v_fmamk_f32 v16, v16, 0x3a800000, v242
	v_rsq_f32_e32 v20, v16
	s_mov_b64 s[48:49], -1
	s_and_b64 vcc, exec, s[46:47]
	v_mul_f32_e32 v20, s99, v20
	v_pk_mul_f32 v[14:15], v[14:15], v[20:21] op_sel_hi:[1,0]
	v_pk_mul_f32 v[12:13], v[12:13], v[20:21] op_sel_hi:[1,0]
	v_pk_mul_f32 v[10:11], v[10:11], v[20:21] op_sel_hi:[1,0]
	v_pk_mul_f32 v[8:9], v[8:9], v[20:21] op_sel_hi:[1,0]
	v_pk_mul_f32 v[16:17], v[6:7], v[20:21] op_sel_hi:[1,0]
	v_pk_mul_f32 v[18:19], v[4:5], v[20:21] op_sel_hi:[1,0]
	v_pk_mul_f32 v[2:3], v[2:3], v[20:21] op_sel_hi:[1,0]
	v_pk_mul_f32 v[0:1], v[0:1], v[20:21] op_sel_hi:[1,0]
	s_cbranch_vccz .LBB0_339
	v_exp_f32_e32 v4, v12
	v_exp_f32_e32 v5, v8
	v_exp_f32_e32 v6, v18
	v_exp_f32_e32 v7, v0
	v_add_f32_e32 v4, 1.0, v4
	v_add_f32_e32 v5, 1.0, v5
	v_min_f32_e32 v4, 0x49742400, v4
	v_min_f32_e32 v20, 0x49742400, v5
	v_add_f32_e32 v5, 1.0, v6
	v_min_f32_e32 v24, 0x49742400, v5
	v_add_f32_e32 v5, 1.0, v7
	v_rcp_f32_e32 v22, v4
	v_min_f32_e32 v28, 0x49742400, v5
	v_exp_f32_e32 v5, v13
	v_exp_f32_e32 v6, v9
	v_exp_f32_e32 v7, v19
	v_exp_f32_e32 v23, v1
	v_add_f32_e32 v5, 1.0, v5
	v_add_f32_e32 v6, 1.0, v6
	v_min_f32_e32 v5, 0x49742400, v5
	v_min_f32_e32 v21, 0x49742400, v6
	v_add_f32_e32 v6, 1.0, v7
	v_min_f32_e32 v25, 0x49742400, v6
	v_add_f32_e32 v6, 1.0, v23
	v_rcp_f32_e32 v23, v5
	v_min_f32_e32 v29, 0x49742400, v6
	v_exp_f32_e32 v6, v14
	v_exp_f32_e32 v7, v10
	v_exp_f32_e32 v33, v16
	v_exp_f32_e32 v35, v2
	v_add_f32_e32 v6, 1.0, v6
	v_add_f32_e32 v7, 1.0, v7
	v_min_f32_e32 v6, 0x49742400, v6
	v_min_f32_e32 v32, 0x49742400, v7
	v_add_f32_e32 v7, 1.0, v33
	v_min_f32_e32 v34, 0x49742400, v7
	v_add_f32_e32 v7, 1.0, v35
	v_rcp_f32_e32 v38, v6
	v_min_f32_e32 v36, 0x49742400, v7
	v_exp_f32_e32 v7, v15
	v_exp_f32_e32 v33, v11
	v_exp_f32_e32 v35, v17
	v_add_f32_e32 v7, 1.0, v7
	v_add_f32_e32 v33, 1.0, v33
	v_exp_f32_e32 v37, v3
	v_add_f32_e32 v35, 1.0, v35
	v_min_f32_e32 v7, 0x49742400, v7
	v_min_f32_e32 v33, 0x49742400, v33
	v_min_f32_e32 v35, 0x49742400, v35
	v_rcp_f32_e32 v26, v20
	v_rcp_f32_e32 v30, v24
	v_rcp_f32_e32 v27, v21
	v_rcp_f32_e32 v31, v25
	v_rcp_f32_e32 v40, v32
	v_rcp_f32_e32 v42, v34
	v_rcp_f32_e32 v39, v7
	v_rcp_f32_e32 v41, v33
	v_rcp_f32_e32 v43, v35
	v_add_f32_e32 v37, 1.0, v37
	v_min_f32_e32 v37, 0x49742400, v37
	v_rcp_f32_e32 v4, v28
	v_rcp_f32_e32 v5, v29
	v_rcp_f32_e32 v6, v36
	v_pk_mul_f32 v[20:21], v[20:21], v[22:23]
	v_pk_mul_f32 v[22:23], v[32:33], v[38:39]
	v_pk_mul_f32 v[24:25], v[24:25], v[26:27]
	v_pk_mul_f32 v[26:27], v[34:35], v[40:41]
	v_rcp_f32_e32 v7, v37
	v_pk_mul_f32 v[28:29], v[28:29], v[30:31]
	v_pk_mul_f32 v[30:31], v[36:37], v[42:43]
	s_mov_b64 s[48:49], 0

; __device__ __forceinline__ unsigned cvt_pk_bf16(float lo, float hi) { typedef float f2 __attribute__((ext_vector_type(2))); typedef __bf16 b2 __attribute__((ext_vector_type(2))); f2 v = {lo, hi}; b2 b = __builtin_convertvector(v, b2); return __builtin_bit_cast(unsigned, b); }
;     __device__ __forceinline__ void operator()(const f32x4 (&acc)[2][2][4][2], const Unit& u, int wr, int wc, int fr, int fq) const {
;     ...
;                 if (sg) { typedef unsigned u32x2 __attribute__((ext_vector_type(2)));
;                     bf16_t* rp = rat + (size_t)(row0 + ai * HALF + m * 16) * 1024 + (u.pn - sig_pn0) * 64 + 16 * wc + 4 * fq; const size_t pl = (size_t)Trows * 1024;
;                     { u32x2 w; w.x = cvt_pk_bf16(g0[0], g0[1]); w.y = cvt_pk_bf16(g0[2], g0[3]); *(u32x2*)rp = w; }
;                     { u32x2 w; w.x = cvt_pk_bf16(g1[0], g1[1]); w.y = cvt_pk_bf16(g1[2], g1[3]); *(u32x2*)(rp + pl) = w; }
;                     { u32x2 w; w.x = cvt_pk_bf16(g2[0], g2[1]); w.y = cvt_pk_bf16(g2[2], g2[3]); *(u32x2*)(rp + 2 * pl) = w; }
;                     { u32x2 w; w.x = cvt_pk_bf16(g3[0], g3[1]); w.y = cvt_pk_bf16(g3[2], g3[3]); *(u32x2*)(rp + 3 * pl) = w; } }
.LBB0_341:
	s_mov_b64 s[8:9], -1
	s_and_b64 vcc, exec, s[40:41]
	v_cvt_pk_bf16_f32 v8, v20, v21
	v_cvt_pk_bf16_f32 v9, v22, v23
	v_cvt_pk_bf16_f32 v10, v24, v25
	v_cvt_pk_bf16_f32 v11, v26, v27
	v_cvt_pk_bf16_f32 v0, v28, v29
	v_cvt_pk_bf16_f32 v1, v30, v31
	v_cvt_pk_bf16_f32 v2, v4, v5
	v_cvt_pk_bf16_f32 v3, v6, v7
	s_cbranch_vccnz .LBB0_344
	v_lshlrev_b64 v[4:5], 11, v[144:145]
	v_lshl_add_u64 v[4:5], s[20:21], 0, v[4:5]
	s_lshl_b32 s16, s6, 7
	v_lshl_add_u64 v[4:5], v[4:5], 0, s[16:17]
	s_lshl_b32 s16, s75, 1
	v_lshl_add_u64 v[4:5], v[4:5], 0, s[16:17]
	v_lshl_add_u64 v[4:5], v[4:5], 0, v[192:193]
	v_lshl_add_u64 v[6:7], v[4:5], 0, s[90:91]
	v_add_co_u32_e32 v4, vcc, s30, v4
	s_nop 1
	v_addc_co_u32_e32 v5, vcc, -1, v5, vcc
	global_store_dwordx2 v[4:5], v[8:9], off
	v_lshl_add_u64 v[4:5], v[6:7], 0, s[12:13]
	global_store_dwordx2 v[4:5], v[10:11], off
	v_lshl_add_u64 v[4:5], v[4:5], 0, s[12:13]
	global_store_dwordx2 v[4:5], v[0:1], off
	v_lshl_add_u64 v[4:5], v[4:5], 0, s[12:13]
	global_store_dwordx2 v[4:5], v[2:3], off
	s_cbranch_execz .LBB0_345

; __device__ __forceinline__ unsigned cvt_pk_bf16(float lo, float hi) { typedef float f2 __attribute__((ext_vector_type(2))); typedef __bf16 b2 __attribute__((ext_vector_type(2))); f2 v = {lo, hi}; b2 b = __builtin_convertvector(v, b2); return __builtin_bit_cast(unsigned, b); }
;     __device__ __forceinline__ void operator()(const f32x4 (&acc)[2][2][4][2], const Unit& u, int wr, int wc, int fr, int fq) const {
;     ...
;                 else {
;                 { u32x4 w; w.x = cvt_pk_bf16(g0[0], g0[1]); w.y = cvt_pk_bf16(g0[2], g0[3]); w.z = cvt_pk_bf16(g1[0], g1[1]); w.w = cvt_pk_bf16(g1[2], g1[3]); *(u32x4*)rowp = w; }
;                 { u32x4 w; w.x = cvt_pk_bf16(g2[0], g2[1]); w.y = cvt_pk_bf16(g2[2], g2[3]); w.z = cvt_pk_bf16(g3[0], g3[1]); w.w = cvt_pk_bf16(g3[2], g3[3]); *(u32x4*)(rowp + HALF) = w; } } }
.LBB0_345:
	v_mov_b64_e32 v[4:5], s[14:15]
	v_mad_i64_i32 v[4:5], s[6:7], v144, s56, v[4:5]
	v_lshl_add_u64 v[4:5], v[116:117], 1, v[4:5]
	global_store_dwordx4 v[4:5], v[8:11], off
	global_store_dwordx4 v[4:5], v[0:3], off offset:256
	s_andn2_b64 vcc, exec, s[38:39]
	s_mov_b64 s[6:7], -1
	s_cbranch_vccnz .LBB0_270

; template <int NTK>
; __device__ __forceinline__ void pp_elem(const int (&toks)[NTK], bf16_t* PROJ, bf16_t* KC, const float2* rope, const float* dqn, const float* dkn, int lane) {
;     int e0, c, sec = 0; bool isD = false; float sc = 1.f; const float* gn = dqn;
;     if (lane < 32) { sec = lane >> 1; c = lane & 1; e0 = PA + sec * 32 + c * 8; }
;     else if (lane < 56) { const int t = lane - 32, hd = t >> 2; sec = (t >> 1) & 1; c = t & 1; e0 = PD + hd * 64 + sec * 32 + c * 8; isD = true; gn = ((hd < 4) ? dqn : dkn) + sec * 32 + c * 8; sc = (hd < 4) ? 0.125f * LOG2E : 1.f; }
;     else { c = lane & 1; e0 = PC + 320 + c * 8; }
;     const bool active = lane < 58, isC = lane >= 56;
;     u32x4 xa[NTK], xb[NTK]; f32x4 rp[NTK][4];
; #pragma unroll
;     for (int k = 0; k < NTK; ++k) { const int tok = toks[k], pos = tok & (SEQ - 1); const bf16_t* row = PROJ + (size_t)tok * PPITCH + e0;
;         const int pe = isD ? (sec ? (pos & 63) : (pos >> 6)) : pos; const f32x4* rq = (const f32x4*)(rope + pe * 16 + c * 8);
;         if (active) { xa[k] = *(const u32x4*)row; xb[k] = *(const u32x4*)(row + 16); } else { xa[k] = (u32x4){0u, 0u, 0u, 0u}; xb[k] = xa[k]; }
; #pragma unroll
;         for (int q = 0; q < 4; ++q) rp[k][q] = rq[q]; }
;     f32x4 g1[2], g2[2];
; #pragma unroll
;     for (int q = 0; q < 2; ++q) { g1[q] = *(const f32x4*)(gn + 4 * q); g2[q] = *(const f32x4*)(gn + 16 + 4 * q); }
; #pragma unroll
;     for (int k = 0; k < NTK; ++k) { const int tok = toks[k];
;         float x1[8], x2[8]; float ss = 0.f;
; #pragma unroll
;         for (int q = 0; q < 4; ++q) { x1[2 * q] = __uint_as_float(xa[k][q] << 16); x1[2 * q + 1] = __uint_as_float(xa[k][q] & 0xffff0000u); x2[2 * q] = __uint_as_float(xb[k][q] << 16); x2[2 * q + 1] = __uint_as_float(xb[k][q] & 0xffff0000u); }
; #pragma unroll
;         for (int j = 0; j < 8; ++j) ss += x1[j] * x1[j] + x2[j] * x2[j];
;         ss += __shfl_xor(ss, 1); ss += __shfl_xor(ss, 2);
;         if (isD) { const float rstd = __builtin_amdgcn_rsqf(ss * (1.f / 64.f) + EPS);
; #pragma unroll
;             for (int j = 0; j < 8; ++j) { x1[j] *= rstd * g1[j >> 2][j & 3]; x2[j] *= rstd * g2[j >> 2][j & 3]; } }
.LBB0_406:
	s_add_i32 s29, s25, s16
	s_cmp_ge_i32 s29, s0
	s_mov_b64 s[8:9], -1
	s_cbranch_scc0 .LBB0_421
	s_mov_b64 s[20:21], 0
	v_mov_b32_e32 v24, 1.0
	v_mov_b64_e32 v[30:31], s[6:7]
	s_waitcnt vmcnt(0)
	v_mov_b32_e32 v0, v86
	v_mov_b32_e32 v192, v87
	s_and_saveexec_b64 s[8:9], s[10:11]
	s_and_b64 s[20:21], s[42:43], exec
	v_mov_b64_e32 v[30:31], v[64:65]
	v_mov_b32_e32 v24, v88
	v_mov_b32_e32 v0, v89
	v_mov_b32_e32 v192, v90
	s_or_b64 exec, exec, s[8:9]
	s_and_saveexec_b64 s[8:9], s[40:41]
	s_xor_b64 s[8:9], exec, s[8:9]
	v_lshl_add_u64 v[26:27], v[192:193], 1, s[14:15]
	s_or_saveexec_b64 s[8:9], s[8:9]
	v_mov_b32_e32 v16, 0
	s_waitcnt lgkmcnt(0)
	v_mov_b32_e32 v17, 0
	v_mov_b32_e32 v18, 0
	v_mov_b32_e32 v19, 0
	v_mov_b32_e32 v20, 0
	v_mov_b32_e32 v21, 0
	v_mov_b32_e32 v22, 0
	v_mov_b32_e32 v23, 0
	s_xor_b64 exec, exec, s[8:9]
	s_cbranch_execz .LBB0_413
	v_lshl_add_u64 v[26:27], v[192:193], 1, s[14:15]
	v_lshl_add_u64 v[2:3], s[4:5], 0, v[26:27]
	v_add_co_u32_e32 v2, vcc, 0x84c8000, v2
	s_nop 1
	v_addc_co_u32_e32 v3, vcc, 0, v3, vcc
	global_load_dwordx4 v[16:19], v[2:3], off
	global_load_dwordx4 v[20:23], v[2:3], off offset:32
.LBB0_413:
	s_or_b64 exec, exec, s[8:9]
	s_and_b32 s9, s16, 63
	s_bfe_u32 s22, s16, 0x50006
	s_and_b32 s8, s16, 0x7ff
	v_mov_b32_e32 v1, s9
	v_mov_b32_e32 v2, s22
	v_cmp_eq_u32_e32 vcc, 0, v0
	s_waitcnt vmcnt(0) lgkmcnt(0)
	v_lshlrev_b32_e32 v40, 16, v20
	v_and_b32_e32 v41, 0xffff0000, v20
	v_cndmask_b32_e32 v0, v1, v2, vcc
	v_mov_b32_e32 v1, s8
	v_cndmask_b32_e64 v0, v1, v0, s[20:21]
	v_lshlrev_b32_e32 v192, 7, v0
	v_lshl_add_u64 v[0:1], v[66:67], 0, v[192:193]
	global_load_dwordx4 v[12:15], v[0:1], off
	global_load_dwordx4 v[8:11], v[0:1], off offset:16
	global_load_dwordx4 v[4:7], v[0:1], off offset:32
	s_nop 0
	global_load_dwordx4 v[0:3], v[0:1], off offset:48
	v_lshlrev_b32_e32 v38, 16, v16
	v_and_b32_e32 v39, 0xffff0000, v16
	v_lshlrev_b32_e32 v34, 16, v17
	v_and_b32_e32 v35, 0xffff0000, v17
	v_lshlrev_b32_e32 v36, 16, v21
	v_and_b32_e32 v37, 0xffff0000, v21
	v_pk_mul_f32 v[16:17], v[40:41], v[40:41]
	v_lshlrev_b32_e32 v28, 16, v18
	v_and_b32_e32 v29, 0xffff0000, v18
	v_lshlrev_b32_e32 v20, 16, v19
	v_and_b32_e32 v21, 0xffff0000, v19
	v_pk_fma_f32 v[16:17], v[38:39], v[38:39], v[16:17]
	v_pk_mul_f32 v[18:19], v[36:37], v[36:37]
	v_lshlrev_b32_e32 v32, 16, v22
	v_and_b32_e32 v33, 0xffff0000, v22
	v_pk_fma_f32 v[18:19], v[34:35], v[34:35], v[18:19]
	v_add_f32_e32 v16, v16, v17
	v_pk_mul_f32 v[42:43], v[32:33], v[32:33]
	v_add_f32_e32 v16, v18, v16
	v_lshlrev_b32_e32 v22, 16, v23
	v_and_b32_e32 v23, 0xffff0000, v23
	v_pk_fma_f32 v[42:43], v[28:29], v[28:29], v[42:43]
	v_add_f32_e32 v16, v19, v16
	v_pk_mul_f32 v[44:45], v[22:23], v[22:23]
	v_add_f32_e32 v16, v42, v16
	v_cmp_lt_i32_e32 vcc, v232, v245
	v_pk_fma_f32 v[44:45], v[20:21], v[20:21], v[44:45]
	v_add_f32_e32 v16, v43, v16
	v_cndmask_b32_e32 v25, v244, v232, vcc
	v_add_f32_e32 v16, v44, v16
	v_add_f32_e32 v16, v45, v16
	v_lshlrev_b32_e32 v17, 2, v25
	ds_bpermute_b32 v17, v17, v16
	v_cmp_lt_i32_e32 vcc, v233, v245
	s_waitcnt lgkmcnt(0)
	v_add_f32_e32 v16, v16, v17
	v_cndmask_b32_e32 v18, v244, v233, vcc
	v_lshlrev_b32_e32 v18, 2, v18
	ds_bpermute_b32 v17, v18, v16
	s_and_saveexec_b64 s[22:23], s[20:21]
	s_cbranch_execz .LBB0_415
	global_load_dwordx4 v[42:45], v[30:31], off
	global_load_dwordx4 v[46:49], v[30:31], off offset:16
	global_load_dwordx4 v[50:53], v[30:31], off offset:64
	global_load_dwordx4 v[54:57], v[30:31], off offset:80
	s_waitcnt lgkmcnt(0)
	v_add_f32_e32 v16, v16, v17
	v_fmamk_f32 v16, v16, 0x3c800000, v242
	v_rsq_f32_e32 v16, v16
	s_waitcnt vmcnt(0)
	v_pk_mul_f32 v[18:19], v[16:17], v[44:45] op_sel_hi:[0,1]
	v_pk_mul_f32 v[30:31], v[16:17], v[48:49] op_sel_hi:[0,1]
	v_pk_mul_f32 v[42:43], v[16:17], v[42:43] op_sel_hi:[0,1]
	v_pk_mul_f32 v[44:45], v[16:17], v[46:47] op_sel_hi:[0,1]
	v_pk_mul_f32 v[46:47], v[16:17], v[52:53] op_sel_hi:[0,1]
	v_pk_mul_f32 v[48:49], v[16:17], v[56:57] op_sel_hi:[0,1]
	v_pk_mul_f32 v[50:51], v[16:17], v[50:51] op_sel_hi:[0,1]
	v_pk_mul_f32 v[16:17], v[16:17], v[54:55] op_sel_hi:[0,1]
	v_pk_mul_f32 v[20:21], v[30:31], v[20:21]
	v_pk_mul_f32 v[34:35], v[18:19], v[34:35]
	v_pk_mul_f32 v[28:29], v[44:45], v[28:29]
	v_pk_mul_f32 v[38:39], v[42:43], v[38:39]
	v_pk_mul_f32 v[22:23], v[48:49], v[22:23]
	v_pk_mul_f32 v[36:37], v[46:47], v[36:37]
	v_pk_mul_f32 v[32:33], v[16:17], v[32:33]
	v_pk_mul_f32 v[40:41], v[50:51], v[40:41]
; __device__ __forceinline__ unsigned cvt_pk_bf16(float lo, float hi) { typedef float f2 __attribute__((ext_vector_type(2))); typedef __bf16 b2 __attribute__((ext_vector_type(2))); f2 v = {lo, hi}; b2 b = __builtin_convertvector(v, b2); return __builtin_bit_cast(unsigned, b); }
; template <int NTK>
; __device__ __forceinline__ void pp_elem(const int (&toks)[NTK], bf16_t* PROJ, bf16_t* KC, const float2* rope, const float* dqn, const float* dkn, int lane) {
;     ...
;         u32x4 oa, ob;
; #pragma unroll
;         for (int q = 0; q < 4; ++q) { const float c0 = rp[k][q][0], s0 = rp[k][q][1], c1 = rp[k][q][2], s1 = rp[k][q][3];
;             oa[q] = cvt_pk_bf16((x1[2 * q] * c0 - x2[2 * q] * s0) * sc, (x1[2 * q + 1] * c1 - x2[2 * q + 1] * s1) * sc);
;             ob[q] = cvt_pk_bf16((x2[2 * q] * c0 + x1[2 * q] * s0) * sc, (x2[2 * q + 1] * c1 + x1[2 * q + 1] * s1) * sc); }
;         if (active) {
;             if (isC) { bf16_t* kc = KC + (size_t)tok * 384 + 64 + c * 8;
; #pragma unroll
;                 for (int hh = 0; hh < 4; ++hh) { *(u32x4*)(kc + hh * 96) = oa; *(u32x4*)(kc + hh * 96 + 16) = ob; } }
;             else { bf16_t* row = PROJ + (size_t)tok * PPITCH + e0; *(u32x4*)row = oa; *(u32x4*)(row + 16) = ob; } }
.LBB0_415:
	s_or_b64 exec, exec, s[22:23]
	s_and_saveexec_b64 s[20:21], s[38:39]
	s_cbranch_execz .LBB0_420
	s_waitcnt vmcnt(0) lgkmcnt(0)
	v_mov_b32_e32 v17, v14
	v_mov_b32_e32 v14, v13
	v_mov_b32_e32 v16, v12
	v_pk_mul_f32 v[12:13], v[14:15], v[40:41]
	v_pk_mul_f32 v[14:15], v[14:15], v[38:39]
	v_pk_fma_f32 v[12:13], v[16:17], v[38:39], v[12:13] neg_lo:[0,0,1] neg_hi:[0,0,1]
	v_pk_fma_f32 v[14:15], v[16:17], v[40:41], v[14:15]
	v_pk_mul_f32 v[12:13], v[24:25], v[12:13] op_sel_hi:[0,1]
	v_pk_mul_f32 v[14:15], v[24:25], v[14:15] op_sel_hi:[0,1]
	v_cvt_pk_bf16_f32 v16, v14, v15
	v_mov_b32_e32 v15, v10
	v_mov_b32_e32 v10, v9
	v_mov_b32_e32 v14, v8
	v_pk_mul_f32 v[8:9], v[10:11], v[36:37]
	v_cvt_pk_bf16_f32 v12, v12, v13
	v_pk_fma_f32 v[8:9], v[14:15], v[34:35], v[8:9] neg_lo:[0,0,1] neg_hi:[0,0,1]
	s_nop 0
	v_pk_mul_f32 v[8:9], v[24:25], v[8:9] op_sel_hi:[0,1]
	v_cvt_pk_bf16_f32 v13, v8, v9
	v_pk_mul_f32 v[8:9], v[10:11], v[34:35]
	s_nop 0
	v_pk_fma_f32 v[8:9], v[14:15], v[36:37], v[8:9]
	s_nop 0
	v_pk_mul_f32 v[8:9], v[24:25], v[8:9] op_sel_hi:[0,1]
	v_cvt_pk_bf16_f32 v17, v8, v9
	v_mov_b32_e32 v9, v6
	v_mov_b32_e32 v6, v5
	v_mov_b32_e32 v8, v4
	v_pk_mul_f32 v[4:5], v[6:7], v[32:33]
	s_nop 0
	v_pk_fma_f32 v[4:5], v[8:9], v[28:29], v[4:5] neg_lo:[0,0,1] neg_hi:[0,0,1]
	s_nop 0
	v_pk_mul_f32 v[4:5], v[24:25], v[4:5] op_sel_hi:[0,1]
	v_cvt_pk_bf16_f32 v14, v4, v5
	v_pk_mul_f32 v[4:5], v[6:7], v[28:29]
	s_nop 0
	v_pk_fma_f32 v[4:5], v[8:9], v[32:33], v[4:5]
	s_nop 0
	v_pk_mul_f32 v[4:5], v[24:25], v[4:5] op_sel_hi:[0,1]
	v_cvt_pk_bf16_f32 v18, v4, v5
	v_mov_b32_e32 v5, v2
	v_mov_b32_e32 v2, v1
	v_mov_b32_e32 v4, v0
	v_pk_mul_f32 v[0:1], v[2:3], v[22:23]
	s_nop 0
	v_pk_fma_f32 v[0:1], v[4:5], v[20:21], v[0:1] neg_lo:[0,0,1] neg_hi:[0,0,1]
	s_nop 0
	v_pk_mul_f32 v[0:1], v[24:25], v[0:1] op_sel_hi:[0,1]
	v_cvt_pk_bf16_f32 v15, v0, v1
	v_pk_mul_f32 v[0:1], v[2:3], v[20:21]
	s_nop 0
	v_pk_fma_f32 v[0:1], v[4:5], v[22:23], v[0:1]
	s_nop 0
	v_pk_mul_f32 v[0:1], v[24:25], v[0:1] op_sel_hi:[0,1]
	v_cvt_pk_bf16_f32 v19, v0, v1
	s_and_saveexec_b64 s[8:9], s[42:43]
	s_xor_b64 s[8:9], exec, s[8:9]
	s_cbranch_execz .LBB0_418
	v_lshl_add_u64 v[0:1], s[4:5], 0, v[26:27]
	v_add_co_u32_e32 v0, vcc, 0x84c8000, v0
	s_nop 1
	v_addc_co_u32_e32 v1, vcc, 0, v1, vcc
	global_store_dwordx4 v[0:1], v[12:15], off
	global_store_dwordx4 v[0:1], v[16:19], off offset:32
.LBB0_418:
	s_andn2_saveexec_b64 s[8:9], s[8:9]
	s_cbranch_execz .LBB0_420
	v_lshl_add_u64 v[0:1], s[4:5], 0, v[70:71]
	v_add_co_u32_e32 v0, vcc, 0x23cc8000, v0
	s_nop 1
	v_addc_co_u32_e32 v1, vcc, 0, v1, vcc
	global_store_dwordx4 v[0:1], v[12:15], off offset:128
	global_store_dwordx4 v[0:1], v[16:19], off offset:160
	global_store_dwordx4 v[0:1], v[12:15], off offset:320
	global_store_dwordx4 v[0:1], v[16:19], off offset:352
	global_store_dwordx4 v[0:1], v[12:15], off offset:512
	global_store_dwordx4 v[0:1], v[16:19], off offset:544
	global_store_dwordx4 v[0:1], v[12:15], off offset:704
	global_store_dwordx4 v[0:1], v[16:19], off offset:736

; template <int NTK>
; __device__ __forceinline__ void pp_elem(const int (&toks)[NTK], bf16_t* PROJ, bf16_t* KC, const float2* rope, const float* dqn, const float* dkn, int lane) {
;     ...
;     for (int k = 0; k < NTK; ++k) { const int tok = toks[k], pos = tok & (SEQ - 1); const bf16_t* row = PROJ + (size_t)tok * PPITCH + e0;
;         const int pe = isD ? (sec ? (pos & 63) : (pos >> 6)) : pos; const f32x4* rq = (const f32x4*)(rope + pe * 16 + c * 8);
;         if (active) { xa[k] = *(const u32x4*)row; xb[k] = *(const u32x4*)(row + 16); } else { xa[k] = (u32x4){0u, 0u, 0u, 0u}; xb[k] = xa[k]; }
; #pragma unroll
;         for (int q = 0; q < 4; ++q) rp[k][q] = rq[q]; }
;     f32x4 g1[2], g2[2];
; #pragma unroll
;     for (int q = 0; q < 2; ++q) { g1[q] = *(const f32x4*)(gn + 4 * q); g2[q] = *(const f32x4*)(gn + 16 + 4 * q); }
; #pragma unroll
;     for (int k = 0; k < NTK; ++k) { const int tok = toks[k];
;         float x1[8], x2[8]; float ss = 0.f;
; #pragma unroll
;         for (int q = 0; q < 4; ++q) { x1[2 * q] = __uint_as_float(xa[k][q] << 16); x1[2 * q + 1] = __uint_as_float(xa[k][q] & 0xffff0000u); x2[2 * q] = __uint_as_float(xb[k][q] << 16); x2[2 * q + 1] = __uint_as_float(xb[k][q] & 0xffff0000u); }
; #pragma unroll
;         for (int j = 0; j < 8; ++j) ss += x1[j] * x1[j] + x2[j] * x2[j];
;         ss += __shfl_xor(ss, 1); ss += __shfl_xor(ss, 2);
;         if (isD) { const float rstd = __builtin_amdgcn_rsqf(ss * (1.f / 64.f) + EPS);
; #pragma unroll
;             for (int j = 0; j < 8; ++j) { x1[j] *= rstd * g1[j >> 2][j & 3]; x2[j] *= rstd * g2[j >> 2][j & 3]; } }
.LBB0_421:
	s_and_b64 vcc, exec, s[8:9]
	s_cbranch_vccz .LBB0_405
	s_mov_b64 s[20:21], 0
	v_mov_b32_e32 v72, 1.0
	v_mov_b64_e32 v[20:21], s[6:7]
	s_waitcnt vmcnt(0)
	v_mov_b32_e32 v0, v86
	v_mov_b32_e32 v192, v87
	s_and_saveexec_b64 s[8:9], s[10:11]
	s_and_b64 s[20:21], s[42:43], exec
	v_mov_b64_e32 v[20:21], v[64:65]
	v_mov_b32_e32 v72, v88
	v_mov_b32_e32 v0, v89
	v_mov_b32_e32 v192, v90
	s_or_b64 exec, exec, s[8:9]
	v_mov_b32_e32 v56, 0
	v_mov_b32_e32 v57, 0
	v_mov_b32_e32 v58, 0
	v_mov_b32_e32 v59, 0
	v_mov_b32_e32 v60, 0
	v_mov_b32_e32 v61, 0
	v_mov_b32_e32 v62, 0
	v_mov_b32_e32 v63, 0
	s_and_saveexec_b64 s[8:9], s[38:39]
	s_cbranch_execz .LBB0_426
	s_add_u32 s22, s4, s14
	s_addc_u32 s23, s5, s15
	v_lshl_add_u64 v[2:3], v[192:193], 1, s[22:23]
	v_add_co_u32_e32 v2, vcc, 0x84c8000, v2
	s_nop 1
	v_addc_co_u32_e32 v3, vcc, 0, v3, vcc
	global_load_dwordx4 v[60:63], v[2:3], off
	global_load_dwordx4 v[56:59], v[2:3], off offset:32
.LBB0_426:
	s_or_b64 exec, exec, s[8:9]
	s_and_b32 s9, s16, 63
	s_bfe_u32 s22, s16, 0x50006
	s_and_b32 s8, s16, 0x7ff
	v_mov_b32_e32 v1, s9
	v_mov_b32_e32 v2, s22
	v_cmp_eq_u32_e64 s[44:45], 0, v0
	s_nop 1
	v_cndmask_b32_e64 v0, v1, v2, s[44:45]
	v_mov_b32_e32 v1, s8
	v_cndmask_b32_e64 v0, v1, v0, s[20:21]
	v_lshlrev_b32_e32 v0, 7, v0
	v_mov_b32_e32 v1, v193
	v_lshl_add_u64 v[0:1], v[66:67], 0, v[0:1]
	global_load_dwordx4 v[52:55], v[0:1], off
	global_load_dwordx4 v[48:51], v[0:1], off offset:16
	global_load_dwordx4 v[44:47], v[0:1], off offset:32
	global_load_dwordx4 v[40:43], v[0:1], off offset:48
	s_and_saveexec_b64 s[8:9], s[40:41]
	s_xor_b64 s[8:9], exec, s[8:9]
	s_or_saveexec_b64 s[22:23], s[8:9]
	v_mov_b32_e32 v32, v193
	v_mov_b32_e32 v33, v193
	v_mov_b32_e32 v34, v193
	v_mov_b32_e32 v35, v193
	v_mov_b32_e32 v36, v193
	v_mov_b32_e32 v37, v193
	v_mov_b32_e32 v38, v193
	s_waitcnt lgkmcnt(0)
	v_mov_b32_e32 v39, v193
	s_xor_b64 exec, exec, s[22:23]
	s_cbranch_execz .LBB0_428
	s_add_u32 s8, s4, s28
	s_addc_u32 s9, s5, s19
	v_lshl_add_u64 v[0:1], v[192:193], 1, s[8:9]
	v_add_co_u32_e32 v0, vcc, 0x84c8000, v0
	s_nop 1
	v_addc_co_u32_e32 v1, vcc, 0, v1, vcc
	global_load_dwordx4 v[32:35], v[0:1], off
	global_load_dwordx4 v[36:39], v[0:1], off offset:32
.LBB0_428:
	s_or_b64 exec, exec, s[22:23]
	s_and_b32 s9, s29, 63
	s_bfe_u32 s22, s29, 0x50006
	s_and_b32 s8, s29, 0x7ff
	v_mov_b32_e32 v0, s9
	v_mov_b32_e32 v1, s22
	v_cndmask_b32_e64 v0, v0, v1, s[44:45]
	v_mov_b32_e32 v1, s8
	v_cndmask_b32_e64 v0, v1, v0, s[20:21]
	v_lshlrev_b32_e32 v0, 7, v0
	v_mov_b32_e32 v1, v193
	v_lshl_add_u64 v[0:1], v[66:67], 0, v[0:1]
	global_load_dwordx4 v[12:15], v[0:1], off
	global_load_dwordx4 v[8:11], v[0:1], off offset:16
	global_load_dwordx4 v[4:7], v[0:1], off offset:32
	s_nop 0
	global_load_dwordx4 v[0:3], v[0:1], off offset:48
	s_nop 0
	global_load_dwordx4 v[24:27], v[20:21], off offset:16
	global_load_dwordx4 v[28:31], v[20:21], off
	s_waitcnt lgkmcnt(0)
	global_load_dwordx4 v[16:19], v[20:21], off offset:80
	s_nop 0
	global_load_dwordx4 v[20:23], v[20:21], off offset:64
	s_waitcnt vmcnt(0)
	v_lshlrev_b32_e32 v82, 16, v60
	v_and_b32_e32 v83, 0xffff0000, v60
	v_lshlrev_b32_e32 v84, 16, v56
	v_and_b32_e32 v85, 0xffff0000, v56
	v_lshlrev_b32_e32 v78, 16, v61
	v_and_b32_e32 v79, 0xffff0000, v61
	v_lshlrev_b32_e32 v80, 16, v57
	v_and_b32_e32 v81, 0xffff0000, v57
	v_pk_mul_f32 v[56:57], v[82:83], v[82:83]
	v_lshlrev_b32_e32 v74, 16, v62
	v_and_b32_e32 v75, 0xffff0000, v62
	v_lshlrev_b32_e32 v76, 16, v58
	v_and_b32_e32 v77, 0xffff0000, v58
	v_lshlrev_b32_e32 v60, 16, v63
	v_and_b32_e32 v61, 0xffff0000, v63
	v_lshlrev_b32_e32 v62, 16, v59
	v_and_b32_e32 v63, 0xffff0000, v59
	v_pk_fma_f32 v[56:57], v[84:85], v[84:85], v[56:57]
	v_pk_mul_f32 v[58:59], v[78:79], v[78:79]
	v_add_f32_e32 v56, v56, v57
	v_pk_fma_f32 v[58:59], v[80:81], v[80:81], v[58:59]
	v_pk_mul_f32 v[92:93], v[74:75], v[74:75]
	v_add_f32_e32 v56, v58, v56
	v_pk_fma_f32 v[92:93], v[76:77], v[76:77], v[92:93]
	v_add_f32_e32 v56, v59, v56
	v_pk_mul_f32 v[94:95], v[60:61], v[60:61]
	v_add_f32_e32 v56, v92, v56
	v_cmp_lt_i32_e32 vcc, v232, v245
	v_pk_fma_f32 v[94:95], v[62:63], v[62:63], v[94:95]
	v_add_f32_e32 v56, v93, v56
	v_cndmask_b32_e32 v73, v244, v232, vcc
	v_add_f32_e32 v56, v94, v56
	v_lshlrev_b32_e32 v91, 2, v73
	v_add_f32_e32 v56, v95, v56
	ds_bpermute_b32 v57, v91, v56
	v_cmp_lt_i32_e32 vcc, v233, v245
	s_waitcnt lgkmcnt(0)
	v_add_f32_e32 v56, v56, v57
	v_cndmask_b32_e32 v58, v244, v233, vcc
	v_lshlrev_b32_e32 v92, 2, v58
	ds_bpermute_b32 v57, v92, v56
	s_and_saveexec_b64 s[22:23], s[20:21]
	s_cbranch_execz .LBB0_430
	s_waitcnt lgkmcnt(0)
	v_add_f32_e32 v56, v56, v57
	v_fmamk_f32 v56, v56, 0x3c800000, v242
	v_rsq_f32_e32 v56, v56
	s_nop 0
	v_pk_mul_f32 v[58:59], v[30:31], v[56:57] op_sel_hi:[1,0]
	v_pk_mul_f32 v[94:95], v[26:27], v[56:57] op_sel_hi:[1,0]
	v_pk_mul_f32 v[96:97], v[28:29], v[56:57] op_sel_hi:[1,0]
	v_pk_mul_f32 v[98:99], v[24:25], v[56:57] op_sel_hi:[1,0]
	v_pk_mul_f32 v[60:61], v[94:95], v[60:61]
	v_pk_mul_f32 v[78:79], v[58:59], v[78:79]
	v_pk_mul_f32 v[82:83], v[96:97], v[82:83]
	v_pk_mul_f32 v[58:59], v[22:23], v[56:57] op_sel_hi:[1,0]
	v_pk_mul_f32 v[94:95], v[18:19], v[56:57] op_sel_hi:[1,0]
	v_pk_mul_f32 v[96:97], v[20:21], v[56:57] op_sel_hi:[1,0]
	v_pk_mul_f32 v[56:57], v[16:17], v[56:57] op_sel_hi:[1,0]
	v_pk_mul_f32 v[74:75], v[98:99], v[74:75]
	v_pk_mul_f32 v[62:63], v[94:95], v[62:63]
	v_pk_mul_f32 v[80:81], v[58:59], v[80:81]
	v_pk_mul_f32 v[76:77], v[56:57], v[76:77]
	v_pk_mul_f32 v[84:85], v[96:97], v[84:85]
; __device__ __forceinline__ unsigned cvt_pk_bf16(float lo, float hi) { typedef float f2 __attribute__((ext_vector_type(2))); typedef __bf16 b2 __attribute__((ext_vector_type(2))); f2 v = {lo, hi}; b2 b = __builtin_convertvector(v, b2); return __builtin_bit_cast(unsigned, b); }
; template <int NTK>
; __device__ __forceinline__ void pp_elem(const int (&toks)[NTK], bf16_t* PROJ, bf16_t* KC, const float2* rope, const float* dqn, const float* dkn, int lane) {
;     ...
;         u32x4 oa, ob;
; #pragma unroll
;         for (int q = 0; q < 4; ++q) { const float c0 = rp[k][q][0], s0 = rp[k][q][1], c1 = rp[k][q][2], s1 = rp[k][q][3];
;             oa[q] = cvt_pk_bf16((x1[2 * q] * c0 - x2[2 * q] * s0) * sc, (x1[2 * q + 1] * c1 - x2[2 * q + 1] * s1) * sc);
;             ob[q] = cvt_pk_bf16((x2[2 * q] * c0 + x1[2 * q] * s0) * sc, (x2[2 * q + 1] * c1 + x1[2 * q + 1] * s1) * sc); }
;         if (active) {
;             if (isC) { bf16_t* kc = KC + (size_t)tok * 384 + 64 + c * 8;
; #pragma unroll
;                 for (int hh = 0; hh < 4; ++hh) { *(u32x4*)(kc + hh * 96) = oa; *(u32x4*)(kc + hh * 96 + 16) = ob; } }
;             else { bf16_t* row = PROJ + (size_t)tok * PPITCH + e0; *(u32x4*)row = oa; *(u32x4*)(row + 16) = ob; } }
.LBB0_430:
	s_or_b64 exec, exec, s[22:23]
	v_mov_b32_e32 v73, v72
	s_and_saveexec_b64 s[22:23], s[38:39]
	s_cbranch_execz .LBB0_435
	s_waitcnt lgkmcnt(0)
	v_mov_b32_e32 v57, v54
	v_mov_b32_e32 v54, v53
	v_mov_b32_e32 v56, v52
	v_pk_mul_f32 v[52:53], v[54:55], v[84:85]
	v_pk_mul_f32 v[54:55], v[54:55], v[82:83]
	v_pk_fma_f32 v[52:53], v[56:57], v[82:83], v[52:53] neg_lo:[0,0,1] neg_hi:[0,0,1]
	v_pk_fma_f32 v[54:55], v[56:57], v[84:85], v[54:55]
	v_pk_mul_f32 v[52:53], v[72:73], v[52:53]
	v_pk_mul_f32 v[54:55], v[72:73], v[54:55]
	v_cvt_pk_bf16_f32 v52, v52, v53
	v_cvt_pk_bf16_f32 v56, v54, v55
	v_mov_b32_e32 v55, v50
	v_mov_b32_e32 v50, v49
	v_mov_b32_e32 v54, v48
	v_pk_mul_f32 v[48:49], v[50:51], v[80:81]
	s_nop 0
	v_pk_fma_f32 v[48:49], v[54:55], v[78:79], v[48:49] neg_lo:[0,0,1] neg_hi:[0,0,1]
	s_nop 0
	v_pk_mul_f32 v[48:49], v[72:73], v[48:49]
	s_nop 0
	v_cvt_pk_bf16_f32 v53, v48, v49
	v_pk_mul_f32 v[48:49], v[50:51], v[78:79]
	s_nop 0
	v_pk_fma_f32 v[48:49], v[54:55], v[80:81], v[48:49]
	s_nop 0
	v_pk_mul_f32 v[48:49], v[72:73], v[48:49]
	s_nop 0
	v_cvt_pk_bf16_f32 v57, v48, v49
	v_mov_b32_e32 v49, v46
	v_mov_b32_e32 v46, v45
	v_mov_b32_e32 v48, v44
	v_pk_mul_f32 v[44:45], v[46:47], v[76:77]
	s_nop 0
	v_pk_fma_f32 v[44:45], v[48:49], v[74:75], v[44:45] neg_lo:[0,0,1] neg_hi:[0,0,1]
	s_nop 0
	v_pk_mul_f32 v[44:45], v[72:73], v[44:45]
	s_nop 0
	v_cvt_pk_bf16_f32 v54, v44, v45
	v_pk_mul_f32 v[44:45], v[46:47], v[74:75]
	s_nop 0
	v_pk_fma_f32 v[44:45], v[48:49], v[76:77], v[44:45]
	s_nop 0
	v_pk_mul_f32 v[44:45], v[72:73], v[44:45]
	s_nop 0
	v_cvt_pk_bf16_f32 v58, v44, v45
	v_mov_b32_e32 v45, v42
	v_mov_b32_e32 v42, v41
	v_mov_b32_e32 v44, v40
	v_pk_mul_f32 v[40:41], v[42:43], v[62:63]
	s_nop 0
	v_pk_fma_f32 v[40:41], v[44:45], v[60:61], v[40:41] neg_lo:[0,0,1] neg_hi:[0,0,1]
	s_nop 0
	v_pk_mul_f32 v[40:41], v[72:73], v[40:41]
	s_nop 0
	v_cvt_pk_bf16_f32 v55, v40, v41
	v_pk_mul_f32 v[40:41], v[42:43], v[60:61]
	s_nop 0
	v_pk_fma_f32 v[40:41], v[44:45], v[62:63], v[40:41]
	s_nop 0
	v_pk_mul_f32 v[40:41], v[72:73], v[40:41]
	s_nop 0
	v_cvt_pk_bf16_f32 v59, v40, v41
	s_and_saveexec_b64 s[8:9], s[42:43]
	s_xor_b64 s[8:9], exec, s[8:9]
	s_cbranch_execz .LBB0_433
	s_add_u32 s34, s4, s14
	s_addc_u32 s35, s5, s15
	v_lshl_add_u64 v[40:41], v[192:193], 1, s[34:35]
	v_add_co_u32_e32 v40, vcc, 0x84c8000, v40
	s_nop 1
	v_addc_co_u32_e32 v41, vcc, 0, v41, vcc
	global_store_dwordx4 v[40:41], v[52:55], off
	global_store_dwordx4 v[40:41], v[56:59], off offset:32
.LBB0_433:
	s_andn2_saveexec_b64 s[8:9], s[8:9]
	s_cbranch_execz .LBB0_435
	v_lshl_add_u64 v[40:41], s[4:5], 0, v[70:71]
	v_add_co_u32_e32 v40, vcc, 0x23cc8000, v40
	s_nop 1
	v_addc_co_u32_e32 v41, vcc, 0, v41, vcc
	global_store_dwordx4 v[40:41], v[52:55], off offset:128
	global_store_dwordx4 v[40:41], v[56:59], off offset:160
	global_store_dwordx4 v[40:41], v[52:55], off offset:320
	global_store_dwordx4 v[40:41], v[56:59], off offset:352
	global_store_dwordx4 v[40:41], v[52:55], off offset:512
	global_store_dwordx4 v[40:41], v[56:59], off offset:544
	global_store_dwordx4 v[40:41], v[52:55], off offset:704
	global_store_dwordx4 v[40:41], v[56:59], off offset:736

; __device__ __forceinline__ unsigned cvt_pk_bf16(float lo, float hi) { typedef float f2 __attribute__((ext_vector_type(2))); typedef __bf16 b2 __attribute__((ext_vector_type(2))); f2 v = {lo, hi}; b2 b = __builtin_convertvector(v, b2); return __builtin_bit_cast(unsigned, b); }
; template <int NTK>
; __device__ __forceinline__ void pp_elem(const int (&toks)[NTK], bf16_t* PROJ, bf16_t* KC, const float2* rope, const float* dqn, const float* dkn, int lane) {
;     ...
;         u32x4 oa, ob;
; #pragma unroll
;         for (int q = 0; q < 4; ++q) { const float c0 = rp[k][q][0], s0 = rp[k][q][1], c1 = rp[k][q][2], s1 = rp[k][q][3];
;             oa[q] = cvt_pk_bf16((x1[2 * q] * c0 - x2[2 * q] * s0) * sc, (x1[2 * q + 1] * c1 - x2[2 * q + 1] * s1) * sc);
;             ob[q] = cvt_pk_bf16((x2[2 * q] * c0 + x1[2 * q] * s0) * sc, (x2[2 * q + 1] * c1 + x1[2 * q + 1] * s1) * sc); }
;         if (active) {
;             if (isC) { bf16_t* kc = KC + (size_t)tok * 384 + 64 + c * 8;
; #pragma unroll
;                 for (int hh = 0; hh < 4; ++hh) { *(u32x4*)(kc + hh * 96) = oa; *(u32x4*)(kc + hh * 96 + 16) = ob; } }
;             else { bf16_t* row = PROJ + (size_t)tok * PPITCH + e0; *(u32x4*)row = oa; *(u32x4*)(row + 16) = ob; } }
.LBB0_437:
	s_or_b64 exec, exec, s[22:23]
	s_and_saveexec_b64 s[20:21], s[38:39]
	s_cbranch_execz .LBB0_404
	v_mov_b32_e32 v17, v14
	v_mov_b32_e32 v14, v13
	v_mov_b32_e32 v16, v12
	v_pk_mul_f32 v[12:13], v[14:15], v[48:49]
	v_pk_mul_f32 v[14:15], v[14:15], v[46:47]
	v_pk_fma_f32 v[12:13], v[16:17], v[46:47], v[12:13] neg_lo:[0,0,1] neg_hi:[0,0,1]
	v_pk_fma_f32 v[14:15], v[16:17], v[48:49], v[14:15]
	v_pk_mul_f32 v[12:13], v[72:73], v[12:13]
	v_pk_mul_f32 v[14:15], v[72:73], v[14:15]
	v_cvt_pk_bf16_f32 v12, v12, v13
	v_cvt_pk_bf16_f32 v16, v14, v15
	v_mov_b32_e32 v15, v10
	v_mov_b32_e32 v10, v9
	v_mov_b32_e32 v14, v8
	v_pk_mul_f32 v[8:9], v[10:11], v[44:45]
	s_nop 0
	v_pk_fma_f32 v[8:9], v[14:15], v[42:43], v[8:9] neg_lo:[0,0,1] neg_hi:[0,0,1]
	s_nop 0
	v_pk_mul_f32 v[8:9], v[72:73], v[8:9]
	s_nop 0
	v_cvt_pk_bf16_f32 v13, v8, v9
	v_pk_mul_f32 v[8:9], v[10:11], v[42:43]
	s_nop 0
	v_pk_fma_f32 v[8:9], v[14:15], v[44:45], v[8:9]
	s_nop 0
	v_pk_mul_f32 v[8:9], v[72:73], v[8:9]
	s_nop 0
	v_cvt_pk_bf16_f32 v17, v8, v9
	v_mov_b32_e32 v9, v6
	v_mov_b32_e32 v6, v5
	v_mov_b32_e32 v8, v4
	v_pk_mul_f32 v[4:5], v[6:7], v[40:41]
	s_nop 0
	v_pk_fma_f32 v[4:5], v[8:9], v[36:37], v[4:5] neg_lo:[0,0,1] neg_hi:[0,0,1]
	s_nop 0
	v_pk_mul_f32 v[4:5], v[72:73], v[4:5]
	s_nop 0
	v_cvt_pk_bf16_f32 v14, v4, v5
	v_pk_mul_f32 v[4:5], v[6:7], v[36:37]
	s_nop 0
	v_pk_fma_f32 v[4:5], v[8:9], v[40:41], v[4:5]
	s_nop 0
	v_pk_mul_f32 v[4:5], v[72:73], v[4:5]
	s_nop 0
	v_cvt_pk_bf16_f32 v18, v4, v5
	v_mov_b32_e32 v5, v2
	v_mov_b32_e32 v2, v1
	v_mov_b32_e32 v4, v0
	v_pk_mul_f32 v[0:1], v[2:3], v[34:35]
	s_nop 0
	v_pk_fma_f32 v[0:1], v[4:5], v[32:33], v[0:1] neg_lo:[0,0,1] neg_hi:[0,0,1]
	s_nop 0
	v_pk_mul_f32 v[0:1], v[72:73], v[0:1]
	s_nop 0
	v_cvt_pk_bf16_f32 v15, v0, v1
	v_pk_mul_f32 v[0:1], v[2:3], v[32:33]
	s_nop 0
	v_pk_fma_f32 v[0:1], v[4:5], v[34:35], v[0:1]
	s_nop 0
	v_pk_mul_f32 v[0:1], v[72:73], v[0:1]
	s_nop 0
	v_cvt_pk_bf16_f32 v19, v0, v1
	s_and_saveexec_b64 s[8:9], s[42:43]
	s_xor_b64 s[8:9], exec, s[8:9]
	s_cbranch_execz .LBB0_440
	s_add_u32 s22, s4, s28
	s_addc_u32 s23, s5, s19
	v_lshl_add_u64 v[0:1], v[192:193], 1, s[22:23]
	v_add_co_u32_e32 v0, vcc, 0x84c8000, v0
	s_nop 1
	v_addc_co_u32_e32 v1, vcc, 0, v1, vcc
	global_store_dwordx4 v[0:1], v[12:15], off
	global_store_dwordx4 v[0:1], v[16:19], off offset:32
.LBB0_440:
	s_andn2_saveexec_b64 s[8:9], s[8:9]
	s_cbranch_execz .LBB0_404
	v_lshl_add_u64 v[0:1], s[4:5], 0, v[68:69]
	v_add_co_u32_e32 v0, vcc, 0x23cc8000, v0
	s_nop 1
	v_addc_co_u32_e32 v1, vcc, 0, v1, vcc
	global_store_dwordx4 v[0:1], v[12:15], off offset:128
	global_store_dwordx4 v[0:1], v[16:19], off offset:160
	global_store_dwordx4 v[0:1], v[12:15], off offset:320
	global_store_dwordx4 v[0:1], v[16:19], off offset:352
	global_store_dwordx4 v[0:1], v[12:15], off offset:512
	global_store_dwordx4 v[0:1], v[16:19], off offset:544
	global_store_dwordx4 v[0:1], v[12:15], off offset:704
	global_store_dwordx4 v[0:1], v[16:19], off offset:736
	s_branch .LBB0_404

; __device__ __forceinline__ float bf2f(bf16_t b) { return __uint_as_float((unsigned)b << 16); }
; __device__ __forceinline__ void pp_mla_lds(int tok0, int hh, const bf16_t* PROJ, bf16_t* QC, bf16_t* KC, bf16_t* VC, const float2* rope, const char* Lq, const char* Lkv, const float* cqn, const float* ckvn, int lane) {
;     const int m = lane & 15, quad = lane >> 4, tok = tok0 + m, pos = tok & (SEQ - 1);
;     const bf16_t* crow_ = PROJ + (size_t)tok * PPITCH + PC;
;     bf16x8 aq[6], ak[4]; float ssq_ = 0.f, ssk_ = 0.f;
; #pragma unroll
;     for (int ks = 0; ks < 6; ++ks) aq[ks] = *(const bf16x8*)(crow_ + ks * 32 + quad * 8);
; #pragma unroll
;     for (int ks = 0; ks < 4; ++ks) ak[ks] = *(const bf16x8*)(crow_ + 192 + ks * 32 + quad * 8);
; #pragma unroll
;     for (int ks = 0; ks < 6; ++ks)
; #pragma unroll
;         for (int e = 0; e < 8; ++e) { const float x = bf2f((bf16_t)aq[ks][e]); ssq_ += x * x; }
; #pragma unroll
;     for (int ks = 0; ks < 4; ++ks)
; #pragma unroll
;         for (int e = 0; e < 8; ++e) { const float x = bf2f((bf16_t)ak[ks][e]); ssk_ += x * x; }
;     ssq_ += __shfl_xor(ssq_, 16); ssq_ += __shfl_xor(ssq_, 32); ssk_ += __shfl_xor(ssk_, 16); ssk_ += __shfl_xor(ssk_, 32);
.LBB0_500:
	v_mov_b64_e32 v[0:1], s[6:7]
	v_mad_i64_i32 v[0:1], s[4:5], v84, s56, v[0:1]
	v_lshl_add_u64 v[0:1], v[0:1], 0, v[192:193]
	v_add_co_u32_e32 v4, vcc, 0x1000, v0
	s_mov_b64 s[4:5], 0x1000
	s_nop 0
	v_addc_co_u32_e32 v5, vcc, 0, v1, vcc
	v_lshl_add_u64 v[2:3], v[0:1], 0, s[4:5]
	global_load_dwordx4 v[16:19], v[4:5], off
	global_load_dwordx4 v[20:23], v[2:3], off offset:64
	global_load_dwordx4 v[24:27], v[2:3], off offset:128
	global_load_dwordx4 v[28:31], v[2:3], off offset:192
	global_load_dwordx4 v[32:35], v[2:3], off offset:256
	global_load_dwordx4 v[36:39], v[2:3], off offset:320
	s_mov_b64 s[4:5], 0x1180
	v_lshl_add_u64 v[6:7], v[0:1], 0, s[4:5]
	global_load_dwordx4 v[64:67], v[4:5], off offset:384
	global_load_dwordx4 v[52:55], v[6:7], off offset:64
	global_load_dwordx4 v[0:3], v[6:7], off offset:128
	s_nop 0
	global_load_dwordx4 v[4:7], v[6:7], off offset:192
	s_nop 0
	global_load_dwordx4 v[96:99], v[72:73], off offset:16
	global_load_dwordx4 v[100:103], v[72:73], off
	global_load_dwordx4 v[104:107], v[72:73], off offset:144
	global_load_dwordx4 v[108:111], v[72:73], off offset:128
	global_load_dwordx4 v[112:115], v[72:73], off offset:272
	global_load_dwordx4 v[116:119], v[72:73], off offset:256
	global_load_dwordx4 v[120:123], v[72:73], off offset:400
	global_load_dwordx4 v[124:127], v[72:73], off offset:384
	global_load_dwordx4 v[128:131], v[72:73], off offset:528
	global_load_dwordx4 v[132:135], v[72:73], off offset:512
	global_load_dwordx4 v[136:139], v[72:73], off offset:656
	global_load_dwordx4 v[140:143], v[72:73], off offset:640
	global_load_dwordx4 v[40:43], v[74:75], off offset:16
	global_load_dwordx4 v[12:15], v[74:75], off
	global_load_dwordx4 v[48:51], v[74:75], off offset:144
	global_load_dwordx4 v[8:11], v[74:75], off offset:128
	global_load_dwordx4 v[60:63], v[74:75], off offset:272
	global_load_dwordx4 v[68:71], v[74:75], off offset:256
	global_load_dwordx4 v[44:47], v[74:75], off offset:400
	global_load_dwordx4 v[56:59], v[74:75], off offset:384
	v_ashrrev_i32_e32 v85, 31, v84
	s_add_i32 s8, s8, s25
	s_cmp_ge_i32 s8, s19
	s_waitcnt vmcnt(0) lgkmcnt(0)
	v_and_b32_e32 v155, 0xffff0000, v16
	v_lshlrev_b32_e32 v154, 16, v16
	v_and_b32_e32 v151, 0xffff0000, v17
	v_lshlrev_b32_e32 v150, 16, v17
	v_pk_mul_f32 v[16:17], v[154:155], v[154:155]
	v_pk_mul_f32 v[152:153], v[150:151], v[150:151]
	v_add_f32_e32 v16, v16, v17
	v_and_b32_e32 v149, 0xffff0000, v18
	v_lshlrev_b32_e32 v148, 16, v18
	v_add_f32_e32 v16, v152, v16
	v_and_b32_e32 v145, 0xffff0000, v19
	v_lshlrev_b32_e32 v144, 16, v19
	v_pk_mul_f32 v[18:19], v[148:149], v[148:149]
	v_add_f32_e32 v16, v153, v16
	v_add_f32_e32 v16, v18, v16
	v_pk_mul_f32 v[146:147], v[144:145], v[144:145]
	v_add_f32_e32 v16, v19, v16
	v_and_b32_e32 v167, 0xffff0000, v20
	v_lshlrev_b32_e32 v166, 16, v20
	v_add_f32_e32 v16, v146, v16
	v_and_b32_e32 v163, 0xffff0000, v21
	v_lshlrev_b32_e32 v162, 16, v21
	v_pk_mul_f32 v[20:21], v[166:167], v[166:167]
	v_add_f32_e32 v16, v147, v16
	v_add_f32_e32 v16, v20, v16
	v_pk_mul_f32 v[164:165], v[162:163], v[162:163]
	v_add_f32_e32 v16, v21, v16
	v_and_b32_e32 v161, 0xffff0000, v22
	v_lshlrev_b32_e32 v160, 16, v22
	v_add_f32_e32 v16, v164, v16
	v_and_b32_e32 v157, 0xffff0000, v23
	v_lshlrev_b32_e32 v156, 16, v23
	v_pk_mul_f32 v[22:23], v[160:161], v[160:161]
	v_add_f32_e32 v16, v165, v16
	v_add_f32_e32 v16, v22, v16
	v_pk_mul_f32 v[158:159], v[156:157], v[156:157]
	v_add_f32_e32 v16, v23, v16
	v_and_b32_e32 v179, 0xffff0000, v24
	v_lshlrev_b32_e32 v178, 16, v24
	v_add_f32_e32 v16, v158, v16
	v_and_b32_e32 v175, 0xffff0000, v25
	v_lshlrev_b32_e32 v174, 16, v25
	v_pk_mul_f32 v[24:25], v[178:179], v[178:179]
	v_add_f32_e32 v16, v159, v16
	v_add_f32_e32 v16, v24, v16
	v_pk_mul_f32 v[176:177], v[174:175], v[174:175]
	v_add_f32_e32 v16, v25, v16
	v_and_b32_e32 v173, 0xffff0000, v26
	v_lshlrev_b32_e32 v172, 16, v26
	v_add_f32_e32 v16, v176, v16
	v_and_b32_e32 v169, 0xffff0000, v27
	v_lshlrev_b32_e32 v168, 16, v27
	v_pk_mul_f32 v[26:27], v[172:173], v[172:173]
	v_add_f32_e32 v16, v177, v16
	v_add_f32_e32 v16, v26, v16
	v_pk_mul_f32 v[170:171], v[168:169], v[168:169]
	v_add_f32_e32 v16, v27, v16
	v_and_b32_e32 v187, 0xffff0000, v29
	v_lshlrev_b32_e32 v186, 16, v29
	v_and_b32_e32 v29, 0xffff0000, v28
	v_lshlrev_b32_e32 v28, 16, v28
	v_add_f32_e32 v16, v170, v16
	v_pk_mul_f32 v[190:191], v[28:29], v[28:29]
	v_add_f32_e32 v16, v171, v16
	v_add_f32_e32 v16, v190, v16
	v_pk_mul_f32 v[188:189], v[186:187], v[186:187]
	v_add_f32_e32 v16, v191, v16
	v_and_b32_e32 v181, 0xffff0000, v31
	v_lshlrev_b32_e32 v180, 16, v31
	v_and_b32_e32 v31, 0xffff0000, v30
	v_lshlrev_b32_e32 v30, 16, v30
	v_add_f32_e32 v16, v188, v16
	v_pk_mul_f32 v[184:185], v[30:31], v[30:31]
	v_add_f32_e32 v16, v189, v16
	v_add_f32_e32 v16, v184, v16
	v_pk_mul_f32 v[182:183], v[180:181], v[180:181]
	v_add_f32_e32 v16, v185, v16
	v_and_b32_e32 v201, 0xffff0000, v33
	v_lshlrev_b32_e32 v200, 16, v33
	v_and_b32_e32 v33, 0xffff0000, v32
	v_lshlrev_b32_e32 v32, 16, v32
	v_add_f32_e32 v16, v182, v16
	v_pk_mul_f32 v[204:205], v[32:33], v[32:33]
	v_add_f32_e32 v16, v183, v16
	v_add_f32_e32 v16, v204, v16
	v_pk_mul_f32 v[202:203], v[200:201], v[200:201]
	v_add_f32_e32 v16, v205, v16
	v_and_b32_e32 v195, 0xffff0000, v35
	v_lshlrev_b32_e32 v194, 16, v35
	v_and_b32_e32 v35, 0xffff0000, v34
	v_lshlrev_b32_e32 v34, 16, v34
	v_add_f32_e32 v16, v202, v16
	v_pk_mul_f32 v[198:199], v[34:35], v[34:35]
	v_add_f32_e32 v16, v203, v16
	v_add_f32_e32 v16, v198, v16
	v_pk_mul_f32 v[196:197], v[194:195], v[194:195]
	v_add_f32_e32 v16, v199, v16
	v_and_b32_e32 v213, 0xffff0000, v37
	v_lshlrev_b32_e32 v212, 16, v37
	v_and_b32_e32 v37, 0xffff0000, v36
	v_lshlrev_b32_e32 v36, 16, v36
	v_add_f32_e32 v16, v196, v16
	v_pk_mul_f32 v[216:217], v[36:37], v[36:37]
	v_add_f32_e32 v16, v197, v16
	v_add_f32_e32 v16, v216, v16
	v_pk_mul_f32 v[214:215], v[212:213], v[212:213]
	v_add_f32_e32 v16, v217, v16
	v_and_b32_e32 v207, 0xffff0000, v39
	v_lshlrev_b32_e32 v206, 16, v39
	v_and_b32_e32 v39, 0xffff0000, v38
	v_lshlrev_b32_e32 v38, 16, v38
	v_add_f32_e32 v16, v214, v16
	v_pk_mul_f32 v[210:211], v[38:39], v[38:39]
	v_add_f32_e32 v16, v215, v16
	v_add_f32_e32 v16, v210, v16
	v_pk_mul_f32 v[208:209], v[206:207], v[206:207]
	v_add_f32_e32 v16, v211, v16
	v_add_f32_e32 v16, v208, v16
	v_add_f32_e32 v16, v209, v16
	ds_bpermute_b32 v17, v86, v16
	s_waitcnt lgkmcnt(0)
; __device__ __forceinline__ unsigned cvt_pk_bf16(float lo, float hi) { typedef float f2 __attribute__((ext_vector_type(2))); typedef __bf16 b2 __attribute__((ext_vector_type(2))); f2 v = {lo, hi}; b2 b = __builtin_convertvector(v, b2); return __builtin_bit_cast(unsigned, b); }
; __device__ __forceinline__ float bf2f(bf16_t b) { return __uint_as_float((unsigned)b << 16); }
; __device__ __forceinline__ void pp_mla_lds(int tok0, int hh, const bf16_t* PROJ, bf16_t* QC, bf16_t* KC, bf16_t* VC, const float2* rope, const char* Lq, const char* Lkv, const float* cqn, const float* ckvn, int lane) {
;     ...
;         for (int e = 0; e < 8; ++e) { const float x = bf2f((bf16_t)ak[ks][e]); ssk_ += x * x; }
;     ssq_ += __shfl_xor(ssq_, 16); ssq_ += __shfl_xor(ssq_, 32); ssk_ += __shfl_xor(ssk_, 16); ssk_ += __shfl_xor(ssk_, 32);
;     const float rq = __builtin_amdgcn_rsqf(ssq_ * (1.f / 192.f) + EPS), rk = __builtin_amdgcn_rsqf(ssk_ * (1.f / 128.f) + EPS);
; #pragma unroll
;     for (int ks = 0; ks < 6; ++ks) { u32x4 w; const f32x4 ga = *(const f32x4*)(cqn + ks * 32 + quad * 8), gb = *(const f32x4*)(cqn + ks * 32 + quad * 8 + 4);
; #pragma unroll
;         for (int e = 0; e < 4; ++e) { const float g0 = e < 2 ? ga[2 * e] : gb[2 * e - 4], g1 = e < 2 ? ga[2 * e + 1] : gb[2 * e - 3]; w[e] = cvt_pk_bf16(bf2f((bf16_t)aq[ks][2 * e]) * rq * g0, bf2f((bf16_t)aq[ks][2 * e + 1]) * rq * g1); }
;         aq[ks] = __builtin_bit_cast(bf16x8, w); }
	v_add_f32_e32 v16, v16, v17
	ds_bpermute_b32 v17, v87, v16
	s_waitcnt lgkmcnt(0)
	v_add_f32_e32 v16, v16, v17
	v_fmamk_f32 v16, v16, 0x3baaaaab, v242
	v_rsq_f32_e32 v146, v16
	s_nop 0
	v_pk_mul_f32 v[16:17], v[146:147], v[36:37] op_sel_hi:[0,1]
	v_pk_mul_f32 v[18:19], v[146:147], v[212:213] op_sel_hi:[0,1]
	v_pk_mul_f32 v[16:17], v[140:141], v[16:17]
	v_pk_mul_f32 v[18:19], v[142:143], v[18:19]
	v_cvt_pk_bf16_f32 v16, v16, v17
	v_cvt_pk_bf16_f32 v17, v18, v19
	v_pk_mul_f32 v[18:19], v[146:147], v[38:39] op_sel_hi:[0,1]
	v_pk_mul_f32 v[20:21], v[146:147], v[206:207] op_sel_hi:[0,1]
	v_pk_mul_f32 v[18:19], v[136:137], v[18:19]
	v_pk_mul_f32 v[20:21], v[138:139], v[20:21]
	v_cvt_pk_bf16_f32 v18, v18, v19
	v_cvt_pk_bf16_f32 v19, v20, v21
	v_pk_mul_f32 v[20:21], v[146:147], v[32:33] op_sel_hi:[0,1]
	v_pk_mul_f32 v[22:23], v[146:147], v[200:201] op_sel_hi:[0,1]
	v_pk_mul_f32 v[20:21], v[132:133], v[20:21]
	v_pk_mul_f32 v[22:23], v[134:135], v[22:23]
	v_cvt_pk_bf16_f32 v20, v20, v21
	v_cvt_pk_bf16_f32 v21, v22, v23
	v_pk_mul_f32 v[22:23], v[146:147], v[34:35] op_sel_hi:[0,1]
	v_pk_mul_f32 v[24:25], v[146:147], v[194:195] op_sel_hi:[0,1]
	v_pk_mul_f32 v[22:23], v[128:129], v[22:23]
	v_pk_mul_f32 v[24:25], v[130:131], v[24:25]
	v_cvt_pk_bf16_f32 v22, v22, v23
	v_cvt_pk_bf16_f32 v23, v24, v25
	v_pk_mul_f32 v[24:25], v[146:147], v[28:29] op_sel_hi:[0,1]
	v_pk_mul_f32 v[26:27], v[146:147], v[186:187] op_sel_hi:[0,1]
	v_pk_mul_f32 v[24:25], v[124:125], v[24:25]
	v_pk_mul_f32 v[26:27], v[126:127], v[26:27]
	v_cvt_pk_bf16_f32 v24, v24, v25
	v_cvt_pk_bf16_f32 v25, v26, v27
	v_pk_mul_f32 v[26:27], v[146:147], v[30:31] op_sel_hi:[0,1]
	v_pk_mul_f32 v[28:29], v[146:147], v[180:181] op_sel_hi:[0,1]
	v_pk_mul_f32 v[26:27], v[120:121], v[26:27]
	v_pk_mul_f32 v[28:29], v[122:123], v[28:29]
	v_cvt_pk_bf16_f32 v26, v26, v27
	v_cvt_pk_bf16_f32 v27, v28, v29
	v_pk_mul_f32 v[28:29], v[146:147], v[178:179] op_sel_hi:[0,1]
	v_pk_mul_f32 v[30:31], v[146:147], v[174:175] op_sel_hi:[0,1]
	v_pk_mul_f32 v[28:29], v[116:117], v[28:29]
	v_pk_mul_f32 v[30:31], v[118:119], v[30:31]
	v_cvt_pk_bf16_f32 v28, v28, v29
	v_cvt_pk_bf16_f32 v29, v30, v31
	v_pk_mul_f32 v[30:31], v[146:147], v[172:173] op_sel_hi:[0,1]
	v_pk_mul_f32 v[32:33], v[146:147], v[168:169] op_sel_hi:[0,1]
	v_pk_mul_f32 v[30:31], v[112:113], v[30:31]
	v_pk_mul_f32 v[32:33], v[114:115], v[32:33]
	v_cvt_pk_bf16_f32 v30, v30, v31
	v_cvt_pk_bf16_f32 v31, v32, v33
	v_pk_mul_f32 v[32:33], v[146:147], v[166:167] op_sel_hi:[0,1]
	v_pk_mul_f32 v[34:35], v[146:147], v[162:163] op_sel_hi:[0,1]
	v_pk_mul_f32 v[32:33], v[108:109], v[32:33]
	v_pk_mul_f32 v[34:35], v[110:111], v[34:35]
	v_pk_mul_f32 v[36:37], v[146:147], v[156:157] op_sel_hi:[0,1]
	v_cvt_pk_bf16_f32 v32, v32, v33
	v_cvt_pk_bf16_f32 v33, v34, v35
	v_pk_mul_f32 v[34:35], v[146:147], v[160:161] op_sel_hi:[0,1]
	v_pk_mul_f32 v[36:37], v[106:107], v[36:37]
	v_and_b32_e32 v107, 0xffff0000, v65
	v_lshlrev_b32_e32 v106, 16, v65
	v_and_b32_e32 v65, 0xffff0000, v64
	v_lshlrev_b32_e32 v64, 16, v64
	v_pk_mul_f32 v[34:35], v[104:105], v[34:35]
	v_pk_mul_f32 v[110:111], v[64:65], v[64:65]
	v_cvt_pk_bf16_f32 v34, v34, v35
	v_cvt_pk_bf16_f32 v35, v36, v37
	v_pk_mul_f32 v[36:37], v[146:147], v[154:155] op_sel_hi:[0,1]
	v_pk_mul_f32 v[108:109], v[106:107], v[106:107]
	v_add_f32_e32 v110, v110, v111
	v_pk_mul_f32 v[36:37], v[100:101], v[36:37]
	v_and_b32_e32 v101, 0xffff0000, v67
	v_lshlrev_b32_e32 v100, 16, v67
	v_and_b32_e32 v67, 0xffff0000, v66
	v_lshlrev_b32_e32 v66, 16, v66
	v_add_f32_e32 v108, v108, v110
	v_pk_mul_f32 v[104:105], v[66:67], v[66:67]
	v_add_f32_e32 v108, v109, v108
	v_pk_mul_f32 v[38:39], v[146:147], v[150:151] op_sel_hi:[0,1]
	v_add_f32_e32 v104, v104, v108
	v_pk_mul_f32 v[38:39], v[102:103], v[38:39]
	v_pk_mul_f32 v[102:103], v[100:101], v[100:101]
	v_add_f32_e32 v104, v105, v104
	v_and_b32_e32 v119, 0xffff0000, v53
	v_lshlrev_b32_e32 v118, 16, v53
	v_and_b32_e32 v53, 0xffff0000, v52
	v_lshlrev_b32_e32 v52, 16, v52
	v_add_f32_e32 v102, v102, v104
	v_pk_mul_f32 v[122:123], v[52:53], v[52:53]
	v_add_f32_e32 v102, v103, v102
	v_add_f32_e32 v102, v122, v102
	v_pk_mul_f32 v[120:121], v[118:119], v[118:119]
	v_add_f32_e32 v102, v123, v102
	v_and_b32_e32 v113, 0xffff0000, v55
	v_lshlrev_b32_e32 v112, 16, v55
	v_and_b32_e32 v55, 0xffff0000, v54
	v_lshlrev_b32_e32 v54, 16, v54
	v_add_f32_e32 v102, v120, v102
	v_pk_mul_f32 v[116:117], v[54:55], v[54:55]
	v_add_f32_e32 v102, v121, v102
	v_add_f32_e32 v102, v116, v102
	v_pk_mul_f32 v[114:115], v[112:113], v[112:113]
	v_add_f32_e32 v102, v117, v102
	v_and_b32_e32 v139, 0xffff0000, v1
	v_lshlrev_b32_e32 v138, 16, v1
	v_and_b32_e32 v1, 0xffff0000, v0
	v_lshlrev_b32_e32 v0, 16, v0
	v_add_f32_e32 v102, v114, v102
	v_pk_mul_f32 v[142:143], v[0:1], v[0:1]
	v_add_f32_e32 v102, v115, v102
	v_add_f32_e32 v102, v142, v102
	v_pk_mul_f32 v[140:141], v[138:139], v[138:139]
	v_add_f32_e32 v102, v143, v102
	v_and_b32_e32 v133, 0xffff0000, v3
	v_lshlrev_b32_e32 v132, 16, v3
	v_and_b32_e32 v3, 0xffff0000, v2
	v_lshlrev_b32_e32 v2, 16, v2
	v_add_f32_e32 v102, v140, v102
	v_pk_mul_f32 v[136:137], v[2:3], v[2:3]
	v_add_f32_e32 v102, v141, v102
	v_add_f32_e32 v102, v136, v102
	v_pk_mul_f32 v[134:135], v[132:133], v[132:133]
	v_add_f32_e32 v102, v137, v102
	v_and_b32_e32 v127, 0xffff0000, v5
	v_lshlrev_b32_e32 v126, 16, v5
	v_and_b32_e32 v5, 0xffff0000, v4
	v_lshlrev_b32_e32 v4, 16, v4
	v_add_f32_e32 v102, v134, v102
	v_cvt_pk_bf16_f32 v36, v36, v37
	v_cvt_pk_bf16_f32 v37, v38, v39
	v_pk_mul_f32 v[38:39], v[146:147], v[148:149] op_sel_hi:[0,1]
	v_pk_mul_f32 v[130:131], v[4:5], v[4:5]
	v_add_f32_e32 v102, v135, v102
	v_pk_mul_f32 v[38:39], v[96:97], v[38:39]
	v_pk_mul_f32 v[96:97], v[146:147], v[144:145] op_sel_hi:[0,1]
	v_add_f32_e32 v102, v130, v102
	v_pk_mul_f32 v[96:97], v[98:99], v[96:97]
	v_pk_mul_f32 v[128:129], v[126:127], v[126:127]
	v_add_f32_e32 v102, v131, v102
	v_cvt_pk_bf16_f32 v38, v38, v39
	v_cvt_pk_bf16_f32 v39, v96, v97
	v_and_b32_e32 v97, 0xffff0000, v7
	v_lshlrev_b32_e32 v96, 16, v7
	v_and_b32_e32 v7, 0xffff0000, v6
	v_lshlrev_b32_e32 v6, 16, v6
	v_add_f32_e32 v102, v128, v102
	v_pk_mul_f32 v[124:125], v[6:7], v[6:7]
	v_add_f32_e32 v102, v129, v102
	v_add_f32_e32 v102, v124, v102
	v_pk_mul_f32 v[98:99], v[96:97], v[96:97]
	v_add_f32_e32 v102, v125, v102
	v_add_f32_e32 v98, v98, v102
	v_add_f32_e32 v98, v99, v98
	ds_bpermute_b32 v99, v86, v98
	s_waitcnt lgkmcnt(0)
; __device__ __forceinline__ unsigned cvt_pk_bf16(float lo, float hi) { typedef float f2 __attribute__((ext_vector_type(2))); typedef __bf16 b2 __attribute__((ext_vector_type(2))); f2 v = {lo, hi}; b2 b = __builtin_convertvector(v, b2); return __builtin_bit_cast(unsigned, b); }
; __device__ __forceinline__ float bf2f(bf16_t b) { return __uint_as_float((unsigned)b << 16); }
; #define MFMA16(a, b, c) __builtin_amdgcn_mfma_f32_16x16x32_bf16((a), (b), (c), 0, 0, 0)
; __device__ __forceinline__ void pp_mla_lds(int tok0, int hh, const bf16_t* PROJ, bf16_t* QC, bf16_t* KC, bf16_t* VC, const float2* rope, const char* Lq, const char* Lkv, const float* cqn, const float* ckvn, int lane) {
;     ...
;     for (int ks = 0; ks < 4; ++ks) { u32x4 w; const f32x4 ga = *(const f32x4*)(ckvn + ks * 32 + quad * 8), gb = *(const f32x4*)(ckvn + ks * 32 + quad * 8 + 4);
; #pragma unroll
;         for (int e = 0; e < 4; ++e) { const float g0 = e < 2 ? ga[2 * e] : gb[2 * e - 4], g1 = e < 2 ? ga[2 * e + 1] : gb[2 * e - 3]; w[e] = cvt_pk_bf16(bf2f((bf16_t)ak[ks][2 * e]) * rk * g0, bf2f((bf16_t)ak[ks][2 * e + 1]) * rk * g1); }
;         ak[ks] = __builtin_bit_cast(bf16x8, w); }
;     const float qs = 0.10206207261596577f * LOG2E;
;     f32x4 cs4[2];
; #pragma unroll
;     for (int q = 0; q < 2; ++q) cs4[q] = *(const f32x4*)(rope + pos * 16 + quad * 4 + 2 * q);
;     {
;         {   f32x4 acc[6];
; #pragma unroll
;             for (int nt = 0; nt < 6; ++nt) { acc[nt] = (f32x4){0.f, 0.f, 0.f, 0.f}; const char* wr_ = Lq + (nt * 16 + m) * 400 + quad * 16;
; #pragma unroll
;                 for (int ks = 0; ks < 6; ++ks) acc[nt] = MFMA16(*(const bf16x8*)(wr_ + ks * 64), aq[ks], acc[nt]); }
	v_add_f32_e32 v98, v98, v99
	ds_bpermute_b32 v99, v87, v98
	s_waitcnt lgkmcnt(0)
	v_add_f32_e32 v98, v98, v99
	v_fmamk_f32 v98, v98, 0x3c000000, v242
	v_rsq_f32_e32 v98, v98
	s_nop 0
	v_pk_mul_f32 v[6:7], v[98:99], v[6:7] op_sel_hi:[0,1]
	v_pk_mul_f32 v[6:7], v[44:45], v[6:7]
	v_pk_mul_f32 v[44:45], v[98:99], v[52:53] op_sel_hi:[0,1]
	v_pk_mul_f32 v[8:9], v[8:9], v[44:45]
	v_pk_mul_f32 v[44:45], v[98:99], v[118:119] op_sel_hi:[0,1]
	v_pk_mul_f32 v[10:11], v[10:11], v[44:45]
	v_cvt_pk_bf16_f32 v8, v8, v9
	v_cvt_pk_bf16_f32 v9, v10, v11
	v_pk_mul_f32 v[10:11], v[98:99], v[54:55] op_sel_hi:[0,1]
	v_pk_mul_f32 v[44:45], v[98:99], v[112:113] op_sel_hi:[0,1]
	v_pk_mul_f32 v[10:11], v[48:49], v[10:11]
	v_pk_mul_f32 v[44:45], v[50:51], v[44:45]
	v_cvt_pk_bf16_f32 v10, v10, v11
	v_cvt_pk_bf16_f32 v11, v44, v45
	v_pk_mul_f32 v[44:45], v[98:99], v[64:65] op_sel_hi:[0,1]
	v_pk_mul_f32 v[12:13], v[12:13], v[44:45]
	v_pk_mul_f32 v[44:45], v[98:99], v[106:107] op_sel_hi:[0,1]
	v_pk_mul_f32 v[14:15], v[14:15], v[44:45]
	v_cvt_pk_bf16_f32 v12, v12, v13
	v_cvt_pk_bf16_f32 v13, v14, v15
	v_pk_mul_f32 v[14:15], v[98:99], v[66:67] op_sel_hi:[0,1]
	v_pk_mul_f32 v[14:15], v[40:41], v[14:15]
	v_pk_mul_f32 v[40:41], v[98:99], v[100:101] op_sel_hi:[0,1]
	v_pk_mul_f32 v[40:41], v[42:43], v[40:41]
	v_cvt_pk_bf16_f32 v14, v14, v15
	v_cvt_pk_bf16_f32 v15, v40, v41
	v_pk_mul_f32 v[40:41], v[98:99], v[96:97] op_sel_hi:[0,1]
	v_pk_mul_f32 v[40:41], v[46:47], v[40:41]
	v_cvt_pk_bf16_f32 v6, v6, v7
	v_cvt_pk_bf16_f32 v7, v40, v41
	v_and_b32_e32 v40, 0x7ff0, v91
	v_lshlrev_b32_e32 v40, 3, v40
	v_mov_b32_e32 v41, v193
	v_lshl_add_u64 v[40:41], v[76:77], 0, v[40:41]
	global_load_dwordx4 v[44:47], v[40:41], off
	s_nop 0
	global_load_dwordx4 v[40:43], v[40:41], off offset:16
	ds_read_b128 v[48:51], v92
	ds_read_b128 v[52:55], v92 offset:64
	s_waitcnt lgkmcnt(0)
	v_mfma_f32_16x16x32_bf16 v[48:51], v[48:51], v[36:39], 0
	v_mul_f32_e64 v4, v98, v4
	v_mul_f32_e64 v5, v98, v5
	v_pk_mul_f32 v[4:5], v[56:57], v[4:5]
	v_pk_mul_f32 v[56:57], v[98:99], v[126:127] op_sel_hi:[0,1]
	v_mfma_f32_16x16x32_bf16 v[48:51], v[52:55], v[32:35], v[48:51]
	ds_read_b128 v[52:55], v92 offset:128
	v_pk_mul_f32 v[56:57], v[58:59], v[56:57]
	v_cvt_pk_bf16_f32 v4, v4, v5
	v_cvt_pk_bf16_f32 v5, v56, v57
	ds_read_b128 v[56:59], v92 offset:6464
	s_waitcnt lgkmcnt(0)
	v_mfma_f32_16x16x32_bf16 v[48:51], v[52:55], v[28:31], v[48:51]
	ds_read_b128 v[52:55], v92 offset:192
	v_pk_mul_f32 v[2:3], v[98:99], v[2:3] op_sel_hi:[0,1]
	v_pk_mul_f32 v[2:3], v[60:61], v[2:3]
	v_pk_mul_f32 v[60:61], v[98:99], v[132:133] op_sel_hi:[0,1]
	v_pk_mul_f32 v[60:61], v[62:63], v[60:61]
	v_cvt_pk_bf16_f32 v2, v2, v3
	v_cvt_pk_bf16_f32 v3, v60, v61
	ds_read_b128 v[60:63], v92 offset:12864
	s_waitcnt lgkmcnt(0)
	v_mfma_f32_16x16x32_bf16 v[48:51], v[52:55], v[24:27], v[48:51]
	ds_read_b128 v[52:55], v92 offset:256
	v_pk_mul_f32 v[0:1], v[98:99], v[0:1] op_sel_hi:[0,1]
	v_pk_mul_f32 v[0:1], v[68:69], v[0:1]
	v_pk_mul_f32 v[68:69], v[98:99], v[138:139] op_sel_hi:[0,1]
	v_pk_mul_f32 v[68:69], v[70:71], v[68:69]
	v_cvt_pk_bf16_f32 v0, v0, v1
	v_cvt_pk_bf16_f32 v1, v68, v69
	ds_read_b128 v[68:71], v92 offset:25664
	s_waitcnt lgkmcnt(0)
	v_mfma_f32_16x16x32_bf16 v[48:51], v[52:55], v[20:23], v[48:51]
	ds_read_b128 v[52:55], v92 offset:320
	ds_read_b128 v[64:67], v93 offset:64
	v_add_u32_e32 v91, s59, v91
	s_waitcnt lgkmcnt(0)
	v_mfma_f32_16x16x32_bf16 v[48:51], v[52:55], v[16:19], v[48:51]
	ds_read_b128 v[52:55], v92 offset:6400
	s_waitcnt lgkmcnt(0)
	v_mfma_f32_16x16x32_bf16 v[52:55], v[52:55], v[36:39], 0
	v_mfma_f32_16x16x32_bf16 v[52:55], v[56:59], v[32:35], v[52:55]
	ds_read_b128 v[56:59], v92 offset:6528
	s_waitcnt lgkmcnt(0)
	v_mfma_f32_16x16x32_bf16 v[52:55], v[56:59], v[28:31], v[52:55]
	ds_read_b128 v[56:59], v92 offset:6592
	s_waitcnt lgkmcnt(0)
	v_mfma_f32_16x16x32_bf16 v[52:55], v[56:59], v[24:27], v[52:55]
	ds_read_b128 v[56:59], v92 offset:6656
	s_waitcnt lgkmcnt(0)
	v_mfma_f32_16x16x32_bf16 v[52:55], v[56:59], v[20:23], v[52:55]
	ds_read_b128 v[56:59], v92 offset:6720
	s_waitcnt lgkmcnt(0)
	v_mfma_f32_16x16x32_bf16 v[52:55], v[56:59], v[16:19], v[52:55]
	ds_read_b128 v[56:59], v92 offset:12800
	s_waitcnt lgkmcnt(0)
	v_mfma_f32_16x16x32_bf16 v[56:59], v[56:59], v[36:39], 0
	v_mfma_f32_16x16x32_bf16 v[56:59], v[60:63], v[32:35], v[56:59]
	ds_read_b128 v[60:63], v92 offset:12928
	s_waitcnt lgkmcnt(0)
	v_mfma_f32_16x16x32_bf16 v[56:59], v[60:63], v[28:31], v[56:59]
	ds_read_b128 v[60:63], v92 offset:12992
	s_waitcnt lgkmcnt(0)
	v_mfma_f32_16x16x32_bf16 v[56:59], v[60:63], v[24:27], v[56:59]
	ds_read_b128 v[60:63], v92 offset:13056
	s_waitcnt lgkmcnt(0)
	v_mfma_f32_16x16x32_bf16 v[56:59], v[60:63], v[20:23], v[56:59]
	ds_read_b128 v[60:63], v92 offset:13120
	s_waitcnt lgkmcnt(0)
	v_mfma_f32_16x16x32_bf16 v[56:59], v[60:63], v[16:19], v[56:59]
	ds_read_b128 v[60:63], v93
	s_waitcnt lgkmcnt(0)
	v_mfma_f32_16x16x32_bf16 v[60:63], v[60:63], v[36:39], 0
	v_mfma_f32_16x16x32_bf16 v[60:63], v[64:67], v[32:35], v[60:63]
	ds_read_b128 v[64:67], v93 offset:128
	s_waitcnt lgkmcnt(0)
	v_mfma_f32_16x16x32_bf16 v[60:63], v[64:67], v[28:31], v[60:63]
	ds_read_b128 v[64:67], v93 offset:192
	s_waitcnt lgkmcnt(0)
	v_mfma_f32_16x16x32_bf16 v[60:63], v[64:67], v[24:27], v[60:63]
	ds_read_b128 v[64:67], v93 offset:256
	s_waitcnt lgkmcnt(0)
	v_mfma_f32_16x16x32_bf16 v[60:63], v[64:67], v[20:23], v[60:63]
	ds_read_b128 v[64:67], v93 offset:320
	s_waitcnt lgkmcnt(0)
	v_mfma_f32_16x16x32_bf16 v[60:63], v[64:67], v[16:19], v[60:63]
	ds_read_b128 v[64:67], v92 offset:25600
	s_waitcnt lgkmcnt(0)
; __device__ __forceinline__ unsigned cvt_pk_bf16(float lo, float hi) { typedef float f2 __attribute__((ext_vector_type(2))); typedef __bf16 b2 __attribute__((ext_vector_type(2))); f2 v = {lo, hi}; b2 b = __builtin_convertvector(v, b2); return __builtin_bit_cast(unsigned, b); }
; #define MFMA16(a, b, c) __builtin_amdgcn_mfma_f32_16x16x32_bf16((a), (b), (c), 0, 0, 0)
; __device__ __forceinline__ void pp_mla_lds(int tok0, int hh, const bf16_t* PROJ, bf16_t* QC, bf16_t* KC, bf16_t* VC, const float2* rope, const char* Lq, const char* Lkv, const float* cqn, const float* ckvn, int lane) {
;     ...
;         {   f32x4 acc[6];
; #pragma unroll
;             for (int nt = 0; nt < 6; ++nt) { acc[nt] = (f32x4){0.f, 0.f, 0.f, 0.f}; const char* wr_ = Lq + (nt * 16 + m) * 400 + quad * 16;
; #pragma unroll
;                 for (int ks = 0; ks < 6; ++ks) acc[nt] = MFMA16(*(const bf16x8*)(wr_ + ks * 64), aq[ks], acc[nt]); }
; #pragma unroll
;             for (int j = 0; j < 4; ++j) { const float c = cs4[j >> 1][2 * (j & 1)], sn = cs4[j >> 1][2 * (j & 1) + 1]; const float x1 = acc[4][j], x2 = acc[5][j]; acc[4][j] = x1 * c - x2 * sn; acc[5][j] = x2 * c + x1 * sn; }
;             bf16_t* qo = QC + (size_t)tok * 384 + hh * 96 + quad * 4;
; #pragma unroll
;             for (int nt = 0; nt < 6; ++nt) { u32x2 w; w.x = cvt_pk_bf16(acc[nt][0] * qs, acc[nt][1] * qs); w.y = cvt_pk_bf16(acc[nt][2] * qs, acc[nt][3] * qs); *(u32x2*)(qo + nt * 16) = w; } }
;         {   f32x4 acc[8];
; #pragma unroll
;             for (int nt = 0; nt < 8; ++nt) { acc[nt] = (f32x4){0.f, 0.f, 0.f, 0.f}; const char* wr_ = Lkv + (nt * 16 + m) * 288 + quad * 16;
; #pragma unroll
;                 for (int ks = 0; ks < 4; ++ks) acc[nt] = MFMA16(*(const bf16x8*)(wr_ + ks * 64), ak[ks], acc[nt]); }
	v_mfma_f32_16x16x32_bf16 v[64:67], v[64:67], v[36:39], 0
	v_mfma_f32_16x16x32_bf16 v[64:67], v[68:71], v[32:35], v[64:67]
	ds_read_b128 v[68:71], v92 offset:25728
	s_waitcnt lgkmcnt(0)
	v_mfma_f32_16x16x32_bf16 v[64:67], v[68:71], v[28:31], v[64:67]
	ds_read_b128 v[68:71], v92 offset:25792
	s_waitcnt lgkmcnt(0)
	v_mfma_f32_16x16x32_bf16 v[64:67], v[68:71], v[24:27], v[64:67]
	ds_read_b128 v[68:71], v92 offset:25856
	s_waitcnt lgkmcnt(0)
	v_mfma_f32_16x16x32_bf16 v[64:67], v[68:71], v[20:23], v[64:67]
	ds_read_b128 v[68:71], v92 offset:25920
	s_waitcnt lgkmcnt(0)
	v_mfma_f32_16x16x32_bf16 v[64:67], v[68:71], v[16:19], v[64:67]
	ds_read_b128 v[68:71], v92 offset:32000
	s_waitcnt lgkmcnt(0)
	v_mfma_f32_16x16x32_bf16 v[36:39], v[68:71], v[36:39], 0
	ds_read_b128 v[68:71], v92 offset:32064
	s_waitcnt lgkmcnt(0)
	v_mfma_f32_16x16x32_bf16 v[32:35], v[68:71], v[32:35], v[36:39]
	s_nop 4
	ds_read_b128 v[36:39], v92 offset:32128
	s_waitcnt lgkmcnt(0)
	v_mfma_f32_16x16x32_bf16 v[28:31], v[36:39], v[28:31], v[32:35]
	s_nop 2
	ds_read_b128 v[32:35], v92 offset:32192
	s_waitcnt lgkmcnt(0)
	v_mfma_f32_16x16x32_bf16 v[24:27], v[32:35], v[24:27], v[28:31]
	s_nop 2
	ds_read_b128 v[28:31], v92 offset:32256
	s_waitcnt lgkmcnt(0)
	v_mfma_f32_16x16x32_bf16 v[20:23], v[28:31], v[20:23], v[24:27]
	s_nop 2
	ds_read_b128 v[24:27], v92 offset:32320
	s_waitcnt lgkmcnt(0)
	v_mfma_f32_16x16x32_bf16 v[16:19], v[24:27], v[16:19], v[20:23]
	s_nop 2
	v_mul_f32_e64 v22, v48, s24
	v_mul_f32_e64 v23, v49, s24
	v_pk_mul_f32 v[24:25], v[50:51], s[24:25] op_sel_hi:[1,0]
	v_mad_i64_i32 v[20:21], s[4:5], v84, s57, v[78:79]
	v_cvt_pk_bf16_f32 v22, v22, v23
	v_cvt_pk_bf16_f32 v23, v24, v25
	global_store_dwordx2 v[20:21], v[22:23], off
	v_pk_mul_f32 v[22:23], v[52:53], s[24:25] op_sel_hi:[1,0]
	v_pk_mul_f32 v[24:25], v[54:55], s[24:25] op_sel_hi:[1,0]
	v_cvt_pk_bf16_f32 v22, v22, v23
	v_cvt_pk_bf16_f32 v23, v24, v25
	global_store_dwordx2 v[20:21], v[22:23], off offset:32
	v_pk_mul_f32 v[22:23], v[56:57], s[24:25] op_sel_hi:[1,0]
	v_pk_mul_f32 v[24:25], v[58:59], s[24:25] op_sel_hi:[1,0]
	v_cvt_pk_bf16_f32 v22, v22, v23
	v_cvt_pk_bf16_f32 v23, v24, v25
	global_store_dwordx2 v[20:21], v[22:23], off offset:64
	v_pk_mul_f32 v[22:23], v[60:61], s[24:25] op_sel_hi:[1,0]
	v_pk_mul_f32 v[24:25], v[62:63], s[24:25] op_sel_hi:[1,0]
	v_cvt_pk_bf16_f32 v22, v22, v23
	v_cvt_pk_bf16_f32 v23, v24, v25
	global_store_dwordx2 v[20:21], v[22:23], off offset:96
	s_waitcnt vmcnt(0)
	v_mov_b32_e32 v22, v44
	v_mov_b32_e32 v23, v46
	v_mov_b32_e32 v46, v45
	v_mov_b32_e32 v26, v40
	v_mov_b32_e32 v27, v42
	v_mov_b32_e32 v42, v41
	v_pk_mul_f32 v[24:25], v[46:47], v[16:17]
	v_pk_mul_f32 v[28:29], v[42:43], v[18:19]
	v_pk_mul_f32 v[16:17], v[22:23], v[16:17]
	v_pk_mul_f32 v[18:19], v[26:27], v[18:19]
	v_pk_fma_f32 v[24:25], v[22:23], v[64:65], v[24:25] neg_lo:[0,0,1] neg_hi:[0,0,1]
	v_pk_fma_f32 v[28:29], v[26:27], v[66:67], v[28:29] neg_lo:[0,0,1] neg_hi:[0,0,1]
	v_pk_fma_f32 v[16:17], v[46:47], v[64:65], v[16:17]
	v_pk_fma_f32 v[18:19], v[42:43], v[66:67], v[18:19]
	v_pk_mul_f32 v[24:25], v[24:25], s[24:25] op_sel_hi:[1,0]
	v_pk_mul_f32 v[28:29], v[28:29], s[24:25] op_sel_hi:[1,0]
	v_pk_mul_f32 v[16:17], v[16:17], s[24:25] op_sel_hi:[1,0]
	v_pk_mul_f32 v[18:19], v[18:19], s[24:25] op_sel_hi:[1,0]
	v_cvt_pk_bf16_f32 v24, v24, v25
	v_cvt_pk_bf16_f32 v25, v28, v29
	v_cvt_pk_bf16_f32 v16, v16, v17
	v_cvt_pk_bf16_f32 v17, v18, v19
	global_store_dwordx2 v[20:21], v[24:25], off offset:128
	global_store_dwordx2 v[20:21], v[16:17], off offset:160
	v_add_u32_e32 v44, v88, v89
	ds_read_b128 v[16:19], v44 offset:38400
	ds_read_b128 v[20:23], v44 offset:38464
	s_waitcnt lgkmcnt(0)
	v_mfma_f32_16x16x32_bf16 v[16:19], v[16:19], v[12:15], 0
	ds_read_b128 v[24:27], v44 offset:43072
	ds_read_b128 v[28:31], v44 offset:47680
	ds_read_b128 v[36:39], v44 offset:56896
	v_mfma_f32_16x16x32_bf16 v[16:19], v[20:23], v[8:11], v[16:19]
	ds_read_b128 v[20:23], v44 offset:38528
	ds_read_b128 v[40:43], v44 offset:61504
	ds_read_b128 v[32:35], v94 offset:38464
	s_waitcnt lgkmcnt(0)
	v_mfma_f32_16x16x32_bf16 v[16:19], v[20:23], v[0:3], v[16:19]
	ds_read_b128 v[20:23], v44 offset:38592
	s_waitcnt lgkmcnt(0)
	v_mfma_f32_16x16x32_bf16 v[16:19], v[20:23], v[4:7], v[16:19]
	ds_read_b128 v[20:23], v44 offset:43008
	s_waitcnt lgkmcnt(0)
; __device__ __forceinline__ unsigned cvt_pk_bf16(float lo, float hi) { typedef float f2 __attribute__((ext_vector_type(2))); typedef __bf16 b2 __attribute__((ext_vector_type(2))); f2 v = {lo, hi}; b2 b = __builtin_convertvector(v, b2); return __builtin_bit_cast(unsigned, b); }
; #define MFMA16(a, b, c) __builtin_amdgcn_mfma_f32_16x16x32_bf16((a), (b), (c), 0, 0, 0)
; __device__ __forceinline__ void pp_mla_lds(int tok0, int hh, const bf16_t* PROJ, bf16_t* QC, bf16_t* KC, bf16_t* VC, const float2* rope, const char* Lq, const char* Lkv, const float* cqn, const float* ckvn, int lane) {
;     ...
;         {   f32x4 acc[8];
; #pragma unroll
;             for (int nt = 0; nt < 8; ++nt) { acc[nt] = (f32x4){0.f, 0.f, 0.f, 0.f}; const char* wr_ = Lkv + (nt * 16 + m) * 288 + quad * 16;
; #pragma unroll
;                 for (int ks = 0; ks < 4; ++ks) acc[nt] = MFMA16(*(const bf16x8*)(wr_ + ks * 64), ak[ks], acc[nt]); }
;             bf16_t* ko = KC + (size_t)tok * 384 + hh * 96 + quad * 4; bf16_t* vo = VC + (size_t)tok * 256 + hh * 64 + quad * 4;
; #pragma unroll
;             for (int nt = 0; nt < 4; ++nt) { u32x2 w; w.x = cvt_pk_bf16(acc[nt][0], acc[nt][1]); w.y = cvt_pk_bf16(acc[nt][2], acc[nt][3]); *(u32x2*)(ko + nt * 16) = w;
;                 u32x2 w2; w2.x = cvt_pk_bf16(acc[nt + 4][0], acc[nt + 4][1]); w2.y = cvt_pk_bf16(acc[nt + 4][2], acc[nt + 4][3]); *(u32x2*)(vo + nt * 16) = w2; } }
	v_mfma_f32_16x16x32_bf16 v[20:23], v[20:23], v[12:15], 0
	v_mfma_f32_16x16x32_bf16 v[20:23], v[24:27], v[8:11], v[20:23]
	ds_read_b128 v[24:27], v44 offset:43136
	s_waitcnt lgkmcnt(0)
	v_mfma_f32_16x16x32_bf16 v[20:23], v[24:27], v[0:3], v[20:23]
	ds_read_b128 v[24:27], v44 offset:43200
	s_waitcnt lgkmcnt(0)
	v_mfma_f32_16x16x32_bf16 v[20:23], v[24:27], v[4:7], v[20:23]
	ds_read_b128 v[24:27], v44 offset:47616
	s_waitcnt lgkmcnt(0)
	v_mfma_f32_16x16x32_bf16 v[24:27], v[24:27], v[12:15], 0
	v_mfma_f32_16x16x32_bf16 v[24:27], v[28:31], v[8:11], v[24:27]
	ds_read_b128 v[28:31], v44 offset:47744
	s_waitcnt lgkmcnt(0)
	v_mfma_f32_16x16x32_bf16 v[24:27], v[28:31], v[0:3], v[24:27]
	ds_read_b128 v[28:31], v44 offset:47808
	s_waitcnt lgkmcnt(0)
	v_mfma_f32_16x16x32_bf16 v[24:27], v[28:31], v[4:7], v[24:27]
	ds_read_b128 v[28:31], v94 offset:38400
	s_waitcnt lgkmcnt(0)
	v_mfma_f32_16x16x32_bf16 v[28:31], v[28:31], v[12:15], 0
	v_mfma_f32_16x16x32_bf16 v[28:31], v[32:35], v[8:11], v[28:31]
	ds_read_b128 v[32:35], v94 offset:38528
	s_waitcnt lgkmcnt(0)
	v_mfma_f32_16x16x32_bf16 v[28:31], v[32:35], v[0:3], v[28:31]
	ds_read_b128 v[32:35], v94 offset:38592
	s_waitcnt lgkmcnt(0)
	v_mfma_f32_16x16x32_bf16 v[28:31], v[32:35], v[4:7], v[28:31]
	ds_read_b128 v[32:35], v44 offset:56832
	s_waitcnt lgkmcnt(0)
	v_mfma_f32_16x16x32_bf16 v[32:35], v[32:35], v[12:15], 0
	v_mfma_f32_16x16x32_bf16 v[32:35], v[36:39], v[8:11], v[32:35]
	ds_read_b128 v[36:39], v44 offset:56960
	s_waitcnt lgkmcnt(0)
	v_mfma_f32_16x16x32_bf16 v[32:35], v[36:39], v[0:3], v[32:35]
	ds_read_b128 v[36:39], v44 offset:57024
	s_waitcnt lgkmcnt(0)
	v_mfma_f32_16x16x32_bf16 v[32:35], v[36:39], v[4:7], v[32:35]
	ds_read_b128 v[36:39], v44 offset:61440
	s_waitcnt lgkmcnt(0)
	v_mfma_f32_16x16x32_bf16 v[36:39], v[36:39], v[12:15], 0
	v_mfma_f32_16x16x32_bf16 v[36:39], v[40:43], v[8:11], v[36:39]
	ds_read_b128 v[40:43], v44 offset:61568
	s_waitcnt lgkmcnt(0)
	v_mfma_f32_16x16x32_bf16 v[36:39], v[40:43], v[0:3], v[36:39]
	ds_read_b128 v[40:43], v44 offset:61632
	ds_read_b128 v[44:47], v90 offset:27712
	s_waitcnt lgkmcnt(0)
	v_mfma_f32_16x16x32_bf16 v[36:39], v[40:43], v[4:7], v[36:39]
	ds_read_b128 v[40:43], v90 offset:27648
	s_waitcnt lgkmcnt(0)
	v_mfma_f32_16x16x32_bf16 v[40:43], v[40:43], v[12:15], 0
	v_mfma_f32_16x16x32_bf16 v[40:43], v[44:47], v[8:11], v[40:43]
	ds_read_b128 v[44:47], v90 offset:27776
	s_waitcnt lgkmcnt(0)
	v_mfma_f32_16x16x32_bf16 v[40:43], v[44:47], v[0:3], v[40:43]
	ds_read_b128 v[44:47], v90 offset:27840
	s_waitcnt lgkmcnt(0)
	v_mfma_f32_16x16x32_bf16 v[40:43], v[44:47], v[4:7], v[40:43]
	ds_read_b128 v[44:47], v95 offset:38400
	s_waitcnt lgkmcnt(0)
	v_mfma_f32_16x16x32_bf16 v[12:15], v[44:47], v[12:15], 0
	ds_read_b128 v[44:47], v95 offset:38464
	s_waitcnt lgkmcnt(0)
	v_mfma_f32_16x16x32_bf16 v[8:11], v[44:47], v[8:11], v[12:15]
	s_nop 4
	ds_read_b128 v[12:15], v95 offset:38528
	s_waitcnt lgkmcnt(0)
	v_mfma_f32_16x16x32_bf16 v[0:3], v[12:15], v[0:3], v[8:11]
	s_nop 2
	ds_read_b128 v[8:11], v95 offset:38592
	s_waitcnt lgkmcnt(0)
	v_mfma_f32_16x16x32_bf16 v[0:3], v[8:11], v[4:7], v[0:3]
	v_mad_i64_i32 v[4:5], s[4:5], v84, s57, v[80:81]
	v_lshlrev_b64 v[6:7], 9, v[84:85]
	v_cvt_pk_bf16_f32 v8, v16, v17
	v_cvt_pk_bf16_f32 v9, v18, v19
	v_lshl_add_u64 v[6:7], v[82:83], 0, v[6:7]
	global_store_dwordx2 v[4:5], v[8:9], off
	v_cvt_pk_bf16_f32 v8, v32, v33
	v_cvt_pk_bf16_f32 v9, v34, v35
	global_store_dwordx2 v[6:7], v[8:9], off
	v_cvt_pk_bf16_f32 v8, v20, v21
	v_cvt_pk_bf16_f32 v9, v22, v23
	global_store_dwordx2 v[4:5], v[8:9], off offset:32
	v_cvt_pk_bf16_f32 v8, v36, v37
	v_cvt_pk_bf16_f32 v9, v38, v39
	global_store_dwordx2 v[6:7], v[8:9], off offset:32
	v_cvt_pk_bf16_f32 v8, v24, v25
	v_cvt_pk_bf16_f32 v9, v26, v27
	global_store_dwordx2 v[4:5], v[8:9], off offset:64
	v_cvt_pk_bf16_f32 v8, v40, v41
	v_cvt_pk_bf16_f32 v9, v42, v43
	global_store_dwordx2 v[6:7], v[8:9], off offset:64
	v_cvt_pk_bf16_f32 v8, v28, v29
	v_cvt_pk_bf16_f32 v9, v30, v31
	v_cvt_pk_bf16_f32 v0, v0, v1
	v_cvt_pk_bf16_f32 v1, v2, v3
	v_add_u32_e32 v84, s58, v84
	global_store_dwordx2 v[4:5], v[8:9], off offset:96
	global_store_dwordx2 v[6:7], v[0:1], off offset:96
	s_cbranch_scc0 .LBB0_500
	s_branch .LBB0_443

; template <int DQK, int NSUB, int MODE>
; __device__ __forceinline__ void flash_unit(LAS char* L, const bf16_t* Qp, int qpitch, const bf16_t* Kp, int kpitch, const bf16_t* Vp, int vpitch,
;                                            bf16_t* Op, int opitch, float lam, float oscale, const float* subln) {
;     ...
;         const float i1 = 1.0f / (lrow[0] + __shfl_xor(lrow[0], 32)), i2 = lam / (lrow[NSUB - 1] + __shfl_xor(lrow[NSUB - 1], 32));
;         float ss = 0.f;
; #pragma unroll
;         for (int db = 0; db < 2; ++db)
; #pragma unroll
;             for (int r = 0; r < 16; ++r) { const float v = o[0][db][r] * i1 - o[NSUB - 1][db][r] * i2; o[0][db][r] = v; ss += v * v; }
;         ss += __shfl_xor(ss, 32);
.LBB0_555:
	s_lshl_b64 s[6:7], s[6:7], 9
	s_add_u32 s4, s4, s6
	s_addc_u32 s5, s5, s7
	s_add_u32 s4, s4, s21
	s_addc_u32 s5, s5, 0
	s_setprio 0
	ds_bpermute_b32 v32, v184, v168
	v_lshlrev_b64 v[36:37], 9, v[156:157]
	v_lshl_add_u64 v[46:47], s[4:5], 0, v[36:37]
	v_lshlrev_b32_e32 v192, 1, v187
	v_lshl_add_u64 v[46:47], v[46:47], 0, v[192:193]
	s_waitcnt lgkmcnt(0)
	v_add_f32_e32 v32, v168, v32
	v_div_scale_f32 v33, s[6:7], v32, v32, 1.0
	v_rcp_f32_e32 v34, v33
	s_add_i32 s20, s20, s88
	s_add_i32 s16, s16, s25
	s_cmp_lt_i32 s20, s19
	v_fma_f32 v35, -v33, v34, 1.0
	v_fmac_f32_e32 v34, v35, v34
	v_div_scale_f32 v35, vcc, 1.0, v32, 1.0
	v_mul_f32_e32 v38, v35, v34
	v_fma_f32 v39, -v33, v38, v35
	v_fmac_f32_e32 v38, v39, v34
	v_fma_f32 v33, -v33, v38, v35
	v_div_fmas_f32 v33, v33, v34, v38
	v_div_fixup_f32 v34, v33, v32, 1.0
	ds_bpermute_b32 v32, v184, v160
	s_waitcnt lgkmcnt(0)
	v_add_f32_e32 v32, v160, v32
	v_div_scale_f32 v33, s[6:7], v32, v32, v186
	v_rcp_f32_e32 v35, v33
	s_nop 0
	v_fma_f32 v38, -v33, v35, 1.0
	v_fmac_f32_e32 v35, v38, v35
	v_div_scale_f32 v38, vcc, v186, v32, v186
	v_mul_f32_e32 v39, v38, v35
	v_fma_f32 v40, -v33, v39, v38
	v_fmac_f32_e32 v39, v40, v35
	v_fma_f32 v33, -v33, v39, v38
	v_div_fmas_f32 v33, v33, v35, v39
	v_div_fixup_f32 v40, v33, v32, v186
	v_pk_mul_f32 v[32:33], v[74:75], v[40:41] op_sel_hi:[1,0]
	v_pk_mul_f32 v[48:49], v[48:49], v[40:41] op_sel_hi:[1,0]
	v_pk_fma_f32 v[32:33], v[26:27], v[34:35], v[32:33] op_sel_hi:[1,0,1] neg_lo:[0,0,1] neg_hi:[0,0,1]
	v_pk_mul_f32 v[26:27], v[76:77], v[40:41] op_sel_hi:[1,0]
	v_lshlrev_b32_e32 v76, 2, v187
	global_load_dwordx4 v[36:39], v76, s[12:13]
	v_pk_mul_f32 v[50:51], v[50:51], v[40:41] op_sel_hi:[1,0]
	v_pk_fma_f32 v[48:49], v[0:1], v[34:35], v[48:49] op_sel_hi:[1,0,1] neg_lo:[0,0,1] neg_hi:[0,0,1]
	v_pk_fma_f32 v[26:27], v[28:29], v[34:35], v[26:27] op_sel_hi:[1,0,1] neg_lo:[0,0,1] neg_hi:[0,0,1]
	v_pk_mul_f32 v[28:29], v[78:79], v[40:41] op_sel_hi:[1,0]
	v_pk_fma_f32 v[2:3], v[2:3], v[34:35], v[50:51] op_sel_hi:[1,0,1] neg_lo:[0,0,1] neg_hi:[0,0,1]
	v_pk_mul_f32 v[74:75], v[48:49], v[48:49]
	v_pk_mul_f32 v[54:55], v[54:55], v[40:41] op_sel_hi:[1,0]
	v_pk_mul_f32 v[52:53], v[52:53], v[40:41] op_sel_hi:[1,0]
	v_pk_mul_f32 v[58:59], v[58:59], v[40:41] op_sel_hi:[1,0]
	v_pk_mul_f32 v[56:57], v[56:57], v[40:41] op_sel_hi:[1,0]
	v_pk_mul_f32 v[62:63], v[62:63], v[40:41] op_sel_hi:[1,0]
	v_pk_mul_f32 v[60:61], v[60:61], v[40:41] op_sel_hi:[1,0]
	v_pk_mul_f32 v[66:67], v[66:67], v[40:41] op_sel_hi:[1,0]
	v_pk_mul_f32 v[64:65], v[64:65], v[40:41] op_sel_hi:[1,0]
	v_pk_mul_f32 v[70:71], v[70:71], v[40:41] op_sel_hi:[1,0]
	v_pk_mul_f32 v[68:69], v[68:69], v[40:41] op_sel_hi:[1,0]
	v_pk_mul_f32 v[40:41], v[72:73], v[40:41] op_sel_hi:[1,0]
	v_pk_mul_f32 v[50:51], v[2:3], v[2:3]
	v_pk_fma_f32 v[24:25], v[24:25], v[34:35], v[40:41] op_sel_hi:[1,0,1] neg_lo:[0,0,1] neg_hi:[0,0,1]
	v_add_f32_e32 v40, v74, v75
	v_pk_fma_f32 v[52:53], v[4:5], v[34:35], v[52:53] op_sel_hi:[1,0,1] neg_lo:[0,0,1] neg_hi:[0,0,1]
	v_add_f32_e32 v40, v50, v40
	v_pk_mul_f32 v[4:5], v[52:53], v[52:53]
	v_add_f32_e32 v40, v51, v40
	v_pk_fma_f32 v[6:7], v[6:7], v[34:35], v[54:55] op_sel_hi:[1,0,1] neg_lo:[0,0,1] neg_hi:[0,0,1]
	v_add_f32_e32 v4, v4, v40
	v_pk_mul_f32 v[54:55], v[6:7], v[6:7]
	v_add_f32_e32 v4, v5, v4
	v_pk_fma_f32 v[8:9], v[8:9], v[34:35], v[56:57] op_sel_hi:[1,0,1] neg_lo:[0,0,1] neg_hi:[0,0,1]
	v_add_f32_e32 v4, v54, v4
	v_pk_mul_f32 v[56:57], v[8:9], v[8:9]
	v_add_f32_e32 v4, v55, v4
	v_pk_fma_f32 v[10:11], v[10:11], v[34:35], v[58:59] op_sel_hi:[1,0,1] neg_lo:[0,0,1] neg_hi:[0,0,1]
	v_add_f32_e32 v4, v56, v4
	v_pk_mul_f32 v[58:59], v[10:11], v[10:11]
	v_add_f32_e32 v4, v57, v4
	v_pk_fma_f32 v[12:13], v[12:13], v[34:35], v[60:61] op_sel_hi:[1,0,1] neg_lo:[0,0,1] neg_hi:[0,0,1]
	v_add_f32_e32 v4, v58, v4
	v_pk_mul_f32 v[60:61], v[12:13], v[12:13]
	v_add_f32_e32 v4, v59, v4
	v_pk_fma_f32 v[14:15], v[14:15], v[34:35], v[62:63] op_sel_hi:[1,0,1] neg_lo:[0,0,1] neg_hi:[0,0,1]
	v_add_f32_e32 v4, v60, v4
	v_pk_mul_f32 v[62:63], v[14:15], v[14:15]
	v_add_f32_e32 v4, v61, v4
	v_pk_fma_f32 v[16:17], v[16:17], v[34:35], v[64:65] op_sel_hi:[1,0,1] neg_lo:[0,0,1] neg_hi:[0,0,1]
	v_add_f32_e32 v4, v62, v4
	v_pk_mul_f32 v[64:65], v[16:17], v[16:17]
	v_add_f32_e32 v4, v63, v4
	v_pk_fma_f32 v[18:19], v[18:19], v[34:35], v[66:67] op_sel_hi:[1,0,1] neg_lo:[0,0,1] neg_hi:[0,0,1]
	v_add_f32_e32 v4, v64, v4
	v_pk_mul_f32 v[66:67], v[18:19], v[18:19]
	v_add_f32_e32 v4, v65, v4
	v_pk_fma_f32 v[20:21], v[20:21], v[34:35], v[68:69] op_sel_hi:[1,0,1] neg_lo:[0,0,1] neg_hi:[0,0,1]
	v_add_f32_e32 v4, v66, v4
	v_pk_mul_f32 v[68:69], v[20:21], v[20:21]
	v_add_f32_e32 v4, v67, v4
	v_pk_fma_f32 v[22:23], v[22:23], v[34:35], v[70:71] op_sel_hi:[1,0,1] neg_lo:[0,0,1] neg_hi:[0,0,1]
	v_add_f32_e32 v4, v68, v4
	v_pk_mul_f32 v[70:71], v[22:23], v[22:23]
	v_add_f32_e32 v4, v69, v4
	v_add_f32_e32 v4, v70, v4
	v_pk_fma_f32 v[28:29], v[30:31], v[34:35], v[28:29] op_sel_hi:[1,0,1] neg_lo:[0,0,1] neg_hi:[0,0,1]
	v_pk_mul_f32 v[34:35], v[24:25], v[24:25]
	v_add_f32_e32 v4, v71, v4
	v_add_f32_e32 v4, v34, v4
	v_pk_mul_f32 v[42:43], v[32:33], v[32:33]
	v_add_f32_e32 v4, v35, v4
	v_add_f32_e32 v4, v42, v4
	v_pk_mul_f32 v[44:45], v[26:27], v[26:27]
	v_add_f32_e32 v4, v43, v4
	v_add_f32_e32 v4, v44, v4
	v_pk_mul_f32 v[30:31], v[28:29], v[28:29]
	v_add_f32_e32 v4, v45, v4
	v_add_f32_e32 v4, v30, v4
	v_add_f32_e32 v4, v31, v4
	ds_bpermute_b32 v5, v184, v4
	v_lshl_add_u64 v[0:1], v[46:47], 0, s[38:39]
	s_waitcnt lgkmcnt(0)
; __device__ __forceinline__ unsigned cvt_pk_bf16(float lo, float hi) { typedef float f2 __attribute__((ext_vector_type(2))); typedef __bf16 b2 __attribute__((ext_vector_type(2))); f2 v = {lo, hi}; b2 b = __builtin_convertvector(v, b2); return __builtin_bit_cast(unsigned, b); }
; template <int DQK, int NSUB, int MODE>
; __device__ __forceinline__ void flash_unit(LAS char* L, const bf16_t* Qp, int qpitch, const bf16_t* Kp, int kpitch, const bf16_t* Vp, int vpitch,
;                                            bf16_t* Op, int opitch, float lam, float oscale, const float* subln) {
;     ...
;     bf16x8 qf[NSUB][ND0];
;     { const bf16_t* qrow = Qp + (size_t)(32 * wid + r32) * qpitch;
; #pragma unroll
;       for (int s = 0; s < NSUB; ++s)
; #pragma unroll
;           for (int d0 = 0; d0 < ND0; ++d0) qf[s][d0] = *(const bf16x8*)(qrow + s * DQK + 16 * d0 + 8 * hi); }
;     const int kr1 = tid / KCH, kc1 = tid % KCH, kr2 = (tid + 512) / KCH, kc2 = (tid + 512) % KCH; const bool has2 = (tid + 512) < NKCH;
;     const int vr1 = tid >> 3, vc1 = tid & 7;
;     const bf16_t* kg1 = Kp + (size_t)kr1 * kpitch + kc1 * 8; const bf16_t* kg2 = Kp + (size_t)kr2 * kpitch + kc2 * 8; const bf16_t* vg1 = Vp + (size_t)vr1 * vpitch + vc1 * 8;
;     const int kl1 = kr1 * KPB + kc1 * 16, kl2 = kr2 * KPB + kc2 * 16, vl1 = vr1 * VPB + vc1 * 16;
;     u32x4 rk1, rk2 = {0u, 0u, 0u, 0u}, rv1;
;     float mref[NSUB], lrow[NSUB]; f32x16 o[NSUB][2], negm[NSUB];
; #pragma unroll
;     for (int s = 0; s < NSUB; ++s) { mref[s] = 0.f; lrow[s] = 0.f;
; #pragma unroll
;         for (int r = 0; r < 16; ++r) { o[s][0][r] = 0.f; o[s][1][r] = 0.f; negm[s][r] = 0.f; } }
;     rk1 = *(const u32x4*)kg1; if (has2) rk2 = *(const u32x4*)kg2; rv1 = *(const u32x4*)vg1;
;     ...
;         const float rn = oscale / sqrtf(ss * (1.f / 64.f) + EPS);
; #pragma unroll
;         for (int db = 0; db < 2; ++db)
; #pragma unroll
;             for (int g = 0; g < 4; ++g) { const int d = 32 * db + 8 * g + 4 * hi; const f32x4 sg = *(const f32x4*)(subln + d);
;                 u32x2 w; w.x = cvt_pk_bf16(o[0][db][4 * g] * rn * sg[0], o[0][db][4 * g + 1] * rn * sg[1]); w.y = cvt_pk_bf16(o[0][db][4 * g + 2] * rn * sg[2], o[0][db][4 * g + 3] * rn * sg[3]);
;                 *(u32x2*)(orow + d) = w; }
	v_add_f32_e32 v4, v4, v5
	v_fmamk_f32 v4, v4, 0x3c800000, v242
	v_cmp_gt_f32_e32 vcc, s31, v4
	v_mul_f32_e32 v5, 0x4f800000, v4
	s_nop 0
	v_cndmask_b32_e32 v4, v4, v5, vcc
	v_sqrt_f32_e32 v5, v4
	s_nop 0
	v_add_u32_e32 v30, -1, v5
	v_fma_f32 v31, -v30, v5, v4
	v_cmp_ge_f32_e64 s[36:37], 0, v31
	v_add_u32_e32 v31, 1, v5
	s_nop 0
	v_cndmask_b32_e64 v30, v5, v30, s[36:37]
	v_fma_f32 v5, -v31, v5, v4
	v_cmp_lt_f32_e64 s[36:37], 0, v5
	s_nop 1
	v_cndmask_b32_e64 v5, v30, v31, s[36:37]
	v_mul_f32_e32 v30, 0x37800000, v5
	v_cndmask_b32_e32 v5, v5, v30, vcc
	v_cmp_class_f32_e32 vcc, v4, v231
	s_nop 1
	v_cndmask_b32_e32 v4, v5, v4, vcc
	v_div_scale_f32 v5, s[4:5], v4, v4, v185
	v_rcp_f32_e32 v30, v5
	s_nop 0
	v_fma_f32 v31, -v5, v30, 1.0
	v_fmac_f32_e32 v30, v31, v30
	v_div_scale_f32 v31, vcc, v185, v4, v185
	v_mul_f32_e32 v34, v31, v30
	v_fma_f32 v35, -v5, v34, v31
	v_fmac_f32_e32 v34, v35, v30
	v_fma_f32 v5, -v5, v34, v31
	v_div_fmas_f32 v5, v5, v30, v34
	v_div_fixup_f32 v30, v5, v4, v185
	v_pk_mul_f32 v[4:5], v[48:49], v[30:31] op_sel_hi:[1,0]
	v_pk_mul_f32 v[2:3], v[2:3], v[30:31] op_sel_hi:[1,0]
	s_waitcnt vmcnt(0)
	v_pk_mul_f32 v[4:5], v[36:37], v[4:5]
	v_pk_mul_f32 v[2:3], v[38:39], v[2:3]
	v_cvt_pk_bf16_f32 v4, v4, v5
	v_cvt_pk_bf16_f32 v5, v2, v3
	v_add_co_u32_e32 v2, vcc, s33, v46
	v_pk_mul_f32 v[34:35], v[52:53], v[30:31] op_sel_hi:[1,0]
	s_nop 0
	v_addc_co_u32_e32 v3, vcc, 0, v47, vcc
	global_store_dwordx2 v[2:3], v[4:5], off
	global_load_dwordx4 v[2:5], v76, s[12:13] offset:32
	v_pk_mul_f32 v[6:7], v[6:7], v[30:31] op_sel_hi:[1,0]
	s_waitcnt vmcnt(0)
	v_pk_mul_f32 v[2:3], v[2:3], v[34:35]
	v_pk_mul_f32 v[4:5], v[4:5], v[6:7]
	v_cvt_pk_bf16_f32 v2, v2, v3
	v_cvt_pk_bf16_f32 v3, v4, v5
	global_store_dwordx2 v[0:1], v[2:3], off offset:16
	global_load_dwordx4 v[2:5], v76, s[12:13] offset:64
	v_pk_mul_f32 v[6:7], v[8:9], v[30:31] op_sel_hi:[1,0]
	s_waitcnt vmcnt(0)
	v_pk_mul_f32 v[2:3], v[2:3], v[6:7]
	v_pk_mul_f32 v[6:7], v[10:11], v[30:31] op_sel_hi:[1,0]
	v_cvt_pk_bf16_f32 v2, v2, v3
	v_pk_mul_f32 v[4:5], v[4:5], v[6:7]
	v_pk_mul_f32 v[6:7], v[12:13], v[30:31] op_sel_hi:[1,0]
	v_cvt_pk_bf16_f32 v3, v4, v5
	global_store_dwordx2 v[0:1], v[2:3], off offset:32
	global_load_dwordx4 v[2:5], v76, s[12:13] offset:96
	s_waitcnt vmcnt(0)
	v_pk_mul_f32 v[2:3], v[2:3], v[6:7]
	v_pk_mul_f32 v[6:7], v[14:15], v[30:31] op_sel_hi:[1,0]
	v_cvt_pk_bf16_f32 v2, v2, v3
	v_pk_mul_f32 v[4:5], v[4:5], v[6:7]
	v_pk_mul_f32 v[6:7], v[16:17], v[30:31] op_sel_hi:[1,0]
	v_cvt_pk_bf16_f32 v3, v4, v5
	global_store_dwordx2 v[0:1], v[2:3], off offset:48
	global_load_dwordx4 v[2:5], v76, s[12:13] offset:128
	s_waitcnt vmcnt(0)
	v_pk_mul_f32 v[2:3], v[2:3], v[6:7]
	v_pk_mul_f32 v[6:7], v[18:19], v[30:31] op_sel_hi:[1,0]
	v_cvt_pk_bf16_f32 v2, v2, v3
	v_pk_mul_f32 v[4:5], v[4:5], v[6:7]
	v_pk_mul_f32 v[6:7], v[20:21], v[30:31] op_sel_hi:[1,0]
	v_cvt_pk_bf16_f32 v3, v4, v5
	global_store_dwordx2 v[0:1], v[2:3], off offset:64
	global_load_dwordx4 v[2:5], v76, s[12:13] offset:160
	s_waitcnt vmcnt(0)
	v_pk_mul_f32 v[2:3], v[2:3], v[6:7]
	v_pk_mul_f32 v[6:7], v[22:23], v[30:31] op_sel_hi:[1,0]
	v_cvt_pk_bf16_f32 v2, v2, v3
	v_pk_mul_f32 v[4:5], v[4:5], v[6:7]
	v_pk_mul_f32 v[6:7], v[24:25], v[30:31] op_sel_hi:[1,0]
	v_cvt_pk_bf16_f32 v3, v4, v5
	global_store_dwordx2 v[0:1], v[2:3], off offset:80
	global_load_dwordx4 v[2:5], v76, s[12:13] offset:192
	s_waitcnt vmcnt(0)
	v_pk_mul_f32 v[2:3], v[2:3], v[6:7]
	v_pk_mul_f32 v[6:7], v[32:33], v[30:31] op_sel_hi:[1,0]
	v_cvt_pk_bf16_f32 v2, v2, v3
	v_pk_mul_f32 v[4:5], v[4:5], v[6:7]
	v_pk_mul_f32 v[6:7], v[26:27], v[30:31] op_sel_hi:[1,0]
	v_cvt_pk_bf16_f32 v3, v4, v5
	global_store_dwordx2 v[0:1], v[2:3], off offset:96
	global_load_dwordx4 v[2:5], v76, s[12:13] offset:224
	s_waitcnt vmcnt(0)
	v_pk_mul_f32 v[2:3], v[2:3], v[6:7]
	v_pk_mul_f32 v[6:7], v[28:29], v[30:31] op_sel_hi:[1,0]
	v_cvt_pk_bf16_f32 v2, v2, v3
	v_pk_mul_f32 v[4:5], v[4:5], v[6:7]
	s_nop 0
	v_cvt_pk_bf16_f32 v3, v4, v5
	global_store_dwordx2 v[0:1], v[2:3], off offset:112
	s_cbranch_scc0 .LBB0_590
.LBB0_556:
	s_mov_b64 s[4:5], s[86:87]
	s_add_u32 s10, s4, 0x84c8000
	s_addc_u32 s11, s5, 0
	s_ashr_i32 s8, s20, 5
	s_ashr_i32 s9, s8, 31
	s_lshl_b64 s[6:7], s[8:9], 11
	s_lshl_b32 s9, s20, 8
	s_and_b32 s9, s9, 0x700
	s_or_b32 s6, s6, s9
	s_mul_i32 s9, s7, 0x1400
	s_mul_hi_u32 s14, s6, 0x1400
	s_add_i32 s14, s14, s9
	s_mul_i32 s9, s6, 0x1400
	s_add_u32 s9, s10, s9
	s_addc_u32 s14, s11, s14
	s_lshl_b32 s15, s20, 3
	s_and_b32 s15, s15, 0xc0
	s_lshl_b32 s21, s15, 1
	s_add_u32 s22, s9, s21
	s_addc_u32 s23, s14, 0
	s_mul_i32 s15, s8, 0xa00000
	s_mul_hi_i32 s14, s8, 0xa00000
	s_add_u32 s8, s10, s15
	v_mov_b32_e32 v15, v240
	s_addc_u32 s9, s11, s14
	s_add_u32 s10, s8, s21
	v_ashrrev_i32_e32 v17, 6, v15
	v_and_b32_e32 v14, 31, v15
	v_bfe_u32 v16, v15, 5, 1
	v_lshl_or_b32 v156, v17, 5, v14
	v_mov_b64_e32 v[0:1], s[22:23]
	s_addc_u32 s11, s9, 0
	v_mad_i64_i32 v[0:1], s[8:9], v156, s56, v[0:1]
	v_lshlrev_b32_e32 v192, 4, v16
	v_lshl_add_u64 v[0:1], v[0:1], 0, v[192:193]
	global_load_dwordx4 v[128:131], v[0:1], off
	global_load_dwordx4 v[132:135], v[0:1], off offset:32
	global_load_dwordx4 v[136:139], v[0:1], off offset:64
	global_load_dwordx4 v[140:143], v[0:1], off offset:96
	v_ashrrev_i32_e32 v0, 31, v15
	v_lshrrev_b32_e32 v0, 29, v0
	v_add_u32_e32 v0, v15, v0
	v_ashrrev_i32_e32 v33, 3, v0
	v_and_b32_e32 v0, -8, v0
	v_sub_u32_e32 v4, v15, v0
	v_lshlrev_b32_e32 v82, 3, v4
	v_mov_b64_e32 v[6:7], s[10:11]
	v_ashrrev_i32_e32 v83, 31, v82
	v_mad_i64_i32 v[0:1], s[8:9], v33, s56, v[6:7]
	v_lshl_add_u64 v[10:11], v[82:83], 1, v[0:1]
	global_load_dwordx4 v[0:3], v[10:11], off offset:512
	v_add_u32_e32 v5, 0x200, v15
	v_ashrrev_i32_e32 v8, 31, v5
	v_lshrrev_b32_e32 v8, 29, v8
	v_add_u32_e32 v8, v5, v8
	v_ashrrev_i32_e32 v81, 3, v8
	v_and_b32_e32 v8, -8, v8
	v_sub_u32_e32 v5, v5, v8
	v_lshlrev_b32_e32 v84, 3, v5
	v_ashrrev_i32_e32 v85, 31, v84
	v_mad_i64_i32 v[6:7], s[8:9], v81, s56, v[6:7]
	v_lshl_add_u64 v[6:7], v[84:85], 1, v[6:7]
	v_cmp_gt_i32_e64 s[36:37], 0, v15
	v_lshl_add_u64 v[8:9], v[6:7], 0, s[34:35]
	v_mov_b32_e32 v144, v193
	v_mov_b32_e32 v145, v193
	v_mov_b32_e32 v146, v193
	v_mov_b32_e32 v147, v193
	s_and_saveexec_b64 s[8:9], s[36:37]
	s_cbranch_execz .LBB0_558
	global_load_dwordx4 v[144:147], v[8:9], off
; template <int DQK, int NSUB, int MODE>
; __device__ __forceinline__ void flash_unit(LAS char* L, const bf16_t* Qp, int qpitch, const bf16_t* Kp, int kpitch, const bf16_t* Vp, int vpitch,
;                                            bf16_t* Op, int opitch, float lam, float oscale, const float* subln) {
;     ...
;     rk1 = *(const u32x4*)kg1; if (has2) rk2 = *(const u32x4*)kg2; rv1 = *(const u32x4*)vg1;
;     __syncthreads();
;     *(u32x4*)(Lg + kl1) = rk1; if (has2) *(u32x4*)(Lg + kl2) = rk2; *(u32x4*)(Lg + OFF_V + vl1) = rv1;
;     __syncthreads();
;     const int vq = (lane & 15) >> 2, vp_ = lane & 3, vblk = (lane >> 4) & 1;
;     const int voff = (4 * hi + vq) * VPB + (16 * vblk + 4 * vp_) * 2;
;     if (__builtin_amdgcn_readfirstlane(wid) >= 4) __builtin_amdgcn_s_setprio(1);
;     for (int t = 0; t < SEQ / 64; ++t) {
;         const int buf = t & 1;
;         if (t + 1 < SEQ / 64) { const size_t ko = (size_t)(t + 1) * 64 * kpitch, vo = (size_t)(t + 1) * 64 * vpitch;
;             rk1 = *(const u32x4*)(kg1 + ko); if (has2) rk2 = *(const u32x4*)(kg2 + ko); rv1 = *(const u32x4*)(vg1 + vo); }
.LBB0_558:
	s_or_b64 exec, exec, s[8:9]
	v_ashrrev_i32_e32 v106, 3, v15
	v_and_b32_e32 v12, 7, v15
	v_mov_b64_e32 v[6:7], s[10:11]
	v_mad_i64_i32 v[6:7], s[8:9], v106, s56, v[6:7]
	v_lshlrev_b32_e32 v86, 4, v12
	v_mov_b32_e32 v87, v193
	v_lshl_add_u64 v[12:13], v[6:7], 0, v[86:87]
	v_mul_lo_u32 v6, v81, s27
	v_lshl_add_u32 v188, v5, 4, v6
	v_mul_lo_u32 v5, v33, s27
	v_lshl_add_u32 v189, v4, 4, v5
	global_load_dwordx4 v[4:7], v[12:13], off offset:1024
	v_add_u32_e32 v107, 0, v189
	v_add_u32_e32 v87, 0, v188
	s_waitcnt lgkmcnt(0)
	s_barrier
	s_waitcnt vmcnt(0)
	ds_write_b128 v107, v[0:3]
	s_and_saveexec_b64 s[8:9], s[36:37]
	ds_write_b128 v87, v[144:147]
	s_or_b64 exec, exec, s[8:9]
	v_mul_lo_u32 v0, v106, s27
	v_readfirstlane_b32 s8, v17
	v_add3_u32 v190, 0, v0, v86
	s_cmp_lt_i32 s8, 4
	ds_write_b128 v190, v[4:7] offset:18432
	s_waitcnt lgkmcnt(0)
	s_barrier
	s_cbranch_scc1 .LBB0_562
	s_setprio 1
.LBB0_562:
	v_lshl_add_u64 v[0:1], v[10:11], 0, s[34:35]
	v_add_co_u32_e32 v0, vcc, 0x50000, v0
	s_nop 1
	v_addc_co_u32_e32 v1, vcc, 0, v1, vcc
	global_load_dwordx4 v[148:151], v[0:1], off
	s_and_saveexec_b64 s[8:9], s[36:37]
	s_cbranch_execz .LBB0_564
	v_add_co_u32_e32 v0, vcc, 0x50000, v8
	s_nop 1
	v_addc_co_u32_e32 v1, vcc, 0, v9, vcc
	global_load_dwordx4 v[144:147], v[0:1], off
; #define LAS __attribute__((address_space(3)))
; #define MFMA32(a, b, c) __builtin_amdgcn_mfma_f32_32x32x16_bf16((a), (b), (c), 0, 0, 0)
; template <int DQK, int NSUB, int MODE>
; __device__ __forceinline__ void flash_unit(LAS char* L, const bf16_t* Qp, int qpitch, const bf16_t* Kp, int kpitch, const bf16_t* Vp, int vpitch,
;                                            bf16_t* Op, int opitch, float lam, float oscale, const float* subln) {
;     ...
;             rk1 = *(const u32x4*)(kg1 + ko); if (has2) rk2 = *(const u32x4*)(kg2 + ko); rv1 = *(const u32x4*)(vg1 + vo); }
;         const char* Kb = Lg + buf * KBUF; LAS const char* Vb = L + OFF_V + buf * VBUF + voff;
; #pragma unroll
;         for (int s = 0; s < NSUB; ++s) {
;             f32x16 p0, p1;
; #pragma unroll
;             for (int d0 = 0; d0 < ND0; ++d0) { const bf16x8 k0 = *(const bf16x8*)(Kb + r32 * KPB + (s * DQK + 16 * d0 + 8 * hi) * 2); const bf16x8 k1 = *(const bf16x8*)(Kb + (32 + r32) * KPB + (s * DQK + 16 * d0 + 8 * hi) * 2);
;                 if (d0 == 0) { p0 = MFMA32(k0, qf[s][d0], negm[s]); p1 = MFMA32(k1, qf[s][d0], negm[s]); }
;                 else { p0 = MFMA32(k0, qf[s][d0], p0); p1 = MFMA32(k1, qf[s][d0], p1); } }
; #pragma unroll
;             for (int hf = 0; hf < 2; ++hf) {
;                 f32x16& ph = hf ? p1 : p0;
;                 float mx = fmaxf(ph[0], ph[1]);
; #pragma unroll
;                 for (int r = 2; r < 16; ++r) mx = fmaxf(mx, ph[r]);
;                 mx = fmaxf(mx, __shfl_xor(mx, 32));
;                 const bool first = (t == 0) && (hf == 0);
;                 if (first || __any(mx > 8.0f)) {
;                     const float dl = first ? mx : fmaxf(mx, 0.f); mref[s] += dl;
; #pragma unroll
;                     for (int r = 0; r < 16; ++r) { ph[r] -= dl; negm[s][r] = -mref[s]; }
;                     if (hf == 0) {
; #pragma unroll
;                         for (int r = 0; r < 16; ++r) p1[r] -= dl;
;                     }
;                     if (!first) { const float alpha = __builtin_amdgcn_exp2f(-dl); lrow[s] *= alpha;
; #pragma unroll
;                         for (int r = 0; r < 16; ++r) { o[s][0][r] *= alpha; o[s][1][r] *= alpha; } }
;                 }
; #pragma unroll
;                 for (int r = 0; r < 16; ++r) ph[r] = __builtin_amdgcn_exp2f(ph[r]);
.LBB0_564:
	s_or_b64 exec, exec, s[8:9]
	v_lshrrev_b32_e32 v2, 2, v15
	v_and_b32_e32 v3, 16, v15
	v_lshlrev_b32_e32 v187, 2, v16
	v_lshlrev_b32_e32 v4, 2, v15
	s_mov_b64 s[8:9], 0x400
	v_and_or_b32 v2, v2, 3, v187
	v_and_or_b32 v3, v4, 12, v3
	v_lshl_add_u64 v[0:1], v[12:13], 0, s[8:9]
	v_mul_u32_u24_e32 v2, 0x90, v2
	v_lshlrev_b32_e32 v3, 1, v3
	v_cmp_lt_i32_e32 vcc, v250, v245
	v_add3_u32 v191, 0, v2, v3
	v_mul_u32_u24_e32 v2, 0x90, v14
	v_cndmask_b32_e32 v3, v244, v250, vcc
	v_add_co_u32_e32 v0, vcc, s30, v0
	v_add3_u32 v192, 0, v2, v192
	s_nop 0
	v_addc_co_u32_e32 v1, vcc, 0, v1, vcc
	v_lshlrev_b32_e32 v184, 2, v3
	global_load_dwordx4 v[152:155], v[0:1], off
	ds_read_b128 v[0:3], v192 offset:4608
	ds_read_b128 v[4:7], v192
	ds_read_b128 v[34:37], v192 offset:32
	s_waitcnt lgkmcnt(0)
	v_mfma_f32_32x32x16_bf16 v[16:31], v[4:7], v[128:131], 0
	ds_read_b128 v[38:41], v192 offset:4640
	v_mfma_f32_32x32x16_bf16 v[16:31], v[34:37], v[132:135], v[16:31]
	v_mfma_f32_32x32x16_bf16 v[0:15], v[0:3], v[128:131], 0
	s_nop 10
	v_max_f32_e32 v32, v17, v17
	v_max_f32_e32 v34, v16, v16
	v_max_f32_e32 v32, v34, v32
	v_max3_f32 v32, v32, v18, v19
	v_max3_f32 v32, v32, v20, v21
	v_max3_f32 v32, v32, v22, v23
	v_max3_f32 v32, v32, v24, v25
	v_max3_f32 v32, v32, v26, v27
	v_max3_f32 v32, v32, v28, v29
	v_max3_f32 v32, v32, v30, v31
	s_waitcnt lgkmcnt(0)
	v_mfma_f32_32x32x16_bf16 v[0:15], v[38:41], v[132:135], v[0:15]
	ds_bpermute_b32 v34, v184, v32
	s_waitcnt lgkmcnt(0)
	v_max_f32_e32 v34, v34, v34
	v_max_f32_e32 v32, v32, v34
	v_sub_f32_e32 v16, v16, v32
	v_sub_f32_e32 v17, v17, v32
	v_sub_f32_e32 v18, v18, v32
	v_sub_f32_e32 v19, v19, v32
	v_sub_f32_e32 v20, v20, v32
	v_sub_f32_e32 v21, v21, v32
	s_nop 1
	v_pk_add_f32 v[36:37], v[0:1], v[32:33] op_sel_hi:[1,0] neg_lo:[0,1] neg_hi:[0,1]
	v_pk_add_f32 v[34:35], v[2:3], v[32:33] op_sel_hi:[1,0] neg_lo:[0,1] neg_hi:[0,1]
	v_exp_f32_e32 v0, v16
	v_exp_f32_e32 v1, v17
	v_exp_f32_e32 v2, v18
	v_exp_f32_e32 v3, v19
	v_sub_f32_e32 v22, v22, v32
	v_sub_f32_e32 v23, v23, v32
	v_pk_add_f32 v[38:39], v[4:5], v[32:33] op_sel_hi:[1,0] neg_lo:[0,1] neg_hi:[0,1]
	v_exp_f32_e32 v4, v20
	v_exp_f32_e32 v5, v21
	v_sub_f32_e32 v24, v24, v32
	v_sub_f32_e32 v25, v25, v32
	v_pk_add_f32 v[40:41], v[6:7], v[32:33] op_sel_hi:[1,0] neg_lo:[0,1] neg_hi:[0,1]
	v_exp_f32_e32 v6, v22
	v_exp_f32_e32 v7, v23
	v_sub_f32_e32 v26, v26, v32
	v_sub_f32_e32 v27, v27, v32
	v_pk_add_f32 v[42:43], v[8:9], v[32:33] op_sel_hi:[1,0] neg_lo:[0,1] neg_hi:[0,1]
	v_exp_f32_e32 v8, v24
	v_exp_f32_e32 v9, v25
	v_sub_f32_e32 v28, v28, v32
	v_sub_f32_e32 v29, v29, v32
	v_pk_add_f32 v[44:45], v[10:11], v[32:33] op_sel_hi:[1,0] neg_lo:[0,1] neg_hi:[0,1]
	v_exp_f32_e32 v10, v26
	v_exp_f32_e32 v11, v27
	v_pk_add_f32 v[16:17], v[0:1], v[2:3]
	v_sub_f32_e32 v30, v30, v32
	v_sub_f32_e32 v31, v31, v32
	v_pk_add_f32 v[46:47], v[12:13], v[32:33] op_sel_hi:[1,0] neg_lo:[0,1] neg_hi:[0,1]
	v_exp_f32_e32 v12, v28
	v_exp_f32_e32 v13, v29
	v_pk_add_f32 v[16:17], v[4:5], v[16:17]
	v_pk_add_f32 v[48:49], v[14:15], v[32:33] op_sel_hi:[1,0] neg_lo:[0,1] neg_hi:[0,1]
	v_exp_f32_e32 v14, v30
	v_exp_f32_e32 v15, v31
	v_pk_add_f32 v[16:17], v[6:7], v[16:17]
	v_cvt_pk_bf16_f32 v18, v4, v5
	v_pk_add_f32 v[16:17], v[8:9], v[16:17]
	v_cvt_pk_bf16_f32 v19, v6, v7
	v_pk_add_f32 v[16:17], v[10:11], v[16:17]
	v_cvt_pk_bf16_f32 v50, v8, v9
	v_pk_add_f32 v[16:17], v[12:13], v[16:17]
	v_cvt_pk_bf16_f32 v51, v10, v11
	v_pk_add_f32 v[58:59], v[14:15], v[16:17]
	v_cvt_pk_bf16_f32 v16, v0, v1
	v_cvt_pk_bf16_f32 v17, v2, v3
	ds_read_b64_tr_b16 v[0:1], v191 offset:18432
	ds_read_b64_tr_b16 v[2:3], v191 offset:19584
	v_cvt_pk_bf16_f32 v52, v12, v13
	v_cvt_pk_bf16_f32 v53, v14, v15
	s_waitcnt lgkmcnt(0)
	v_mfma_f32_32x32x16_bf16 v[0:15], v[0:3], v[16:19], 0
	ds_read_b64_tr_b16 v[20:21], v191 offset:20736
	ds_read_b64_tr_b16 v[22:23], v191 offset:21888
	s_waitcnt lgkmcnt(0)
	v_mfma_f32_32x32x16_bf16 v[0:15], v[20:23], v[50:53], v[0:15]
	ds_read_b64_tr_b16 v[20:21], v191 offset:18496
	ds_read_b64_tr_b16 v[22:23], v191 offset:19648
	ds_read_b64_tr_b16 v[54:55], v191 offset:20800
	ds_read_b64_tr_b16 v[56:57], v191 offset:21952
	s_waitcnt lgkmcnt(0)
	v_mfma_f32_32x32x16_bf16 v[16:31], v[20:23], v[16:19], 0
	v_mfma_f32_32x32x16_bf16 v[16:31], v[54:57], v[50:53], v[16:31]
	v_add_f32_e64 v50, v58, v59
	v_add_f32_e64 v51, v59, v58
	v_mov_b32_e32 v51, v32
	v_max_f32_e32 v32, v36, v37
	v_max3_f32 v32, v32, v34, v35
	v_max3_f32 v32, v32, v38, v39
	v_max3_f32 v32, v32, v40, v41
	v_max3_f32 v32, v32, v42, v43
	v_max3_f32 v32, v32, v44, v45
	v_max3_f32 v32, v32, v46, v47
	v_max3_f32 v32, v32, v48, v49
	v_pk_add_f32 v[158:159], v[50:51], 0 op_sel_hi:[1,0]
	ds_bpermute_b32 v50, v184, v32
	s_waitcnt lgkmcnt(0)
	v_max_f32_e32 v50, v50, v50
	v_max_f32_e32 v32, v32, v50
	v_cmp_lt_f32_e32 vcc, s61, v32
	s_cbranch_vccz .LBB0_566
	v_max_f32_e32 v32, v32, v32
	v_max_f32_e32 v32, 0, v32
	v_exp_f32_e64 v50, -v32
	v_add_f32_e32 v159, v159, v32
	v_sub_f32_e32 v36, v36, v32
	v_sub_f32_e32 v37, v37, v32
	v_sub_f32_e32 v34, v34, v32
	v_sub_f32_e32 v35, v35, v32
	v_sub_f32_e32 v38, v38, v32
	v_sub_f32_e32 v39, v39, v32
	v_sub_f32_e32 v40, v40, v32
	v_sub_f32_e32 v41, v41, v32
	v_sub_f32_e32 v42, v42, v32
	v_sub_f32_e32 v43, v43, v32
	v_sub_f32_e32 v44, v44, v32
	v_sub_f32_e32 v45, v45, v32
	v_sub_f32_e32 v46, v46, v32
	v_sub_f32_e32 v47, v47, v32
	v_sub_f32_e32 v48, v48, v32
	v_sub_f32_e32 v49, v49, v32
	v_pk_mul_f32 v[14:15], v[14:15], v[50:51] op_sel_hi:[1,0]
	v_pk_mul_f32 v[12:13], v[12:13], v[50:51] op_sel_hi:[1,0]
	v_pk_mul_f32 v[10:11], v[10:11], v[50:51] op_sel_hi:[1,0]
	v_pk_mul_f32 v[8:9], v[8:9], v[50:51] op_sel_hi:[1,0]
	v_pk_mul_f32 v[6:7], v[6:7], v[50:51] op_sel_hi:[1,0]
	v_pk_mul_f32 v[4:5], v[4:5], v[50:51] op_sel_hi:[1,0]
	v_pk_mul_f32 v[2:3], v[2:3], v[50:51] op_sel_hi:[1,0]
	v_pk_mul_f32 v[0:1], v[0:1], v[50:51] op_sel_hi:[1,0]
	v_pk_mul_f32 v[30:31], v[30:31], v[50:51] op_sel_hi:[1,0]
	v_pk_mul_f32 v[28:29], v[28:29], v[50:51] op_sel_hi:[1,0]
	v_pk_mul_f32 v[26:27], v[26:27], v[50:51] op_sel_hi:[1,0]
	v_pk_mul_f32 v[24:25], v[24:25], v[50:51] op_sel_hi:[1,0]
	v_pk_mul_f32 v[22:23], v[22:23], v[50:51] op_sel_hi:[1,0]
	v_pk_mul_f32 v[20:21], v[20:21], v[50:51] op_sel_hi:[1,0]
	v_pk_mul_f32 v[18:19], v[18:19], v[50:51] op_sel_hi:[1,0]
	v_pk_mul_f32 v[16:17], v[16:17], v[50:51] op_sel_hi:[1,0]
	v_xor_b32_e32 v32, 0x80000000, v159
	v_mul_f32_e32 v158, v158, v50
	s_branch .LBB0_567

; template <int DQK, int NSUB, int MODE>
; __device__ __forceinline__ void flash_unit(LAS char* L, const bf16_t* Qp, int qpitch, const bf16_t* Kp, int kpitch, const bf16_t* Vp, int vpitch,
;                                            bf16_t* Op, int opitch, float lam, float oscale, const float* subln) {
;     ...
;         if (t + 1 < SEQ / 64) { const size_t ko = (size_t)(t + 1) * 64 * kpitch, vo = (size_t)(t + 1) * 64 * vpitch;
;             rk1 = *(const u32x4*)(kg1 + ko); if (has2) rk2 = *(const u32x4*)(kg2 + ko); rv1 = *(const u32x4*)(vg1 + vo); }
.LBB0_575:
	s_cmp_lg_u32 s10, 0x960000
	s_cselect_b64 s[14:15], -1, 0
	s_cmp_eq_u32 s10, 0x960000
	s_cbranch_scc1 .LBB0_579
	v_lshl_add_u64 v[96:97], v[166:167], 0, s[10:11]
	s_waitcnt vmcnt(0)
	global_load_dwordx4 v[148:151], v[96:97], off
	s_and_saveexec_b64 s[8:9], s[36:37]
	s_cbranch_execz .LBB0_578
	v_lshl_add_u64 v[96:97], v[164:165], 0, s[10:11]
	global_load_dwordx4 v[144:147], v[96:97], off
.LBB0_578:
	s_or_b64 exec, exec, s[8:9]
	v_lshl_add_u64 v[96:97], v[162:163], 0, s[10:11]
	global_load_dwordx4 v[152:155], v[96:97], off

; __device__ __forceinline__ unsigned cvt_pk_bf16(float lo, float hi) { typedef float f2 __attribute__((ext_vector_type(2))); typedef __bf16 b2 __attribute__((ext_vector_type(2))); f2 v = {lo, hi}; b2 b = __builtin_convertvector(v, b2); return __builtin_bit_cast(unsigned, b); }
; template <int DQK, int NSUB, int MODE>
; __device__ __forceinline__ void flash_unit(LAS char* L, const bf16_t* Qp, int qpitch, const bf16_t* Kp, int kpitch, const bf16_t* Vp, int vpitch,
;                                            bf16_t* Op, int opitch, float lam, float oscale, const float* subln) {
;     ...
;     bf16x8 qf[NSUB][ND0];
;     { const bf16_t* qrow = Qp + (size_t)(32 * wid + r32) * qpitch;
; #pragma unroll
;       for (int s = 0; s < NSUB; ++s)
; #pragma unroll
;           for (int d0 = 0; d0 < ND0; ++d0) qf[s][d0] = *(const bf16x8*)(qrow + s * DQK + 16 * d0 + 8 * hi); }
;     const int kr1 = tid / KCH, kc1 = tid % KCH, kr2 = (tid + 512) / KCH, kc2 = (tid + 512) % KCH; const bool has2 = (tid + 512) < NKCH;
;     const int vr1 = tid >> 3, vc1 = tid & 7;
;     const bf16_t* kg1 = Kp + (size_t)kr1 * kpitch + kc1 * 8; const bf16_t* kg2 = Kp + (size_t)kr2 * kpitch + kc2 * 8; const bf16_t* vg1 = Vp + (size_t)vr1 * vpitch + vc1 * 8;
;     const int kl1 = kr1 * KPB + kc1 * 16, kl2 = kr2 * KPB + kc2 * 16, vl1 = vr1 * VPB + vc1 * 16;
;     u32x4 rk1, rk2 = {0u, 0u, 0u, 0u}, rv1;
;     float mref[NSUB], lrow[NSUB]; f32x16 o[NSUB][2], negm[NSUB];
; #pragma unroll
;     for (int s = 0; s < NSUB; ++s) { mref[s] = 0.f; lrow[s] = 0.f;
; #pragma unroll
;         for (int r = 0; r < 16; ++r) { o[s][0][r] = 0.f; o[s][1][r] = 0.f; negm[s][r] = 0.f; } }
;     rk1 = *(const u32x4*)kg1; if (has2) rk2 = *(const u32x4*)kg2; rv1 = *(const u32x4*)vg1;
;     ...
;     bf16_t* orow = Op + (size_t)(32 * wid + r32) * opitch;
;     if (MODE == 0) {
;         const float inv = 1.0f / (lrow[0] + __shfl_xor(lrow[0], 32));
; #pragma unroll
;         for (int db = 0; db < 2; ++db)
; #pragma unroll
;             for (int g = 0; g < 4; ++g) { u32x2 w; w.x = cvt_pk_bf16(o[0][db][4 * g] * inv, o[0][db][4 * g + 1] * inv); w.y = cvt_pk_bf16(o[0][db][4 * g + 2] * inv, o[0][db][4 * g + 3] * inv);
;                 *(u32x2*)(orow + 32 * db + 8 * g + 4 * hi) = w; }
.LBB0_591:
	s_add_u32 s8, s6, s4
	s_addc_u32 s9, s7, s5
	s_lshl_b64 s[6:7], s[10:11], 9
	s_add_u32 s6, s8, s6
	s_addc_u32 s7, s9, s7
	s_lshl_b32 s8, s20, 1
	s_add_u32 s6, s6, s8
	s_addc_u32 s7, s7, 0
	s_setprio 0
	ds_bpermute_b32 v34, v184, v118
	v_lshlrev_b64 v[32:33], 9, v[116:117]
	v_lshlrev_b32_e32 v192, 1, v129
	v_lshl_add_u64 v[32:33], s[6:7], 0, v[32:33]
	v_lshl_add_u64 v[32:33], v[32:33], 0, v[192:193]
	s_waitcnt lgkmcnt(0)
	v_add_f32_e32 v34, v118, v34
	v_div_scale_f32 v35, s[8:9], v34, v34, 1.0
	v_rcp_f32_e32 v36, v35
	v_div_scale_f32 v37, vcc, 1.0, v34, 1.0
	s_add_i32 s16, s16, s88
	v_fma_f32 v38, -v35, v36, 1.0
	v_fmac_f32_e32 v36, v38, v36
	v_mul_f32_e32 v38, v37, v36
	v_fma_f32 v39, -v35, v38, v37
	v_fmac_f32_e32 v38, v39, v36
	v_fma_f32 v35, -v35, v38, v37
	v_div_fmas_f32 v35, v35, v36, v38
	v_div_fixup_f32 v34, v35, v34, 1.0
	v_pk_mul_f32 v[0:1], v[0:1], v[34:35] op_sel_hi:[1,0]
	v_pk_mul_f32 v[2:3], v[2:3], v[34:35] op_sel_hi:[1,0]
	v_cvt_pk_bf16_f32 v0, v0, v1
	v_cvt_pk_bf16_f32 v1, v2, v3
	v_add_co_u32_e32 v2, vcc, s33, v32
	v_lshl_add_u64 v[36:37], v[32:33], 0, s[38:39]
	s_nop 0
	v_addc_co_u32_e32 v3, vcc, 0, v33, vcc
	global_store_dwordx2 v[2:3], v[0:1], off
	v_pk_mul_f32 v[0:1], v[4:5], v[34:35] op_sel_hi:[1,0]
	v_pk_mul_f32 v[2:3], v[6:7], v[34:35] op_sel_hi:[1,0]
	v_cvt_pk_bf16_f32 v0, v0, v1
	v_cvt_pk_bf16_f32 v1, v2, v3
	global_store_dwordx2 v[36:37], v[0:1], off offset:16
	v_pk_mul_f32 v[0:1], v[8:9], v[34:35] op_sel_hi:[1,0]
	v_pk_mul_f32 v[2:3], v[10:11], v[34:35] op_sel_hi:[1,0]
	v_cvt_pk_bf16_f32 v0, v0, v1
	v_cvt_pk_bf16_f32 v1, v2, v3
	global_store_dwordx2 v[36:37], v[0:1], off offset:32
	v_pk_mul_f32 v[0:1], v[12:13], v[34:35] op_sel_hi:[1,0]
	v_pk_mul_f32 v[2:3], v[14:15], v[34:35] op_sel_hi:[1,0]
	v_cvt_pk_bf16_f32 v0, v0, v1
	v_cvt_pk_bf16_f32 v1, v2, v3
	global_store_dwordx2 v[36:37], v[0:1], off offset:48
	v_pk_mul_f32 v[0:1], v[16:17], v[34:35] op_sel_hi:[1,0]
	v_pk_mul_f32 v[2:3], v[18:19], v[34:35] op_sel_hi:[1,0]
	v_cvt_pk_bf16_f32 v0, v0, v1
	v_cvt_pk_bf16_f32 v1, v2, v3
	global_store_dwordx2 v[36:37], v[0:1], off offset:64
	v_pk_mul_f32 v[0:1], v[20:21], v[34:35] op_sel_hi:[1,0]
	v_pk_mul_f32 v[2:3], v[22:23], v[34:35] op_sel_hi:[1,0]
	v_cvt_pk_bf16_f32 v0, v0, v1
	v_cvt_pk_bf16_f32 v1, v2, v3
	global_store_dwordx2 v[36:37], v[0:1], off offset:80
	v_pk_mul_f32 v[0:1], v[24:25], v[34:35] op_sel_hi:[1,0]
	v_pk_mul_f32 v[2:3], v[26:27], v[34:35] op_sel_hi:[1,0]
	v_cvt_pk_bf16_f32 v0, v0, v1
	v_cvt_pk_bf16_f32 v1, v2, v3
	global_store_dwordx2 v[36:37], v[0:1], off offset:96
	v_pk_mul_f32 v[0:1], v[28:29], v[34:35] op_sel_hi:[1,0]
	v_pk_mul_f32 v[2:3], v[30:31], v[34:35] op_sel_hi:[1,0]
	v_cvt_pk_bf16_f32 v0, v0, v1
	v_cvt_pk_bf16_f32 v1, v2, v3
	s_cmp_lt_i32 s16, s19
	global_store_dwordx2 v[36:37], v[0:1], off offset:112
	s_cbranch_scc0 .LBB0_619
.LBB0_592:
	s_ashr_i32 s14, s16, 5
	s_ashr_i32 s15, s14, 31
	s_lshl_b32 s8, s16, 8
	s_lshl_b64 s[10:11], s[14:15], 11
	s_and_b32 s8, s8, 0x700
	s_or_b32 s10, s10, s8
	s_mul_i32 s8, s11, 0x300
	s_mul_hi_u32 s9, s10, 0x300
	s_mov_b64 s[6:7], s[86:87]
	s_bfe_u32 s20, s16, 0x20003
	s_add_i32 s9, s9, s8
	s_mul_i32 s8, s10, 0x300
	s_add_u32 s8, s6, s8
	s_addc_u32 s9, s7, s9
	s_mul_i32 s21, s20, 0xc0
	s_add_u32 s8, s8, s21
	s_addc_u32 s9, s9, 0
	s_add_u32 s8, s8, 0x224c8000
	s_addc_u32 s9, s9, 0
	s_mul_i32 s12, s14, 0x180000
	s_mul_hi_i32 s13, s14, 0x180000
	s_add_u32 s22, s6, s12
	v_mov_b32_e32 v17, v240
	s_addc_u32 s23, s7, s13
	s_add_u32 s21, s22, s21
	v_ashrrev_i32_e32 v19, 6, v17
	v_and_b32_e32 v16, 31, v17
	v_mul_hi_i32 v2, v17, s95
	v_bfe_u32 v18, v17, 5, 1
	v_lshl_or_b32 v116, v19, 5, v16
	v_mov_b64_e32 v[0:1], s[8:9]
	v_lshrrev_b32_e32 v3, 31, v2
	v_ashrrev_i32_e32 v2, 1, v2
	s_addc_u32 s23, s23, 0
	v_mad_i64_i32 v[0:1], s[8:9], v116, s57, v[0:1]
	v_lshlrev_b32_e32 v192, 4, v18
	v_add_u32_e32 v33, v2, v3
	s_add_u32 s22, s21, 0x23cc8000
	v_lshl_add_u64 v[0:1], v[0:1], 0, v[192:193]
	v_mul_lo_u32 v2, v33, 12
	s_addc_u32 s23, s23, 0
	global_load_dwordx4 v[80:83], v[0:1], off offset:32
	global_load_dwordx4 v[84:87], v[0:1], off offset:64
	global_load_dwordx4 v[88:91], v[0:1], off offset:96
	global_load_dwordx4 v[92:95], v[0:1], off offset:128
	global_load_dwordx4 v[96:99], v[0:1], off offset:160
	v_sub_u32_e32 v20, v17, v2
	v_lshlrev_b32_e32 v34, 3, v20
	v_mov_b64_e32 v[4:5], s[22:23]
	v_ashrrev_i32_e32 v35, 31, v34
	v_mad_i64_i32 v[2:3], s[8:9], v33, s57, v[4:5]
	v_lshl_add_u64 v[8:9], v[34:35], 1, v[2:3]
	global_load_dwordx4 v[100:103], v[0:1], off
	s_nop 0
	global_load_dwordx4 v[0:3], v[8:9], off
	v_add_u32_e32 v6, 0x200, v17
	v_mul_hi_i32 v7, v6, s95
	v_lshrrev_b32_e32 v10, 31, v7
	v_ashrrev_i32_e32 v7, 1, v7
	v_add_u32_e32 v58, v7, v10
	v_mul_lo_u32 v7, v58, 12
	v_sub_u32_e32 v21, v6, v7
	v_lshlrev_b32_e32 v36, 3, v21
	s_movk_i32 s8, 0x100
	v_ashrrev_i32_e32 v37, 31, v36
	v_cmp_gt_i32_e64 s[36:37], s8, v17
	v_mad_i64_i32 v[4:5], s[8:9], v58, s57, v[4:5]
	v_lshl_add_u64 v[10:11], v[36:37], 1, v[4:5]
	s_waitcnt vmcnt(0)
	v_mov_b32_e32 v104, v193
	v_mov_b32_e32 v105, v193
	v_mov_b32_e32 v106, v193
	v_mov_b32_e32 v107, v193
	s_and_saveexec_b64 s[8:9], s[36:37]
	s_cbranch_execz .LBB0_594
	global_load_dwordx4 v[104:107], v[10:11], off
; #define LAS __attribute__((address_space(3)))
; #define MFMA32(a, b, c) __builtin_amdgcn_mfma_f32_32x32x16_bf16((a), (b), (c), 0, 0, 0)
; template <int DQK, int NSUB, int MODE>
; __device__ __forceinline__ void flash_unit(LAS char* L, const bf16_t* Qp, int qpitch, const bf16_t* Kp, int kpitch, const bf16_t* Vp, int vpitch,
;                                            bf16_t* Op, int opitch, float lam, float oscale, const float* subln) {
;     ...
;     rk1 = *(const u32x4*)kg1; if (has2) rk2 = *(const u32x4*)kg2; rv1 = *(const u32x4*)vg1;
;     __syncthreads();
;     *(u32x4*)(Lg + kl1) = rk1; if (has2) *(u32x4*)(Lg + kl2) = rk2; *(u32x4*)(Lg + OFF_V + vl1) = rv1;
;     __syncthreads();
;     const int vq = (lane & 15) >> 2, vp_ = lane & 3, vblk = (lane >> 4) & 1;
;     const int voff = (4 * hi + vq) * VPB + (16 * vblk + 4 * vp_) * 2;
;     if (__builtin_amdgcn_readfirstlane(wid) >= 4) __builtin_amdgcn_s_setprio(1);
;     for (int t = 0; t < SEQ / 64; ++t) {
;         const int buf = t & 1;
;         if (t + 1 < SEQ / 64) { const size_t ko = (size_t)(t + 1) * 64 * kpitch, vo = (size_t)(t + 1) * 64 * vpitch;
;             rk1 = *(const u32x4*)(kg1 + ko); if (has2) rk2 = *(const u32x4*)(kg2 + ko); rv1 = *(const u32x4*)(vg1 + vo); }
;         const char* Kb = Lg + buf * KBUF; LAS const char* Vb = L + OFF_V + buf * VBUF + voff;
; #pragma unroll
;         for (int s = 0; s < NSUB; ++s) {
;             f32x16 p0, p1;
; #pragma unroll
;             for (int d0 = 0; d0 < ND0; ++d0) { const bf16x8 k0 = *(const bf16x8*)(Kb + r32 * KPB + (s * DQK + 16 * d0 + 8 * hi) * 2); const bf16x8 k1 = *(const bf16x8*)(Kb + (32 + r32) * KPB + (s * DQK + 16 * d0 + 8 * hi) * 2);
;                 if (d0 == 0) { p0 = MFMA32(k0, qf[s][d0], negm[s]); p1 = MFMA32(k1, qf[s][d0], negm[s]); }
;                 else { p0 = MFMA32(k0, qf[s][d0], p0); p1 = MFMA32(k1, qf[s][d0], p1); } }
; #pragma unroll
;             for (int hf = 0; hf < 2; ++hf) {
;                 f32x16& ph = hf ? p1 : p0;
;                 float mx = fmaxf(ph[0], ph[1]);
; #pragma unroll
;                 for (int r = 2; r < 16; ++r) mx = fmaxf(mx, ph[r]);
.LBB0_594:
	s_or_b64 exec, exec, s[8:9]
	s_lshl_b64 s[14:15], s[14:15], 20
	s_add_u32 s8, s6, s14
	s_addc_u32 s9, s7, s15
	s_lshl_b32 s21, s20, 7
	v_ashrrev_i32_e32 v14, 3, v17
	s_add_u32 s8, s8, s21
	v_ashrrev_i32_e32 v15, 31, v14
	s_addc_u32 s9, s9, 0
	v_and_b32_e32 v6, 7, v17
	v_lshlrev_b64 v[40:41], 9, v[14:15]
	v_lshl_add_u64 v[4:5], s[8:9], 0, v[40:41]
	v_lshlrev_b32_e32 v38, 4, v6
	v_mov_b32_e32 v39, v193
	v_lshl_add_u64 v[12:13], v[4:5], 0, v[38:39]
	v_add_co_u32_e32 v4, vcc, 0x254c8000, v12
	v_mul_lo_u32 v15, v58, s18
	s_nop 0
	v_addc_co_u32_e32 v5, vcc, 0, v13, vcc
	global_load_dwordx4 v[4:7], v[4:5], off
	v_lshl_add_u32 v126, v21, 4, v15
	v_mul_lo_u32 v15, v33, s18
	v_lshl_add_u32 v127, v20, 4, v15
	v_add_u32_e32 v59, 0, v127
	v_add_u32_e32 v39, 0, v126
	s_waitcnt lgkmcnt(0)
	s_barrier
	s_waitcnt vmcnt(0)
	ds_write_b128 v59, v[0:3]
	s_and_saveexec_b64 s[8:9], s[36:37]
	ds_write_b128 v39, v[104:107]
	s_or_b64 exec, exec, s[8:9]
	v_mul_lo_u32 v0, v14, s27
	v_readfirstlane_b32 s8, v19
	v_add3_u32 v128, 0, v0, v38
	s_cmp_lt_i32 s8, 4
	ds_write_b128 v128, v[4:7] offset:26624
	s_waitcnt lgkmcnt(0)
	s_barrier
	s_cbranch_scc1 .LBB0_598
	s_setprio 1
.LBB0_598:
	v_add_co_u32_e32 v0, vcc, 0xc000, v8
	s_nop 1
	v_addc_co_u32_e32 v1, vcc, 0, v9, vcc
	global_load_dwordx4 v[108:111], v[0:1], off
	s_and_saveexec_b64 s[8:9], s[36:37]
	s_cbranch_execz .LBB0_600
	v_add_co_u32_e32 v0, vcc, 0xc000, v10
	s_nop 1
	v_addc_co_u32_e32 v1, vcc, 0, v11, vcc
	global_load_dwordx4 v[104:107], v[0:1], off
.LBB0_600:
	s_or_b64 exec, exec, s[8:9]
	v_lshrrev_b32_e32 v2, 2, v17
	v_and_b32_e32 v3, 16, v17
	v_lshlrev_b32_e32 v129, 2, v18
	v_lshlrev_b32_e32 v4, 2, v17
	s_mov_b64 s[8:9], 0x254c8000
	v_and_or_b32 v2, v2, 3, v129
	v_and_or_b32 v3, v4, 12, v3
	v_lshl_add_u64 v[0:1], v[12:13], 0, s[8:9]
	v_mul_u32_u24_e32 v2, 0x90, v2
	v_lshlrev_b32_e32 v3, 1, v3
	v_add3_u32 v130, 0, v2, v3
	v_mul_u32_u24_e32 v2, 0xd0, v16
	v_add_co_u32_e32 v0, vcc, 0x8000, v0
	v_add3_u32 v131, 0, v2, v192
	s_nop 0
	v_addc_co_u32_e32 v1, vcc, 0, v1, vcc
	global_load_dwordx4 v[112:115], v[0:1], off
	ds_read_b128 v[0:3], v131 offset:6656
	ds_read_b128 v[4:7], v131
	ds_read_b128 v[42:45], v131 offset:32
	s_waitcnt lgkmcnt(0)
	v_mfma_f32_32x32x16_bf16 v[16:31], v[4:7], v[100:103], 0
	ds_read_b128 v[46:49], v131 offset:6688
	v_mfma_f32_32x32x16_bf16 v[0:15], v[0:3], v[100:103], 0
	v_mfma_f32_32x32x16_bf16 v[16:31], v[42:45], v[80:83], v[16:31]
	s_waitcnt lgkmcnt(0)
	v_mfma_f32_32x32x16_bf16 v[0:15], v[46:49], v[80:83], v[0:15]
	ds_read_b128 v[42:45], v131 offset:6720
	ds_read_b128 v[46:49], v131 offset:64
	s_waitcnt lgkmcnt(0)
	v_mfma_f32_32x32x16_bf16 v[16:31], v[46:49], v[84:87], v[16:31]
	v_mfma_f32_32x32x16_bf16 v[0:15], v[42:45], v[84:87], v[0:15]
	ds_read_b128 v[42:45], v131 offset:6752
	ds_read_b128 v[46:49], v131 offset:96
	s_waitcnt lgkmcnt(0)
	v_mfma_f32_32x32x16_bf16 v[16:31], v[46:49], v[88:91], v[16:31]
	v_mfma_f32_32x32x16_bf16 v[0:15], v[42:45], v[88:91], v[0:15]
	ds_read_b128 v[42:45], v131 offset:6784
	ds_read_b128 v[46:49], v131 offset:128
	s_waitcnt lgkmcnt(0)
	v_mfma_f32_32x32x16_bf16 v[16:31], v[46:49], v[92:95], v[16:31]
	v_mfma_f32_32x32x16_bf16 v[0:15], v[42:45], v[92:95], v[0:15]
	ds_read_b128 v[42:45], v131 offset:6816
	ds_read_b128 v[46:49], v131 offset:160
	s_waitcnt lgkmcnt(0)
	v_mfma_f32_32x32x16_bf16 v[16:31], v[46:49], v[96:99], v[16:31]
	v_mfma_f32_32x32x16_bf16 v[0:15], v[42:45], v[96:99], v[0:15]
	s_nop 10
	v_max_f32_e32 v32, v17, v17
	v_max_f32_e32 v42, v16, v16
	v_max_f32_e32 v32, v42, v32
	v_max3_f32 v32, v32, v18, v19
	v_max3_f32 v32, v32, v20, v21
	v_max3_f32 v32, v32, v22, v23
	v_max3_f32 v32, v32, v24, v25
	v_max3_f32 v32, v32, v26, v27
	v_max3_f32 v32, v32, v28, v29
	v_max3_f32 v32, v32, v30, v31
	ds_bpermute_b32 v42, v184, v32
	s_waitcnt lgkmcnt(0)
; template <int DQK, int NSUB, int MODE>
; __device__ __forceinline__ void flash_unit(LAS char* L, const bf16_t* Qp, int qpitch, const bf16_t* Kp, int kpitch, const bf16_t* Vp, int vpitch,
;                                            bf16_t* Op, int opitch, float lam, float oscale, const float* subln) {
;     ...
;             for (int hf = 0; hf < 2; ++hf) {
;                 f32x16& ph = hf ? p1 : p0;
;                 float mx = fmaxf(ph[0], ph[1]);
; #pragma unroll
;                 for (int r = 2; r < 16; ++r) mx = fmaxf(mx, ph[r]);
;                 mx = fmaxf(mx, __shfl_xor(mx, 32));
;                 const bool first = (t == 0) && (hf == 0);
;                 if (first || __any(mx > 8.0f)) {
;                     const float dl = first ? mx : fmaxf(mx, 0.f); mref[s] += dl;
; #pragma unroll
;                     for (int r = 0; r < 16; ++r) { ph[r] -= dl; negm[s][r] = -mref[s]; }
;                     if (hf == 0) {
; #pragma unroll
;                         for (int r = 0; r < 16; ++r) p1[r] -= dl;
;                     }
;                     if (!first) { const float alpha = __builtin_amdgcn_exp2f(-dl); lrow[s] *= alpha;
; #pragma unroll
;                         for (int r = 0; r < 16; ++r) { o[s][0][r] *= alpha; o[s][1][r] *= alpha; } }
;                 }
; #pragma unroll
;                 for (int r = 0; r < 16; ++r) ph[r] = __builtin_amdgcn_exp2f(ph[r]);
;                 { typedef float f32x2_ __attribute__((ext_vector_type(2))); f32x2_ r2 = {ph[0], ph[1]};
; #pragma unroll
;                   for (int r = 2; r < 16; r += 2) r2 += (f32x2_){ph[r], ph[r + 1]};
;                   lrow[s] += r2[0] + r2[1]; }
;                 bf16x8 pf[2];
; #pragma unroll
;                 for (int k2 = 0; k2 < 2; ++k2) { u32x4 w;
; #pragma unroll
;                     for (int e = 0; e < 4; ++e) w[e] = cvt_pk_bf16(ph[8 * k2 + 2 * e], ph[8 * k2 + 2 * e + 1]);
;                     pf[k2] = __builtin_bit_cast(bf16x8, w); }
; #pragma unroll
;                 for (int db = 0; db < 2; ++db)
; #pragma unroll
;                     for (int k2 = 0; k2 < 2; ++k2) { const int ks = 2 * hf + k2; const v4i16_t lo = vtr(Vb + (16 * ks) * VPB + db * 64), hh = vtr(Vb + (16 * ks + 8) * VPB + db * 64);
;                         const bf16x8 vf = {lo[0], lo[1], lo[2], lo[3], hh[0], hh[1], hh[2], hh[3]};
;                         o[s][db] = MFMA32(vf, pf[k2], o[s][db]); }
	v_max_f32_e32 v42, v42, v42
	v_max_f32_e32 v32, v32, v42
	v_sub_f32_e32 v16, v16, v32
	v_sub_f32_e32 v17, v17, v32
	v_sub_f32_e32 v18, v18, v32
	v_sub_f32_e32 v19, v19, v32
	v_sub_f32_e32 v20, v20, v32
	v_sub_f32_e32 v21, v21, v32
	v_pk_add_f32 v[44:45], v[0:1], v[32:33] op_sel_hi:[1,0] neg_lo:[0,1] neg_hi:[0,1]
	v_pk_add_f32 v[42:43], v[2:3], v[32:33] op_sel_hi:[1,0] neg_lo:[0,1] neg_hi:[0,1]
	v_exp_f32_e32 v0, v16
	v_exp_f32_e32 v1, v17
	v_exp_f32_e32 v2, v18
	v_exp_f32_e32 v3, v19
	v_sub_f32_e32 v22, v22, v32
	v_sub_f32_e32 v23, v23, v32
	v_pk_add_f32 v[46:47], v[4:5], v[32:33] op_sel_hi:[1,0] neg_lo:[0,1] neg_hi:[0,1]
	v_exp_f32_e32 v4, v20
	v_exp_f32_e32 v5, v21
	v_sub_f32_e32 v24, v24, v32
	v_sub_f32_e32 v25, v25, v32
	v_pk_add_f32 v[48:49], v[6:7], v[32:33] op_sel_hi:[1,0] neg_lo:[0,1] neg_hi:[0,1]
	v_exp_f32_e32 v6, v22
	v_exp_f32_e32 v7, v23
	v_sub_f32_e32 v26, v26, v32
	v_sub_f32_e32 v27, v27, v32
	v_pk_add_f32 v[50:51], v[8:9], v[32:33] op_sel_hi:[1,0] neg_lo:[0,1] neg_hi:[0,1]
	v_exp_f32_e32 v8, v24
	v_exp_f32_e32 v9, v25
	v_sub_f32_e32 v28, v28, v32
	v_sub_f32_e32 v29, v29, v32
	v_pk_add_f32 v[52:53], v[10:11], v[32:33] op_sel_hi:[1,0] neg_lo:[0,1] neg_hi:[0,1]
	v_exp_f32_e32 v10, v26
	v_exp_f32_e32 v11, v27
	v_pk_add_f32 v[16:17], v[0:1], v[2:3]
	v_sub_f32_e32 v30, v30, v32
	v_sub_f32_e32 v31, v31, v32
	v_pk_add_f32 v[54:55], v[12:13], v[32:33] op_sel_hi:[1,0] neg_lo:[0,1] neg_hi:[0,1]
	v_exp_f32_e32 v12, v28
	v_exp_f32_e32 v13, v29
	v_pk_add_f32 v[16:17], v[4:5], v[16:17]
	v_pk_add_f32 v[56:57], v[14:15], v[32:33] op_sel_hi:[1,0] neg_lo:[0,1] neg_hi:[0,1]
	v_exp_f32_e32 v14, v30
	v_exp_f32_e32 v15, v31
	v_pk_add_f32 v[16:17], v[6:7], v[16:17]
	v_cvt_pk_bf16_f32 v18, v4, v5
	v_pk_add_f32 v[16:17], v[8:9], v[16:17]
	v_cvt_pk_bf16_f32 v19, v6, v7
	v_pk_add_f32 v[16:17], v[10:11], v[16:17]
	v_cvt_pk_bf16_f32 v60, v8, v9
	v_pk_add_f32 v[16:17], v[12:13], v[16:17]
	v_cvt_pk_bf16_f32 v61, v10, v11
	v_pk_add_f32 v[68:69], v[14:15], v[16:17]
	v_cvt_pk_bf16_f32 v16, v0, v1
	v_cvt_pk_bf16_f32 v17, v2, v3
	ds_read_b64_tr_b16 v[0:1], v130 offset:26624
	ds_read_b64_tr_b16 v[2:3], v130 offset:27776
	v_cvt_pk_bf16_f32 v62, v12, v13
	v_cvt_pk_bf16_f32 v63, v14, v15
	s_waitcnt lgkmcnt(0)
	v_mfma_f32_32x32x16_bf16 v[0:15], v[0:3], v[16:19], 0
	ds_read_b64_tr_b16 v[20:21], v130 offset:28928
	ds_read_b64_tr_b16 v[22:23], v130 offset:30080
	s_waitcnt lgkmcnt(0)
	v_mfma_f32_32x32x16_bf16 v[0:15], v[20:23], v[60:63], v[0:15]
	ds_read_b64_tr_b16 v[20:21], v130 offset:26688
	ds_read_b64_tr_b16 v[22:23], v130 offset:27840
	ds_read_b64_tr_b16 v[64:65], v130 offset:28992
	ds_read_b64_tr_b16 v[66:67], v130 offset:30144
	s_waitcnt lgkmcnt(0)
	v_mfma_f32_32x32x16_bf16 v[16:31], v[20:23], v[16:19], 0
	v_mfma_f32_32x32x16_bf16 v[16:31], v[64:67], v[60:63], v[16:31]
	v_add_f32_e64 v60, v68, v69
	v_add_f32_e64 v61, v69, v68
	v_mov_b32_e32 v61, v32
	v_max_f32_e32 v32, v44, v45
	v_max3_f32 v32, v32, v42, v43
	v_max3_f32 v32, v32, v46, v47
	v_max3_f32 v32, v32, v48, v49
	v_max3_f32 v32, v32, v50, v51
	v_max3_f32 v32, v32, v52, v53
	v_max3_f32 v32, v32, v54, v55
	v_max3_f32 v32, v32, v56, v57
	v_pk_add_f32 v[118:119], v[60:61], 0 op_sel_hi:[1,0]
	ds_bpermute_b32 v60, v184, v32
	s_waitcnt lgkmcnt(0)
	v_max_f32_e32 v60, v60, v60
	v_max_f32_e32 v32, v32, v60
	v_cmp_lt_f32_e32 vcc, s61, v32
	s_cbranch_vccz .LBB0_602
	v_max_f32_e32 v32, v32, v32
	v_max_f32_e32 v32, 0, v32
	v_exp_f32_e64 v60, -v32
	v_add_f32_e32 v119, v119, v32
	v_sub_f32_e32 v44, v44, v32
	v_sub_f32_e32 v45, v45, v32
	v_sub_f32_e32 v42, v42, v32
	v_sub_f32_e32 v43, v43, v32
	v_sub_f32_e32 v46, v46, v32
	v_sub_f32_e32 v47, v47, v32
	v_sub_f32_e32 v48, v48, v32
	v_sub_f32_e32 v49, v49, v32
	v_sub_f32_e32 v50, v50, v32
	v_sub_f32_e32 v51, v51, v32
	v_sub_f32_e32 v52, v52, v32
	v_sub_f32_e32 v53, v53, v32
	v_sub_f32_e32 v54, v54, v32
	v_sub_f32_e32 v55, v55, v32
	v_sub_f32_e32 v56, v56, v32
	v_sub_f32_e32 v57, v57, v32
	v_pk_mul_f32 v[14:15], v[14:15], v[60:61] op_sel_hi:[1,0]
	v_pk_mul_f32 v[12:13], v[12:13], v[60:61] op_sel_hi:[1,0]
	v_pk_mul_f32 v[10:11], v[10:11], v[60:61] op_sel_hi:[1,0]
	v_pk_mul_f32 v[8:9], v[8:9], v[60:61] op_sel_hi:[1,0]
	v_pk_mul_f32 v[6:7], v[6:7], v[60:61] op_sel_hi:[1,0]
	v_pk_mul_f32 v[4:5], v[4:5], v[60:61] op_sel_hi:[1,0]
	v_pk_mul_f32 v[2:3], v[2:3], v[60:61] op_sel_hi:[1,0]
	v_pk_mul_f32 v[0:1], v[0:1], v[60:61] op_sel_hi:[1,0]
	v_pk_mul_f32 v[30:31], v[30:31], v[60:61] op_sel_hi:[1,0]
	v_pk_mul_f32 v[28:29], v[28:29], v[60:61] op_sel_hi:[1,0]
	v_pk_mul_f32 v[26:27], v[26:27], v[60:61] op_sel_hi:[1,0]
	v_pk_mul_f32 v[24:25], v[24:25], v[60:61] op_sel_hi:[1,0]
	v_pk_mul_f32 v[22:23], v[22:23], v[60:61] op_sel_hi:[1,0]
	v_pk_mul_f32 v[20:21], v[20:21], v[60:61] op_sel_hi:[1,0]
	v_pk_mul_f32 v[18:19], v[18:19], v[60:61] op_sel_hi:[1,0]
	v_pk_mul_f32 v[16:17], v[16:17], v[60:61] op_sel_hi:[1,0]
	v_xor_b32_e32 v32, 0x80000000, v119
	v_mul_f32_e32 v118, v118, v60
	s_branch .LBB0_603

; template <int DQK, int NSUB, int MODE>
; __device__ __forceinline__ void flash_unit(LAS char* L, const bf16_t* Qp, int qpitch, const bf16_t* Kp, int kpitch, const bf16_t* Vp, int vpitch,
;                                            bf16_t* Op, int opitch, float lam, float oscale, const float* subln) {
;     ...
;         if (t + 1 < SEQ / 64) { const size_t ko = (size_t)(t + 1) * 64 * kpitch, vo = (size_t)(t + 1) * 64 * vpitch;
;             rk1 = *(const u32x4*)(kg1 + ko); if (has2) rk2 = *(const u32x4*)(kg2 + ko); rv1 = *(const u32x4*)(vg1 + vo); }
.LBB0_608:
	s_cmp_lg_u32 s12, 0x168000
	s_cselect_b64 s[14:15], -1, 0
	s_cmp_eq_u32 s12, 0x168000
	s_cbranch_scc1 .LBB0_612
	v_lshl_add_u64 v[48:49], v[124:125], 0, s[12:13]
	s_waitcnt vmcnt(0)
	global_load_dwordx4 v[108:111], v[48:49], off
	s_and_saveexec_b64 s[8:9], s[36:37]
	s_cbranch_execz .LBB0_611
	v_lshl_add_u64 v[48:49], v[122:123], 0, s[12:13]
	global_load_dwordx4 v[104:107], v[48:49], off
.LBB0_611:
	s_or_b64 exec, exec, s[8:9]
	global_load_dwordx4 v[112:115], v[120:121], off

; __device__ __forceinline__ v4i16_t vtr(LAS const char* p) { return __builtin_amdgcn_ds_read_tr16_b64_v4i16((LAS v4i16_t*)p); }
; template <int DQK, int NSUB, int MODE>
; __device__ __forceinline__ void flash_unit(LAS char* L, const bf16_t* Qp, int qpitch, const bf16_t* Kp, int kpitch, const bf16_t* Vp, int vpitch,
;                                            bf16_t* Op, int opitch, float lam, float oscale, const float* subln) {
;     ...
; #pragma unroll
;                 for (int r = 0; r < 16; ++r) ph[r] = __builtin_amdgcn_exp2f(ph[r]);
;                 { typedef float f32x2_ __attribute__((ext_vector_type(2))); f32x2_ r2 = {ph[0], ph[1]};
; #pragma unroll
;                   for (int r = 2; r < 16; r += 2) r2 += (f32x2_){ph[r], ph[r + 1]};
;                   lrow[s] += r2[0] + r2[1]; }
;                 bf16x8 pf[2];
; #pragma unroll
;                 for (int k2 = 0; k2 < 2; ++k2) { u32x4 w;
; #pragma unroll
;                     for (int e = 0; e < 4; ++e) w[e] = cvt_pk_bf16(ph[8 * k2 + 2 * e], ph[8 * k2 + 2 * e + 1]);
;                     pf[k2] = __builtin_bit_cast(bf16x8, w); }
; #pragma unroll
;                 for (int db = 0; db < 2; ++db)
; #pragma unroll
;                     for (int k2 = 0; k2 < 2; ++k2) { const int ks = 2 * hf + k2; const v4i16_t lo = vtr(Vb + (16 * ks) * VPB + db * 64), hh = vtr(Vb + (16 * ks + 8) * VPB + db * 64);
;                         const bf16x8 vf = {lo[0], lo[1], lo[2], lo[3], hh[0], hh[1], hh[2], hh[3]};
;                         o[s][db] = MFMA32(vf, pf[k2], o[s][db]); }
;             }
;         }
;         if (t + 1 < SEQ / 64) { char* Kn = Lg + (buf ^ 1) * KBUF; *(u32x4*)(Kn + kl1) = rk1; if (has2) *(u32x4*)(Kn + kl2) = rk2; *(u32x4*)(Lg + OFF_V + (buf ^ 1) * VBUF + vl1) = rv1; }
;         __syncthreads();
;     }
;     __builtin_amdgcn_s_setprio(0);
;     bf16_t* orow = Op + (size_t)(32 * wid + r32) * opitch;
;     if (MODE == 0) {
;         const float inv = 1.0f / (lrow[0] + __shfl_xor(lrow[0], 32));
; #pragma unroll
;         for (int db = 0; db < 2; ++db)
; #pragma unroll
;             for (int g = 0; g < 4; ++g) { u32x2 w; w.x = cvt_pk_bf16(o[0][db][4 * g] * inv, o[0][db][4 * g + 1] * inv); w.y = cvt_pk_bf16(o[0][db][4 * g + 2] * inv, o[0][db][4 * g + 3] * inv);
;                 *(u32x2*)(orow + 32 * db + 8 * g + 4 * hi) = w; }
.LBB0_620:
	v_exp_f32_e32 v50, v32
	v_exp_f32_e32 v51, v33
	v_exp_f32_e32 v52, v34
	v_exp_f32_e32 v53, v35
	v_exp_f32_e32 v54, v36
	v_exp_f32_e32 v55, v37
	v_exp_f32_e32 v56, v38
	v_exp_f32_e32 v57, v39
	v_exp_f32_e32 v58, v40
	v_exp_f32_e32 v59, v41
	v_exp_f32_e32 v60, v42
	v_exp_f32_e32 v61, v43
	ds_read_b64_tr_b16 v[40:41], v135 offset:32256
	ds_read_b64_tr_b16 v[42:43], v135 offset:33408
	v_cvt_pk_bf16_f32 v32, v50, v51
	v_cvt_pk_bf16_f32 v33, v52, v53
	v_cvt_pk_bf16_f32 v34, v54, v55
	v_cvt_pk_bf16_f32 v35, v56, v57
	v_exp_f32_e32 v44, v44
	v_exp_f32_e32 v45, v45
	s_waitcnt lgkmcnt(0)
	v_mfma_f32_32x32x16_bf16 v[0:15], v[40:43], v[32:35], v[0:15]
	v_exp_f32_e32 v46, v46
	v_exp_f32_e32 v47, v47
	ds_read_b64_tr_b16 v[40:41], v135 offset:34560
	ds_read_b64_tr_b16 v[42:43], v135 offset:35712
	v_cvt_pk_bf16_f32 v36, v58, v59
	v_cvt_pk_bf16_f32 v37, v60, v61
	v_cvt_pk_bf16_f32 v38, v44, v45
	v_cvt_pk_bf16_f32 v39, v46, v47
	s_mul_i32 s8, s0, 0x600
	s_add_u32 s8, s4, s8
	s_waitcnt lgkmcnt(0)
	v_mfma_f32_32x32x16_bf16 v[0:15], v[40:43], v[36:39], v[0:15]
	ds_read_b64_tr_b16 v[40:41], v135 offset:32320
	ds_read_b64_tr_b16 v[42:43], v135 offset:33472
	s_mul_hi_i32 s4, s0, 0x600
	s_addc_u32 s9, s5, s4
	s_lshl_b64 s[4:5], s[6:7], 9
	s_add_u32 s4, s8, s4
	s_addc_u32 s5, s9, s5
	s_lshl_b32 s6, s13, 1
	s_waitcnt lgkmcnt(0)
	v_mfma_f32_32x32x16_bf16 v[16:31], v[40:43], v[32:35], v[16:31]
	ds_read_b64_tr_b16 v[32:33], v135 offset:34624
	ds_read_b64_tr_b16 v[34:35], v135 offset:35776
	s_add_u32 s4, s4, s6
	s_addc_u32 s5, s5, 0
	s_waitcnt lgkmcnt(0)
	s_barrier
	v_mfma_f32_32x32x16_bf16 v[16:31], v[32:35], v[36:39], v[16:31]
	v_add_f32_e64 v32, v50, v52
	v_add_f32_e64 v33, v51, v53
	v_add_f32_e64 v32, v54, v32
	v_add_f32_e64 v33, v55, v33
	v_add_f32_e64 v32, v56, v32
	v_add_f32_e64 v33, v57, v33
	v_pk_add_f32 v[32:33], v[58:59], v[32:33]
	s_nop 0
	v_pk_add_f32 v[32:33], v[60:61], v[32:33]
	s_nop 0
	v_pk_add_f32 v[32:33], v[44:45], v[32:33]
	s_nop 0
	v_pk_add_f32 v[32:33], v[46:47], v[32:33]
	s_nop 0
	v_add_f32_e32 v32, v32, v33
	v_add_f32_e32 v34, v48, v32
	s_setprio 0
	ds_bpermute_b32 v35, v184, v34
	v_lshlrev_b64 v[32:33], 9, v[124:125]
	v_lshlrev_b32_e32 v192, 1, v134
	v_lshl_add_u64 v[32:33], s[4:5], 0, v[32:33]
	v_lshl_add_u64 v[32:33], v[32:33], 0, v[192:193]
	s_waitcnt lgkmcnt(0)
	v_add_f32_e32 v34, v34, v35
	v_div_scale_f32 v35, s[6:7], v34, v34, 1.0
	v_rcp_f32_e32 v36, v35
	v_div_scale_f32 v37, vcc, 1.0, v34, 1.0
	s_add_i32 s12, s12, s88
	v_fma_f32 v38, -v35, v36, 1.0
	v_fmac_f32_e32 v36, v38, v36
	v_mul_f32_e32 v38, v37, v36
	v_fma_f32 v39, -v35, v38, v37
	v_fmac_f32_e32 v38, v39, v36
	v_fma_f32 v35, -v35, v38, v37
	v_div_fmas_f32 v35, v35, v36, v38
	v_div_fixup_f32 v34, v35, v34, 1.0
	v_pk_mul_f32 v[0:1], v[0:1], v[34:35] op_sel_hi:[1,0]
	v_pk_mul_f32 v[2:3], v[2:3], v[34:35] op_sel_hi:[1,0]
	v_cvt_pk_bf16_f32 v0, v0, v1
	v_cvt_pk_bf16_f32 v1, v2, v3
	v_add_co_u32_e32 v2, vcc, s33, v32
	v_lshl_add_u64 v[36:37], v[32:33], 0, s[38:39]
	s_nop 0
	v_addc_co_u32_e32 v3, vcc, 0, v33, vcc
	global_store_dwordx2 v[2:3], v[0:1], off
	v_pk_mul_f32 v[0:1], v[4:5], v[34:35] op_sel_hi:[1,0]
	v_pk_mul_f32 v[2:3], v[6:7], v[34:35] op_sel_hi:[1,0]
	v_cvt_pk_bf16_f32 v0, v0, v1
	v_cvt_pk_bf16_f32 v1, v2, v3
	global_store_dwordx2 v[36:37], v[0:1], off offset:16
	v_pk_mul_f32 v[0:1], v[8:9], v[34:35] op_sel_hi:[1,0]
	v_pk_mul_f32 v[2:3], v[10:11], v[34:35] op_sel_hi:[1,0]
	v_cvt_pk_bf16_f32 v0, v0, v1
	v_cvt_pk_bf16_f32 v1, v2, v3
	global_store_dwordx2 v[36:37], v[0:1], off offset:32
	v_pk_mul_f32 v[0:1], v[12:13], v[34:35] op_sel_hi:[1,0]
	v_pk_mul_f32 v[2:3], v[14:15], v[34:35] op_sel_hi:[1,0]
	v_cvt_pk_bf16_f32 v0, v0, v1
	v_cvt_pk_bf16_f32 v1, v2, v3
	global_store_dwordx2 v[36:37], v[0:1], off offset:48
	v_pk_mul_f32 v[0:1], v[16:17], v[34:35] op_sel_hi:[1,0]
	v_pk_mul_f32 v[2:3], v[18:19], v[34:35] op_sel_hi:[1,0]
	v_cvt_pk_bf16_f32 v0, v0, v1
	v_cvt_pk_bf16_f32 v1, v2, v3
	global_store_dwordx2 v[36:37], v[0:1], off offset:64
	v_pk_mul_f32 v[0:1], v[20:21], v[34:35] op_sel_hi:[1,0]
	v_pk_mul_f32 v[2:3], v[22:23], v[34:35] op_sel_hi:[1,0]
	v_cvt_pk_bf16_f32 v0, v0, v1
	v_cvt_pk_bf16_f32 v1, v2, v3
	global_store_dwordx2 v[36:37], v[0:1], off offset:80
	v_pk_mul_f32 v[0:1], v[24:25], v[34:35] op_sel_hi:[1,0]
	v_pk_mul_f32 v[2:3], v[26:27], v[34:35] op_sel_hi:[1,0]
	v_cvt_pk_bf16_f32 v0, v0, v1
	v_cvt_pk_bf16_f32 v1, v2, v3
	global_store_dwordx2 v[36:37], v[0:1], off offset:96
	v_pk_mul_f32 v[0:1], v[28:29], v[34:35] op_sel_hi:[1,0]
	v_pk_mul_f32 v[2:3], v[30:31], v[34:35] op_sel_hi:[1,0]
	v_cvt_pk_bf16_f32 v0, v0, v1
	v_cvt_pk_bf16_f32 v1, v2, v3
	s_cmp_lt_i32 s12, s19
	global_store_dwordx2 v[36:37], v[0:1], off offset:112
	s_cbranch_scc0 .LBB0_649
; template <int DQK, int NSUB, int MODE>
; __device__ __forceinline__ void flash_unit(LAS char* L, const bf16_t* Qp, int qpitch, const bf16_t* Kp, int kpitch, const bf16_t* Vp, int vpitch,
;                                            bf16_t* Op, int opitch, float lam, float oscale, const float* subln) {
;     ...
;     bf16x8 qf[NSUB][ND0];
;     { const bf16_t* qrow = Qp + (size_t)(32 * wid + r32) * qpitch;
; #pragma unroll
;       for (int s = 0; s < NSUB; ++s)
; #pragma unroll
;           for (int d0 = 0; d0 < ND0; ++d0) qf[s][d0] = *(const bf16x8*)(qrow + s * DQK + 16 * d0 + 8 * hi); }
;     const int kr1 = tid / KCH, kc1 = tid % KCH, kr2 = (tid + 512) / KCH, kc2 = (tid + 512) % KCH; const bool has2 = (tid + 512) < NKCH;
;     const int vr1 = tid >> 3, vc1 = tid & 7;
;     const bf16_t* kg1 = Kp + (size_t)kr1 * kpitch + kc1 * 8; const bf16_t* kg2 = Kp + (size_t)kr2 * kpitch + kc2 * 8; const bf16_t* vg1 = Vp + (size_t)vr1 * vpitch + vc1 * 8;
;     const int kl1 = kr1 * KPB + kc1 * 16, kl2 = kr2 * KPB + kc2 * 16, vl1 = vr1 * VPB + vc1 * 16;
;     u32x4 rk1, rk2 = {0u, 0u, 0u, 0u}, rv1;
;     float mref[NSUB], lrow[NSUB]; f32x16 o[NSUB][2], negm[NSUB];
; #pragma unroll
;     for (int s = 0; s < NSUB; ++s) { mref[s] = 0.f; lrow[s] = 0.f;
; #pragma unroll
;         for (int r = 0; r < 16; ++r) { o[s][0][r] = 0.f; o[s][1][r] = 0.f; negm[s][r] = 0.f; } }
;     rk1 = *(const u32x4*)kg1; if (has2) rk2 = *(const u32x4*)kg2; rv1 = *(const u32x4*)vg1;
;     __syncthreads();
;     *(u32x4*)(Lg + kl1) = rk1; if (has2) *(u32x4*)(Lg + kl2) = rk2; *(u32x4*)(Lg + OFF_V + vl1) = rv1;
;     __syncthreads();
;     const int vq = (lane & 15) >> 2, vp_ = lane & 3, vblk = (lane >> 4) & 1;
;     const int voff = (4 * hi + vq) * VPB + (16 * vblk + 4 * vp_) * 2;
;     if (__builtin_amdgcn_readfirstlane(wid) >= 4) __builtin_amdgcn_s_setprio(1);
;     for (int t = 0; t < SEQ / 64; ++t) {
;         const int buf = t & 1;
;         if (t + 1 < SEQ / 64) { const size_t ko = (size_t)(t + 1) * 64 * kpitch, vo = (size_t)(t + 1) * 64 * vpitch;
;             rk1 = *(const u32x4*)(kg1 + ko); if (has2) rk2 = *(const u32x4*)(kg2 + ko); rv1 = *(const u32x4*)(vg1 + vo); }
.LBB0_621:
	s_mov_b64 s[4:5], s[86:87]
	s_add_u32 s10, s4, 0x84c8000
	s_addc_u32 s11, s5, 0
	s_ashr_i32 s8, s12, 5
	s_ashr_i32 s9, s8, 31
	s_lshl_b64 s[6:7], s[8:9], 11
	s_lshl_b32 s9, s12, 8
	s_and_b32 s9, s9, 0x700
	s_or_b32 s6, s6, s9
	s_mul_i32 s9, s7, 0x1400
	s_mul_hi_u32 s14, s6, 0x1400
	s_bfe_u32 s13, s12, 0x20003
	s_add_i32 s14, s14, s9
	s_mul_i32 s9, s6, 0x1400
	s_add_u32 s9, s10, s9
	s_addc_u32 s14, s11, s14
	s_lshl_b32 s15, s13, 7
	s_add_u32 s20, s9, s15
	s_addc_u32 s21, s14, 0
	s_mul_i32 s15, s8, 0xa00000
	s_mul_hi_i32 s14, s8, 0xa00000
	s_add_u32 s8, s10, s15
	s_addc_u32 s9, s11, s14
	s_lshl_b32 s10, s12, 3
	v_mov_b32_e32 v15, v240
	s_and_b32 s10, s10, 0x80
	s_add_u32 s10, s8, s10
	v_ashrrev_i32_e32 v17, 6, v15
	v_and_b32_e32 v14, 31, v15
	v_bfe_u32 v16, v15, 5, 1
	v_lshl_or_b32 v124, v17, 5, v14
	v_mov_b64_e32 v[0:1], s[20:21]
	s_addc_u32 s11, s9, 0
	v_mad_i64_i32 v[0:1], s[8:9], v124, s56, v[0:1]
	v_lshlrev_b32_e32 v192, 4, v16
	v_lshl_add_u64 v[0:1], v[0:1], 0, v[192:193]
	s_waitcnt vmcnt(0)
	global_load_dwordx4 v[108:111], v[0:1], off offset:3072
	global_load_dwordx4 v[104:107], v[0:1], off offset:3104
	global_load_dwordx4 v[100:103], v[0:1], off offset:3136
	global_load_dwordx4 v[96:99], v[0:1], off offset:3168
	v_ashrrev_i32_e32 v0, 31, v15
	v_lshrrev_b32_e32 v0, 29, v0
	v_add_u32_e32 v0, v15, v0
	v_ashrrev_i32_e32 v49, 3, v0
	v_and_b32_e32 v0, -8, v0
	v_sub_u32_e32 v4, v15, v0
	v_lshlrev_b32_e32 v40, 3, v4
	v_mov_b64_e32 v[6:7], s[10:11]
	v_ashrrev_i32_e32 v41, 31, v40
	v_mad_i64_i32 v[0:1], s[8:9], v49, s56, v[6:7]
	v_lshl_add_u64 v[10:11], v[40:41], 1, v[0:1]
	global_load_dwordx4 v[0:3], v[10:11], off offset:3584
	v_add_u32_e32 v5, 0x200, v15
	v_ashrrev_i32_e32 v8, 31, v5
	v_lshrrev_b32_e32 v8, 29, v8
	v_add_u32_e32 v8, v5, v8
	v_ashrrev_i32_e32 v64, 3, v8
	v_and_b32_e32 v8, -8, v8
	v_sub_u32_e32 v5, v5, v8
	v_lshlrev_b32_e32 v42, 3, v5
	v_ashrrev_i32_e32 v43, 31, v42
	v_mad_i64_i32 v[6:7], s[8:9], v64, s56, v[6:7]
	v_lshl_add_u64 v[6:7], v[42:43], 1, v[6:7]
	v_cmp_gt_i32_e64 s[36:37], 0, v15
	v_lshl_add_u64 v[8:9], v[6:7], 0, s[28:29]
	v_mov_b32_e32 v112, v193
	v_mov_b32_e32 v113, v193
	v_mov_b32_e32 v114, v193
	v_mov_b32_e32 v115, v193
	s_and_saveexec_b64 s[8:9], s[36:37]
	s_cbranch_execz .LBB0_623
	global_load_dwordx4 v[112:115], v[8:9], off
.LBB0_623:
	s_or_b64 exec, exec, s[8:9]
	v_ashrrev_i32_e32 v65, 3, v15
	v_and_b32_e32 v12, 7, v15
	v_mov_b64_e32 v[6:7], s[10:11]
	v_mad_i64_i32 v[6:7], s[8:9], v65, s56, v[6:7]
	v_lshlrev_b32_e32 v44, 4, v12
	v_mov_b32_e32 v45, v193
	v_lshl_add_u64 v[12:13], v[6:7], 0, v[44:45]
	v_mul_lo_u32 v6, v64, s27
	v_lshl_add_u32 v136, v5, 4, v6
	v_mul_lo_u32 v5, v49, s27
	v_lshl_add_u32 v137, v4, 4, v5
	global_load_dwordx4 v[4:7], v[12:13], off offset:3840
	v_add_u32_e32 v66, 0, v137
	v_add_u32_e32 v45, 0, v136
	s_waitcnt lgkmcnt(0)
	s_barrier
	s_waitcnt vmcnt(0)
	ds_write_b128 v66, v[0:3]
	s_and_saveexec_b64 s[8:9], s[36:37]
	ds_write_b128 v45, v[112:115]
	s_or_b64 exec, exec, s[8:9]
	v_mul_lo_u32 v0, v65, s27
	v_readfirstlane_b32 s8, v17
	v_add3_u32 v138, 0, v0, v44
	s_cmp_lt_i32 s8, 4
	ds_write_b128 v138, v[4:7] offset:18432
	s_waitcnt lgkmcnt(0)
	s_barrier
	s_cbranch_scc1 .LBB0_627
	s_setprio 1
.LBB0_627:
	v_lshl_add_u64 v[0:1], v[10:11], 0, s[28:29]
	v_add_co_u32_e32 v0, vcc, 0x50000, v0
	s_nop 1
	v_addc_co_u32_e32 v1, vcc, 0, v1, vcc
	global_load_dwordx4 v[32:35], v[0:1], off
	s_and_saveexec_b64 s[8:9], s[36:37]
	s_cbranch_execz .LBB0_629
	v_add_co_u32_e32 v0, vcc, 0x50000, v8
	s_nop 1
	v_addc_co_u32_e32 v1, vcc, 0, v9, vcc
	global_load_dwordx4 v[112:115], v[0:1], off
; #define LAS __attribute__((address_space(3)))
; #define MFMA32(a, b, c) __builtin_amdgcn_mfma_f32_32x32x16_bf16((a), (b), (c), 0, 0, 0)
; template <int DQK, int NSUB, int MODE>
; __device__ __forceinline__ void flash_unit(LAS char* L, const bf16_t* Qp, int qpitch, const bf16_t* Kp, int kpitch, const bf16_t* Vp, int vpitch,
;                                            bf16_t* Op, int opitch, float lam, float oscale, const float* subln) {
;     ...
;             rk1 = *(const u32x4*)(kg1 + ko); if (has2) rk2 = *(const u32x4*)(kg2 + ko); rv1 = *(const u32x4*)(vg1 + vo); }
;         const char* Kb = Lg + buf * KBUF; LAS const char* Vb = L + OFF_V + buf * VBUF + voff;
; #pragma unroll
;         for (int s = 0; s < NSUB; ++s) {
;             f32x16 p0, p1;
; #pragma unroll
;             for (int d0 = 0; d0 < ND0; ++d0) { const bf16x8 k0 = *(const bf16x8*)(Kb + r32 * KPB + (s * DQK + 16 * d0 + 8 * hi) * 2); const bf16x8 k1 = *(const bf16x8*)(Kb + (32 + r32) * KPB + (s * DQK + 16 * d0 + 8 * hi) * 2);
;                 if (d0 == 0) { p0 = MFMA32(k0, qf[s][d0], negm[s]); p1 = MFMA32(k1, qf[s][d0], negm[s]); }
;                 else { p0 = MFMA32(k0, qf[s][d0], p0); p1 = MFMA32(k1, qf[s][d0], p1); } }
; #pragma unroll
;             for (int hf = 0; hf < 2; ++hf) {
;                 f32x16& ph = hf ? p1 : p0;
;                 float mx = fmaxf(ph[0], ph[1]);
; #pragma unroll
;                 for (int r = 2; r < 16; ++r) mx = fmaxf(mx, ph[r]);
;                 mx = fmaxf(mx, __shfl_xor(mx, 32));
;                 const bool first = (t == 0) && (hf == 0);
;                 if (first || __any(mx > 8.0f)) {
;                     const float dl = first ? mx : fmaxf(mx, 0.f); mref[s] += dl;
; #pragma unroll
;                     for (int r = 0; r < 16; ++r) { ph[r] -= dl; negm[s][r] = -mref[s]; }
;                     if (hf == 0) {
; #pragma unroll
;                         for (int r = 0; r < 16; ++r) p1[r] -= dl;
;                     }
;                     if (!first) { const float alpha = __builtin_amdgcn_exp2f(-dl); lrow[s] *= alpha;
; #pragma unroll
;                         for (int r = 0; r < 16; ++r) { o[s][0][r] *= alpha; o[s][1][r] *= alpha; } }
;                 }
; #pragma unroll
;                 for (int r = 0; r < 16; ++r) ph[r] = __builtin_amdgcn_exp2f(ph[r]);
.LBB0_629:
	s_or_b64 exec, exec, s[8:9]
	v_lshrrev_b32_e32 v2, 2, v15
	v_and_b32_e32 v3, 16, v15
	v_lshlrev_b32_e32 v134, 2, v16
	v_lshlrev_b32_e32 v4, 2, v15
	s_mov_b64 s[8:9], 0xf00
	v_and_or_b32 v2, v2, 3, v134
	v_and_or_b32 v3, v4, 12, v3
	v_lshl_add_u64 v[0:1], v[12:13], 0, s[8:9]
	v_mul_u32_u24_e32 v2, 0x90, v2
	v_lshlrev_b32_e32 v3, 1, v3
	v_add3_u32 v135, 0, v2, v3
	v_mul_u32_u24_e32 v2, 0x90, v14
	v_add_co_u32_e32 v0, vcc, 0x50000, v0
	v_add3_u32 v139, 0, v2, v192
	s_nop 0
	v_addc_co_u32_e32 v1, vcc, 0, v1, vcc
	global_load_dwordx4 v[36:39], v[0:1], off
	ds_read_b128 v[0:3], v139 offset:4608
	ds_read_b128 v[4:7], v139
	ds_read_b128 v[50:53], v139 offset:32
	s_waitcnt lgkmcnt(0)
	v_mfma_f32_32x32x16_bf16 v[16:31], v[4:7], v[108:111], 0
	ds_read_b128 v[54:57], v139 offset:4640
	v_mfma_f32_32x32x16_bf16 v[0:15], v[0:3], v[108:111], 0
	v_mfma_f32_32x32x16_bf16 v[16:31], v[50:53], v[104:107], v[16:31]
	s_waitcnt lgkmcnt(0)
	v_mfma_f32_32x32x16_bf16 v[0:15], v[54:57], v[104:107], v[0:15]
	ds_read_b128 v[50:53], v139 offset:4672
	ds_read_b128 v[54:57], v139 offset:64
	s_waitcnt lgkmcnt(0)
	v_mfma_f32_32x32x16_bf16 v[16:31], v[54:57], v[100:103], v[16:31]
	v_mfma_f32_32x32x16_bf16 v[0:15], v[50:53], v[100:103], v[0:15]
	ds_read_b128 v[50:53], v139 offset:4704
	ds_read_b128 v[54:57], v139 offset:96
	s_waitcnt lgkmcnt(0)
	v_mfma_f32_32x32x16_bf16 v[16:31], v[54:57], v[96:99], v[16:31]
	v_mfma_f32_32x32x16_bf16 v[0:15], v[50:53], v[96:99], v[0:15]
	s_nop 10
	v_max_f32_e32 v46, v17, v17
	v_max_f32_e32 v47, v16, v16
	v_max_f32_e32 v46, v47, v46
	v_max3_f32 v46, v46, v18, v19
	v_max3_f32 v46, v46, v20, v21
	v_max3_f32 v46, v46, v22, v23
	v_max3_f32 v46, v46, v24, v25
	v_max3_f32 v46, v46, v26, v27
	v_max3_f32 v46, v46, v28, v29
	v_max3_f32 v46, v46, v30, v31
	ds_bpermute_b32 v47, v184, v46
	s_waitcnt lgkmcnt(0)
	v_max_f32_e32 v47, v47, v47
	v_max_f32_e32 v48, v46, v47
	v_sub_f32_e32 v16, v16, v48
	v_sub_f32_e32 v17, v17, v48
	v_sub_f32_e32 v18, v18, v48
	v_sub_f32_e32 v19, v19, v48
	v_sub_f32_e32 v20, v20, v48
	v_sub_f32_e32 v21, v21, v48
	v_pk_add_f32 v[50:51], v[0:1], v[48:49] op_sel_hi:[1,0] neg_lo:[0,1] neg_hi:[0,1]
	v_pk_add_f32 v[46:47], v[2:3], v[48:49] op_sel_hi:[1,0] neg_lo:[0,1] neg_hi:[0,1]
	v_exp_f32_e32 v0, v16
	v_exp_f32_e32 v1, v17
	v_exp_f32_e32 v2, v18
	v_exp_f32_e32 v3, v19
	v_sub_f32_e32 v22, v22, v48
	v_sub_f32_e32 v23, v23, v48
	v_pk_add_f32 v[52:53], v[4:5], v[48:49] op_sel_hi:[1,0] neg_lo:[0,1] neg_hi:[0,1]
	v_exp_f32_e32 v4, v20
	v_exp_f32_e32 v5, v21
	v_sub_f32_e32 v24, v24, v48
	v_sub_f32_e32 v25, v25, v48
	v_pk_add_f32 v[54:55], v[6:7], v[48:49] op_sel_hi:[1,0] neg_lo:[0,1] neg_hi:[0,1]
	v_exp_f32_e32 v6, v22
	v_exp_f32_e32 v7, v23
	v_sub_f32_e32 v26, v26, v48
	v_sub_f32_e32 v27, v27, v48
	v_pk_add_f32 v[56:57], v[8:9], v[48:49] op_sel_hi:[1,0] neg_lo:[0,1] neg_hi:[0,1]
	v_exp_f32_e32 v8, v24
	v_exp_f32_e32 v9, v25
	v_sub_f32_e32 v28, v28, v48
	v_sub_f32_e32 v29, v29, v48
	v_pk_add_f32 v[58:59], v[10:11], v[48:49] op_sel_hi:[1,0] neg_lo:[0,1] neg_hi:[0,1]
	v_exp_f32_e32 v10, v26
	v_exp_f32_e32 v11, v27
	v_pk_add_f32 v[16:17], v[0:1], v[2:3]
	v_sub_f32_e32 v30, v30, v48
	v_sub_f32_e32 v31, v31, v48
	v_pk_add_f32 v[60:61], v[12:13], v[48:49] op_sel_hi:[1,0] neg_lo:[0,1] neg_hi:[0,1]
	v_exp_f32_e32 v12, v28
	v_exp_f32_e32 v13, v29
	v_pk_add_f32 v[16:17], v[4:5], v[16:17]
	v_pk_add_f32 v[62:63], v[14:15], v[48:49] op_sel_hi:[1,0] neg_lo:[0,1] neg_hi:[0,1]
	v_exp_f32_e32 v14, v30
	v_exp_f32_e32 v15, v31
	v_pk_add_f32 v[16:17], v[6:7], v[16:17]
	v_cvt_pk_bf16_f32 v18, v4, v5
	v_pk_add_f32 v[16:17], v[8:9], v[16:17]
	v_cvt_pk_bf16_f32 v19, v6, v7
	v_pk_add_f32 v[16:17], v[10:11], v[16:17]
	v_cvt_pk_bf16_f32 v68, v8, v9
	v_pk_add_f32 v[16:17], v[12:13], v[16:17]
	v_cvt_pk_bf16_f32 v69, v10, v11
	v_pk_add_f32 v[76:77], v[14:15], v[16:17]
	v_cvt_pk_bf16_f32 v16, v0, v1
	v_cvt_pk_bf16_f32 v17, v2, v3
	ds_read_b64_tr_b16 v[0:1], v135 offset:18432
	ds_read_b64_tr_b16 v[2:3], v135 offset:19584
	v_cvt_pk_bf16_f32 v70, v12, v13
	v_cvt_pk_bf16_f32 v71, v14, v15
	s_waitcnt lgkmcnt(0)
	v_mfma_f32_32x32x16_bf16 v[0:15], v[0:3], v[16:19], 0
	ds_read_b64_tr_b16 v[20:21], v135 offset:20736
	ds_read_b64_tr_b16 v[22:23], v135 offset:21888
	s_waitcnt lgkmcnt(0)
	v_mfma_f32_32x32x16_bf16 v[0:15], v[20:23], v[68:71], v[0:15]
	ds_read_b64_tr_b16 v[20:21], v135 offset:18496
	ds_read_b64_tr_b16 v[22:23], v135 offset:19648
	ds_read_b64_tr_b16 v[72:73], v135 offset:20800
	ds_read_b64_tr_b16 v[74:75], v135 offset:21952
	s_waitcnt lgkmcnt(0)
	v_mfma_f32_32x32x16_bf16 v[16:31], v[20:23], v[16:19], 0
	v_mfma_f32_32x32x16_bf16 v[16:31], v[72:75], v[68:71], v[16:31]
	v_add_f32_e64 v68, v76, v77
	v_add_f32_e64 v69, v77, v76
	v_mov_b32_e32 v69, v48
	v_max_f32_e32 v48, v50, v51
	v_max3_f32 v48, v48, v46, v47
	v_max3_f32 v48, v48, v52, v53
	v_max3_f32 v48, v48, v54, v55
	v_max3_f32 v48, v48, v56, v57
	v_max3_f32 v48, v48, v58, v59
	v_max3_f32 v48, v48, v60, v61
	v_max3_f32 v48, v48, v62, v63
	ds_bpermute_b32 v67, v184, v48
	v_pk_add_f32 v[126:127], v[68:69], 0 op_sel_hi:[1,0]
	s_waitcnt lgkmcnt(0)
	v_max_f32_e32 v67, v67, v67
	v_max_f32_e32 v48, v48, v67
	v_cmp_lt_f32_e32 vcc, s61, v48
	s_cbranch_vccz .LBB0_631
	v_max_f32_e32 v48, v48, v48
	v_max_f32_e32 v48, 0, v48
	v_exp_f32_e64 v68, -v48
	v_add_f32_e32 v127, v127, v48
	v_sub_f32_e32 v50, v50, v48
	v_sub_f32_e32 v51, v51, v48
	v_sub_f32_e32 v46, v46, v48
	v_sub_f32_e32 v47, v47, v48
	v_sub_f32_e32 v52, v52, v48
	v_sub_f32_e32 v53, v53, v48
	v_sub_f32_e32 v54, v54, v48
	v_sub_f32_e32 v55, v55, v48
	v_sub_f32_e32 v56, v56, v48
	v_sub_f32_e32 v57, v57, v48
	v_sub_f32_e32 v58, v58, v48
	v_sub_f32_e32 v59, v59, v48
	v_sub_f32_e32 v60, v60, v48
	v_sub_f32_e32 v61, v61, v48
	v_sub_f32_e32 v62, v62, v48
	v_sub_f32_e32 v63, v63, v48
	v_pk_mul_f32 v[14:15], v[14:15], v[68:69] op_sel_hi:[1,0]
	v_pk_mul_f32 v[12:13], v[12:13], v[68:69] op_sel_hi:[1,0]
	v_pk_mul_f32 v[10:11], v[10:11], v[68:69] op_sel_hi:[1,0]
	v_pk_mul_f32 v[8:9], v[8:9], v[68:69] op_sel_hi:[1,0]
	v_pk_mul_f32 v[6:7], v[6:7], v[68:69] op_sel_hi:[1,0]
	v_pk_mul_f32 v[4:5], v[4:5], v[68:69] op_sel_hi:[1,0]
	v_pk_mul_f32 v[2:3], v[2:3], v[68:69] op_sel_hi:[1,0]
	v_pk_mul_f32 v[0:1], v[0:1], v[68:69] op_sel_hi:[1,0]
	v_pk_mul_f32 v[30:31], v[30:31], v[68:69] op_sel_hi:[1,0]
	v_pk_mul_f32 v[28:29], v[28:29], v[68:69] op_sel_hi:[1,0]
	v_pk_mul_f32 v[26:27], v[26:27], v[68:69] op_sel_hi:[1,0]
	v_pk_mul_f32 v[24:25], v[24:25], v[68:69] op_sel_hi:[1,0]
	v_pk_mul_f32 v[22:23], v[22:23], v[68:69] op_sel_hi:[1,0]
	v_pk_mul_f32 v[20:21], v[20:21], v[68:69] op_sel_hi:[1,0]
	v_pk_mul_f32 v[18:19], v[18:19], v[68:69] op_sel_hi:[1,0]
	v_pk_mul_f32 v[16:17], v[16:17], v[68:69] op_sel_hi:[1,0]
	v_xor_b32_e32 v48, 0x80000000, v127
	v_mul_f32_e32 v126, v126, v68
	s_branch .LBB0_632

; __device__ __forceinline__ int otid() { int t = threadIdx.x; asm volatile("" : "+v"(t)); return t; }
; __device__ __forceinline__ unsigned cvt_pk_bf16(float lo, float hi) { typedef float f2 __attribute__((ext_vector_type(2))); typedef __bf16 b2 __attribute__((ext_vector_type(2))); f2 v = {lo, hi}; b2 b = __builtin_convertvector(v, b2); return __builtin_bit_cast(unsigned, b); }
;     __device__ __forceinline__ void operator()(f32x4 (&acc)[2][2][4][2], const Unit& u, int wr, int wc, int fr, int fq) const {
;         const int i = u.pn >> 2, pn = u.pn & 3, pm = u.pm - i * nM;
;         { const int t_ = otid(), l_ = t_ & 63, w_ = t_ >> 6; wr = w_ >> 2; wc = w_ & 3; fr = l_ & 15; fq = l_ >> 4; }
;         const int row0 = pm * BM + wr * 64 + fr; const int col0 = pn * BM + wc * 32 + 8 * fq;
;         u32x4 gwv[2][4][2];
; #pragma unroll
;         for (int ai = 0; ai < 2; ++ai)
; #pragma unroll
;             for (int m = 0; m < 4; ++m) { const bf16_t* grow = rat + ((size_t)i * Trows + (row0 + ai * HALF + m * 16)) * 1024 + col0;
; #pragma unroll
;                 for (int bj = 0; bj < 2; ++bj) gwv[ai][m][bj] = __builtin_nontemporal_load((const u32x4*)(grow + bj * HALF)); }
; #pragma unroll
;         for (int ai = 0; ai < 2; ++ai)
; #pragma unroll
;             for (int m = 0; m < 4; ++m) { bf16_t* brow = mb + (size_t)(row0 + ai * HALF + m * 16) * 1024 + col0;
; #pragma unroll
;                 for (int bj = 0; bj < 2; ++bj) { const u32x4 gw = gwv[ai][m][bj]; u32x4 w = {0u, 0u, 0u, 0u};
; #pragma unroll
;                     for (int n = 0; n < 2; ++n) { const unsigned lo = gw[2 * n], hi_ = gw[2 * n + 1];
;                         f32x4 g; g[0] = __uint_as_float(lo << 16); g[1] = __uint_as_float(lo & 0xffff0000u); g[2] = __uint_as_float(hi_ << 16); g[3] = __uint_as_float(hi_ & 0xffff0000u);
;                         const f32x4 v = acc[ai][bj][m][n] * g; acc[ai][bj][m][n] = v;
;                         if (i == 3) { w[2 * n] = cvt_pk_bf16(v[0], v[1]); w[2 * n + 1] = cvt_pk_bf16(v[2], v[3]); } }
;                     if (i == 3) *(u32x4*)(brow + bj * HALF) = w; } }
.LBB0_867:
	s_ashr_i32 s21, s60, 2
	v_mov_b32_e32 v80, v240
	s_mul_i32 s23, s21, s75
	s_sub_i32 s23, s62, s23
	v_ashrrev_i32_e32 v81, 2, v80
	v_and_b32_e32 v81, 0xffffffc0, v81
	v_lshl_add_u32 v81, s23, 8, v81
	v_and_or_b32 v216, v80, 15, v81
	s_lshl_b32 s23, s60, 8
	v_lshrrev_b32_e32 v80, 1, v80
	s_and_b32 s23, s23, 0x300
	v_and_b32_e32 v80, 0x78, v80
	v_or_b32_e32 v80, s23, v80
	v_ashrrev_i32_e32 v217, 31, v216
	v_mov_b32_e32 v132, s0
	v_lshlrev_b32_e32 v192, 1, v80
	v_mad_i64_i32 v[80:81], s[36:37], s21, v132, v[216:217]
	v_lshl_add_u64 v[128:129], s[6:7], 0, v[192:193]
	v_lshlrev_b64 v[80:81], 11, v[80:81]
	v_or_b32_e32 v214, 16, v216
	v_lshl_add_u64 v[80:81], v[128:129], 0, v[80:81]
	v_ashrrev_i32_e32 v215, 31, v214
	global_load_dwordx4 v[188:191], v[80:81], off nt
	global_load_dwordx4 v[184:187], v[80:81], off offset:256 nt
	v_mad_i64_i32 v[80:81], s[36:37], s21, v132, v[214:215]
	v_lshlrev_b64 v[80:81], 11, v[80:81]
	v_or_b32_e32 v212, 32, v216
	v_lshl_add_u64 v[80:81], v[128:129], 0, v[80:81]
	v_ashrrev_i32_e32 v213, 31, v212
	global_load_dwordx4 v[180:183], v[80:81], off nt
	global_load_dwordx4 v[176:179], v[80:81], off offset:256 nt
	v_mad_i64_i32 v[80:81], s[36:37], s21, v132, v[212:213]
	v_lshlrev_b64 v[80:81], 11, v[80:81]
	v_or_b32_e32 v210, 48, v216
	v_lshl_add_u64 v[80:81], v[128:129], 0, v[80:81]
	v_ashrrev_i32_e32 v211, 31, v210
	global_load_dwordx4 v[172:175], v[80:81], off nt
	global_load_dwordx4 v[168:171], v[80:81], off offset:256 nt
	v_mad_i64_i32 v[80:81], s[36:37], s21, v132, v[210:211]
	v_lshlrev_b64 v[80:81], 11, v[80:81]
	v_add_u32_e32 v208, 0x80, v216
	v_lshl_add_u64 v[130:131], v[128:129], 0, v[80:81]
	v_ashrrev_i32_e32 v209, 31, v208
	global_load_dwordx4 v[80:83], v[130:131], off nt
	global_load_dwordx4 v[164:167], v[130:131], off offset:256 nt
	v_mad_i64_i32 v[130:131], s[36:37], s21, v132, v[208:209]
	v_lshlrev_b64 v[130:131], 11, v[130:131]
	v_add_u32_e32 v206, 0x90, v216
	v_lshl_add_u64 v[130:131], v[128:129], 0, v[130:131]
	v_ashrrev_i32_e32 v207, 31, v206
	global_load_dwordx4 v[160:163], v[130:131], off nt
	global_load_dwordx4 v[156:159], v[130:131], off offset:256 nt
	v_mad_i64_i32 v[130:131], s[36:37], s21, v132, v[206:207]
	v_lshlrev_b64 v[130:131], 11, v[130:131]
	v_add_u32_e32 v204, 0xa0, v216
	v_lshl_add_u64 v[130:131], v[128:129], 0, v[130:131]
	v_ashrrev_i32_e32 v205, 31, v204
	global_load_dwordx4 v[148:151], v[130:131], off nt
	global_load_dwordx4 v[144:147], v[130:131], off offset:256 nt
	v_mad_i64_i32 v[130:131], s[36:37], s21, v132, v[204:205]
	v_lshlrev_b64 v[130:131], 11, v[130:131]
	v_add_u32_e32 v202, 0xb0, v216
	v_lshl_add_u64 v[130:131], v[128:129], 0, v[130:131]
	v_ashrrev_i32_e32 v203, 31, v202
	global_load_dwordx4 v[140:143], v[130:131], off nt
	global_load_dwordx4 v[136:139], v[130:131], off offset:256 nt
	v_mad_i64_i32 v[130:131], s[36:37], s21, v132, v[202:203]
	v_lshlrev_b64 v[130:131], 11, v[130:131]
	v_lshl_add_u64 v[128:129], v[128:129], 0, v[130:131]
	global_load_dwordx4 v[132:135], v[128:129], off nt
	s_nop 0
	global_load_dwordx4 v[128:131], v[128:129], off offset:256 nt
	s_cmp_eq_u32 s21, 3
	s_cselect_b64 s[40:41], -1, 0
	s_cmp_lg_u32 s21, 3
	s_waitcnt vmcnt(0) lgkmcnt(0)
	v_lshlrev_b32_e32 v220, 16, v188
	v_and_b32_e32 v221, 0xffff0000, v188
	v_lshlrev_b32_e32 v188, 16, v189
	v_and_b32_e32 v189, 0xffff0000, v189
	v_pk_mul_f32 v[2:3], v[2:3], v[188:189]
	v_pk_mul_f32 v[0:1], v[0:1], v[220:221]
	v_mov_b32_e32 v188, 0
	v_mov_b32_e32 v189, 0
	s_cbranch_scc1 .LBB0_869
	v_cvt_pk_bf16_f32 v188, v0, v1
	v_cvt_pk_bf16_f32 v189, v2, v3
.LBB0_869:
	v_lshlrev_b64 v[216:217], 11, v[216:217]
	v_lshlrev_b32_e32 v220, 16, v190
	v_and_b32_e32 v221, 0xffff0000, v190
	v_lshlrev_b32_e32 v190, 16, v191
	v_and_b32_e32 v191, 0xffff0000, v191
	v_lshl_add_u64 v[216:217], s[10:11], 0, v[216:217]
	v_pk_mul_f32 v[14:15], v[14:15], v[190:191]
	v_cndmask_b32_e64 v190, 0, 1, s[40:41]
	v_lshl_add_u64 v[216:217], v[216:217], 0, v[192:193]
	v_cmp_ne_u32_e64 s[36:37], 1, v190
	s_andn2_b64 vcc, exec, s[40:41]
	v_pk_mul_f32 v[12:13], v[12:13], v[220:221]
	s_cbranch_vccnz .LBB0_871
	v_cvt_pk_bf16_f32 v190, v12, v13
	v_cvt_pk_bf16_f32 v191, v14, v15
	global_store_dwordx4 v[216:217], v[188:191], off

; __device__ __forceinline__ unsigned cvt_pk_bf16(float lo, float hi) { typedef float f2 __attribute__((ext_vector_type(2))); typedef __bf16 b2 __attribute__((ext_vector_type(2))); f2 v = {lo, hi}; b2 b = __builtin_convertvector(v, b2); return __builtin_bit_cast(unsigned, b); }
;     __device__ __forceinline__ void operator()(f32x4 (&acc)[2][2][4][2], const Unit& u, int wr, int wc, int fr, int fq) const {
;     ...
;                 for (int bj = 0; bj < 2; ++bj) { const u32x4 gw = gwv[ai][m][bj]; u32x4 w = {0u, 0u, 0u, 0u};
; #pragma unroll
;                     for (int n = 0; n < 2; ++n) { const unsigned lo = gw[2 * n], hi_ = gw[2 * n + 1];
;                         f32x4 g; g[0] = __uint_as_float(lo << 16); g[1] = __uint_as_float(lo & 0xffff0000u); g[2] = __uint_as_float(hi_ << 16); g[3] = __uint_as_float(hi_ & 0xffff0000u);
;                         const f32x4 v = acc[ai][bj][m][n] * g; acc[ai][bj][m][n] = v;
;                         if (i == 3) { w[2 * n] = cvt_pk_bf16(v[0], v[1]); w[2 * n + 1] = cvt_pk_bf16(v[2], v[3]); } }
;                     if (i == 3) *(u32x4*)(brow + bj * HALF) = w; } }
.LBB0_873:
	v_lshlrev_b32_e32 v188, 16, v186
	v_and_b32_e32 v189, 0xffff0000, v186
	v_lshlrev_b32_e32 v186, 16, v187
	v_and_b32_e32 v187, 0xffff0000, v187
	v_pk_mul_f32 v[10:11], v[10:11], v[186:187]
	s_and_b64 vcc, exec, s[36:37]
	v_pk_mul_f32 v[8:9], v[8:9], v[188:189]
	s_cbranch_vccnz .LBB0_875
	v_cvt_pk_bf16_f32 v186, v8, v9
	v_cvt_pk_bf16_f32 v187, v10, v11
	global_store_dwordx4 v[216:217], v[184:187], off offset:256

; __device__ __forceinline__ unsigned cvt_pk_bf16(float lo, float hi) { typedef float f2 __attribute__((ext_vector_type(2))); typedef __bf16 b2 __attribute__((ext_vector_type(2))); f2 v = {lo, hi}; b2 b = __builtin_convertvector(v, b2); return __builtin_bit_cast(unsigned, b); }
;     __device__ __forceinline__ void operator()(f32x4 (&acc)[2][2][4][2], const Unit& u, int wr, int wc, int fr, int fq) const {
;     ...
;                 for (int bj = 0; bj < 2; ++bj) { const u32x4 gw = gwv[ai][m][bj]; u32x4 w = {0u, 0u, 0u, 0u};
; #pragma unroll
;                     for (int n = 0; n < 2; ++n) { const unsigned lo = gw[2 * n], hi_ = gw[2 * n + 1];
;                         f32x4 g; g[0] = __uint_as_float(lo << 16); g[1] = __uint_as_float(lo & 0xffff0000u); g[2] = __uint_as_float(hi_ << 16); g[3] = __uint_as_float(hi_ & 0xffff0000u);
;                         const f32x4 v = acc[ai][bj][m][n] * g; acc[ai][bj][m][n] = v;
;                         if (i == 3) { w[2 * n] = cvt_pk_bf16(v[0], v[1]); w[2 * n + 1] = cvt_pk_bf16(v[2], v[3]); } }
;                     if (i == 3) *(u32x4*)(brow + bj * HALF) = w; } }
.LBB0_877:
	v_lshlrev_b64 v[184:185], 11, v[214:215]
	v_lshl_add_u64 v[184:185], s[10:11], 0, v[184:185]
	v_lshlrev_b32_e32 v186, 16, v182
	v_and_b32_e32 v187, 0xffff0000, v182
	v_lshlrev_b32_e32 v182, 16, v183
	v_and_b32_e32 v183, 0xffff0000, v183
	v_lshl_add_u64 v[184:185], v[184:185], 0, v[192:193]
	v_pk_mul_f32 v[30:31], v[30:31], v[182:183]
	s_and_b64 vcc, exec, s[36:37]
	v_pk_mul_f32 v[28:29], v[28:29], v[186:187]
	s_cbranch_vccnz .LBB0_879
	v_cvt_pk_bf16_f32 v182, v28, v29
	v_cvt_pk_bf16_f32 v183, v30, v31
	global_store_dwordx4 v[184:185], v[180:183], off

; __device__ __forceinline__ unsigned cvt_pk_bf16(float lo, float hi) { typedef float f2 __attribute__((ext_vector_type(2))); typedef __bf16 b2 __attribute__((ext_vector_type(2))); f2 v = {lo, hi}; b2 b = __builtin_convertvector(v, b2); return __builtin_bit_cast(unsigned, b); }
;     __device__ __forceinline__ void operator()(f32x4 (&acc)[2][2][4][2], const Unit& u, int wr, int wc, int fr, int fq) const {
;     ...
;                 for (int bj = 0; bj < 2; ++bj) { const u32x4 gw = gwv[ai][m][bj]; u32x4 w = {0u, 0u, 0u, 0u};
; #pragma unroll
;                     for (int n = 0; n < 2; ++n) { const unsigned lo = gw[2 * n], hi_ = gw[2 * n + 1];
;                         f32x4 g; g[0] = __uint_as_float(lo << 16); g[1] = __uint_as_float(lo & 0xffff0000u); g[2] = __uint_as_float(hi_ << 16); g[3] = __uint_as_float(hi_ & 0xffff0000u);
;                         const f32x4 v = acc[ai][bj][m][n] * g; acc[ai][bj][m][n] = v;
;                         if (i == 3) { w[2 * n] = cvt_pk_bf16(v[0], v[1]); w[2 * n + 1] = cvt_pk_bf16(v[2], v[3]); } }
;                     if (i == 3) *(u32x4*)(brow + bj * HALF) = w; } }
.LBB0_881:
	v_lshlrev_b32_e32 v180, 16, v178
	v_and_b32_e32 v181, 0xffff0000, v178
	v_lshlrev_b32_e32 v178, 16, v179
	v_and_b32_e32 v179, 0xffff0000, v179
	v_pk_mul_f32 v[22:23], v[22:23], v[178:179]
	s_and_b64 vcc, exec, s[36:37]
	v_pk_mul_f32 v[20:21], v[20:21], v[180:181]
	s_cbranch_vccnz .LBB0_883
	v_cvt_pk_bf16_f32 v178, v20, v21
	v_cvt_pk_bf16_f32 v179, v22, v23
	global_store_dwordx4 v[184:185], v[176:179], off offset:256

; __device__ __forceinline__ unsigned cvt_pk_bf16(float lo, float hi) { typedef float f2 __attribute__((ext_vector_type(2))); typedef __bf16 b2 __attribute__((ext_vector_type(2))); f2 v = {lo, hi}; b2 b = __builtin_convertvector(v, b2); return __builtin_bit_cast(unsigned, b); }
;     __device__ __forceinline__ void operator()(f32x4 (&acc)[2][2][4][2], const Unit& u, int wr, int wc, int fr, int fq) const {
;     ...
;                 for (int bj = 0; bj < 2; ++bj) { const u32x4 gw = gwv[ai][m][bj]; u32x4 w = {0u, 0u, 0u, 0u};
; #pragma unroll
;                     for (int n = 0; n < 2; ++n) { const unsigned lo = gw[2 * n], hi_ = gw[2 * n + 1];
;                         f32x4 g; g[0] = __uint_as_float(lo << 16); g[1] = __uint_as_float(lo & 0xffff0000u); g[2] = __uint_as_float(hi_ << 16); g[3] = __uint_as_float(hi_ & 0xffff0000u);
;                         const f32x4 v = acc[ai][bj][m][n] * g; acc[ai][bj][m][n] = v;
;                         if (i == 3) { w[2 * n] = cvt_pk_bf16(v[0], v[1]); w[2 * n + 1] = cvt_pk_bf16(v[2], v[3]); } }
;                     if (i == 3) *(u32x4*)(brow + bj * HALF) = w; } }
.LBB0_885:
	v_lshlrev_b64 v[176:177], 11, v[212:213]
	v_lshl_add_u64 v[176:177], s[10:11], 0, v[176:177]
	v_lshlrev_b32_e32 v178, 16, v174
	v_and_b32_e32 v179, 0xffff0000, v174
	v_lshlrev_b32_e32 v174, 16, v175
	v_and_b32_e32 v175, 0xffff0000, v175
	v_lshl_add_u64 v[176:177], v[176:177], 0, v[192:193]
	v_pk_mul_f32 v[50:51], v[50:51], v[174:175]
	s_and_b64 vcc, exec, s[36:37]
	v_pk_mul_f32 v[48:49], v[48:49], v[178:179]
	s_cbranch_vccnz .LBB0_887
	v_cvt_pk_bf16_f32 v174, v48, v49
	v_cvt_pk_bf16_f32 v175, v50, v51
	global_store_dwordx4 v[176:177], v[172:175], off

; __device__ __forceinline__ unsigned cvt_pk_bf16(float lo, float hi) { typedef float f2 __attribute__((ext_vector_type(2))); typedef __bf16 b2 __attribute__((ext_vector_type(2))); f2 v = {lo, hi}; b2 b = __builtin_convertvector(v, b2); return __builtin_bit_cast(unsigned, b); }
;     __device__ __forceinline__ void operator()(f32x4 (&acc)[2][2][4][2], const Unit& u, int wr, int wc, int fr, int fq) const {
;     ...
;                 for (int bj = 0; bj < 2; ++bj) { const u32x4 gw = gwv[ai][m][bj]; u32x4 w = {0u, 0u, 0u, 0u};
; #pragma unroll
;                     for (int n = 0; n < 2; ++n) { const unsigned lo = gw[2 * n], hi_ = gw[2 * n + 1];
;                         f32x4 g; g[0] = __uint_as_float(lo << 16); g[1] = __uint_as_float(lo & 0xffff0000u); g[2] = __uint_as_float(hi_ << 16); g[3] = __uint_as_float(hi_ & 0xffff0000u);
;                         const f32x4 v = acc[ai][bj][m][n] * g; acc[ai][bj][m][n] = v;
;                         if (i == 3) { w[2 * n] = cvt_pk_bf16(v[0], v[1]); w[2 * n + 1] = cvt_pk_bf16(v[2], v[3]); } }
;                     if (i == 3) *(u32x4*)(brow + bj * HALF) = w; } }
.LBB0_889:
	v_lshlrev_b32_e32 v172, 16, v170
	v_and_b32_e32 v173, 0xffff0000, v170
	v_lshlrev_b32_e32 v170, 16, v171
	v_and_b32_e32 v171, 0xffff0000, v171
	v_pk_mul_f32 v[38:39], v[38:39], v[170:171]
	s_and_b64 vcc, exec, s[36:37]
	v_pk_mul_f32 v[36:37], v[36:37], v[172:173]
	s_cbranch_vccnz .LBB0_891
	v_cvt_pk_bf16_f32 v170, v36, v37
	v_cvt_pk_bf16_f32 v171, v38, v39
	global_store_dwordx4 v[176:177], v[168:171], off offset:256

; __device__ __forceinline__ unsigned cvt_pk_bf16(float lo, float hi) { typedef float f2 __attribute__((ext_vector_type(2))); typedef __bf16 b2 __attribute__((ext_vector_type(2))); f2 v = {lo, hi}; b2 b = __builtin_convertvector(v, b2); return __builtin_bit_cast(unsigned, b); }
;     __device__ __forceinline__ void operator()(f32x4 (&acc)[2][2][4][2], const Unit& u, int wr, int wc, int fr, int fq) const {
;     ...
;                 for (int bj = 0; bj < 2; ++bj) { const u32x4 gw = gwv[ai][m][bj]; u32x4 w = {0u, 0u, 0u, 0u};
; #pragma unroll
;                     for (int n = 0; n < 2; ++n) { const unsigned lo = gw[2 * n], hi_ = gw[2 * n + 1];
;                         f32x4 g; g[0] = __uint_as_float(lo << 16); g[1] = __uint_as_float(lo & 0xffff0000u); g[2] = __uint_as_float(hi_ << 16); g[3] = __uint_as_float(hi_ & 0xffff0000u);
;                         const f32x4 v = acc[ai][bj][m][n] * g; acc[ai][bj][m][n] = v;
;                         if (i == 3) { w[2 * n] = cvt_pk_bf16(v[0], v[1]); w[2 * n + 1] = cvt_pk_bf16(v[2], v[3]); } }
;                     if (i == 3) *(u32x4*)(brow + bj * HALF) = w; } }
.LBB0_893:
	v_lshlrev_b64 v[80:81], 11, v[210:211]
	v_lshl_add_u64 v[80:81], s[10:11], 0, v[80:81]
	v_lshl_add_u64 v[172:173], v[80:81], 0, v[192:193]
	v_lshlrev_b32_e32 v80, 16, v82
	v_and_b32_e32 v81, 0xffff0000, v82
	v_lshlrev_b32_e32 v82, 16, v83
	v_and_b32_e32 v83, 0xffff0000, v83
	v_pk_mul_f32 v[82:83], v[70:71], v[82:83]
	s_and_b64 vcc, exec, s[36:37]
	v_pk_mul_f32 v[80:81], v[68:69], v[80:81]
	s_cbranch_vccnz .LBB0_895
	v_cvt_pk_bf16_f32 v170, v80, v81
	v_cvt_pk_bf16_f32 v171, v82, v83
	global_store_dwordx4 v[172:173], v[168:171], off

; __device__ __forceinline__ unsigned cvt_pk_bf16(float lo, float hi) { typedef float f2 __attribute__((ext_vector_type(2))); typedef __bf16 b2 __attribute__((ext_vector_type(2))); f2 v = {lo, hi}; b2 b = __builtin_convertvector(v, b2); return __builtin_bit_cast(unsigned, b); }
;     __device__ __forceinline__ void operator()(f32x4 (&acc)[2][2][4][2], const Unit& u, int wr, int wc, int fr, int fq) const {
;     ...
;                 for (int bj = 0; bj < 2; ++bj) { const u32x4 gw = gwv[ai][m][bj]; u32x4 w = {0u, 0u, 0u, 0u};
; #pragma unroll
;                     for (int n = 0; n < 2; ++n) { const unsigned lo = gw[2 * n], hi_ = gw[2 * n + 1];
;                         f32x4 g; g[0] = __uint_as_float(lo << 16); g[1] = __uint_as_float(lo & 0xffff0000u); g[2] = __uint_as_float(hi_ << 16); g[3] = __uint_as_float(hi_ & 0xffff0000u);
;                         const f32x4 v = acc[ai][bj][m][n] * g; acc[ai][bj][m][n] = v;
;                         if (i == 3) { w[2 * n] = cvt_pk_bf16(v[0], v[1]); w[2 * n + 1] = cvt_pk_bf16(v[2], v[3]); } }
;                     if (i == 3) *(u32x4*)(brow + bj * HALF) = w; } }
.LBB0_897:
	v_lshlrev_b32_e32 v68, 16, v166
	v_and_b32_e32 v69, 0xffff0000, v166
	v_lshlrev_b32_e32 v70, 16, v167
	v_and_b32_e32 v71, 0xffff0000, v167
	v_pk_mul_f32 v[70:71], v[58:59], v[70:71]
	s_and_b64 vcc, exec, s[36:37]
	v_pk_mul_f32 v[68:69], v[56:57], v[68:69]
	s_cbranch_vccnz .LBB0_899
	v_cvt_pk_bf16_f32 v166, v68, v69
	v_cvt_pk_bf16_f32 v167, v70, v71
	global_store_dwordx4 v[172:173], v[164:167], off offset:256

; __device__ __forceinline__ unsigned cvt_pk_bf16(float lo, float hi) { typedef float f2 __attribute__((ext_vector_type(2))); typedef __bf16 b2 __attribute__((ext_vector_type(2))); f2 v = {lo, hi}; b2 b = __builtin_convertvector(v, b2); return __builtin_bit_cast(unsigned, b); }
;     __device__ __forceinline__ void operator()(f32x4 (&acc)[2][2][4][2], const Unit& u, int wr, int wc, int fr, int fq) const {
;     ...
;                 for (int bj = 0; bj < 2; ++bj) { const u32x4 gw = gwv[ai][m][bj]; u32x4 w = {0u, 0u, 0u, 0u};
; #pragma unroll
;                     for (int n = 0; n < 2; ++n) { const unsigned lo = gw[2 * n], hi_ = gw[2 * n + 1];
;                         f32x4 g; g[0] = __uint_as_float(lo << 16); g[1] = __uint_as_float(lo & 0xffff0000u); g[2] = __uint_as_float(hi_ << 16); g[3] = __uint_as_float(hi_ & 0xffff0000u);
;                         const f32x4 v = acc[ai][bj][m][n] * g; acc[ai][bj][m][n] = v;
;                         if (i == 3) { w[2 * n] = cvt_pk_bf16(v[0], v[1]); w[2 * n + 1] = cvt_pk_bf16(v[2], v[3]); } }
;                     if (i == 3) *(u32x4*)(brow + bj * HALF) = w; } }
.LBB0_901:
	v_lshlrev_b64 v[154:155], 11, v[208:209]
	v_lshl_add_u64 v[154:155], s[10:11], 0, v[154:155]
	v_lshl_add_u64 v[160:161], v[154:155], 0, v[192:193]
	v_lshlrev_b32_e32 v154, 16, v162
	v_and_b32_e32 v155, 0xffff0000, v162
	v_lshlrev_b32_e32 v162, 16, v163
	v_and_b32_e32 v163, 0xffff0000, v163
	v_pk_mul_f32 v[66:67], v[66:67], v[162:163]
	s_and_b64 vcc, exec, s[36:37]
	v_pk_mul_f32 v[64:65], v[64:65], v[154:155]
	s_cbranch_vccnz .LBB0_903
	v_cvt_pk_bf16_f32 v154, v64, v65
	v_cvt_pk_bf16_f32 v155, v66, v67
	global_store_dwordx4 v[160:161], v[152:155], off

; __device__ __forceinline__ unsigned cvt_pk_bf16(float lo, float hi) { typedef float f2 __attribute__((ext_vector_type(2))); typedef __bf16 b2 __attribute__((ext_vector_type(2))); f2 v = {lo, hi}; b2 b = __builtin_convertvector(v, b2); return __builtin_bit_cast(unsigned, b); }
;     __device__ __forceinline__ void operator()(f32x4 (&acc)[2][2][4][2], const Unit& u, int wr, int wc, int fr, int fq) const {
;     ...
;                 for (int bj = 0; bj < 2; ++bj) { const u32x4 gw = gwv[ai][m][bj]; u32x4 w = {0u, 0u, 0u, 0u};
; #pragma unroll
;                     for (int n = 0; n < 2; ++n) { const unsigned lo = gw[2 * n], hi_ = gw[2 * n + 1];
;                         f32x4 g; g[0] = __uint_as_float(lo << 16); g[1] = __uint_as_float(lo & 0xffff0000u); g[2] = __uint_as_float(hi_ << 16); g[3] = __uint_as_float(hi_ & 0xffff0000u);
;                         const f32x4 v = acc[ai][bj][m][n] * g; acc[ai][bj][m][n] = v;
;                         if (i == 3) { w[2 * n] = cvt_pk_bf16(v[0], v[1]); w[2 * n + 1] = cvt_pk_bf16(v[2], v[3]); } }
;                     if (i == 3) *(u32x4*)(brow + bj * HALF) = w; } }
.LBB0_905:
	v_lshlrev_b32_e32 v154, 16, v158
	v_and_b32_e32 v155, 0xffff0000, v158
	v_lshlrev_b32_e32 v156, 16, v159
	v_and_b32_e32 v157, 0xffff0000, v159
	v_pk_mul_f32 v[54:55], v[54:55], v[156:157]
	s_and_b64 vcc, exec, s[36:37]
	v_pk_mul_f32 v[52:53], v[52:53], v[154:155]
	s_cbranch_vccnz .LBB0_907
	v_cvt_pk_bf16_f32 v154, v52, v53
	v_cvt_pk_bf16_f32 v155, v54, v55
	global_store_dwordx4 v[160:161], v[152:155], off offset:256

; __device__ __forceinline__ unsigned cvt_pk_bf16(float lo, float hi) { typedef float f2 __attribute__((ext_vector_type(2))); typedef __bf16 b2 __attribute__((ext_vector_type(2))); f2 v = {lo, hi}; b2 b = __builtin_convertvector(v, b2); return __builtin_bit_cast(unsigned, b); }
;     __device__ __forceinline__ void operator()(f32x4 (&acc)[2][2][4][2], const Unit& u, int wr, int wc, int fr, int fq) const {
;     ...
;             for (int m = 0; m < 4; ++m) { bf16_t* brow = mb + (size_t)(row0 + ai * HALF + m * 16) * 1024 + col0;
; #pragma unroll
;                 for (int bj = 0; bj < 2; ++bj) { const u32x4 gw = gwv[ai][m][bj]; u32x4 w = {0u, 0u, 0u, 0u};
; #pragma unroll
;                     for (int n = 0; n < 2; ++n) { const unsigned lo = gw[2 * n], hi_ = gw[2 * n + 1];
;                         f32x4 g; g[0] = __uint_as_float(lo << 16); g[1] = __uint_as_float(lo & 0xffff0000u); g[2] = __uint_as_float(hi_ << 16); g[3] = __uint_as_float(hi_ & 0xffff0000u);
;                         const f32x4 v = acc[ai][bj][m][n] * g; acc[ai][bj][m][n] = v;
;                         if (i == 3) { w[2 * n] = cvt_pk_bf16(v[0], v[1]); w[2 * n + 1] = cvt_pk_bf16(v[2], v[3]); } }
;                     if (i == 3) *(u32x4*)(brow + bj * HALF) = w; } }
.LBB0_909:
	v_lshlrev_b64 v[152:153], 11, v[206:207]
	v_lshl_add_u64 v[152:153], s[10:11], 0, v[152:153]
	v_lshlrev_b32_e32 v154, 16, v150
	v_and_b32_e32 v155, 0xffff0000, v150
	v_lshlrev_b32_e32 v150, 16, v151
	v_and_b32_e32 v151, 0xffff0000, v151
	v_lshl_add_u64 v[152:153], v[152:153], 0, v[192:193]
	v_pk_mul_f32 v[94:95], v[94:95], v[150:151]
	s_and_b64 vcc, exec, s[36:37]
	v_pk_mul_f32 v[92:93], v[92:93], v[154:155]
	s_cbranch_vccnz .LBB0_911
	v_cvt_pk_bf16_f32 v150, v92, v93
	v_cvt_pk_bf16_f32 v151, v94, v95
	global_store_dwordx4 v[152:153], v[148:151], off

; __device__ __forceinline__ unsigned cvt_pk_bf16(float lo, float hi) { typedef float f2 __attribute__((ext_vector_type(2))); typedef __bf16 b2 __attribute__((ext_vector_type(2))); f2 v = {lo, hi}; b2 b = __builtin_convertvector(v, b2); return __builtin_bit_cast(unsigned, b); }
;     __device__ __forceinline__ void operator()(f32x4 (&acc)[2][2][4][2], const Unit& u, int wr, int wc, int fr, int fq) const {
;     ...
;                 for (int bj = 0; bj < 2; ++bj) { const u32x4 gw = gwv[ai][m][bj]; u32x4 w = {0u, 0u, 0u, 0u};
; #pragma unroll
;                     for (int n = 0; n < 2; ++n) { const unsigned lo = gw[2 * n], hi_ = gw[2 * n + 1];
;                         f32x4 g; g[0] = __uint_as_float(lo << 16); g[1] = __uint_as_float(lo & 0xffff0000u); g[2] = __uint_as_float(hi_ << 16); g[3] = __uint_as_float(hi_ & 0xffff0000u);
;                         const f32x4 v = acc[ai][bj][m][n] * g; acc[ai][bj][m][n] = v;
;                         if (i == 3) { w[2 * n] = cvt_pk_bf16(v[0], v[1]); w[2 * n + 1] = cvt_pk_bf16(v[2], v[3]); } }
;                     if (i == 3) *(u32x4*)(brow + bj * HALF) = w; } }
.LBB0_913:
	v_lshlrev_b32_e32 v148, 16, v146
	v_and_b32_e32 v149, 0xffff0000, v146
	v_lshlrev_b32_e32 v146, 16, v147
	v_and_b32_e32 v147, 0xffff0000, v147
	v_pk_mul_f32 v[86:87], v[86:87], v[146:147]
	s_and_b64 vcc, exec, s[36:37]
	v_pk_mul_f32 v[84:85], v[84:85], v[148:149]
	s_cbranch_vccnz .LBB0_915
	v_cvt_pk_bf16_f32 v146, v84, v85
	v_cvt_pk_bf16_f32 v147, v86, v87
	global_store_dwordx4 v[152:153], v[144:147], off offset:256

; __device__ __forceinline__ unsigned cvt_pk_bf16(float lo, float hi) { typedef float f2 __attribute__((ext_vector_type(2))); typedef __bf16 b2 __attribute__((ext_vector_type(2))); f2 v = {lo, hi}; b2 b = __builtin_convertvector(v, b2); return __builtin_bit_cast(unsigned, b); }
;     __device__ __forceinline__ void operator()(f32x4 (&acc)[2][2][4][2], const Unit& u, int wr, int wc, int fr, int fq) const {
;     ...
;             for (int m = 0; m < 4; ++m) { bf16_t* brow = mb + (size_t)(row0 + ai * HALF + m * 16) * 1024 + col0;
; #pragma unroll
;                 for (int bj = 0; bj < 2; ++bj) { const u32x4 gw = gwv[ai][m][bj]; u32x4 w = {0u, 0u, 0u, 0u};
; #pragma unroll
;                     for (int n = 0; n < 2; ++n) { const unsigned lo = gw[2 * n], hi_ = gw[2 * n + 1];
;                         f32x4 g; g[0] = __uint_as_float(lo << 16); g[1] = __uint_as_float(lo & 0xffff0000u); g[2] = __uint_as_float(hi_ << 16); g[3] = __uint_as_float(hi_ & 0xffff0000u);
;                         const f32x4 v = acc[ai][bj][m][n] * g; acc[ai][bj][m][n] = v;
;                         if (i == 3) { w[2 * n] = cvt_pk_bf16(v[0], v[1]); w[2 * n + 1] = cvt_pk_bf16(v[2], v[3]); } }
;                     if (i == 3) *(u32x4*)(brow + bj * HALF) = w; } }
.LBB0_917:
	v_lshlrev_b64 v[144:145], 11, v[204:205]
	v_lshl_add_u64 v[144:145], s[10:11], 0, v[144:145]
	v_lshlrev_b32_e32 v146, 16, v142
	v_and_b32_e32 v147, 0xffff0000, v142
	v_lshlrev_b32_e32 v142, 16, v143
	v_and_b32_e32 v143, 0xffff0000, v143
	v_lshl_add_u64 v[144:145], v[144:145], 0, v[192:193]
	v_pk_mul_f32 v[110:111], v[110:111], v[142:143]
	s_and_b64 vcc, exec, s[36:37]
	v_pk_mul_f32 v[108:109], v[108:109], v[146:147]
	s_cbranch_vccnz .LBB0_919
	v_cvt_pk_bf16_f32 v142, v108, v109
	v_cvt_pk_bf16_f32 v143, v110, v111
	global_store_dwordx4 v[144:145], v[140:143], off

; __device__ __forceinline__ unsigned cvt_pk_bf16(float lo, float hi) { typedef float f2 __attribute__((ext_vector_type(2))); typedef __bf16 b2 __attribute__((ext_vector_type(2))); f2 v = {lo, hi}; b2 b = __builtin_convertvector(v, b2); return __builtin_bit_cast(unsigned, b); }
;     __device__ __forceinline__ void operator()(f32x4 (&acc)[2][2][4][2], const Unit& u, int wr, int wc, int fr, int fq) const {
;     ...
;                 for (int bj = 0; bj < 2; ++bj) { const u32x4 gw = gwv[ai][m][bj]; u32x4 w = {0u, 0u, 0u, 0u};
; #pragma unroll
;                     for (int n = 0; n < 2; ++n) { const unsigned lo = gw[2 * n], hi_ = gw[2 * n + 1];
;                         f32x4 g; g[0] = __uint_as_float(lo << 16); g[1] = __uint_as_float(lo & 0xffff0000u); g[2] = __uint_as_float(hi_ << 16); g[3] = __uint_as_float(hi_ & 0xffff0000u);
;                         const f32x4 v = acc[ai][bj][m][n] * g; acc[ai][bj][m][n] = v;
;                         if (i == 3) { w[2 * n] = cvt_pk_bf16(v[0], v[1]); w[2 * n + 1] = cvt_pk_bf16(v[2], v[3]); } }
;                     if (i == 3) *(u32x4*)(brow + bj * HALF) = w; } }
.LBB0_921:
	v_lshlrev_b32_e32 v140, 16, v138
	v_and_b32_e32 v141, 0xffff0000, v138
	v_lshlrev_b32_e32 v138, 16, v139
	v_and_b32_e32 v139, 0xffff0000, v139
	v_pk_mul_f32 v[102:103], v[102:103], v[138:139]
	s_and_b64 vcc, exec, s[36:37]
	v_pk_mul_f32 v[100:101], v[100:101], v[140:141]
	s_cbranch_vccnz .LBB0_923
	v_cvt_pk_bf16_f32 v138, v100, v101
	v_cvt_pk_bf16_f32 v139, v102, v103
	global_store_dwordx4 v[144:145], v[136:139], off offset:256

; __device__ __forceinline__ unsigned cvt_pk_bf16(float lo, float hi) { typedef float f2 __attribute__((ext_vector_type(2))); typedef __bf16 b2 __attribute__((ext_vector_type(2))); f2 v = {lo, hi}; b2 b = __builtin_convertvector(v, b2); return __builtin_bit_cast(unsigned, b); }
;     __device__ __forceinline__ void operator()(f32x4 (&acc)[2][2][4][2], const Unit& u, int wr, int wc, int fr, int fq) const {
;     ...
;             for (int m = 0; m < 4; ++m) { bf16_t* brow = mb + (size_t)(row0 + ai * HALF + m * 16) * 1024 + col0;
; #pragma unroll
;                 for (int bj = 0; bj < 2; ++bj) { const u32x4 gw = gwv[ai][m][bj]; u32x4 w = {0u, 0u, 0u, 0u};
; #pragma unroll
;                     for (int n = 0; n < 2; ++n) { const unsigned lo = gw[2 * n], hi_ = gw[2 * n + 1];
;                         f32x4 g; g[0] = __uint_as_float(lo << 16); g[1] = __uint_as_float(lo & 0xffff0000u); g[2] = __uint_as_float(hi_ << 16); g[3] = __uint_as_float(hi_ & 0xffff0000u);
;                         const f32x4 v = acc[ai][bj][m][n] * g; acc[ai][bj][m][n] = v;
;                         if (i == 3) { w[2 * n] = cvt_pk_bf16(v[0], v[1]); w[2 * n + 1] = cvt_pk_bf16(v[2], v[3]); } }
;                     if (i == 3) *(u32x4*)(brow + bj * HALF) = w; } }
.LBB0_925:
	v_lshlrev_b64 v[136:137], 11, v[202:203]
	v_lshl_add_u64 v[136:137], s[10:11], 0, v[136:137]
	v_lshlrev_b32_e32 v138, 16, v134
	v_and_b32_e32 v139, 0xffff0000, v134
	v_lshlrev_b32_e32 v134, 16, v135
	v_and_b32_e32 v135, 0xffff0000, v135
	v_lshl_add_u64 v[136:137], v[136:137], 0, v[192:193]
	v_pk_mul_f32 v[126:127], v[126:127], v[134:135]
	s_and_b64 vcc, exec, s[36:37]
	v_pk_mul_f32 v[124:125], v[124:125], v[138:139]
	s_cbranch_vccnz .LBB0_927
	v_cvt_pk_bf16_f32 v134, v124, v125
	v_cvt_pk_bf16_f32 v135, v126, v127
	global_store_dwordx4 v[136:137], v[132:135], off

; __device__ __forceinline__ unsigned cvt_pk_bf16(float lo, float hi) { typedef float f2 __attribute__((ext_vector_type(2))); typedef __bf16 b2 __attribute__((ext_vector_type(2))); f2 v = {lo, hi}; b2 b = __builtin_convertvector(v, b2); return __builtin_bit_cast(unsigned, b); }
;     __device__ __forceinline__ void operator()(f32x4 (&acc)[2][2][4][2], const Unit& u, int wr, int wc, int fr, int fq) const {
;     ...
;                 for (int bj = 0; bj < 2; ++bj) { const u32x4 gw = gwv[ai][m][bj]; u32x4 w = {0u, 0u, 0u, 0u};
; #pragma unroll
;                     for (int n = 0; n < 2; ++n) { const unsigned lo = gw[2 * n], hi_ = gw[2 * n + 1];
;                         f32x4 g; g[0] = __uint_as_float(lo << 16); g[1] = __uint_as_float(lo & 0xffff0000u); g[2] = __uint_as_float(hi_ << 16); g[3] = __uint_as_float(hi_ & 0xffff0000u);
;                         const f32x4 v = acc[ai][bj][m][n] * g; acc[ai][bj][m][n] = v;
;                         if (i == 3) { w[2 * n] = cvt_pk_bf16(v[0], v[1]); w[2 * n + 1] = cvt_pk_bf16(v[2], v[3]); } }
;                     if (i == 3) *(u32x4*)(brow + bj * HALF) = w; } }
.LBB0_929:
	v_lshlrev_b32_e32 v132, 16, v130
	v_and_b32_e32 v133, 0xffff0000, v130
	v_lshlrev_b32_e32 v130, 16, v131
	v_and_b32_e32 v131, 0xffff0000, v131
	v_pk_mul_f32 v[118:119], v[118:119], v[130:131]
	s_and_b64 vcc, exec, s[36:37]
	v_pk_mul_f32 v[116:117], v[116:117], v[132:133]
	s_cbranch_vccnz .LBB0_931
	v_cvt_pk_bf16_f32 v130, v116, v117
	v_cvt_pk_bf16_f32 v131, v118, v119
	global_store_dwordx4 v[136:137], v[128:131], off offset:256

; __device__ __forceinline__ unsigned cvt_pk_bf16(float lo, float hi) { typedef float f2 __attribute__((ext_vector_type(2))); typedef __bf16 b2 __attribute__((ext_vector_type(2))); f2 v = {lo, hi}; b2 b = __builtin_convertvector(v, b2); return __builtin_bit_cast(unsigned, b); }
;     __device__ __forceinline__ void operator()(const f32x4 (&acc)[2][2][4][2], const Unit& u, int wr, int wc, int fr, int fq) const {
;         const int row0 = u.pm * BM + wr * 64 + fr; const int col0 = u.pn * BM + wc * 32 + 8 * fq;
;         u32x4 owv[2][4][2];
; #pragma unroll
;         for (int ai = 0; ai < 2; ++ai)
; #pragma unroll
;             for (int m = 0; m < 4; ++m) { const bf16_t* xp = xr + (size_t)(row0 + ai * HALF + m * 16) * 1024 + col0;
; #pragma unroll
;                 for (int bj = 0; bj < 2; ++bj) owv[ai][m][bj] = *(const u32x4*)(xp + bj * HALF); }
; #pragma unroll
;         for (int ai = 0; ai < 2; ++ai)
; #pragma unroll
;             for (int m = 0; m < 4; ++m) { const int row = row0 + ai * HALF + m * 16; bf16_t* xp = xr + (size_t)row * 1024 + col0; float sq = 0.f;
; #pragma unroll
;                 for (int bj = 0; bj < 2; ++bj) { const u32x4 ow = owv[ai][m][bj]; u32x4 w;
; #pragma unroll
;                     for (int n = 0; n < 2; ++n) { f32x4 v = acc[ai][bj][m][n]; const unsigned lo = ow[2 * n], hi_ = ow[2 * n + 1];
;                         v[0] += __uint_as_float(lo << 16); v[1] += __uint_as_float(lo & 0xffff0000u); v[2] += __uint_as_float(hi_ << 16); v[3] += __uint_as_float(hi_ & 0xffff0000u);
;                         sq += (v[0] * v[0] + v[1] * v[1]) + (v[2] * v[2] + v[3] * v[3]);
;                         w[2 * n] = cvt_pk_bf16(v[0], v[1]); w[2 * n + 1] = cvt_pk_bf16(v[2], v[3]); }
;                     *(u32x4*)(xp + bj * HALF) = w; }
;                 sq += __shfl_xor(sq, 16); sq += __shfl_xor(sq, 32);
;                 if (fq == 0) ssq[(size_t)row * 16 + u.pn * 4 + wc] = sq; }
.LBB0_1008:
	v_lshl_or_b32 v204, s44, 8, v241
	v_lshl_add_u32 v232, s46, 8, v249
	v_ashrrev_i32_e32 v205, 31, v204
	v_lshlrev_b64 v[236:237], 1, v[204:205]
	v_ashrrev_i32_e32 v233, 31, v232
	v_lshl_add_u64 v[100:101], s[12:13], 0, v[236:237]
	v_lshlrev_b64 v[238:239], 11, v[232:233]
	v_lshl_add_u64 v[102:103], v[100:101], 0, v[238:239]
	global_load_dwordx4 v[188:191], v[102:103], off
	global_load_dwordx4 v[184:187], v[102:103], off offset:256
	v_or_b32_e32 v228, 16, v232
	v_ashrrev_i32_e32 v229, 31, v228
	v_or_b32_e32 v224, 32, v232
	v_lshlrev_b64 v[234:235], 11, v[228:229]
	v_ashrrev_i32_e32 v225, 31, v224
	v_or_b32_e32 v220, 48, v232
	v_lshl_add_u64 v[102:103], v[100:101], 0, v[234:235]
	v_lshlrev_b64 v[230:231], 11, v[224:225]
	v_ashrrev_i32_e32 v221, 31, v220
	v_add_u32_e32 v216, 0x80, v232
	global_load_dwordx4 v[180:183], v[102:103], off
	global_load_dwordx4 v[176:179], v[102:103], off offset:256
	v_lshl_add_u64 v[102:103], v[100:101], 0, v[230:231]
	v_lshlrev_b64 v[226:227], 11, v[220:221]
	v_ashrrev_i32_e32 v217, 31, v216
	v_add_u32_e32 v212, 0x90, v232
	global_load_dwordx4 v[172:175], v[102:103], off
	global_load_dwordx4 v[168:171], v[102:103], off offset:256
	v_lshl_add_u64 v[102:103], v[100:101], 0, v[226:227]
	v_lshlrev_b64 v[222:223], 11, v[216:217]
	v_ashrrev_i32_e32 v213, 31, v212
	v_add_u32_e32 v208, 0xa0, v232
	v_add_u32_e32 v206, 0xb0, v232
	global_load_dwordx4 v[164:167], v[102:103], off
	global_load_dwordx4 v[160:163], v[102:103], off offset:256
	v_lshl_add_u64 v[102:103], v[100:101], 0, v[222:223]
	v_lshlrev_b64 v[218:219], 11, v[212:213]
	v_ashrrev_i32_e32 v209, 31, v208
	v_ashrrev_i32_e32 v207, 31, v206
	global_load_dwordx4 v[156:159], v[102:103], off
	global_load_dwordx4 v[144:147], v[102:103], off offset:256
	v_lshl_add_u64 v[102:103], v[100:101], 0, v[218:219]
	v_lshlrev_b64 v[214:215], 11, v[208:209]
	v_lshlrev_b64 v[210:211], 11, v[206:207]
	global_load_dwordx4 v[136:139], v[102:103], off
	global_load_dwordx4 v[128:131], v[102:103], off offset:256
	v_lshl_add_u64 v[102:103], v[100:101], 0, v[214:215]
	v_lshl_add_u64 v[100:101], v[100:101], 0, v[210:211]
	global_load_dwordx4 v[116:119], v[102:103], off
	global_load_dwordx4 v[108:111], v[102:103], off offset:256
	global_load_dwordx4 v[112:115], v[100:101], off
	s_nop 0
	global_load_dwordx4 v[100:103], v[100:101], off offset:256
	v_lshl_add_u64 v[238:239], s[12:13], 0, v[238:239]
	v_lshl_add_u64 v[236:237], v[238:239], 0, v[236:237]
	v_cmp_lt_i32_e32 vcc, v247, v245
	s_lshl_b32 s44, s44, 2
	s_ashr_i32 s45, s44, 31
	v_cndmask_b32_e32 v246, v244, v247, vcc
	v_cmp_lt_i32_e32 vcc, v250, v245
	v_lshlrev_b32_e32 v246, 2, v246
	s_waitcnt vmcnt(0) lgkmcnt(0)
	v_lshlrev_b32_e32 v238, 16, v188
	v_and_b32_e32 v239, 0xffff0000, v188
	v_lshlrev_b32_e32 v188, 16, v189
	v_and_b32_e32 v189, 0xffff0000, v189
	v_pk_add_f32 v[152:153], v[152:153], v[238:239]
	v_pk_add_f32 v[154:155], v[154:155], v[188:189]
	v_pk_mul_f32 v[188:189], v[152:153], v[152:153]
	v_pk_mul_f32 v[238:239], v[154:155], v[154:155]
	v_cvt_pk_bf16_f32 v152, v152, v153
	v_cvt_pk_bf16_f32 v153, v154, v155
	v_lshlrev_b32_e32 v154, 16, v190
	v_and_b32_e32 v155, 0xffff0000, v190
	v_pk_add_f32 v[148:149], v[148:149], v[154:155]
	v_lshlrev_b32_e32 v154, 16, v191
	v_and_b32_e32 v155, 0xffff0000, v191
	v_pk_add_f32 v[150:151], v[150:151], v[154:155]
	v_pk_mul_f32 v[190:191], v[148:149], v[148:149]
	v_cvt_pk_bf16_f32 v154, v148, v149
	v_lshlrev_b32_e32 v148, 16, v184
	v_and_b32_e32 v149, 0xffff0000, v184
	v_pk_add_f32 v[140:141], v[140:141], v[148:149]
	v_lshlrev_b32_e32 v148, 16, v185
	v_and_b32_e32 v149, 0xffff0000, v185
	v_pk_add_f32 v[142:143], v[142:143], v[148:149]
	v_cndmask_b32_e32 v248, v244, v250, vcc
	v_pk_mul_f32 v[250:251], v[150:151], v[150:151]
	v_cvt_pk_bf16_f32 v155, v150, v151
	v_pk_mul_f32 v[148:149], v[140:141], v[140:141]
	v_pk_mul_f32 v[150:151], v[142:143], v[142:143]
	v_cvt_pk_bf16_f32 v140, v140, v141
	v_cvt_pk_bf16_f32 v141, v142, v143
	v_lshlrev_b32_e32 v142, 16, v186
	v_and_b32_e32 v143, 0xffff0000, v186
	global_store_dwordx4 v[236:237], v[152:155], off
	v_pk_add_f32 v[132:133], v[132:133], v[142:143]
	v_lshlrev_b32_e32 v142, 16, v187
	v_and_b32_e32 v143, 0xffff0000, v187
	v_add_f32_e32 v154, v250, v251
	v_add_f32_e32 v155, v190, v191
	v_pk_add_f32 v[134:135], v[134:135], v[142:143]
	v_add_f32_e32 v154, v155, v154
	v_add_f32_e32 v155, v238, v239
	v_add_f32_e32 v184, v188, v189
	v_pk_mul_f32 v[142:143], v[132:133], v[132:133]
	v_pk_mul_f32 v[152:153], v[134:135], v[134:135]
	v_add_f32_e32 v155, v184, v155
	v_add_f32_e32 v150, v150, v151
	v_add_f32_e32 v148, v148, v149
	v_add_f32_e32 v154, v155, v154
	v_add_f32_e32 v148, v148, v150
	v_add_f32_e32 v149, v152, v153
	v_add_f32_e32 v142, v142, v143
	v_add_f32_e32 v148, v154, v148
	v_add_f32_e32 v142, v142, v149
	v_add_f32_e32 v148, v142, v148
	v_cvt_pk_bf16_f32 v142, v132, v133
	ds_bpermute_b32 v132, v246, v148
	v_lshlrev_b32_e32 v248, 2, v248
	v_cvt_pk_bf16_f32 v143, v134, v135
	global_store_dwordx4 v[236:237], v[140:143], off offset:256
	s_waitcnt lgkmcnt(0)
	v_add_f32_e32 v132, v148, v132
	ds_bpermute_b32 v133, v248, v132
	s_and_saveexec_b64 s[8:9], s[38:39]
	s_cbranch_execz .LBB0_1010
	s_waitcnt lgkmcnt(0)
	v_add_f32_e32 v134, v132, v133
	v_lshlrev_b64 v[132:133], 6, v[232:233]
	v_lshl_add_u64 v[132:133], s[20:21], 0, v[132:133]
	v_lshl_add_u64 v[132:133], s[44:45], 2, v[132:133]
	s_lshl_b32 s16, s60, 2
	v_lshl_add_u64 v[132:133], v[132:133], 0, s[16:17]
	global_store_dword v[132:133], v134, off
; __device__ __forceinline__ unsigned cvt_pk_bf16(float lo, float hi) { typedef float f2 __attribute__((ext_vector_type(2))); typedef __bf16 b2 __attribute__((ext_vector_type(2))); f2 v = {lo, hi}; b2 b = __builtin_convertvector(v, b2); return __builtin_bit_cast(unsigned, b); }
;     __device__ __forceinline__ void operator()(const f32x4 (&acc)[2][2][4][2], const Unit& u, int wr, int wc, int fr, int fq) const {
;     ...
;         for (int ai = 0; ai < 2; ++ai)
; #pragma unroll
;             for (int m = 0; m < 4; ++m) { const int row = row0 + ai * HALF + m * 16; bf16_t* xp = xr + (size_t)row * 1024 + col0; float sq = 0.f;
; #pragma unroll
;                 for (int bj = 0; bj < 2; ++bj) { const u32x4 ow = owv[ai][m][bj]; u32x4 w;
; #pragma unroll
;                     for (int n = 0; n < 2; ++n) { f32x4 v = acc[ai][bj][m][n]; const unsigned lo = ow[2 * n], hi_ = ow[2 * n + 1];
;                         v[0] += __uint_as_float(lo << 16); v[1] += __uint_as_float(lo & 0xffff0000u); v[2] += __uint_as_float(hi_ << 16); v[3] += __uint_as_float(hi_ & 0xffff0000u);
;                         sq += (v[0] * v[0] + v[1] * v[1]) + (v[2] * v[2] + v[3] * v[3]);
;                         w[2 * n] = cvt_pk_bf16(v[0], v[1]); w[2 * n + 1] = cvt_pk_bf16(v[2], v[3]); }
;                     *(u32x4*)(xp + bj * HALF) = w; }
;                 sq += __shfl_xor(sq, 16); sq += __shfl_xor(sq, 32);
;                 if (fq == 0) ssq[(size_t)row * 16 + u.pn * 4 + wc] = sq; }
.LBB0_1010:
	s_or_b64 exec, exec, s[8:9]
	v_lshlrev_b32_e32 v134, 16, v180
	v_and_b32_e32 v135, 0xffff0000, v180
	v_pk_add_f32 v[124:125], v[124:125], v[134:135]
	v_lshlrev_b32_e32 v134, 16, v181
	v_and_b32_e32 v135, 0xffff0000, v181
	v_pk_add_f32 v[126:127], v[126:127], v[134:135]
	v_pk_mul_f32 v[134:135], v[124:125], v[124:125]
	v_pk_mul_f32 v[140:141], v[126:127], v[126:127]
	v_cvt_pk_bf16_f32 v124, v124, v125
	v_cvt_pk_bf16_f32 v125, v126, v127
	v_lshlrev_b32_e32 v126, 16, v182
	v_and_b32_e32 v127, 0xffff0000, v182
	v_pk_add_f32 v[120:121], v[120:121], v[126:127]
	v_lshlrev_b32_e32 v126, 16, v183
	v_and_b32_e32 v127, 0xffff0000, v183
	v_pk_add_f32 v[122:123], v[122:123], v[126:127]
	v_pk_mul_f32 v[142:143], v[120:121], v[120:121]
	v_cvt_pk_bf16_f32 v126, v120, v121
	v_lshlrev_b32_e32 v120, 16, v176
	v_and_b32_e32 v121, 0xffff0000, v176
	v_pk_add_f32 v[104:105], v[104:105], v[120:121]
	v_lshlrev_b32_e32 v120, 16, v177
	v_and_b32_e32 v121, 0xffff0000, v177
	s_waitcnt lgkmcnt(0)
	v_lshl_add_u64 v[132:133], s[12:13], 0, v[234:235]
	v_pk_add_f32 v[106:107], v[106:107], v[120:121]
	v_lshl_add_u64 v[132:133], v[204:205], 1, v[132:133]
	v_pk_mul_f32 v[148:149], v[122:123], v[122:123]
	v_cvt_pk_bf16_f32 v127, v122, v123
	v_pk_mul_f32 v[120:121], v[104:105], v[104:105]
	v_pk_mul_f32 v[122:123], v[106:107], v[106:107]
	v_cvt_pk_bf16_f32 v104, v104, v105
	v_cvt_pk_bf16_f32 v105, v106, v107
	v_lshlrev_b32_e32 v106, 16, v178
	v_and_b32_e32 v107, 0xffff0000, v178
	global_store_dwordx4 v[132:133], v[124:127], off
	v_pk_add_f32 v[96:97], v[96:97], v[106:107]
	v_lshlrev_b32_e32 v106, 16, v179
	v_and_b32_e32 v107, 0xffff0000, v179
	v_add_f32_e32 v126, v148, v149
	v_add_f32_e32 v127, v142, v143
	v_pk_add_f32 v[98:99], v[98:99], v[106:107]
	v_add_f32_e32 v126, v127, v126
	v_add_f32_e32 v127, v140, v141
	v_add_f32_e32 v134, v134, v135
	v_pk_mul_f32 v[106:107], v[96:97], v[96:97]
	v_pk_mul_f32 v[124:125], v[98:99], v[98:99]
	v_add_f32_e32 v127, v134, v127
	v_add_f32_e32 v122, v122, v123
	v_add_f32_e32 v120, v120, v121
	v_add_f32_e32 v126, v127, v126
	v_add_f32_e32 v120, v120, v122
	v_add_f32_e32 v121, v124, v125
	v_add_f32_e32 v106, v106, v107
	v_add_f32_e32 v120, v126, v120
	v_add_f32_e32 v106, v106, v121
	v_add_f32_e32 v120, v106, v120
	v_cvt_pk_bf16_f32 v106, v96, v97
	ds_bpermute_b32 v96, v246, v120
	v_cvt_pk_bf16_f32 v107, v98, v99
	global_store_dwordx4 v[132:133], v[104:107], off offset:256
	s_waitcnt lgkmcnt(0)
	v_add_f32_e32 v96, v120, v96
	ds_bpermute_b32 v97, v248, v96
	s_and_saveexec_b64 s[8:9], s[38:39]
	s_cbranch_execz .LBB0_1012
	s_waitcnt lgkmcnt(0)
	v_add_f32_e32 v98, v96, v97
	v_lshlrev_b64 v[96:97], 6, v[228:229]
	v_lshl_add_u64 v[96:97], s[20:21], 0, v[96:97]
	v_lshl_add_u64 v[96:97], s[44:45], 2, v[96:97]
	s_lshl_b32 s16, s60, 2
	v_lshl_add_u64 v[96:97], v[96:97], 0, s[16:17]
	global_store_dword v[96:97], v98, off
.LBB0_1012:
	s_or_b64 exec, exec, s[8:9]
	v_lshlrev_b32_e32 v98, 16, v172
	v_and_b32_e32 v99, 0xffff0000, v172
	v_pk_add_f32 v[92:93], v[92:93], v[98:99]
	v_lshlrev_b32_e32 v98, 16, v173
	v_and_b32_e32 v99, 0xffff0000, v173
	v_pk_add_f32 v[94:95], v[94:95], v[98:99]
	v_pk_mul_f32 v[98:99], v[92:93], v[92:93]
	v_pk_mul_f32 v[104:105], v[94:95], v[94:95]
	v_cvt_pk_bf16_f32 v92, v92, v93
	v_cvt_pk_bf16_f32 v93, v94, v95
	v_lshlrev_b32_e32 v94, 16, v174
	v_and_b32_e32 v95, 0xffff0000, v174
	v_pk_add_f32 v[88:89], v[88:89], v[94:95]
	v_lshlrev_b32_e32 v94, 16, v175
	v_and_b32_e32 v95, 0xffff0000, v175
	v_pk_add_f32 v[90:91], v[90:91], v[94:95]
	v_pk_mul_f32 v[106:107], v[88:89], v[88:89]
	v_cvt_pk_bf16_f32 v94, v88, v89
	v_lshlrev_b32_e32 v88, 16, v168
	v_and_b32_e32 v89, 0xffff0000, v168
	v_pk_add_f32 v[84:85], v[84:85], v[88:89]
	v_lshlrev_b32_e32 v88, 16, v169
	v_and_b32_e32 v89, 0xffff0000, v169
	s_waitcnt lgkmcnt(0)
	v_lshl_add_u64 v[96:97], s[12:13], 0, v[230:231]
	v_pk_add_f32 v[86:87], v[86:87], v[88:89]
	v_lshl_add_u64 v[96:97], v[204:205], 1, v[96:97]
	v_pk_mul_f32 v[120:121], v[90:91], v[90:91]
	v_cvt_pk_bf16_f32 v95, v90, v91
	v_pk_mul_f32 v[88:89], v[84:85], v[84:85]
	v_pk_mul_f32 v[90:91], v[86:87], v[86:87]
	v_cvt_pk_bf16_f32 v84, v84, v85
	v_cvt_pk_bf16_f32 v85, v86, v87
	v_lshlrev_b32_e32 v86, 16, v170
	v_and_b32_e32 v87, 0xffff0000, v170
	global_store_dwordx4 v[96:97], v[92:95], off
	v_pk_add_f32 v[80:81], v[80:81], v[86:87]
	v_lshlrev_b32_e32 v86, 16, v171
	v_and_b32_e32 v87, 0xffff0000, v171
	v_add_f32_e32 v94, v120, v121
	v_add_f32_e32 v95, v106, v107
	v_pk_add_f32 v[82:83], v[82:83], v[86:87]
	v_add_f32_e32 v94, v95, v94
	v_add_f32_e32 v95, v104, v105
	v_add_f32_e32 v98, v98, v99
	v_pk_mul_f32 v[86:87], v[80:81], v[80:81]
	v_pk_mul_f32 v[92:93], v[82:83], v[82:83]
	v_add_f32_e32 v95, v98, v95
	v_add_f32_e32 v90, v90, v91
	v_add_f32_e32 v88, v88, v89
	v_add_f32_e32 v94, v95, v94
	v_add_f32_e32 v88, v88, v90
	v_add_f32_e32 v89, v92, v93
	v_add_f32_e32 v86, v86, v87
	v_add_f32_e32 v88, v94, v88
	v_add_f32_e32 v86, v86, v89
	v_add_f32_e32 v88, v86, v88
	v_cvt_pk_bf16_f32 v86, v80, v81
	ds_bpermute_b32 v80, v246, v88
	v_cvt_pk_bf16_f32 v87, v82, v83
	global_store_dwordx4 v[96:97], v[84:87], off offset:256
	s_waitcnt lgkmcnt(0)
	v_add_f32_e32 v80, v88, v80
	ds_bpermute_b32 v81, v248, v80
	s_mov_b64 s[8:9], exec
	s_and_b64 s[48:49], s[8:9], s[38:39]
	v_xor_b32_e32 v250, 32, v244
	s_mov_b64 exec, s[48:49]
	s_cbranch_execz .LBB0_1014
	s_waitcnt lgkmcnt(0)
	v_add_f32_e32 v82, v80, v81
	v_lshlrev_b64 v[80:81], 6, v[224:225]
	v_lshl_add_u64 v[80:81], s[20:21], 0, v[80:81]
	v_lshl_add_u64 v[80:81], s[44:45], 2, v[80:81]
	s_lshl_b32 s16, s60, 2
	v_lshl_add_u64 v[80:81], v[80:81], 0, s[16:17]
	global_store_dword v[80:81], v82, off
; __device__ __forceinline__ unsigned cvt_pk_bf16(float lo, float hi) { typedef float f2 __attribute__((ext_vector_type(2))); typedef __bf16 b2 __attribute__((ext_vector_type(2))); f2 v = {lo, hi}; b2 b = __builtin_convertvector(v, b2); return __builtin_bit_cast(unsigned, b); }
;     __device__ __forceinline__ void operator()(const f32x4 (&acc)[2][2][4][2], const Unit& u, int wr, int wc, int fr, int fq) const {
;     ...
;         for (int ai = 0; ai < 2; ++ai)
; #pragma unroll
;             for (int m = 0; m < 4; ++m) { const int row = row0 + ai * HALF + m * 16; bf16_t* xp = xr + (size_t)row * 1024 + col0; float sq = 0.f;
; #pragma unroll
;                 for (int bj = 0; bj < 2; ++bj) { const u32x4 ow = owv[ai][m][bj]; u32x4 w;
; #pragma unroll
;                     for (int n = 0; n < 2; ++n) { f32x4 v = acc[ai][bj][m][n]; const unsigned lo = ow[2 * n], hi_ = ow[2 * n + 1];
;                         v[0] += __uint_as_float(lo << 16); v[1] += __uint_as_float(lo & 0xffff0000u); v[2] += __uint_as_float(hi_ << 16); v[3] += __uint_as_float(hi_ & 0xffff0000u);
;                         sq += (v[0] * v[0] + v[1] * v[1]) + (v[2] * v[2] + v[3] * v[3]);
;                         w[2 * n] = cvt_pk_bf16(v[0], v[1]); w[2 * n + 1] = cvt_pk_bf16(v[2], v[3]); }
;                     *(u32x4*)(xp + bj * HALF) = w; }
;                 sq += __shfl_xor(sq, 16); sq += __shfl_xor(sq, 32);
;                 if (fq == 0) ssq[(size_t)row * 16 + u.pn * 4 + wc] = sq; }
.LBB0_1014:
	s_or_b64 exec, exec, s[8:9]
	v_lshlrev_b32_e32 v82, 16, v164
	v_and_b32_e32 v83, 0xffff0000, v164
	v_pk_add_f32 v[76:77], v[76:77], v[82:83]
	v_lshlrev_b32_e32 v82, 16, v165
	v_and_b32_e32 v83, 0xffff0000, v165
	v_pk_add_f32 v[78:79], v[78:79], v[82:83]
	v_pk_mul_f32 v[82:83], v[76:77], v[76:77]
	v_pk_mul_f32 v[84:85], v[78:79], v[78:79]
	v_cvt_pk_bf16_f32 v76, v76, v77
	v_cvt_pk_bf16_f32 v77, v78, v79
	v_lshlrev_b32_e32 v78, 16, v166
	v_and_b32_e32 v79, 0xffff0000, v166
	v_pk_add_f32 v[72:73], v[72:73], v[78:79]
	v_lshlrev_b32_e32 v78, 16, v167
	v_and_b32_e32 v79, 0xffff0000, v167
	v_pk_add_f32 v[74:75], v[74:75], v[78:79]
	v_pk_mul_f32 v[86:87], v[72:73], v[72:73]
	v_cvt_pk_bf16_f32 v78, v72, v73
	v_lshlrev_b32_e32 v72, 16, v160
	v_and_b32_e32 v73, 0xffff0000, v160
	v_pk_add_f32 v[68:69], v[68:69], v[72:73]
	v_lshlrev_b32_e32 v72, 16, v161
	v_and_b32_e32 v73, 0xffff0000, v161
	s_waitcnt lgkmcnt(0)
	v_lshl_add_u64 v[80:81], s[12:13], 0, v[226:227]
	v_pk_add_f32 v[70:71], v[70:71], v[72:73]
	v_lshl_add_u64 v[80:81], v[204:205], 1, v[80:81]
	v_pk_mul_f32 v[88:89], v[74:75], v[74:75]
	v_cvt_pk_bf16_f32 v79, v74, v75
	v_pk_mul_f32 v[72:73], v[68:69], v[68:69]
	v_pk_mul_f32 v[74:75], v[70:71], v[70:71]
	v_cvt_pk_bf16_f32 v68, v68, v69
	v_cvt_pk_bf16_f32 v69, v70, v71
	v_lshlrev_b32_e32 v70, 16, v162
	v_and_b32_e32 v71, 0xffff0000, v162
	global_store_dwordx4 v[80:81], v[76:79], off
	v_pk_add_f32 v[64:65], v[64:65], v[70:71]
	v_lshlrev_b32_e32 v70, 16, v163
	v_and_b32_e32 v71, 0xffff0000, v163
	v_add_f32_e32 v78, v88, v89
	v_add_f32_e32 v79, v86, v87
	v_pk_add_f32 v[66:67], v[66:67], v[70:71]
	v_add_f32_e32 v78, v79, v78
	v_add_f32_e32 v79, v84, v85
	v_add_f32_e32 v82, v82, v83
	v_pk_mul_f32 v[70:71], v[64:65], v[64:65]
	v_pk_mul_f32 v[76:77], v[66:67], v[66:67]
	v_add_f32_e32 v79, v82, v79
	v_add_f32_e32 v74, v74, v75
	v_add_f32_e32 v72, v72, v73
	v_add_f32_e32 v78, v79, v78
	v_add_f32_e32 v72, v72, v74
	v_add_f32_e32 v73, v76, v77
	v_add_f32_e32 v70, v70, v71
	v_add_f32_e32 v72, v78, v72
	v_add_f32_e32 v70, v70, v73
	v_add_f32_e32 v72, v70, v72
	v_cvt_pk_bf16_f32 v70, v64, v65
	ds_bpermute_b32 v64, v246, v72
	v_cvt_pk_bf16_f32 v71, v66, v67
	global_store_dwordx4 v[80:81], v[68:71], off offset:256
	s_waitcnt lgkmcnt(0)
	v_add_f32_e32 v64, v72, v64
	ds_bpermute_b32 v65, v248, v64
	s_and_saveexec_b64 s[8:9], s[38:39]
	s_cbranch_execz .LBB0_1016
	s_waitcnt lgkmcnt(0)
	v_add_f32_e32 v66, v64, v65
	v_lshlrev_b64 v[64:65], 6, v[220:221]
	v_lshl_add_u64 v[64:65], s[20:21], 0, v[64:65]
	v_lshl_add_u64 v[64:65], s[44:45], 2, v[64:65]
	s_lshl_b32 s16, s60, 2
	v_lshl_add_u64 v[64:65], v[64:65], 0, s[16:17]
	global_store_dword v[64:65], v66, off
.LBB0_1016:
	s_or_b64 exec, exec, s[8:9]
	v_lshlrev_b32_e32 v66, 16, v156
	v_and_b32_e32 v67, 0xffff0000, v156
	v_pk_add_f32 v[60:61], v[60:61], v[66:67]
	v_lshlrev_b32_e32 v66, 16, v157
	v_and_b32_e32 v67, 0xffff0000, v157
	v_pk_add_f32 v[62:63], v[62:63], v[66:67]
	v_pk_mul_f32 v[66:67], v[60:61], v[60:61]
	v_pk_mul_f32 v[68:69], v[62:63], v[62:63]
	v_cvt_pk_bf16_f32 v60, v60, v61
	v_cvt_pk_bf16_f32 v61, v62, v63
	v_lshlrev_b32_e32 v62, 16, v158
	v_and_b32_e32 v63, 0xffff0000, v158
	v_pk_add_f32 v[56:57], v[56:57], v[62:63]
	v_lshlrev_b32_e32 v62, 16, v159
	v_and_b32_e32 v63, 0xffff0000, v159
	v_pk_add_f32 v[58:59], v[58:59], v[62:63]
	v_pk_mul_f32 v[70:71], v[56:57], v[56:57]
	v_cvt_pk_bf16_f32 v62, v56, v57
	v_lshlrev_b32_e32 v56, 16, v144
	v_and_b32_e32 v57, 0xffff0000, v144
	v_pk_add_f32 v[52:53], v[52:53], v[56:57]
	v_lshlrev_b32_e32 v56, 16, v145
	v_and_b32_e32 v57, 0xffff0000, v145
	s_waitcnt lgkmcnt(0)
	v_lshl_add_u64 v[64:65], s[12:13], 0, v[222:223]
	v_pk_add_f32 v[54:55], v[54:55], v[56:57]
	v_lshl_add_u64 v[64:65], v[204:205], 1, v[64:65]
	v_pk_mul_f32 v[72:73], v[58:59], v[58:59]
	v_cvt_pk_bf16_f32 v63, v58, v59
	v_pk_mul_f32 v[56:57], v[52:53], v[52:53]
	v_pk_mul_f32 v[58:59], v[54:55], v[54:55]
	v_cvt_pk_bf16_f32 v52, v52, v53
	v_cvt_pk_bf16_f32 v53, v54, v55
	v_lshlrev_b32_e32 v54, 16, v146
	v_and_b32_e32 v55, 0xffff0000, v146
	global_store_dwordx4 v[64:65], v[60:63], off
	v_pk_add_f32 v[48:49], v[48:49], v[54:55]
	v_lshlrev_b32_e32 v54, 16, v147
	v_and_b32_e32 v55, 0xffff0000, v147
	v_add_f32_e32 v62, v72, v73
	v_add_f32_e32 v63, v70, v71
	v_pk_add_f32 v[50:51], v[50:51], v[54:55]
	v_add_f32_e32 v62, v63, v62
	v_add_f32_e32 v63, v68, v69
	v_add_f32_e32 v66, v66, v67
	v_pk_mul_f32 v[54:55], v[48:49], v[48:49]
	v_pk_mul_f32 v[60:61], v[50:51], v[50:51]
	v_add_f32_e32 v63, v66, v63
	v_add_f32_e32 v58, v58, v59
	v_add_f32_e32 v56, v56, v57
	v_add_f32_e32 v62, v63, v62
	v_add_f32_e32 v56, v56, v58
	v_add_f32_e32 v57, v60, v61
	v_add_f32_e32 v54, v54, v55
	v_add_f32_e32 v56, v62, v56
	v_add_f32_e32 v54, v54, v57
	v_add_f32_e32 v56, v54, v56
	v_cvt_pk_bf16_f32 v54, v48, v49
	ds_bpermute_b32 v48, v246, v56
	v_cvt_pk_bf16_f32 v55, v50, v51
	global_store_dwordx4 v[64:65], v[52:55], off offset:256
	s_waitcnt lgkmcnt(0)
	v_add_f32_e32 v48, v56, v48
	ds_bpermute_b32 v49, v248, v48
	s_and_saveexec_b64 s[8:9], s[38:39]
	s_cbranch_execz .LBB0_1018
	s_waitcnt lgkmcnt(0)
	v_add_f32_e32 v50, v48, v49
	v_lshlrev_b64 v[48:49], 6, v[216:217]
	v_lshl_add_u64 v[48:49], s[20:21], 0, v[48:49]
	v_lshl_add_u64 v[48:49], s[44:45], 2, v[48:49]
	s_lshl_b32 s16, s60, 2
	v_lshl_add_u64 v[48:49], v[48:49], 0, s[16:17]
	global_store_dword v[48:49], v50, off
; __device__ __forceinline__ unsigned cvt_pk_bf16(float lo, float hi) { typedef float f2 __attribute__((ext_vector_type(2))); typedef __bf16 b2 __attribute__((ext_vector_type(2))); f2 v = {lo, hi}; b2 b = __builtin_convertvector(v, b2); return __builtin_bit_cast(unsigned, b); }
;     __device__ __forceinline__ void operator()(const f32x4 (&acc)[2][2][4][2], const Unit& u, int wr, int wc, int fr, int fq) const {
;     ...
;         for (int ai = 0; ai < 2; ++ai)
; #pragma unroll
;             for (int m = 0; m < 4; ++m) { const int row = row0 + ai * HALF + m * 16; bf16_t* xp = xr + (size_t)row * 1024 + col0; float sq = 0.f;
; #pragma unroll
;                 for (int bj = 0; bj < 2; ++bj) { const u32x4 ow = owv[ai][m][bj]; u32x4 w;
; #pragma unroll
;                     for (int n = 0; n < 2; ++n) { f32x4 v = acc[ai][bj][m][n]; const unsigned lo = ow[2 * n], hi_ = ow[2 * n + 1];
;                         v[0] += __uint_as_float(lo << 16); v[1] += __uint_as_float(lo & 0xffff0000u); v[2] += __uint_as_float(hi_ << 16); v[3] += __uint_as_float(hi_ & 0xffff0000u);
;                         sq += (v[0] * v[0] + v[1] * v[1]) + (v[2] * v[2] + v[3] * v[3]);
;                         w[2 * n] = cvt_pk_bf16(v[0], v[1]); w[2 * n + 1] = cvt_pk_bf16(v[2], v[3]); }
;                     *(u32x4*)(xp + bj * HALF) = w; }
;                 sq += __shfl_xor(sq, 16); sq += __shfl_xor(sq, 32);
;                 if (fq == 0) ssq[(size_t)row * 16 + u.pn * 4 + wc] = sq; }
.LBB0_1018:
	s_or_b64 exec, exec, s[8:9]
	v_lshlrev_b32_e32 v50, 16, v136
	v_and_b32_e32 v51, 0xffff0000, v136
	v_pk_add_f32 v[44:45], v[44:45], v[50:51]
	v_lshlrev_b32_e32 v50, 16, v137
	v_and_b32_e32 v51, 0xffff0000, v137
	v_pk_add_f32 v[46:47], v[46:47], v[50:51]
	v_pk_mul_f32 v[50:51], v[44:45], v[44:45]
	v_pk_mul_f32 v[52:53], v[46:47], v[46:47]
	v_cvt_pk_bf16_f32 v44, v44, v45
	v_cvt_pk_bf16_f32 v45, v46, v47
	v_lshlrev_b32_e32 v46, 16, v138
	v_and_b32_e32 v47, 0xffff0000, v138
	v_pk_add_f32 v[40:41], v[40:41], v[46:47]
	v_lshlrev_b32_e32 v46, 16, v139
	v_and_b32_e32 v47, 0xffff0000, v139
	v_pk_add_f32 v[42:43], v[42:43], v[46:47]
	v_pk_mul_f32 v[54:55], v[40:41], v[40:41]
	v_cvt_pk_bf16_f32 v46, v40, v41
	v_lshlrev_b32_e32 v40, 16, v128
	v_and_b32_e32 v41, 0xffff0000, v128
	v_pk_add_f32 v[36:37], v[36:37], v[40:41]
	v_lshlrev_b32_e32 v40, 16, v129
	v_and_b32_e32 v41, 0xffff0000, v129
	s_waitcnt lgkmcnt(0)
	v_lshl_add_u64 v[48:49], s[12:13], 0, v[218:219]
	v_pk_add_f32 v[38:39], v[38:39], v[40:41]
	v_lshl_add_u64 v[48:49], v[204:205], 1, v[48:49]
	v_pk_mul_f32 v[56:57], v[42:43], v[42:43]
	v_cvt_pk_bf16_f32 v47, v42, v43
	v_pk_mul_f32 v[40:41], v[36:37], v[36:37]
	v_pk_mul_f32 v[42:43], v[38:39], v[38:39]
	v_cvt_pk_bf16_f32 v36, v36, v37
	v_cvt_pk_bf16_f32 v37, v38, v39
	v_lshlrev_b32_e32 v38, 16, v130
	v_and_b32_e32 v39, 0xffff0000, v130
	global_store_dwordx4 v[48:49], v[44:47], off
	v_pk_add_f32 v[32:33], v[32:33], v[38:39]
	v_lshlrev_b32_e32 v38, 16, v131
	v_and_b32_e32 v39, 0xffff0000, v131
	v_add_f32_e32 v46, v56, v57
	v_add_f32_e32 v47, v54, v55
	v_pk_add_f32 v[34:35], v[34:35], v[38:39]
	v_add_f32_e32 v46, v47, v46
	v_add_f32_e32 v47, v52, v53
	v_add_f32_e32 v50, v50, v51
	v_pk_mul_f32 v[38:39], v[32:33], v[32:33]
	v_pk_mul_f32 v[44:45], v[34:35], v[34:35]
	v_add_f32_e32 v47, v50, v47
	v_add_f32_e32 v42, v42, v43
	v_add_f32_e32 v40, v40, v41
	v_add_f32_e32 v46, v47, v46
	v_add_f32_e32 v40, v40, v42
	v_add_f32_e32 v41, v44, v45
	v_add_f32_e32 v38, v38, v39
	v_add_f32_e32 v40, v46, v40
	v_add_f32_e32 v38, v38, v41
	v_add_f32_e32 v40, v38, v40
	v_cvt_pk_bf16_f32 v38, v32, v33
	ds_bpermute_b32 v32, v246, v40
	v_cvt_pk_bf16_f32 v39, v34, v35
	global_store_dwordx4 v[48:49], v[36:39], off offset:256
	s_waitcnt lgkmcnt(0)
	v_add_f32_e32 v32, v40, v32
	ds_bpermute_b32 v33, v248, v32
	s_and_saveexec_b64 s[8:9], s[38:39]
	s_cbranch_execz .LBB0_1020
	s_waitcnt lgkmcnt(0)
	v_add_f32_e32 v34, v32, v33
	v_lshlrev_b64 v[32:33], 6, v[212:213]
	v_lshl_add_u64 v[32:33], s[20:21], 0, v[32:33]
	v_lshl_add_u64 v[32:33], s[44:45], 2, v[32:33]
	s_lshl_b32 s16, s60, 2
	v_lshl_add_u64 v[32:33], v[32:33], 0, s[16:17]
	global_store_dword v[32:33], v34, off
; __device__ __forceinline__ unsigned cvt_pk_bf16(float lo, float hi) { typedef float f2 __attribute__((ext_vector_type(2))); typedef __bf16 b2 __attribute__((ext_vector_type(2))); f2 v = {lo, hi}; b2 b = __builtin_convertvector(v, b2); return __builtin_bit_cast(unsigned, b); }
;     __device__ __forceinline__ void operator()(const f32x4 (&acc)[2][2][4][2], const Unit& u, int wr, int wc, int fr, int fq) const {
;     ...
;         for (int ai = 0; ai < 2; ++ai)
; #pragma unroll
;             for (int m = 0; m < 4; ++m) { const int row = row0 + ai * HALF + m * 16; bf16_t* xp = xr + (size_t)row * 1024 + col0; float sq = 0.f;
; #pragma unroll
;                 for (int bj = 0; bj < 2; ++bj) { const u32x4 ow = owv[ai][m][bj]; u32x4 w;
; #pragma unroll
;                     for (int n = 0; n < 2; ++n) { f32x4 v = acc[ai][bj][m][n]; const unsigned lo = ow[2 * n], hi_ = ow[2 * n + 1];
;                         v[0] += __uint_as_float(lo << 16); v[1] += __uint_as_float(lo & 0xffff0000u); v[2] += __uint_as_float(hi_ << 16); v[3] += __uint_as_float(hi_ & 0xffff0000u);
;                         sq += (v[0] * v[0] + v[1] * v[1]) + (v[2] * v[2] + v[3] * v[3]);
;                         w[2 * n] = cvt_pk_bf16(v[0], v[1]); w[2 * n + 1] = cvt_pk_bf16(v[2], v[3]); }
;                     *(u32x4*)(xp + bj * HALF) = w; }
;                 sq += __shfl_xor(sq, 16); sq += __shfl_xor(sq, 32);
;                 if (fq == 0) ssq[(size_t)row * 16 + u.pn * 4 + wc] = sq; }
.LBB0_1020:
	s_or_b64 exec, exec, s[8:9]
	v_lshlrev_b32_e32 v34, 16, v116
	v_and_b32_e32 v35, 0xffff0000, v116
	v_pk_add_f32 v[28:29], v[28:29], v[34:35]
	v_lshlrev_b32_e32 v34, 16, v117
	v_and_b32_e32 v35, 0xffff0000, v117
	v_pk_add_f32 v[30:31], v[30:31], v[34:35]
	v_pk_mul_f32 v[34:35], v[28:29], v[28:29]
	v_pk_mul_f32 v[36:37], v[30:31], v[30:31]
	v_cvt_pk_bf16_f32 v28, v28, v29
	v_cvt_pk_bf16_f32 v29, v30, v31
	v_lshlrev_b32_e32 v30, 16, v118
	v_and_b32_e32 v31, 0xffff0000, v118
	v_pk_add_f32 v[24:25], v[24:25], v[30:31]
	v_lshlrev_b32_e32 v30, 16, v119
	v_and_b32_e32 v31, 0xffff0000, v119
	v_pk_add_f32 v[26:27], v[26:27], v[30:31]
	v_pk_mul_f32 v[38:39], v[24:25], v[24:25]
	v_cvt_pk_bf16_f32 v30, v24, v25
	v_lshlrev_b32_e32 v24, 16, v108
	v_and_b32_e32 v25, 0xffff0000, v108
	v_pk_add_f32 v[20:21], v[20:21], v[24:25]
	v_lshlrev_b32_e32 v24, 16, v109
	v_and_b32_e32 v25, 0xffff0000, v109
	s_waitcnt lgkmcnt(0)
	v_lshl_add_u64 v[32:33], s[12:13], 0, v[214:215]
	v_pk_add_f32 v[22:23], v[22:23], v[24:25]
	v_lshl_add_u64 v[32:33], v[204:205], 1, v[32:33]
	v_pk_mul_f32 v[40:41], v[26:27], v[26:27]
	v_cvt_pk_bf16_f32 v31, v26, v27
	v_pk_mul_f32 v[24:25], v[20:21], v[20:21]
	v_pk_mul_f32 v[26:27], v[22:23], v[22:23]
	v_cvt_pk_bf16_f32 v20, v20, v21
	v_cvt_pk_bf16_f32 v21, v22, v23
	v_lshlrev_b32_e32 v22, 16, v110
	v_and_b32_e32 v23, 0xffff0000, v110
	global_store_dwordx4 v[32:33], v[28:31], off
	v_pk_add_f32 v[16:17], v[16:17], v[22:23]
	v_lshlrev_b32_e32 v22, 16, v111
	v_and_b32_e32 v23, 0xffff0000, v111
	v_add_f32_e32 v30, v40, v41
	v_add_f32_e32 v31, v38, v39
	v_pk_add_f32 v[18:19], v[18:19], v[22:23]
	v_add_f32_e32 v30, v31, v30
	v_add_f32_e32 v31, v36, v37
	v_add_f32_e32 v34, v34, v35
	v_pk_mul_f32 v[22:23], v[16:17], v[16:17]
	v_pk_mul_f32 v[28:29], v[18:19], v[18:19]
	v_add_f32_e32 v31, v34, v31
	v_add_f32_e32 v26, v26, v27
	v_add_f32_e32 v24, v24, v25
	v_add_f32_e32 v30, v31, v30
	v_add_f32_e32 v24, v24, v26
	v_add_f32_e32 v25, v28, v29
	v_add_f32_e32 v22, v22, v23
	v_add_f32_e32 v24, v30, v24
	v_add_f32_e32 v22, v22, v25
	v_add_f32_e32 v24, v22, v24
	v_cvt_pk_bf16_f32 v22, v16, v17
	ds_bpermute_b32 v16, v246, v24
	v_cvt_pk_bf16_f32 v23, v18, v19
	global_store_dwordx4 v[32:33], v[20:23], off offset:256
	s_waitcnt lgkmcnt(0)
	v_add_f32_e32 v16, v24, v16
	ds_bpermute_b32 v17, v248, v16
	s_and_saveexec_b64 s[8:9], s[38:39]
	s_cbranch_execz .LBB0_1022
	s_waitcnt lgkmcnt(0)
	v_add_f32_e32 v18, v16, v17
	v_lshlrev_b64 v[16:17], 6, v[208:209]
	v_lshl_add_u64 v[16:17], s[20:21], 0, v[16:17]
	v_lshl_add_u64 v[16:17], s[44:45], 2, v[16:17]
	s_lshl_b32 s16, s60, 2
	v_lshl_add_u64 v[16:17], v[16:17], 0, s[16:17]
	global_store_dword v[16:17], v18, off
.LBB0_1022:
	s_or_b64 exec, exec, s[8:9]
	v_lshlrev_b32_e32 v18, 16, v112
	v_and_b32_e32 v19, 0xffff0000, v112
	v_pk_add_f32 v[12:13], v[12:13], v[18:19]
	v_lshlrev_b32_e32 v18, 16, v113
	v_and_b32_e32 v19, 0xffff0000, v113
	v_pk_add_f32 v[14:15], v[14:15], v[18:19]
	v_pk_mul_f32 v[18:19], v[12:13], v[12:13]
	v_pk_mul_f32 v[20:21], v[14:15], v[14:15]
	v_cvt_pk_bf16_f32 v12, v12, v13
	v_cvt_pk_bf16_f32 v13, v14, v15
	v_lshlrev_b32_e32 v14, 16, v114
	v_and_b32_e32 v15, 0xffff0000, v114
	v_pk_add_f32 v[8:9], v[8:9], v[14:15]
	v_lshlrev_b32_e32 v14, 16, v115
	v_and_b32_e32 v15, 0xffff0000, v115
	v_pk_add_f32 v[10:11], v[10:11], v[14:15]
	v_pk_mul_f32 v[22:23], v[8:9], v[8:9]
	v_cvt_pk_bf16_f32 v14, v8, v9
	v_lshlrev_b32_e32 v8, 16, v100
	v_and_b32_e32 v9, 0xffff0000, v100
	v_pk_add_f32 v[4:5], v[4:5], v[8:9]
	v_lshlrev_b32_e32 v8, 16, v101
	v_and_b32_e32 v9, 0xffff0000, v101
	s_waitcnt lgkmcnt(0)
	v_lshl_add_u64 v[16:17], s[12:13], 0, v[210:211]
	v_pk_add_f32 v[6:7], v[6:7], v[8:9]
	v_lshl_add_u64 v[16:17], v[204:205], 1, v[16:17]
	v_pk_mul_f32 v[24:25], v[10:11], v[10:11]
	v_cvt_pk_bf16_f32 v15, v10, v11
	v_pk_mul_f32 v[8:9], v[4:5], v[4:5]
	v_pk_mul_f32 v[10:11], v[6:7], v[6:7]
	v_cvt_pk_bf16_f32 v4, v4, v5
	v_cvt_pk_bf16_f32 v5, v6, v7
	v_lshlrev_b32_e32 v6, 16, v102
	v_and_b32_e32 v7, 0xffff0000, v102
	global_store_dwordx4 v[16:17], v[12:15], off
	v_pk_add_f32 v[0:1], v[0:1], v[6:7]
	v_lshlrev_b32_e32 v6, 16, v103
	v_and_b32_e32 v7, 0xffff0000, v103
	v_add_f32_e32 v14, v24, v25
	v_add_f32_e32 v15, v22, v23
	v_pk_add_f32 v[2:3], v[2:3], v[6:7]
	v_add_f32_e32 v14, v15, v14
	v_add_f32_e32 v15, v20, v21
	v_add_f32_e32 v18, v18, v19
	v_pk_mul_f32 v[6:7], v[0:1], v[0:1]
	v_pk_mul_f32 v[12:13], v[2:3], v[2:3]
	v_add_f32_e32 v15, v18, v15
	v_add_f32_e32 v10, v10, v11
	v_add_f32_e32 v8, v8, v9
	v_add_f32_e32 v14, v15, v14
	v_add_f32_e32 v8, v8, v10
	v_add_f32_e32 v9, v12, v13
	v_add_f32_e32 v6, v6, v7
	v_add_f32_e32 v8, v14, v8
	v_add_f32_e32 v6, v6, v9
	v_add_f32_e32 v8, v6, v8
	v_cvt_pk_bf16_f32 v6, v0, v1
	ds_bpermute_b32 v0, v246, v8
	v_cvt_pk_bf16_f32 v7, v2, v3
	global_store_dwordx4 v[16:17], v[4:7], off offset:256
	s_waitcnt lgkmcnt(0)
	v_add_f32_e32 v0, v8, v0
	ds_bpermute_b32 v1, v248, v0
	s_and_saveexec_b64 s[8:9], s[38:39]
	s_cbranch_execz .LBB0_1024
	s_waitcnt lgkmcnt(0)
	v_add_f32_e32 v2, v0, v1
	v_lshlrev_b64 v[0:1], 6, v[206:207]
	v_lshl_add_u64 v[0:1], s[20:21], 0, v[0:1]
	v_lshl_add_u64 v[0:1], s[44:45], 2, v[0:1]
	s_lshl_b32 s16, s60, 2
	v_lshl_add_u64 v[0:1], v[0:1], 0, s[16:17]
	global_store_dword v[0:1], v2, off

; __device__ __forceinline__ int otid() { int t = threadIdx.x; asm volatile("" : "+v"(t)); return t; }
; __device__ __forceinline__ float dpp_ror15(float x) { return __builtin_bit_cast(float, __builtin_amdgcn_update_dpp(0, __builtin_bit_cast(int, x), 0x12F, 0xf, 0xf, false)); }
; __device__ __forceinline__ void rows_rstd8(const float* ssq, int row0, int fq, float (&rs)[2][4]) {
;     f32x4 p[2][4];
; #pragma unroll
;     for (int ai = 0; ai < 2; ++ai)
; #pragma unroll
;         for (int m = 0; m < 4; ++m) p[ai][m] = ((const f32x4*)(ssq + (size_t)(row0 + ai * HALF + m * 16) * 16))[fq];
; #pragma unroll
;     for (int ai = 0; ai < 2; ++ai)
; #pragma unroll
;         for (int m = 0; m < 4; ++m) { float v = (p[ai][m][0] + p[ai][m][1]) + (p[ai][m][2] + p[ai][m][3]); v += __shfl_xor(v, 16); v += __shfl_xor(v, 32); rs[ai][m] = __builtin_amdgcn_rsqf(v * (1.0f / 1024.0f) + 1e-6f); }
;     __device__ __forceinline__ void operator()(const f32x4 (&acc)[2][2][4][2], const Unit& u, int wr, int wc, int fr, int fq) const {
;     ...
;         { const int t_ = otid(), l_ = t_ & 63, w_ = t_ >> 6; wr = w_ >> 2; wc = w_ & 3; fr = l_ & 15; fq = l_ >> 4; }
;         const int row0 = u.pm * BM + wr * 64 + fr; const int ch0 = u.pn * 128 + wc * 32 + 8 * fq;
;         constexpr bool r1up = true;
;         const size_t esz = (size_t)nblk * 2 * 2816;
;         float rs8[2][4]; rows_rstd8(ssq, row0, fq, rs8);
;         f32x4 cwv[2][4];
; #pragma unroll
;         for (int n = 0; n < 2; ++n) { const int ch = ch0 + 4 * n; cwv[n][0] = *(const f32x4*)(cw + ch); cwv[n][1] = *(const f32x4*)(cw + 2816 + ch); cwv[n][2] = *(const f32x4*)(cw + 2 * 2816 + ch); cwv[n][3] = *(const f32x4*)(cb + ch); }
; #pragma unroll
;         for (int ai = 0; ai < 2; ++ai) {
;             const int blk = (u.pm * BM + ai * HALF + wr * 64) >> 6;
;             f32x4 ua_prev[2], db_next[2], gcur[2];
; #pragma unroll
;             for (int n = 0; n < 2; ++n) { gcur[n] = acc[ai][1][0][n] * rs8[ai][0]; ua_prev[n] = (f32x4){0.f, 0.f, 0.f, 0.f};
; #pragma unroll
;                 for (int j = 0; j < 4; ++j) db_next[n][j] = dpp_ror15(gcur[n][j]); }
.LBB0_1099:
	v_mov_b32_e32 v64, v240
	s_lshl_b32 s29, s42, 8
	v_ashrrev_i32_e32 v189, 2, v64
	v_and_b32_e32 v66, 0xffffffc0, v189
	v_and_b32_e32 v194, 15, v64
	v_add_u32_e32 v66, s29, v66
	v_bfe_u32 v65, v64, 4, 2
	v_or_b32_e32 v190, v66, v194
	v_lshrrev_b32_e32 v64, 1, v64
	s_lshl_b32 s8, s40, 7
	v_and_b32_e32 v64, 0x60, v64
	v_lshlrev_b32_e32 v66, 3, v65
	v_lshlrev_b32_e32 v192, 4, v65
	v_ashrrev_i32_e32 v191, 31, v190
	v_or3_b32 v172, v64, s8, v66
	v_lshl_add_u64 v[96:97], s[10:11], 0, v[192:193]
	v_lshlrev_b64 v[64:65], 6, v[190:191]
	v_lshl_add_u64 v[64:65], v[96:97], 0, v[64:65]
	global_load_dwordx4 v[64:67], v[64:65], off
	v_or_b32_e32 v186, 16, v190
	v_ashrrev_i32_e32 v187, 31, v186
	v_lshlrev_b64 v[68:69], 6, v[186:187]
	v_lshl_add_u64 v[68:69], v[96:97], 0, v[68:69]
	global_load_dwordx4 v[68:71], v[68:69], off
	v_or_b32_e32 v184, 32, v190
	v_ashrrev_i32_e32 v185, 31, v184
	v_lshlrev_b64 v[72:73], 6, v[184:185]
	v_lshl_add_u64 v[72:73], v[96:97], 0, v[72:73]
	global_load_dwordx4 v[72:75], v[72:73], off
	v_or_b32_e32 v182, 48, v190
	v_ashrrev_i32_e32 v183, 31, v182
	v_lshlrev_b64 v[76:77], 6, v[182:183]
	v_lshl_add_u64 v[76:77], v[96:97], 0, v[76:77]
	global_load_dwordx4 v[76:79], v[76:77], off
	v_add_u32_e32 v180, 0x80, v190
	v_ashrrev_i32_e32 v181, 31, v180
	v_lshlrev_b64 v[80:81], 6, v[180:181]
	v_lshl_add_u64 v[80:81], v[96:97], 0, v[80:81]
	global_load_dwordx4 v[80:83], v[80:81], off
	v_add_u32_e32 v178, 0x90, v190
	v_ashrrev_i32_e32 v179, 31, v178
	v_lshlrev_b64 v[84:85], 6, v[178:179]
	v_lshl_add_u64 v[84:85], v[96:97], 0, v[84:85]
	global_load_dwordx4 v[84:87], v[84:85], off
	v_add_u32_e32 v176, 0xa0, v190
	v_ashrrev_i32_e32 v177, 31, v176
	v_lshlrev_b64 v[92:93], 6, v[176:177]
	v_lshl_add_u64 v[92:93], v[96:97], 0, v[92:93]
	global_load_dwordx4 v[92:95], v[92:93], off
	v_add_u32_e32 v174, 0xb0, v190
	v_ashrrev_i32_e32 v175, 31, v174
	v_lshlrev_b64 v[98:99], 6, v[174:175]
	v_lshl_add_u64 v[96:97], v[96:97], 0, v[98:99]
	global_load_dwordx4 v[96:99], v[96:97], off
	v_cmp_lt_i32_e32 vcc, v247, v245
	v_mov_b32_e32 v220, v193
	v_mov_b32_e32 v221, v193
	v_cndmask_b32_e32 v173, v244, v247, vcc
	v_lshlrev_b32_e32 v173, 2, v173
	v_cmp_lt_i32_e32 vcc, v250, v245
	v_cmp_ne_u32_e64 s[40:41], 15, v194
	v_cmp_eq_u32_e64 s[42:43], 15, v194
	v_cndmask_b32_e32 v175, v244, v250, vcc
	v_lshlrev_b32_e32 v181, 2, v175
	v_cmp_ne_u32_e64 s[46:47], 0, v194
	v_cmp_eq_u32_e64 s[44:45], 0, v194
	v_mov_b32_e32 v194, v193
	v_mov_b32_e32 v195, v193
	v_mov_b32_e32 v222, v193
	v_mov_b32_e32 v223, v193
	v_mov_b32_e32 v216, v193
	v_mov_b32_e32 v217, v193
	v_mov_b32_e32 v208, v193
	v_mov_b32_e32 v209, v193
	v_mov_b32_e32 v218, v193
	v_mov_b32_e32 v219, v193
	v_mov_b32_e32 v212, v193
	v_mov_b32_e32 v213, v193
	v_mov_b32_e32 v224, v193
	v_mov_b32_e32 v225, v193
	v_mov_b32_e32 v214, v193
	v_mov_b32_e32 v215, v193
	v_mov_b32_e32 v228, v193
	v_mov_b32_e32 v229, v193
	v_mov_b32_e32 v210, v193
	v_mov_b32_e32 v211, v193
	s_waitcnt vmcnt(0) lgkmcnt(0)
	v_mov_b32_e32 v196, v65
	v_mov_b32_e32 v197, v66
	v_mov_b32_e32 v65, v67
	v_pk_add_f32 v[64:65], v[196:197], v[64:65]
	s_nop 0
	v_add_f32_e32 v64, v64, v65
	ds_bpermute_b32 v65, v173, v64
	s_waitcnt lgkmcnt(0)
	v_add_f32_e32 v64, v64, v65
	ds_bpermute_b32 v65, v181, v64
	s_waitcnt lgkmcnt(0)
	v_add_f32_e32 v64, v64, v65
	v_fmamk_f32 v64, v64, 0x3a800000, v242
	v_rsq_f32_e32 v192, v64
	v_mov_b32_e32 v64, v69
	v_mov_b32_e32 v65, v70
	v_mov_b32_e32 v69, v71
	v_pk_add_f32 v[64:65], v[64:65], v[68:69]
	v_pk_mul_f32 v[156:157], v[156:157], v[192:193] op_sel_hi:[1,0]
	v_add_f32_e32 v64, v64, v65
	ds_bpermute_b32 v65, v173, v64
	v_mov_b32_dpp v220, v156 row_ror:1 row_mask:0xf bank_mask:0xf
	v_mov_b32_dpp v221, v157 row_ror:1 row_mask:0xf bank_mask:0xf
	v_pk_mul_f32 v[158:159], v[158:159], v[192:193] op_sel_hi:[1,0]
	v_mov_b32_dpp v194, v156 row_ror:15 row_mask:0xf bank_mask:0xf
	s_waitcnt lgkmcnt(0)
	v_add_f32_e32 v64, v64, v65
	ds_bpermute_b32 v65, v181, v64
	v_mov_b32_dpp v195, v157 row_ror:15 row_mask:0xf bank_mask:0xf
	v_mov_b32_dpp v216, v158 row_ror:1 row_mask:0xf bank_mask:0xf
	v_mov_b32_dpp v217, v159 row_ror:1 row_mask:0xf bank_mask:0xf
	v_pk_mul_f32 v[152:153], v[152:153], v[192:193] op_sel_hi:[1,0]
	s_waitcnt lgkmcnt(0)
	v_add_f32_e32 v64, v64, v65
	v_fmamk_f32 v64, v64, 0x3a800000, v242
	v_rsq_f32_e32 v188, v64
	v_add_f32_e32 v64, v72, v73
	v_add_f32_e32 v65, v74, v75
	v_add_f32_e32 v64, v64, v65
	ds_bpermute_b32 v65, v173, v64
	v_pk_mul_f32 v[198:199], v[148:149], v[188:189] op_sel_hi:[1,0]
	v_cndmask_b32_e64 v149, v221, 0, s[44:45]
	v_cndmask_b32_e64 v148, v220, 0, s[44:45]
	v_mov_b32_dpp v222, v198 row_ror:15 row_mask:0xf bank_mask:0xf
	s_waitcnt lgkmcnt(0)
	v_add_f32_e32 v204, v64, v65
	v_add_f32_e32 v64, v76, v77
	v_add_f32_e32 v65, v78, v79
	v_add_f32_e32 v64, v64, v65
	ds_bpermute_b32 v65, v173, v64
	v_mov_b32_dpp v223, v199 row_ror:15 row_mask:0xf bank_mask:0xf
	v_pk_mul_f32 v[200:201], v[150:151], v[188:189] op_sel_hi:[1,0]
	v_cndmask_b32_e64 v151, v195, v223, s[42:43]
	v_cndmask_b32_e64 v150, v194, v222, s[42:43]
	s_waitcnt lgkmcnt(0)
	v_add_f32_e32 v206, v64, v65
	v_add_f32_e32 v64, v80, v81
	v_add_f32_e32 v65, v82, v83
	v_add_f32_e32 v64, v64, v65
	ds_bpermute_b32 v65, v173, v64
	v_mov_b32_dpp v208, v158 row_ror:15 row_mask:0xf bank_mask:0xf
	v_mov_b32_dpp v209, v159 row_ror:15 row_mask:0xf bank_mask:0xf
	v_mov_b32_dpp v218, v200 row_ror:15 row_mask:0xf bank_mask:0xf
	v_mov_b32_dpp v219, v201 row_ror:15 row_mask:0xf bank_mask:0xf
	s_waitcnt lgkmcnt(0)
;     __device__ __forceinline__ void operator()(const f32x4 (&acc)[2][2][4][2], const Unit& u, int wr, int wc, int fr, int fq) const {
;     ...
;         f32x4 cwv[2][4];
; #pragma unroll
;         for (int n = 0; n < 2; ++n) { const int ch = ch0 + 4 * n; cwv[n][0] = *(const f32x4*)(cw + ch); cwv[n][1] = *(const f32x4*)(cw + 2816 + ch); cwv[n][2] = *(const f32x4*)(cw + 2 * 2816 + ch); cwv[n][3] = *(const f32x4*)(cb + ch); }
; #pragma unroll
;         for (int ai = 0; ai < 2; ++ai) {
;             const int blk = (u.pm * BM + ai * HALF + wr * 64) >> 6;
;             f32x4 ua_prev[2], db_next[2], gcur[2];
; #pragma unroll
;             for (int n = 0; n < 2; ++n) { gcur[n] = acc[ai][1][0][n] * rs8[ai][0]; ua_prev[n] = (f32x4){0.f, 0.f, 0.f, 0.f};
; #pragma unroll
;                 for (int j = 0; j < 4; ++j) db_next[n][j] = dpp_ror15(gcur[n][j]); }
; #pragma unroll
;             for (int m = 0; m < 4; ++m) { f32x4 ua[2], db[2], gnext[2]; u32x4 w4; f32x4 cvs[2], uus[2];
;                 const bool isF = (m == 0) && (fr == 0), isL = (m == 3) && (fr == 15);
; #pragma unroll
;                 for (int n = 0; n < 2; ++n) { db[n] = db_next[n];
; #pragma unroll
;                     for (int j = 0; j < 4; ++j) ua[n][j] = dpp_ror1(gcur[n][j]);
;                     if (m < 3) { gnext[n] = acc[ai][1][m < 3 ? m + 1 : 3][n] * rs8[ai][m < 3 ? m + 1 : 3];
; #pragma unroll
;                         for (int j = 0; j < 4; ++j) db_next[n][j] = dpp_ror15(gnext[n][j]); }
;                     else { gnext[n] = (f32x4){0.f, 0.f, 0.f, 0.f}; db_next[n] = gnext[n]; }
;                     const f32x4 w0 = cwv[n][0], w1 = cwv[n][1], w2 = cwv[n][2], bb = cwv[n][3]; const f32x4 uu = acc[ai][0][m][n] * rs8[ai][m]; f32x4 cv;
; #pragma unroll
;                     for (int j = 0; j < 4; ++j) { const float up = (fr > 0) ? ua[n][j] : ua_prev[n][j]; const float dn = (fr < 15) ? db[n][j] : db_next[n][j];
;                         cv[j] = w0[j] * up + w1[j] * gcur[n][j] + w2[j] * dn + bb[j]; }
;                     cvs[n] = cv; uus[n] = uu;
;                     f32x4 a4;
; #pragma unroll
;                     for (int j = 0; j < 4; ++j) a4[j] = cv[j] * sigm(cv[j]) * uu[j];
;                     w4[2 * n] = cvt_pk_bf16(a4[0], a4[1]); w4[2 * n + 1] = cvt_pk_bf16(a4[2], a4[3]); }
;                 if (isF || isL) { float* e = edge + ((size_t)blk * 2 + (isL ? 1 : 0)) * 2816 + ch0;
; #pragma unroll
	v_add_f32_e32 v183, v64, v65
	v_add_f32_e32 v64, v84, v85
	v_add_f32_e32 v65, v86, v87
	v_add_f32_e32 v64, v64, v65
	ds_bpermute_b32 v65, v173, v64
	v_mov_b32_dpp v212, v152 row_ror:1 row_mask:0xf bank_mask:0xf
	v_mov_b32_dpp v213, v153 row_ror:1 row_mask:0xf bank_mask:0xf
	v_pk_mul_f32 v[154:155], v[154:155], v[192:193] op_sel_hi:[1,0]
	v_mov_b32_dpp v224, v152 row_ror:15 row_mask:0xf bank_mask:0xf
	s_waitcnt lgkmcnt(0)
	v_add_f32_e32 v187, v64, v65
	v_add_f32_e32 v64, v92, v93
	v_add_f32_e32 v65, v94, v95
	v_add_f32_e32 v64, v64, v65
	ds_bpermute_b32 v65, v173, v64
	v_mov_b32_dpp v225, v153 row_ror:15 row_mask:0xf bank_mask:0xf
	ds_bpermute_b32 v205, v181, v204
	ds_bpermute_b32 v207, v181, v206
	ds_bpermute_b32 v185, v181, v183
	s_waitcnt lgkmcnt(3)
	v_add_f32_e32 v175, v64, v65
	v_add_f32_e32 v64, v96, v97
	v_add_f32_e32 v65, v98, v99
	v_add_f32_e32 v64, v64, v65
	ds_bpermute_b32 v65, v173, v64
	v_ashrrev_i32_e32 v173, 31, v172
	v_lshlrev_b64 v[72:73], 2, v[172:173]
	v_lshl_add_u64 v[68:69], s[82:83], 0, v[72:73]
	v_lshl_add_u64 v[74:75], s[20:21], 0, v[72:73]
	s_waitcnt lgkmcnt(0)
	v_add_f32_e32 v179, v64, v65
	global_load_dwordx4 v[64:67], v[68:69], off offset:16
	global_load_dwordx4 v[80:83], v[68:69], off
	v_lshl_add_u64 v[68:69], s[48:49], 0, v[72:73]
	global_load_dwordx4 v[76:79], v[68:69], off offset:16
	global_load_dwordx4 v[96:99], v[68:69], off
	s_nop 0
	global_load_dwordx4 v[68:71], v[74:75], off offset:16
	global_load_dwordx4 v[84:87], v[74:75], off
	v_lshl_add_u64 v[92:93], s[68:69], 0, v[72:73]
	global_load_dwordx4 v[72:75], v[92:93], off offset:16
	s_nop 0
	global_load_dwordx4 v[92:95], v[92:93], off
	ds_bpermute_b32 v191, v181, v187
	ds_bpermute_b32 v177, v181, v175
	ds_bpermute_b32 v181, v181, v179
	v_mov_b32_dpp v228, v154 row_ror:15 row_mask:0xf bank_mask:0xf
	v_mov_b32_dpp v229, v155 row_ror:15 row_mask:0xf bank_mask:0xf
	v_pk_mul_f32 v[146:147], v[146:147], v[192:193] op_sel_hi:[1,0]
	v_pk_mul_f32 v[144:145], v[144:145], v[192:193] op_sel_hi:[1,0]
	v_pk_mul_f32 v[138:139], v[138:139], v[192:193] op_sel_hi:[1,0]
	v_pk_mul_f32 v[136:137], v[136:137], v[192:193] op_sel_hi:[1,0]
	s_waitcnt vmcnt(5)
	v_pk_mul_f32 v[226:227], v[152:153], v[76:77]
	s_waitcnt vmcnt(4)
	v_pk_mul_f32 v[196:197], v[156:157], v[96:97]
	v_pk_mul_f32 v[194:195], v[158:159], v[98:99]
	v_pk_fma_f32 v[148:149], v[80:81], v[148:149], v[196:197]
	v_cndmask_b32_e64 v197, v209, v219, s[42:43]
	s_waitcnt vmcnt(2)
	v_pk_fma_f32 v[148:149], v[84:85], v[150:151], v[148:149]
	v_cndmask_b32_e64 v151, v217, 0, s[44:45]
	v_cndmask_b32_e64 v150, v216, 0, s[44:45]
	v_pk_fma_f32 v[150:151], v[82:83], v[150:151], v[194:195]
	v_pk_mul_f32 v[194:195], v[140:141], v[188:189] op_sel_hi:[1,0]
	v_cndmask_b32_e64 v196, v208, v218, s[42:43]
	v_mov_b32_e32 v208, v193
	v_mov_b32_e32 v209, v193
	v_mov_b32_dpp v214, v194 row_ror:15 row_mask:0xf bank_mask:0xf
	v_mov_b32_dpp v215, v195 row_ror:15 row_mask:0xf bank_mask:0xf
	v_cndmask_b32_e64 v141, v213, 0, s[44:45]
	v_cndmask_b32_e64 v140, v212, 0, s[44:45]
	v_pk_fma_f32 v[150:151], v[86:87], v[196:197], v[150:151]
	v_mov_b32_dpp v208, v154 row_ror:1 row_mask:0xf bank_mask:0xf
	v_mov_b32_dpp v209, v155 row_ror:1 row_mask:0xf bank_mask:0xf
	v_pk_mul_f32 v[196:197], v[142:143], v[188:189] op_sel_hi:[1,0]
	v_cndmask_b32_e64 v143, v225, v215, s[42:43]
	v_cndmask_b32_e64 v142, v224, v214, s[42:43]
	v_pk_fma_f32 v[140:141], v[64:65], v[140:141], v[226:227]
	v_mov_b32_dpp v210, v196 row_ror:15 row_mask:0xf bank_mask:0xf
	v_mov_b32_dpp v211, v197 row_ror:15 row_mask:0xf bank_mask:0xf
	v_pk_mul_f32 v[224:225], v[154:155], v[78:79]
	v_pk_fma_f32 v[140:141], v[68:69], v[142:143], v[140:141]
	v_cndmask_b32_e64 v143, v209, 0, s[44:45]
	v_cndmask_b32_e64 v142, v208, 0, s[44:45]
	v_cndmask_b32_e64 v227, v229, v211, s[42:43]
	v_cndmask_b32_e64 v226, v228, v210, s[42:43]
	v_pk_fma_f32 v[142:143], v[66:67], v[142:143], v[224:225]
	s_waitcnt vmcnt(0)
	v_pk_add_f32 v[148:149], v[92:93], v[148:149]
	v_pk_fma_f32 v[142:143], v[70:71], v[226:227], v[142:143]
	v_pk_add_f32 v[150:151], v[94:95], v[150:151]
	v_pk_add_f32 v[140:141], v[72:73], v[140:141]
	v_pk_add_f32 v[142:143], v[74:75], v[142:143]
	s_and_saveexec_b64 s[8:9], s[46:47]
	s_xor_b64 vcc, exec, s[8:9]
	s_cbranch_execz .LBB0_1101
	v_mul_f32_e32 v152, 0xbfb8aa3b, v148
	v_mul_f32_e32 v153, 0xbfb8aa3b, v149
	v_exp_f32_e32 v152, v152
	v_exp_f32_e32 v153, v153
	v_add_f32_e32 v152, 1.0, v152
	v_add_f32_e32 v153, 1.0, v153
	v_rcp_f32_e32 v152, v152
	v_rcp_f32_e32 v153, v153
	s_nop 0
	v_pk_mul_f32 v[148:149], v[148:149], v[152:153]
	s_nop 0
	v_pk_mul_f32 v[144:145], v[144:145], v[148:149]
	s_nop 0
	v_cvt_pk_bf16_f32 v144, v144, v145
	v_mul_f32_e32 v145, 0xbfb8aa3b, v150
	v_exp_f32_e32 v145, v145
	s_nop 0
	v_add_f32_e32 v145, 1.0, v145
	v_rcp_f32_e32 v148, v145
	v_mul_f32_e32 v145, 0xbfb8aa3b, v151
	v_exp_f32_e32 v145, v145
	s_nop 0
	v_add_f32_e32 v145, 1.0, v145
	v_rcp_f32_e32 v149, v145
	s_nop 0
	v_pk_mul_f32 v[148:149], v[150:151], v[148:149]
	s_nop 0
	v_pk_mul_f32 v[146:147], v[146:147], v[148:149]
	s_nop 0
	v_cvt_pk_bf16_f32 v145, v146, v147
	v_mul_f32_e32 v146, 0xbfb8aa3b, v140
	v_mul_f32_e32 v147, 0xbfb8aa3b, v141
	v_exp_f32_e32 v146, v146
	v_exp_f32_e32 v147, v147
	v_add_f32_e32 v146, 1.0, v146
	v_add_f32_e32 v147, 1.0, v147
	v_rcp_f32_e32 v146, v146
	v_rcp_f32_e32 v147, v147
	s_nop 0
	v_pk_mul_f32 v[140:141], v[140:141], v[146:147]
	s_nop 0
	v_pk_mul_f32 v[136:137], v[136:137], v[140:141]
	s_nop 0
	v_cvt_pk_bf16_f32 v146, v136, v137
	v_mul_f32_e32 v136, 0xbfb8aa3b, v142
	v_mul_f32_e32 v137, 0xbfb8aa3b, v143
	v_exp_f32_e32 v136, v136
	v_exp_f32_e32 v137, v137
	v_add_f32_e32 v136, 1.0, v136
	v_add_f32_e32 v137, 1.0, v137
	v_rcp_f32_e32 v136, v136
	v_rcp_f32_e32 v137, v137
	s_nop 0
	v_pk_mul_f32 v[136:137], v[142:143], v[136:137]
	s_nop 0
	v_pk_mul_f32 v[136:137], v[138:139], v[136:137]
	s_nop 0
	v_cvt_pk_bf16_f32 v147, v136, v137
	v_mov_b64_e32 v[136:137], s[36:37]
	v_mad_i64_i32 v[136:137], s[8:9], v190, s72, v[136:137]
	v_lshl_add_u64 v[136:137], v[172:173], 1, v[136:137]
	global_store_dwordx4 v[136:137], v[144:147], off
; __device__ __forceinline__ unsigned cvt_pk_bf16(float lo, float hi) { typedef float f2 __attribute__((ext_vector_type(2))); typedef __bf16 b2 __attribute__((ext_vector_type(2))); f2 v = {lo, hi}; b2 b = __builtin_convertvector(v, b2); return __builtin_bit_cast(unsigned, b); }
;     __device__ __forceinline__ void operator()(const f32x4 (&acc)[2][2][4][2], const Unit& u, int wr, int wc, int fr, int fq) const {
;     ...
;             for (int m = 0; m < 4; ++m) { f32x4 ua[2], db[2], gnext[2]; u32x4 w4; f32x4 cvs[2], uus[2];
;                 const bool isF = (m == 0) && (fr == 0), isL = (m == 3) && (fr == 15);
; #pragma unroll
;                 for (int n = 0; n < 2; ++n) { db[n] = db_next[n];
; #pragma unroll
;                     for (int j = 0; j < 4; ++j) ua[n][j] = dpp_ror1(gcur[n][j]);
;                     if (m < 3) { gnext[n] = acc[ai][1][m < 3 ? m + 1 : 3][n] * rs8[ai][m < 3 ? m + 1 : 3];
; #pragma unroll
;                         for (int j = 0; j < 4; ++j) db_next[n][j] = dpp_ror15(gnext[n][j]); }
;                     else { gnext[n] = (f32x4){0.f, 0.f, 0.f, 0.f}; db_next[n] = gnext[n]; }
;                     const f32x4 w0 = cwv[n][0], w1 = cwv[n][1], w2 = cwv[n][2], bb = cwv[n][3]; const f32x4 uu = acc[ai][0][m][n] * rs8[ai][m]; f32x4 cv;
; #pragma unroll
;                     for (int j = 0; j < 4; ++j) { const float up = (fr > 0) ? ua[n][j] : ua_prev[n][j]; const float dn = (fr < 15) ? db[n][j] : db_next[n][j];
;                         cv[j] = w0[j] * up + w1[j] * gcur[n][j] + w2[j] * dn + bb[j]; }
;                     cvs[n] = cv; uus[n] = uu;
;                     f32x4 a4;
; #pragma unroll
;                     for (int j = 0; j < 4; ++j) a4[j] = cv[j] * sigm(cv[j]) * uu[j];
;                     w4[2 * n] = cvt_pk_bf16(a4[0], a4[1]); w4[2 * n + 1] = cvt_pk_bf16(a4[2], a4[3]); }
;                 if (isF || isL) { float* e = edge + ((size_t)blk * 2 + (isL ? 1 : 0)) * 2816 + ch0;
; #pragma unroll
;                     for (int n = 0; n < 2; ++n) { *(f32x4*)(e + 4 * n) = cvs[n]; *(f32x4*)(e + esz + 4 * n) = uus[n]; *(f32x4*)(e + 2 * esz + 4 * n) = gcur[n]; } }
;                 else *(u32x4*)(act + (size_t)(row0 + ai * HALF + m * 16) * 2816 + ch0) = w4;
; #pragma unroll
;                 for (int n = 0; n < 2; ++n) { ua_prev[n] = ua[n]; gcur[n] = gnext[n]; }
.LBB0_1101:
	s_or_saveexec_b64 s[8:9], vcc
	v_add_u32_e32 v190, s29, v189
	v_ashrrev_i32_e32 v192, 6, v190
	s_xor_b64 exec, exec, s[8:9]
	s_cbranch_execz .LBB0_1103
	v_mov_b64_e32 v[224:225], s[6:7]
	v_mad_i64_i32 v[224:225], s[90:91], v192, s71, v[224:225]
	v_lshl_add_u64 v[224:225], v[172:173], 2, v[224:225]
	v_lshl_add_u64 v[226:227], v[224:225], 0, s[66:67]
	v_lshl_add_u64 v[228:229], v[226:227], 0, s[66:67]
	global_store_dwordx4 v[224:225], v[148:151], off
	global_store_dwordx4 v[226:227], v[144:147], off
	global_store_dwordx4 v[228:229], v[156:159], off
	global_store_dwordx4 v[224:225], v[140:143], off offset:16
	global_store_dwordx4 v[226:227], v[136:139], off offset:16
	global_store_dwordx4 v[228:229], v[152:155], off offset:16
.LBB0_1103:
	s_or_b64 exec, exec, s[8:9]
	v_add_f32_e32 v136, v204, v205
	v_fmamk_f32 v136, v136, 0x3a800000, v242
	v_rsq_f32_e32 v140, v136
	v_mov_b32_e32 v141, v193
	v_mov_b32_e32 v150, v193
	v_mov_b32_e32 v153, v193
	v_mov_b32_dpp v141, v198 row_ror:1 row_mask:0xf bank_mask:0xf
	v_mov_b32_dpp v150, v199 row_ror:1 row_mask:0xf bank_mask:0xf
	v_pk_mul_f32 v[138:139], v[130:131], v[140:141] op_sel_hi:[1,0]
	v_pk_mul_f32 v[130:131], v[128:129], v[140:141] op_sel_hi:[1,0]
	v_mov_b32_e32 v154, v193
	v_mov_b32_e32 v142, v188
	v_mov_b32_e32 v143, v188
	v_mov_b32_dpp v153, v130 row_ror:15 row_mask:0xf bank_mask:0xf
	v_mov_b32_dpp v154, v131 row_ror:15 row_mask:0xf bank_mask:0xf
	v_pk_mul_f32 v[128:129], v[134:135], v[142:143]
	v_cndmask_b32_e64 v135, v150, v221, s[44:45]
	v_cndmask_b32_e64 v134, v141, v220, s[44:45]
	v_pk_mul_f32 v[148:149], v[198:199], v[96:97]
	v_cndmask_b32_e64 v145, v223, v154, s[42:43]
	v_cndmask_b32_e64 v144, v222, v153, s[42:43]
	v_pk_fma_f32 v[134:135], v[80:81], v[134:135], v[148:149]
	v_mov_b32_e32 v189, v188
	v_pk_fma_f32 v[134:135], v[84:85], v[144:145], v[134:135]
	v_mov_b32_e32 v151, v193
	v_pk_add_f32 v[134:135], v[92:93], v[134:135]
	v_mov_b32_e32 v152, v193
	v_mul_f32_e32 v137, 0xbfb8aa3b, v134
	v_exp_f32_e32 v137, v137
	v_mov_b32_dpp v151, v200 row_ror:1 row_mask:0xf bank_mask:0xf
	v_mov_b32_dpp v152, v201 row_ror:1 row_mask:0xf bank_mask:0xf
	v_mov_b32_e32 v155, v193
	v_add_f32_e32 v137, 1.0, v137
	v_rcp_f32_e32 v144, v137
	v_mul_f32_e32 v137, 0xbfb8aa3b, v135
	v_exp_f32_e32 v137, v137
	v_mov_b32_e32 v156, v193
	v_pk_mul_f32 v[132:133], v[132:133], v[188:189]
	v_mov_b32_dpp v155, v138 row_ror:15 row_mask:0xf bank_mask:0xf
	v_add_f32_e32 v137, 1.0, v137
	v_rcp_f32_e32 v145, v137
	v_mov_b32_dpp v156, v139 row_ror:15 row_mask:0xf bank_mask:0xf
	v_pk_mul_f32 v[146:147], v[200:201], v[98:99]
	v_mov_b32_e32 v149, v193
	v_pk_mul_f32 v[134:135], v[134:135], v[144:145]
	v_cndmask_b32_e64 v145, v219, v156, s[42:43]
	v_pk_mul_f32 v[132:133], v[132:133], v[134:135]
	v_cndmask_b32_e64 v135, v152, v217, s[44:45]
	v_cndmask_b32_e64 v134, v151, v216, s[44:45]
	v_cndmask_b32_e64 v144, v218, v155, s[42:43]
	v_pk_fma_f32 v[134:135], v[82:83], v[134:135], v[146:147]
	v_mov_b32_e32 v146, v193
	v_pk_fma_f32 v[134:135], v[86:87], v[144:145], v[134:135]
	v_mov_b32_e32 v147, v193
	v_pk_add_f32 v[134:135], v[94:95], v[134:135]
	v_cvt_pk_bf16_f32 v132, v132, v133
	v_mul_f32_e32 v137, 0xbfb8aa3b, v134
	v_exp_f32_e32 v137, v137
	v_mov_b32_dpp v146, v194 row_ror:1 row_mask:0xf bank_mask:0xf
	v_mov_b32_dpp v147, v195 row_ror:1 row_mask:0xf bank_mask:0xf
	v_mov_b32_e32 v157, v193
	v_add_f32_e32 v137, 1.0, v137
	v_rcp_f32_e32 v144, v137
	v_mul_f32_e32 v137, 0xbfb8aa3b, v135
	v_exp_f32_e32 v137, v137
	v_mov_b32_e32 v148, v193
	v_pk_mul_f32 v[124:125], v[124:125], v[188:189]
	v_mov_b32_e32 v158, v193
	v_add_f32_e32 v137, 1.0, v137
	v_rcp_f32_e32 v145, v137
	v_mov_b32_e32 v137, v193
	v_mov_b32_dpp v148, v197 row_ror:1 row_mask:0xf bank_mask:0xf
	v_mov_b32_e32 v159, v193
	v_pk_mul_f32 v[134:135], v[134:135], v[144:145]
	v_pk_mul_f32 v[144:145], v[194:195], v[76:77]
	v_pk_mul_f32 v[128:129], v[128:129], v[134:135]
	v_mov_b32_dpp v137, v196 row_ror:1 row_mask:0xf bank_mask:0xf
	v_cvt_pk_bf16_f32 v133, v128, v129
	v_pk_mul_f32 v[128:129], v[122:123], v[140:141] op_sel_hi:[1,0]
	v_pk_mul_f32 v[122:123], v[120:121], v[140:141] op_sel_hi:[1,0]
	v_pk_mul_f32 v[120:121], v[126:127], v[142:143]
	v_cndmask_b32_e64 v127, v147, v213, s[44:45]
	v_mov_b32_dpp v149, v122 row_ror:15 row_mask:0xf bank_mask:0xf
	v_mov_b32_dpp v157, v123 row_ror:15 row_mask:0xf bank_mask:0xf
	v_cndmask_b32_e64 v126, v146, v212, s[44:45]
	v_cndmask_b32_e64 v135, v215, v157, s[42:43]
	v_cndmask_b32_e64 v134, v214, v149, s[42:43]
	v_pk_fma_f32 v[126:127], v[64:65], v[126:127], v[144:145]
	v_mov_b32_dpp v158, v128 row_ror:15 row_mask:0xf bank_mask:0xf
	v_pk_fma_f32 v[126:127], v[68:69], v[134:135], v[126:127]
	v_mov_b32_dpp v159, v129 row_ror:15 row_mask:0xf bank_mask:0xf
	v_pk_add_f32 v[126:127], v[72:73], v[126:127]
	v_pk_mul_f32 v[142:143], v[196:197], v[78:79]
	v_mul_f32_e32 v134, 0xbfb8aa3b, v126
	v_mul_f32_e32 v135, 0xbfb8aa3b, v127
	v_exp_f32_e32 v134, v134
	v_exp_f32_e32 v135, v135
	v_add_f32_e32 v136, v206, v207
	v_fmamk_f32 v136, v136, 0x3a800000, v242
	v_add_f32_e32 v134, 1.0, v134
	v_add_f32_e32 v135, 1.0, v135
	v_rcp_f32_e32 v134, v134
	v_rcp_f32_e32 v135, v135
	v_rsq_f32_e32 v136, v136
	v_mov_b32_e32 v188, v193
	v_pk_mul_f32 v[118:119], v[118:119], v[140:141] op_sel_hi:[1,0]
	v_pk_mul_f32 v[126:127], v[126:127], v[134:135]
	v_pk_mul_f32 v[108:109], v[108:109], v[136:137] op_sel_hi:[1,0]
	v_pk_mul_f32 v[124:125], v[124:125], v[126:127]
	v_cndmask_b32_e64 v127, v211, v159, s[42:43]
	v_cvt_pk_bf16_f32 v134, v124, v125
	v_cndmask_b32_e64 v125, v148, v209, s[44:45]
	v_cndmask_b32_e64 v124, v137, v208, s[44:45]
	v_pk_fma_f32 v[124:125], v[66:67], v[124:125], v[142:143]
; __device__ __forceinline__ unsigned cvt_pk_bf16(float lo, float hi) { typedef float f2 __attribute__((ext_vector_type(2))); typedef __bf16 b2 __attribute__((ext_vector_type(2))); f2 v = {lo, hi}; b2 b = __builtin_convertvector(v, b2); return __builtin_bit_cast(unsigned, b); }
;     __device__ __forceinline__ void operator()(const f32x4 (&acc)[2][2][4][2], const Unit& u, int wr, int wc, int fr, int fq) const {
;     ...
;             for (int m = 0; m < 4; ++m) { f32x4 ua[2], db[2], gnext[2]; u32x4 w4; f32x4 cvs[2], uus[2];
;                 const bool isF = (m == 0) && (fr == 0), isL = (m == 3) && (fr == 15);
; #pragma unroll
;                 for (int n = 0; n < 2; ++n) { db[n] = db_next[n];
; #pragma unroll
;                     for (int j = 0; j < 4; ++j) ua[n][j] = dpp_ror1(gcur[n][j]);
;                     if (m < 3) { gnext[n] = acc[ai][1][m < 3 ? m + 1 : 3][n] * rs8[ai][m < 3 ? m + 1 : 3];
; #pragma unroll
;                         for (int j = 0; j < 4; ++j) db_next[n][j] = dpp_ror15(gnext[n][j]); }
;                     else { gnext[n] = (f32x4){0.f, 0.f, 0.f, 0.f}; db_next[n] = gnext[n]; }
;                     const f32x4 w0 = cwv[n][0], w1 = cwv[n][1], w2 = cwv[n][2], bb = cwv[n][3]; const f32x4 uu = acc[ai][0][m][n] * rs8[ai][m]; f32x4 cv;
; #pragma unroll
;                     for (int j = 0; j < 4; ++j) { const float up = (fr > 0) ? ua[n][j] : ua_prev[n][j]; const float dn = (fr < 15) ? db[n][j] : db_next[n][j];
;                         cv[j] = w0[j] * up + w1[j] * gcur[n][j] + w2[j] * dn + bb[j]; }
;                     cvs[n] = cv; uus[n] = uu;
;                     f32x4 a4;
; #pragma unroll
;                     for (int j = 0; j < 4; ++j) a4[j] = cv[j] * sigm(cv[j]) * uu[j];
;                     w4[2 * n] = cvt_pk_bf16(a4[0], a4[1]); w4[2 * n + 1] = cvt_pk_bf16(a4[2], a4[3]); }
;                 if (isF || isL) { float* e = edge + ((size_t)blk * 2 + (isL ? 1 : 0)) * 2816 + ch0;
; #pragma unroll
;                     for (int n = 0; n < 2; ++n) { *(f32x4*)(e + 4 * n) = cvs[n]; *(f32x4*)(e + esz + 4 * n) = uus[n]; *(f32x4*)(e + 2 * esz + 4 * n) = gcur[n]; } }
;                 else *(u32x4*)(act + (size_t)(row0 + ai * HALF + m * 16) * 2816 + ch0) = w4;
; #pragma unroll
;                 for (int n = 0; n < 2; ++n) { ua_prev[n] = ua[n]; gcur[n] = gnext[n]; }
	v_cndmask_b32_e64 v126, v210, v158, s[42:43]
	v_pk_fma_f32 v[124:125], v[70:71], v[126:127], v[124:125]
	v_mov_b32_e32 v142, v193
	v_pk_add_f32 v[124:125], v[74:75], v[124:125]
	v_mov_b32_e32 v143, v193
	v_mul_f32_e32 v126, 0xbfb8aa3b, v124
	v_mul_f32_e32 v127, 0xbfb8aa3b, v125
	v_exp_f32_e32 v126, v126
	v_exp_f32_e32 v127, v127
	v_mov_b32_dpp v142, v130 row_ror:1 row_mask:0xf bank_mask:0xf
	v_mov_b32_dpp v143, v131 row_ror:1 row_mask:0xf bank_mask:0xf
	v_add_f32_e32 v126, 1.0, v126
	v_add_f32_e32 v127, 1.0, v127
	v_rcp_f32_e32 v126, v126
	v_rcp_f32_e32 v127, v127
	v_mov_b32_dpp v188, v109 row_ror:15 row_mask:0xf bank_mask:0xf
	v_pk_mul_f32 v[116:117], v[116:117], v[140:141] op_sel_hi:[1,0]
	v_mov_b32_e32 v144, v193
	v_pk_mul_f32 v[124:125], v[124:125], v[126:127]
	v_mov_b32_e32 v145, v193
	v_pk_mul_f32 v[120:121], v[120:121], v[124:125]
	v_lshlrev_b64 v[124:125], 1, v[172:173]
	v_cvt_pk_bf16_f32 v135, v120, v121
	v_mov_b64_e32 v[120:121], s[36:37]
	v_mad_i64_i32 v[126:127], s[8:9], v186, s72, v[120:121]
	v_lshl_add_u64 v[126:127], v[126:127], 0, v[124:125]
	v_mov_b32_e32 v186, v193
	global_store_dwordx4 v[126:127], v[132:135], off
	v_mov_b32_dpp v144, v138 row_ror:1 row_mask:0xf bank_mask:0xf
	v_mov_b32_dpp v186, v108 row_ror:15 row_mask:0xf bank_mask:0xf
	v_pk_mul_f32 v[134:135], v[112:113], v[140:141] op_sel_hi:[1,0]
	v_mad_i64_i32 v[112:113], s[8:9], v184, s72, v[120:121]
	v_pk_mul_f32 v[120:121], v[130:131], v[96:97]
	v_cndmask_b32_e64 v131, v143, v150, s[44:45]
	v_cndmask_b32_e64 v130, v142, v141, s[44:45]
	v_lshl_add_u64 v[126:127], v[112:113], 0, v[124:125]
	v_cndmask_b32_e64 v113, v154, v188, s[42:43]
	v_cndmask_b32_e64 v112, v153, v186, s[42:43]
	v_pk_fma_f32 v[120:121], v[80:81], v[130:131], v[120:121]
	v_pk_mul_f32 v[132:133], v[114:115], v[140:141] op_sel_hi:[1,0]
	v_pk_fma_f32 v[112:113], v[84:85], v[112:113], v[120:121]
	v_mov_b32_e32 v140, v193
	v_pk_add_f32 v[112:113], v[92:93], v[112:113]
	v_mov_b32_e32 v184, v193
	v_mul_f32_e32 v120, 0xbfb8aa3b, v112
	v_mul_f32_e32 v121, 0xbfb8aa3b, v113
	v_exp_f32_e32 v120, v120
	v_exp_f32_e32 v121, v121
	v_mov_b32_dpp v140, v108 row_ror:1 row_mask:0xf bank_mask:0xf
	v_mov_b32_dpp v184, v109 row_ror:1 row_mask:0xf bank_mask:0xf
	v_add_f32_e32 v120, 1.0, v120
	v_add_f32_e32 v121, 1.0, v121
	v_rcp_f32_e32 v120, v120
	v_rcp_f32_e32 v121, v121
	v_mov_b32_dpp v145, v139 row_ror:1 row_mask:0xf bank_mask:0xf
	v_pk_mul_f32 v[110:111], v[110:111], v[136:137] op_sel_hi:[1,0]
	v_mov_b32_e32 v189, v193
	v_pk_mul_f32 v[112:113], v[112:113], v[120:121]
	v_mov_b32_e32 v194, v193
	v_pk_mul_f32 v[112:113], v[116:117], v[112:113]
	v_pk_mul_f32 v[114:115], v[138:139], v[98:99]
	v_cvt_pk_bf16_f32 v120, v112, v113
	v_cndmask_b32_e64 v113, v184, v143, s[44:45]
	v_cndmask_b32_e64 v112, v140, v142, s[44:45]
	v_pk_mul_f32 v[138:139], v[108:109], v[96:97]
	v_mov_b32_dpp v189, v110 row_ror:15 row_mask:0xf bank_mask:0xf
	v_mov_b32_dpp v194, v111 row_ror:15 row_mask:0xf bank_mask:0xf
	v_cndmask_b32_e64 v117, v188, 0, s[42:43]
	v_cndmask_b32_e64 v116, v186, 0, s[42:43]
	v_pk_fma_f32 v[112:113], v[80:81], v[112:113], v[138:139]
	v_cndmask_b32_e64 v139, v145, v152, s[44:45]
	v_cndmask_b32_e64 v138, v144, v151, s[44:45]
	v_pk_fma_f32 v[112:113], v[84:85], v[116:117], v[112:113]
	v_cndmask_b32_e64 v117, v156, v194, s[42:43]
	v_cndmask_b32_e64 v116, v155, v189, s[42:43]
	v_pk_fma_f32 v[114:115], v[82:83], v[138:139], v[114:115]
	v_mov_b32_e32 v205, v193
	v_pk_fma_f32 v[114:115], v[86:87], v[116:117], v[114:115]
	v_mov_b32_e32 v206, v193
	v_pk_add_f32 v[114:115], v[94:95], v[114:115]
	v_mov_b32_e32 v195, v193
	v_mul_f32_e32 v116, 0xbfb8aa3b, v114
	v_mul_f32_e32 v117, 0xbfb8aa3b, v115
	v_exp_f32_e32 v116, v116
	v_exp_f32_e32 v117, v117
	v_mov_b32_e32 v196, v193
	v_mov_b32_dpp v205, v110 row_ror:1 row_mask:0xf bank_mask:0xf
	v_add_f32_e32 v116, 1.0, v116
	v_add_f32_e32 v117, 1.0, v117
	v_rcp_f32_e32 v116, v116
	v_rcp_f32_e32 v117, v117
	v_mov_b32_dpp v206, v111 row_ror:1 row_mask:0xf bank_mask:0xf
	v_mov_b32_dpp v195, v122 row_ror:1 row_mask:0xf bank_mask:0xf
	v_mov_b32_dpp v196, v123 row_ror:1 row_mask:0xf bank_mask:0xf
	v_pk_mul_f32 v[114:115], v[114:115], v[116:117]
	v_mov_b32_e32 v197, v193
	v_pk_mul_f32 v[114:115], v[118:119], v[114:115]
	v_mov_b32_e32 v198, v193
	v_pk_mul_f32 v[104:105], v[104:105], v[136:137] op_sel_hi:[1,0]
	v_mov_b32_e32 v199, v193
	v_mov_b32_e32 v200, v193
	v_pk_mul_f32 v[130:131], v[110:111], v[98:99]
	v_cvt_pk_bf16_f32 v121, v114, v115
	v_cndmask_b32_e64 v115, v206, v145, s[44:45]
	v_cndmask_b32_e64 v114, v205, v144, s[44:45]
	v_mov_b32_dpp v197, v128 row_ror:1 row_mask:0xf bank_mask:0xf
	v_mov_b32_dpp v198, v129 row_ror:1 row_mask:0xf bank_mask:0xf
	v_mov_b32_dpp v199, v104 row_ror:15 row_mask:0xf bank_mask:0xf
	v_mov_b32_dpp v200, v105 row_ror:15 row_mask:0xf bank_mask:0xf
	v_cndmask_b32_e64 v117, v194, 0, s[42:43]
	v_cndmask_b32_e64 v116, v189, 0, s[42:43]
	v_pk_fma_f32 v[114:115], v[82:83], v[114:115], v[130:131]
	v_pk_mul_f32 v[118:119], v[102:103], v[136:137] op_sel_hi:[1,0]
	v_pk_mul_f32 v[102:103], v[128:129], v[78:79]
	v_pk_mul_f32 v[122:123], v[122:123], v[76:77]
	v_cndmask_b32_e64 v129, v196, v147, s[44:45]
	v_cndmask_b32_e64 v128, v195, v146, s[44:45]
	v_pk_fma_f32 v[114:115], v[86:87], v[116:117], v[114:115]
	v_pk_mul_f32 v[116:117], v[100:101], v[136:137] op_sel_hi:[1,0]
	v_cndmask_b32_e64 v101, v157, v200, s[42:43]
	v_cndmask_b32_e64 v100, v149, v199, s[42:43]
	v_pk_fma_f32 v[122:123], v[64:65], v[128:129], v[122:123]
	v_mov_b32_e32 v130, v193
	v_pk_fma_f32 v[100:101], v[68:69], v[100:101], v[122:123]
	v_mov_b32_e32 v131, v193
	v_pk_add_f32 v[100:101], v[72:73], v[100:101]
; __device__ __forceinline__ unsigned cvt_pk_bf16(float lo, float hi) { typedef float f2 __attribute__((ext_vector_type(2))); typedef __bf16 b2 __attribute__((ext_vector_type(2))); f2 v = {lo, hi}; b2 b = __builtin_convertvector(v, b2); return __builtin_bit_cast(unsigned, b); }
;     __device__ __forceinline__ void operator()(const f32x4 (&acc)[2][2][4][2], const Unit& u, int wr, int wc, int fr, int fq) const {
;     ...
;             for (int m = 0; m < 4; ++m) { f32x4 ua[2], db[2], gnext[2]; u32x4 w4; f32x4 cvs[2], uus[2];
;                 const bool isF = (m == 0) && (fr == 0), isL = (m == 3) && (fr == 15);
; #pragma unroll
;                 for (int n = 0; n < 2; ++n) { db[n] = db_next[n];
; #pragma unroll
;                     for (int j = 0; j < 4; ++j) ua[n][j] = dpp_ror1(gcur[n][j]);
;                     if (m < 3) { gnext[n] = acc[ai][1][m < 3 ? m + 1 : 3][n] * rs8[ai][m < 3 ? m + 1 : 3];
; #pragma unroll
;                         for (int j = 0; j < 4; ++j) db_next[n][j] = dpp_ror15(gnext[n][j]); }
;                     else { gnext[n] = (f32x4){0.f, 0.f, 0.f, 0.f}; db_next[n] = gnext[n]; }
;                     const f32x4 w0 = cwv[n][0], w1 = cwv[n][1], w2 = cwv[n][2], bb = cwv[n][3]; const f32x4 uu = acc[ai][0][m][n] * rs8[ai][m]; f32x4 cv;
; #pragma unroll
;                     for (int j = 0; j < 4; ++j) { const float up = (fr > 0) ? ua[n][j] : ua_prev[n][j]; const float dn = (fr < 15) ? db[n][j] : db_next[n][j];
;                         cv[j] = w0[j] * up + w1[j] * gcur[n][j] + w2[j] * dn + bb[j]; }
;                     cvs[n] = cv; uus[n] = uu;
;                     f32x4 a4;
; #pragma unroll
;                     for (int j = 0; j < 4; ++j) a4[j] = cv[j] * sigm(cv[j]) * uu[j];
;                     w4[2 * n] = cvt_pk_bf16(a4[0], a4[1]); w4[2 * n + 1] = cvt_pk_bf16(a4[2], a4[3]); }
;                 if (isF || isL) { float* e = edge + ((size_t)blk * 2 + (isL ? 1 : 0)) * 2816 + ch0;
; #pragma unroll
;                     for (int n = 0; n < 2; ++n) { *(f32x4*)(e + 4 * n) = cvs[n]; *(f32x4*)(e + esz + 4 * n) = uus[n]; *(f32x4*)(e + 2 * esz + 4 * n) = gcur[n]; } }
;                 else *(u32x4*)(act + (size_t)(row0 + ai * HALF + m * 16) * 2816 + ch0) = w4;
; #pragma unroll
;                 for (int n = 0; n < 2; ++n) { ua_prev[n] = ua[n]; gcur[n] = gnext[n]; }
	v_mov_b32_dpp v130, v104 row_ror:1 row_mask:0xf bank_mask:0xf
	v_mul_f32_e32 v122, 0xbfb8aa3b, v100
	v_mul_f32_e32 v123, 0xbfb8aa3b, v101
	v_exp_f32_e32 v122, v122
	v_exp_f32_e32 v123, v123
	v_mov_b32_dpp v131, v105 row_ror:1 row_mask:0xf bank_mask:0xf
	v_pk_mul_f32 v[106:107], v[106:107], v[136:137] op_sel_hi:[1,0]
	v_add_f32_e32 v122, 1.0, v122
	v_add_f32_e32 v123, 1.0, v123
	v_rcp_f32_e32 v122, v122
	v_rcp_f32_e32 v123, v123
	v_mov_b32_e32 v201, v193
	v_mov_b32_e32 v204, v193
	v_cndmask_b32_e64 v129, v200, 0, s[42:43]
	v_pk_mul_f32 v[100:101], v[100:101], v[122:123]
	v_mov_b32_dpp v201, v106 row_ror:15 row_mask:0xf bank_mask:0xf
	v_pk_mul_f32 v[100:101], v[134:135], v[100:101]
	v_pk_mul_f32 v[134:135], v[104:105], v[76:77]
	v_cvt_pk_bf16_f32 v122, v100, v101
	v_cndmask_b32_e64 v101, v131, v196, s[44:45]
	v_cndmask_b32_e64 v100, v130, v195, s[44:45]
	v_mov_b32_dpp v204, v107 row_ror:15 row_mask:0xf bank_mask:0xf
	v_cndmask_b32_e64 v128, v199, 0, s[42:43]
	v_pk_fma_f32 v[100:101], v[64:65], v[100:101], v[134:135]
	v_cndmask_b32_e64 v135, v198, v148, s[44:45]
	v_cndmask_b32_e64 v134, v197, v137, s[44:45]
	v_pk_fma_f32 v[100:101], v[68:69], v[128:129], v[100:101]
	v_cndmask_b32_e64 v129, v159, v204, s[42:43]
	v_cndmask_b32_e64 v128, v158, v201, s[42:43]
	v_pk_fma_f32 v[102:103], v[66:67], v[134:135], v[102:103]
	v_mov_b32_e32 v138, v193
	v_pk_fma_f32 v[102:103], v[70:71], v[128:129], v[102:103]
	v_mov_b32_e32 v139, v193
	v_pk_add_f32 v[102:103], v[74:75], v[102:103]
	v_mov_b32_dpp v138, v106 row_ror:1 row_mask:0xf bank_mask:0xf
	v_mul_f32_e32 v123, 0xbfb8aa3b, v102
	v_exp_f32_e32 v123, v123
	v_mov_b32_dpp v139, v107 row_ror:1 row_mask:0xf bank_mask:0xf
	v_pk_mul_f32 v[130:131], v[106:107], v[78:79]
	v_pk_add_f32 v[112:113], v[92:93], v[112:113]
	v_add_f32_e32 v123, 1.0, v123
	v_rcp_f32_e32 v128, v123
	v_mul_f32_e32 v123, 0xbfb8aa3b, v103
	v_exp_f32_e32 v123, v123
	v_pk_add_f32 v[114:115], v[94:95], v[114:115]
	v_pk_add_f32 v[100:101], v[72:73], v[100:101]
	v_pk_mul_f32 v[90:91], v[90:91], v[136:137] op_sel_hi:[1,0]
	v_add_f32_e32 v123, 1.0, v123
	v_rcp_f32_e32 v129, v123
	v_pk_mul_f32 v[88:89], v[88:89], v[136:137] op_sel_hi:[1,0]
	v_pk_mul_f32 v[102:103], v[102:103], v[128:129]
	s_nop 0
	v_pk_mul_f32 v[102:103], v[132:133], v[102:103]
	s_nop 0
	v_cvt_pk_bf16_f32 v123, v102, v103
	v_cndmask_b32_e64 v103, v139, v198, s[44:45]
	v_cndmask_b32_e64 v102, v138, v197, s[44:45]
	global_store_dwordx4 v[126:127], v[120:123], off
	v_pk_fma_f32 v[102:103], v[66:67], v[102:103], v[130:131]
	s_nop 0
	v_cndmask_b32_e64 v121, v204, 0, s[42:43]
	v_cndmask_b32_e64 v120, v201, 0, s[42:43]
	v_pk_fma_f32 v[102:103], v[70:71], v[120:121], v[102:103]
	s_nop 0
	v_pk_add_f32 v[102:103], v[74:75], v[102:103]
	s_and_saveexec_b64 s[8:9], s[40:41]
	s_xor_b64 vcc, exec, s[8:9]
	s_mov_b32 s93, s70
	s_mov_b32 s94, s73
	s_cbranch_execz .LBB0_1105
	v_mul_f32_e32 v104, 0xbfb8aa3b, v112
	v_mul_f32_e32 v105, 0xbfb8aa3b, v113
	v_exp_f32_e32 v104, v104
	v_exp_f32_e32 v105, v105
	v_add_f32_e32 v104, 1.0, v104
	v_add_f32_e32 v105, 1.0, v105
	v_rcp_f32_e32 v104, v104
	v_rcp_f32_e32 v105, v105
	s_nop 0
	v_pk_mul_f32 v[104:105], v[112:113], v[104:105]
	s_nop 0
	v_pk_mul_f32 v[104:105], v[116:117], v[104:105]
	s_nop 0
	v_cvt_pk_bf16_f32 v104, v104, v105
	v_mul_f32_e32 v105, 0xbfb8aa3b, v114
	v_exp_f32_e32 v105, v105
	s_nop 0
	v_add_f32_e32 v105, 1.0, v105
	v_rcp_f32_e32 v106, v105
	v_mul_f32_e32 v105, 0xbfb8aa3b, v115
	v_exp_f32_e32 v105, v105
	s_nop 0
	v_add_f32_e32 v105, 1.0, v105
	v_rcp_f32_e32 v107, v105
	s_nop 0
	v_pk_mul_f32 v[106:107], v[114:115], v[106:107]
	s_nop 0
	v_pk_mul_f32 v[106:107], v[118:119], v[106:107]
	s_nop 0
	v_cvt_pk_bf16_f32 v105, v106, v107
	v_mul_f32_e32 v106, 0xbfb8aa3b, v100
	v_mul_f32_e32 v107, 0xbfb8aa3b, v101
	v_exp_f32_e32 v106, v106
	v_exp_f32_e32 v107, v107
	v_add_f32_e32 v106, 1.0, v106
	v_add_f32_e32 v107, 1.0, v107
	v_rcp_f32_e32 v106, v106
	v_rcp_f32_e32 v107, v107
	s_nop 0
	v_pk_mul_f32 v[100:101], v[100:101], v[106:107]
	s_nop 0
	v_pk_mul_f32 v[88:89], v[88:89], v[100:101]
	s_nop 0
	v_cvt_pk_bf16_f32 v106, v88, v89
	v_mul_f32_e32 v88, 0xbfb8aa3b, v102
	v_mul_f32_e32 v89, 0xbfb8aa3b, v103
	v_exp_f32_e32 v88, v88
	v_exp_f32_e32 v89, v89
	v_add_f32_e32 v88, 1.0, v88
	v_add_f32_e32 v89, 1.0, v89
	v_rcp_f32_e32 v88, v88
	v_rcp_f32_e32 v89, v89
	s_nop 0
	v_pk_mul_f32 v[88:89], v[102:103], v[88:89]
	s_nop 0
	v_pk_mul_f32 v[88:89], v[90:91], v[88:89]
	s_nop 0
	v_cvt_pk_bf16_f32 v107, v88, v89
	v_mov_b64_e32 v[88:89], s[36:37]
	v_mad_i64_i32 v[88:89], s[8:9], v182, s72, v[88:89]
	v_lshl_add_u64 v[88:89], v[172:173], 1, v[88:89]
	global_store_dwordx4 v[88:89], v[104:107], off
.LBB0_1105:
	s_andn2_saveexec_b64 s[8:9], vcc
	s_cbranch_execz .LBB0_1107
	v_mov_b64_e32 v[120:121], s[6:7]
	v_mad_i64_i32 v[120:121], s[90:91], v192, s71, v[120:121]
	v_lshl_add_u64 v[120:121], v[172:173], 2, v[120:121]
	s_mov_b64 s[74:75], 0x2c00
	v_lshl_add_u64 v[122:123], v[120:121], 0, s[74:75]
	v_add_co_u32_e32 v120, vcc, 0x2000, v120
	v_readlane_b32 s75, v255, 1
	v_lshl_add_u64 v[126:127], v[122:123], 0, s[66:67]
	v_addc_co_u32_e32 v121, vcc, 0, v121, vcc
	v_lshl_add_u64 v[128:129], v[126:127], 0, s[66:67]
	global_store_dwordx4 v[120:121], v[112:115], off offset:3072
	global_store_dwordx4 v[126:127], v[116:119], off
	global_store_dwordx4 v[128:129], v[108:111], off
	global_store_dwordx4 v[122:123], v[100:103], off offset:16
	global_store_dwordx4 v[126:127], v[88:91], off offset:16
	global_store_dwordx4 v[128:129], v[104:107], off offset:16
; __device__ __forceinline__ unsigned cvt_pk_bf16(float lo, float hi) { typedef float f2 __attribute__((ext_vector_type(2))); typedef __bf16 b2 __attribute__((ext_vector_type(2))); f2 v = {lo, hi}; b2 b = __builtin_convertvector(v, b2); return __builtin_bit_cast(unsigned, b); }
;     __device__ __forceinline__ void operator()(const f32x4 (&acc)[2][2][4][2], const Unit& u, int wr, int wc, int fr, int fq) const {
;     ...
;             for (int m = 0; m < 4; ++m) { f32x4 ua[2], db[2], gnext[2]; u32x4 w4; f32x4 cvs[2], uus[2];
;                 const bool isF = (m == 0) && (fr == 0), isL = (m == 3) && (fr == 15);
; #pragma unroll
;                 for (int n = 0; n < 2; ++n) { db[n] = db_next[n];
; #pragma unroll
;                     for (int j = 0; j < 4; ++j) ua[n][j] = dpp_ror1(gcur[n][j]);
;                     if (m < 3) { gnext[n] = acc[ai][1][m < 3 ? m + 1 : 3][n] * rs8[ai][m < 3 ? m + 1 : 3];
; #pragma unroll
;                         for (int j = 0; j < 4; ++j) db_next[n][j] = dpp_ror15(gnext[n][j]); }
;                     else { gnext[n] = (f32x4){0.f, 0.f, 0.f, 0.f}; db_next[n] = gnext[n]; }
;                     const f32x4 w0 = cwv[n][0], w1 = cwv[n][1], w2 = cwv[n][2], bb = cwv[n][3]; const f32x4 uu = acc[ai][0][m][n] * rs8[ai][m]; f32x4 cv;
; #pragma unroll
;                     for (int j = 0; j < 4; ++j) { const float up = (fr > 0) ? ua[n][j] : ua_prev[n][j]; const float dn = (fr < 15) ? db[n][j] : db_next[n][j];
;                         cv[j] = w0[j] * up + w1[j] * gcur[n][j] + w2[j] * dn + bb[j]; }
;                     cvs[n] = cv; uus[n] = uu;
;                     f32x4 a4;
; #pragma unroll
;                     for (int j = 0; j < 4; ++j) a4[j] = cv[j] * sigm(cv[j]) * uu[j];
;                     w4[2 * n] = cvt_pk_bf16(a4[0], a4[1]); w4[2 * n + 1] = cvt_pk_bf16(a4[2], a4[3]); }
;                 if (isF || isL) { float* e = edge + ((size_t)blk * 2 + (isL ? 1 : 0)) * 2816 + ch0;
; #pragma unroll
;                     for (int n = 0; n < 2; ++n) { *(f32x4*)(e + 4 * n) = cvs[n]; *(f32x4*)(e + esz + 4 * n) = uus[n]; *(f32x4*)(e + 2 * esz + 4 * n) = gcur[n]; } }
;                 else *(u32x4*)(act + (size_t)(row0 + ai * HALF + m * 16) * 2816 + ch0) = w4;
; #pragma unroll
;                 for (int n = 0; n < 2; ++n) { ua_prev[n] = ua[n]; gcur[n] = gnext[n]; }
.LBB0_1107:
	s_or_b64 exec, exec, s[8:9]
	v_add_f32_e32 v88, v183, v185
	v_fmamk_f32 v88, v88, 0x3a800000, v242
	v_rsq_f32_e32 v106, v88
	s_waitcnt lgkmcnt(0)
	v_add_f32_e32 v88, v187, v191
	v_fmamk_f32 v88, v88, 0x3a800000, v242
	v_rsq_f32_e32 v88, v88
	v_pk_mul_f32 v[60:61], v[60:61], v[106:107] op_sel_hi:[1,0]
	v_mov_b32_e32 v89, v193
	v_mov_b32_e32 v119, v193
	v_mov_b32_e32 v120, v193
	v_mov_b32_dpp v89, v60 row_ror:15 row_mask:0xf bank_mask:0xf
	v_mov_b32_e32 v90, v193
	v_mov_b32_dpp v119, v60 row_ror:1 row_mask:0xf bank_mask:0xf
	v_mov_b32_dpp v120, v61 row_ror:1 row_mask:0xf bank_mask:0xf
	v_pk_mul_f32 v[102:103], v[48:49], v[88:89] op_sel_hi:[1,0]
	v_mov_b32_e32 v121, v193
	v_mov_b32_e32 v122, v193
	v_pk_mul_f32 v[62:63], v[62:63], v[106:107] op_sel_hi:[1,0]
	v_mov_b32_dpp v90, v61 row_ror:15 row_mask:0xf bank_mask:0xf
	v_mov_b32_e32 v107, v193
	v_mov_b32_e32 v115, v193
	v_mov_b32_e32 v116, v193
	v_mov_b32_dpp v121, v102 row_ror:15 row_mask:0xf bank_mask:0xf
	v_mov_b32_dpp v122, v103 row_ror:15 row_mask:0xf bank_mask:0xf
	v_cndmask_b32_e64 v49, v120, 0, s[44:45]
	v_cndmask_b32_e64 v48, v119, 0, s[44:45]
	v_pk_mul_f32 v[100:101], v[96:97], v[60:61]
	v_mov_b32_dpp v107, v62 row_ror:15 row_mask:0xf bank_mask:0xf
	v_mov_b32_dpp v115, v62 row_ror:1 row_mask:0xf bank_mask:0xf
	v_mov_b32_dpp v116, v63 row_ror:1 row_mask:0xf bank_mask:0xf
	v_pk_mul_f32 v[104:105], v[50:51], v[88:89] op_sel_hi:[1,0]
	v_cndmask_b32_e64 v51, v90, v122, s[42:43]
	v_cndmask_b32_e64 v50, v89, v121, s[42:43]
	v_pk_fma_f32 v[48:49], v[80:81], v[48:49], v[100:101]
	v_mov_b32_e32 v108, v193
	v_pk_mul_f32 v[56:57], v[56:57], v[106:107] op_sel_hi:[1,0]
	v_mov_b32_e32 v117, v193
	v_mov_b32_e32 v118, v193
	v_pk_mul_f32 v[90:91], v[98:99], v[62:63]
	v_pk_fma_f32 v[48:49], v[84:85], v[50:51], v[48:49]
	v_cndmask_b32_e64 v51, v116, 0, s[44:45]
	v_cndmask_b32_e64 v50, v115, 0, s[44:45]
	v_mov_b32_e32 v111, v193
	v_mov_b32_e32 v112, v193
	v_mov_b32_dpp v108, v63 row_ror:15 row_mask:0xf bank_mask:0xf
	v_mov_b32_e32 v123, v193
	v_mov_b32_e32 v126, v193
	v_mov_b32_dpp v117, v104 row_ror:15 row_mask:0xf bank_mask:0xf
	v_mov_b32_dpp v118, v105 row_ror:15 row_mask:0xf bank_mask:0xf
	v_pk_fma_f32 v[50:51], v[82:83], v[50:51], v[90:91]
	v_mov_b32_dpp v111, v56 row_ror:1 row_mask:0xf bank_mask:0xf
	v_mov_b32_dpp v112, v57 row_ror:1 row_mask:0xf bank_mask:0xf
	v_pk_mul_f32 v[90:91], v[40:41], v[88:89] op_sel_hi:[1,0]
	v_mov_b32_e32 v113, v193
	v_mov_b32_e32 v114, v193
	v_pk_mul_f32 v[58:59], v[58:59], v[106:107] op_sel_hi:[1,0]
	v_mov_b32_dpp v123, v56 row_ror:15 row_mask:0xf bank_mask:0xf
	v_mov_b32_dpp v126, v57 row_ror:15 row_mask:0xf bank_mask:0xf
	v_cndmask_b32_e64 v101, v108, v118, s[42:43]
	v_cndmask_b32_e64 v100, v107, v117, s[42:43]
	v_pk_mul_f32 v[54:55], v[54:55], v[106:107] op_sel_hi:[1,0]
	v_pk_mul_f32 v[52:53], v[52:53], v[106:107] op_sel_hi:[1,0]
	v_mov_b32_e32 v107, v193
	v_mov_b32_e32 v108, v193
	v_mov_b32_dpp v113, v90 row_ror:15 row_mask:0xf bank_mask:0xf
	v_mov_b32_dpp v114, v91 row_ror:15 row_mask:0xf bank_mask:0xf
	v_cndmask_b32_e64 v41, v112, 0, s[44:45]
	v_cndmask_b32_e64 v40, v111, 0, s[44:45]
	v_pk_mul_f32 v[128:129], v[56:57], v[76:77]
	v_mov_b32_e32 v130, v193
	v_mov_b32_e32 v131, v193
	v_pk_fma_f32 v[50:51], v[86:87], v[100:101], v[50:51]
	v_mov_b32_dpp v107, v58 row_ror:1 row_mask:0xf bank_mask:0xf
	v_mov_b32_dpp v108, v59 row_ror:1 row_mask:0xf bank_mask:0xf
	v_pk_mul_f32 v[100:101], v[42:43], v[88:89] op_sel_hi:[1,0]
	v_mov_b32_e32 v109, v193
	v_mov_b32_e32 v110, v193
	v_cndmask_b32_e64 v43, v126, v114, s[42:43]
	v_cndmask_b32_e64 v42, v123, v113, s[42:43]
	v_pk_fma_f32 v[40:41], v[64:65], v[40:41], v[128:129]
	v_mov_b32_dpp v130, v58 row_ror:15 row_mask:0xf bank_mask:0xf
	v_mov_b32_dpp v131, v59 row_ror:15 row_mask:0xf bank_mask:0xf
	v_mov_b32_dpp v109, v100 row_ror:15 row_mask:0xf bank_mask:0xf
	v_mov_b32_dpp v110, v101 row_ror:15 row_mask:0xf bank_mask:0xf
	v_pk_mul_f32 v[126:127], v[58:59], v[78:79]
	v_pk_fma_f32 v[40:41], v[68:69], v[42:43], v[40:41]
	v_cndmask_b32_e64 v43, v108, 0, s[44:45]
	v_cndmask_b32_e64 v42, v107, 0, s[44:45]
	v_cndmask_b32_e64 v129, v131, v110, s[42:43]
	v_cndmask_b32_e64 v128, v130, v109, s[42:43]
	v_pk_fma_f32 v[42:43], v[66:67], v[42:43], v[126:127]
	v_pk_add_f32 v[48:49], v[92:93], v[48:49]
	v_pk_fma_f32 v[42:43], v[70:71], v[128:129], v[42:43]
	v_pk_add_f32 v[50:51], v[94:95], v[50:51]
	v_pk_add_f32 v[40:41], v[72:73], v[40:41]
	v_pk_add_f32 v[42:43], v[74:75], v[42:43]
	v_pk_mul_f32 v[46:47], v[46:47], v[106:107] op_sel_hi:[1,0]
	v_pk_mul_f32 v[44:45], v[44:45], v[106:107] op_sel_hi:[1,0]
	s_and_saveexec_b64 s[8:9], s[46:47]
	s_xor_b64 s[46:47], exec, s[8:9]
	s_cbranch_execz .LBB0_1109
	v_mul_f32_e32 v56, 0xbfb8aa3b, v48
	v_mul_f32_e32 v57, 0xbfb8aa3b, v49
	v_exp_f32_e32 v56, v56
	v_exp_f32_e32 v57, v57
	v_add_f32_e32 v56, 1.0, v56
	v_add_f32_e32 v57, 1.0, v57
	v_rcp_f32_e32 v56, v56
	v_rcp_f32_e32 v57, v57
	s_nop 0
	v_pk_mul_f32 v[48:49], v[48:49], v[56:57]
	s_nop 0
	v_pk_mul_f32 v[48:49], v[52:53], v[48:49]
	s_nop 0
	v_cvt_pk_bf16_f32 v48, v48, v49
	v_mul_f32_e32 v49, 0xbfb8aa3b, v50
	v_exp_f32_e32 v49, v49
	s_nop 0
	v_add_f32_e32 v49, 1.0, v49
	v_rcp_f32_e32 v52, v49
	v_mul_f32_e32 v49, 0xbfb8aa3b, v51
	v_exp_f32_e32 v49, v49
	s_nop 0
	v_add_f32_e32 v49, 1.0, v49
	v_rcp_f32_e32 v53, v49
	s_nop 0
	v_pk_mul_f32 v[50:51], v[50:51], v[52:53]
	s_nop 0
	v_pk_mul_f32 v[50:51], v[54:55], v[50:51]
	s_nop 0
	v_cvt_pk_bf16_f32 v49, v50, v51
	v_mul_f32_e32 v50, 0xbfb8aa3b, v40
	v_mul_f32_e32 v51, 0xbfb8aa3b, v41
	v_exp_f32_e32 v50, v50
	v_exp_f32_e32 v51, v51
	v_add_f32_e32 v50, 1.0, v50
	v_add_f32_e32 v51, 1.0, v51
	v_rcp_f32_e32 v50, v50
	v_rcp_f32_e32 v51, v51
	s_nop 0
	v_pk_mul_f32 v[40:41], v[40:41], v[50:51]
	s_nop 0
	v_pk_mul_f32 v[40:41], v[44:45], v[40:41]
	s_nop 0
	v_cvt_pk_bf16_f32 v50, v40, v41
	v_mul_f32_e32 v40, 0xbfb8aa3b, v42
	v_mul_f32_e32 v41, 0xbfb8aa3b, v43
	v_exp_f32_e32 v40, v40
	v_exp_f32_e32 v41, v41
	v_add_f32_e32 v40, 1.0, v40
	v_add_f32_e32 v41, 1.0, v41
	v_rcp_f32_e32 v40, v40
	v_rcp_f32_e32 v41, v41
	s_nop 0
	v_pk_mul_f32 v[40:41], v[42:43], v[40:41]
	s_nop 0
	v_pk_mul_f32 v[40:41], v[46:47], v[40:41]
	s_nop 0
	v_cvt_pk_bf16_f32 v51, v40, v41
	v_mov_b64_e32 v[40:41], s[36:37]
	v_mad_i64_i32 v[40:41], s[8:9], v180, s72, v[40:41]
	v_lshl_add_u64 v[40:41], v[172:173], 1, v[40:41]
	global_store_dwordx4 v[40:41], v[48:51], off
; __device__ __forceinline__ unsigned cvt_pk_bf16(float lo, float hi) { typedef float f2 __attribute__((ext_vector_type(2))); typedef __bf16 b2 __attribute__((ext_vector_type(2))); f2 v = {lo, hi}; b2 b = __builtin_convertvector(v, b2); return __builtin_bit_cast(unsigned, b); }
;     __device__ __forceinline__ void operator()(const f32x4 (&acc)[2][2][4][2], const Unit& u, int wr, int wc, int fr, int fq) const {
;     ...
;             for (int m = 0; m < 4; ++m) { f32x4 ua[2], db[2], gnext[2]; u32x4 w4; f32x4 cvs[2], uus[2];
;                 const bool isF = (m == 0) && (fr == 0), isL = (m == 3) && (fr == 15);
; #pragma unroll
;                 for (int n = 0; n < 2; ++n) { db[n] = db_next[n];
; #pragma unroll
;                     for (int j = 0; j < 4; ++j) ua[n][j] = dpp_ror1(gcur[n][j]);
;                     if (m < 3) { gnext[n] = acc[ai][1][m < 3 ? m + 1 : 3][n] * rs8[ai][m < 3 ? m + 1 : 3];
; #pragma unroll
;                         for (int j = 0; j < 4; ++j) db_next[n][j] = dpp_ror15(gnext[n][j]); }
;                     else { gnext[n] = (f32x4){0.f, 0.f, 0.f, 0.f}; db_next[n] = gnext[n]; }
;                     const f32x4 w0 = cwv[n][0], w1 = cwv[n][1], w2 = cwv[n][2], bb = cwv[n][3]; const f32x4 uu = acc[ai][0][m][n] * rs8[ai][m]; f32x4 cv;
; #pragma unroll
;                     for (int j = 0; j < 4; ++j) { const float up = (fr > 0) ? ua[n][j] : ua_prev[n][j]; const float dn = (fr < 15) ? db[n][j] : db_next[n][j];
;                         cv[j] = w0[j] * up + w1[j] * gcur[n][j] + w2[j] * dn + bb[j]; }
;                     cvs[n] = cv; uus[n] = uu;
;                     f32x4 a4;
; #pragma unroll
;                     for (int j = 0; j < 4; ++j) a4[j] = cv[j] * sigm(cv[j]) * uu[j];
;                     w4[2 * n] = cvt_pk_bf16(a4[0], a4[1]); w4[2 * n + 1] = cvt_pk_bf16(a4[2], a4[3]); }
;                 if (isF || isL) { float* e = edge + ((size_t)blk * 2 + (isL ? 1 : 0)) * 2816 + ch0;
; #pragma unroll
;                     for (int n = 0; n < 2; ++n) { *(f32x4*)(e + 4 * n) = cvs[n]; *(f32x4*)(e + esz + 4 * n) = uus[n]; *(f32x4*)(e + 2 * esz + 4 * n) = gcur[n]; } }
;                 else *(u32x4*)(act + (size_t)(row0 + ai * HALF + m * 16) * 2816 + ch0) = w4;
; #pragma unroll
;                 for (int n = 0; n < 2; ++n) { ua_prev[n] = ua[n]; gcur[n] = gnext[n]; }
.LBB0_1109:
	s_or_saveexec_b64 s[8:9], s[46:47]
	v_add_u32_e32 v89, 0x80, v190
	v_ashrrev_i32_e32 v106, 6, v89
	s_xor_b64 exec, exec, s[8:9]
	s_cbranch_execz .LBB0_1111
	v_mov_b64_e32 v[126:127], s[6:7]
	v_mad_i64_i32 v[126:127], s[46:47], v106, s71, v[126:127]
	v_lshl_add_u64 v[126:127], v[172:173], 2, v[126:127]
	v_lshl_add_u64 v[128:129], v[126:127], 0, s[66:67]
	v_lshl_add_u64 v[130:131], v[128:129], 0, s[66:67]
	global_store_dwordx4 v[126:127], v[48:51], off
	global_store_dwordx4 v[128:129], v[52:55], off
	global_store_dwordx4 v[130:131], v[60:63], off
	global_store_dwordx4 v[126:127], v[40:43], off offset:16
	global_store_dwordx4 v[128:129], v[44:47], off offset:16
	global_store_dwordx4 v[130:131], v[56:59], off offset:16
.LBB0_1111:
	s_or_b64 exec, exec, s[8:9]
	v_add_f32_e32 v40, v175, v177
	v_fmamk_f32 v40, v40, 0x3a800000, v242
	v_rsq_f32_e32 v44, v40
	v_mov_b32_e32 v45, v193
	v_mov_b32_e32 v41, v193
	v_mov_b32_e32 v56, v193
	v_mov_b32_dpp v45, v103 row_ror:1 row_mask:0xf bank_mask:0xf
	v_mov_b32_dpp v41, v102 row_ror:1 row_mask:0xf bank_mask:0xf
	v_pk_mul_f32 v[42:43], v[34:35], v[44:45] op_sel_hi:[1,0]
	v_pk_mul_f32 v[34:35], v[32:33], v[44:45] op_sel_hi:[1,0]
	v_mov_b32_e32 v57, v193
	v_mov_b32_e32 v48, v88
	v_mov_b32_e32 v49, v88
	v_mov_b32_dpp v56, v34 row_ror:15 row_mask:0xf bank_mask:0xf
	v_mov_b32_dpp v57, v35 row_ror:15 row_mask:0xf bank_mask:0xf
	v_pk_mul_f32 v[32:33], v[38:39], v[48:49]
	v_cndmask_b32_e64 v39, v45, v120, s[44:45]
	v_cndmask_b32_e64 v38, v41, v119, s[44:45]
	v_pk_mul_f32 v[52:53], v[96:97], v[102:103]
	v_cndmask_b32_e64 v47, v122, v57, s[42:43]
	v_cndmask_b32_e64 v46, v121, v56, s[42:43]
	v_pk_fma_f32 v[38:39], v[80:81], v[38:39], v[52:53]
	v_mov_b32_e32 v89, v88
	v_pk_fma_f32 v[38:39], v[84:85], v[46:47], v[38:39]
	v_mov_b32_e32 v54, v193
	v_pk_add_f32 v[38:39], v[92:93], v[38:39]
	v_mov_b32_e32 v55, v193
	v_mul_f32_e32 v46, 0xbfb8aa3b, v38
	v_mul_f32_e32 v47, 0xbfb8aa3b, v39
	v_exp_f32_e32 v46, v46
	v_exp_f32_e32 v47, v47
	v_mov_b32_dpp v54, v104 row_ror:1 row_mask:0xf bank_mask:0xf
	v_mov_b32_dpp v55, v105 row_ror:1 row_mask:0xf bank_mask:0xf
	v_add_f32_e32 v46, 1.0, v46
	v_add_f32_e32 v47, 1.0, v47
	v_rcp_f32_e32 v46, v46
	v_rcp_f32_e32 v47, v47
	v_mov_b32_e32 v58, v193
	v_mov_b32_e32 v59, v193
	v_pk_mul_f32 v[36:37], v[36:37], v[88:89]
	v_pk_mul_f32 v[38:39], v[38:39], v[46:47]
	v_mov_b32_dpp v58, v42 row_ror:15 row_mask:0xf bank_mask:0xf
	v_mov_b32_dpp v59, v43 row_ror:15 row_mask:0xf bank_mask:0xf
	v_pk_mul_f32 v[50:51], v[98:99], v[104:105]
	v_pk_mul_f32 v[36:37], v[36:37], v[38:39]
	v_cndmask_b32_e64 v39, v55, v116, s[44:45]
	v_cndmask_b32_e64 v38, v54, v115, s[44:45]
	v_cndmask_b32_e64 v47, v118, v59, s[42:43]
	v_cndmask_b32_e64 v46, v117, v58, s[42:43]
	v_pk_fma_f32 v[38:39], v[82:83], v[38:39], v[50:51]
	v_mov_b32_e32 v52, v193
	v_pk_fma_f32 v[38:39], v[86:87], v[46:47], v[38:39]
	v_mov_b32_e32 v60, v193
	v_pk_add_f32 v[38:39], v[94:95], v[38:39]
	v_mov_b32_dpp v52, v91 row_ror:1 row_mask:0xf bank_mask:0xf
	v_mul_f32_e32 v46, 0xbfb8aa3b, v38
	v_mul_f32_e32 v47, 0xbfb8aa3b, v39
	v_exp_f32_e32 v46, v46
	v_exp_f32_e32 v47, v47
	v_mov_b32_e32 v61, v193
	v_mov_b32_e32 v53, v193
	v_add_f32_e32 v46, 1.0, v46
	v_add_f32_e32 v47, 1.0, v47
	v_rcp_f32_e32 v46, v46
	v_rcp_f32_e32 v47, v47
	v_pk_mul_f32 v[28:29], v[28:29], v[88:89]
	v_mov_b32_dpp v53, v101 row_ror:1 row_mask:0xf bank_mask:0xf
	v_mov_b32_e32 v62, v193
	v_pk_mul_f32 v[38:39], v[38:39], v[46:47]
	v_cvt_pk_bf16_f32 v46, v36, v37
	v_pk_mul_f32 v[32:33], v[32:33], v[38:39]
	v_mov_b32_e32 v39, v193
	v_cvt_pk_bf16_f32 v47, v32, v33
	v_pk_mul_f32 v[32:33], v[26:27], v[44:45] op_sel_hi:[1,0]
	v_mov_b32_dpp v39, v90 row_ror:1 row_mask:0xf bank_mask:0xf
	v_pk_mul_f32 v[26:27], v[24:25], v[44:45] op_sel_hi:[1,0]
	v_pk_mul_f32 v[24:25], v[30:31], v[48:49]
	v_cndmask_b32_e64 v31, v52, v112, s[44:45]
	v_mov_b32_dpp v60, v26 row_ror:15 row_mask:0xf bank_mask:0xf
	v_mov_b32_dpp v61, v27 row_ror:15 row_mask:0xf bank_mask:0xf
	v_cndmask_b32_e64 v30, v39, v111, s[44:45]
	v_pk_mul_f32 v[48:49], v[90:91], v[76:77]
	v_cndmask_b32_e64 v37, v114, v61, s[42:43]
	v_cndmask_b32_e64 v36, v113, v60, s[42:43]
	v_pk_fma_f32 v[30:31], v[64:65], v[30:31], v[48:49]
	v_mov_b32_e32 v38, v193
	v_pk_fma_f32 v[30:31], v[68:69], v[36:37], v[30:31]
	v_mov_b32_e32 v63, v193
	v_pk_add_f32 v[30:31], v[72:73], v[30:31]
	v_mov_b32_dpp v38, v100 row_ror:1 row_mask:0xf bank_mask:0xf
	v_mul_f32_e32 v36, 0xbfb8aa3b, v30
	v_mul_f32_e32 v37, 0xbfb8aa3b, v31
	v_exp_f32_e32 v36, v36
	v_exp_f32_e32 v37, v37
	v_mov_b32_dpp v62, v32 row_ror:15 row_mask:0xf bank_mask:0xf
	v_mov_b32_dpp v63, v33 row_ror:15 row_mask:0xf bank_mask:0xf
	v_add_f32_e32 v36, 1.0, v36
	v_add_f32_e32 v37, 1.0, v37
	v_rcp_f32_e32 v36, v36
	v_rcp_f32_e32 v37, v37
	v_pk_mul_f32 v[50:51], v[100:101], v[78:79]
	v_add_f32_e32 v40, v179, v181
	v_fmamk_f32 v40, v40, 0x3a800000, v242
	v_pk_mul_f32 v[30:31], v[30:31], v[36:37]
	v_rsq_f32_e32 v40, v40
	v_pk_mul_f32 v[28:29], v[28:29], v[30:31]
	v_cndmask_b32_e64 v31, v110, v63, s[42:43]
	v_cvt_pk_bf16_f32 v48, v28, v29
	v_cndmask_b32_e64 v29, v53, v108, s[44:45]
	v_cndmask_b32_e64 v28, v38, v107, s[44:45]
	v_pk_fma_f32 v[28:29], v[66:67], v[28:29], v[50:51]
	v_cndmask_b32_e64 v30, v109, v62, s[42:43]
	v_pk_fma_f32 v[28:29], v[70:71], v[30:31], v[28:29]
	v_pk_mul_f32 v[12:13], v[12:13], v[40:41] op_sel_hi:[1,0]
	v_pk_add_f32 v[28:29], v[74:75], v[28:29]
	v_mov_b32_e32 v50, v193
	v_mul_f32_e32 v30, 0xbfb8aa3b, v28
	v_mul_f32_e32 v31, 0xbfb8aa3b, v29
	v_exp_f32_e32 v30, v30
	v_exp_f32_e32 v31, v31
	v_mov_b32_e32 v51, v193
	v_mov_b32_dpp v50, v12 row_ror:15 row_mask:0xf bank_mask:0xf
; __device__ __forceinline__ unsigned cvt_pk_bf16(float lo, float hi) { typedef float f2 __attribute__((ext_vector_type(2))); typedef __bf16 b2 __attribute__((ext_vector_type(2))); f2 v = {lo, hi}; b2 b = __builtin_convertvector(v, b2); return __builtin_bit_cast(unsigned, b); }
;     __device__ __forceinline__ void operator()(const f32x4 (&acc)[2][2][4][2], const Unit& u, int wr, int wc, int fr, int fq) const {
;     ...
;             for (int m = 0; m < 4; ++m) { f32x4 ua[2], db[2], gnext[2]; u32x4 w4; f32x4 cvs[2], uus[2];
;                 const bool isF = (m == 0) && (fr == 0), isL = (m == 3) && (fr == 15);
; #pragma unroll
;                 for (int n = 0; n < 2; ++n) { db[n] = db_next[n];
; #pragma unroll
;                     for (int j = 0; j < 4; ++j) ua[n][j] = dpp_ror1(gcur[n][j]);
;                     if (m < 3) { gnext[n] = acc[ai][1][m < 3 ? m + 1 : 3][n] * rs8[ai][m < 3 ? m + 1 : 3];
; #pragma unroll
;                         for (int j = 0; j < 4; ++j) db_next[n][j] = dpp_ror15(gnext[n][j]); }
;                     else { gnext[n] = (f32x4){0.f, 0.f, 0.f, 0.f}; db_next[n] = gnext[n]; }
;                     const f32x4 w0 = cwv[n][0], w1 = cwv[n][1], w2 = cwv[n][2], bb = cwv[n][3]; const f32x4 uu = acc[ai][0][m][n] * rs8[ai][m]; f32x4 cv;
; #pragma unroll
;                     for (int j = 0; j < 4; ++j) { const float up = (fr > 0) ? ua[n][j] : ua_prev[n][j]; const float dn = (fr < 15) ? db[n][j] : db_next[n][j];
;                         cv[j] = w0[j] * up + w1[j] * gcur[n][j] + w2[j] * dn + bb[j]; }
;                     cvs[n] = cv; uus[n] = uu;
;                     f32x4 a4;
; #pragma unroll
;                     for (int j = 0; j < 4; ++j) a4[j] = cv[j] * sigm(cv[j]) * uu[j];
;                     w4[2 * n] = cvt_pk_bf16(a4[0], a4[1]); w4[2 * n + 1] = cvt_pk_bf16(a4[2], a4[3]); }
;                 if (isF || isL) { float* e = edge + ((size_t)blk * 2 + (isL ? 1 : 0)) * 2816 + ch0;
; #pragma unroll
;                     for (int n = 0; n < 2; ++n) { *(f32x4*)(e + 4 * n) = cvs[n]; *(f32x4*)(e + esz + 4 * n) = uus[n]; *(f32x4*)(e + 2 * esz + 4 * n) = gcur[n]; } }
;                 else *(u32x4*)(act + (size_t)(row0 + ai * HALF + m * 16) * 2816 + ch0) = w4;
; #pragma unroll
;                 for (int n = 0; n < 2; ++n) { ua_prev[n] = ua[n]; gcur[n] = gnext[n]; }
	v_add_f32_e32 v30, 1.0, v30
	v_add_f32_e32 v31, 1.0, v31
	v_rcp_f32_e32 v30, v30
	v_rcp_f32_e32 v31, v31
	v_mov_b32_dpp v51, v13 row_ror:15 row_mask:0xf bank_mask:0xf
	v_pk_mul_f32 v[36:37], v[16:17], v[44:45] op_sel_hi:[1,0]
	v_pk_mul_f32 v[22:23], v[22:23], v[44:45] op_sel_hi:[1,0]
	v_pk_mul_f32 v[28:29], v[28:29], v[30:31]
	v_pk_mul_f32 v[20:21], v[20:21], v[44:45] op_sel_hi:[1,0]
	v_pk_mul_f32 v[24:25], v[24:25], v[28:29]
	v_pk_mul_f32 v[30:31], v[18:19], v[44:45] op_sel_hi:[1,0]
	v_cvt_pk_bf16_f32 v49, v24, v25
	v_mov_b64_e32 v[24:25], s[36:37]
	v_mad_i64_i32 v[28:29], s[8:9], v178, s72, v[24:25]
	v_lshl_add_u64 v[28:29], v[28:29], 0, v[124:125]
	global_store_dwordx4 v[28:29], v[46:49], off
	v_mad_i64_i32 v[16:17], s[8:9], v176, s72, v[24:25]
	s_nop 0
	v_mov_b32_e32 v46, v193
	v_mov_b32_e32 v47, v193
	v_pk_mul_f32 v[24:25], v[96:97], v[34:35]
	v_mov_b32_dpp v46, v34 row_ror:1 row_mask:0xf bank_mask:0xf
	v_mov_b32_dpp v47, v35 row_ror:1 row_mask:0xf bank_mask:0xf
	v_cndmask_b32_e64 v35, v47, v45, s[44:45]
	v_cndmask_b32_e64 v34, v46, v41, s[44:45]
	v_lshl_add_u64 v[28:29], v[16:17], 0, v[124:125]
	v_cndmask_b32_e64 v17, v57, v51, s[42:43]
	v_cndmask_b32_e64 v16, v56, v50, s[42:43]
	v_pk_fma_f32 v[24:25], v[80:81], v[34:35], v[24:25]
	v_mov_b32_e32 v44, v193
	v_pk_fma_f32 v[16:17], v[84:85], v[16:17], v[24:25]
	v_mov_b32_e32 v107, v193
	v_pk_add_f32 v[16:17], v[92:93], v[16:17]
	v_mov_b32_e32 v48, v193
	v_mul_f32_e32 v24, 0xbfb8aa3b, v16
	v_mul_f32_e32 v25, 0xbfb8aa3b, v17
	v_exp_f32_e32 v24, v24
	v_exp_f32_e32 v25, v25
	v_mov_b32_e32 v49, v193
	v_mov_b32_dpp v44, v12 row_ror:1 row_mask:0xf bank_mask:0xf
	v_add_f32_e32 v24, 1.0, v24
	v_add_f32_e32 v25, 1.0, v25
	v_rcp_f32_e32 v24, v24
	v_rcp_f32_e32 v25, v25
	v_mov_b32_dpp v107, v13 row_ror:1 row_mask:0xf bank_mask:0xf
	v_mov_b32_dpp v48, v42 row_ror:1 row_mask:0xf bank_mask:0xf
	v_mov_b32_dpp v49, v43 row_ror:1 row_mask:0xf bank_mask:0xf
	v_pk_mul_f32 v[16:17], v[16:17], v[24:25]
	v_pk_mul_f32 v[14:15], v[14:15], v[40:41] op_sel_hi:[1,0]
	v_pk_mul_f32 v[16:17], v[20:21], v[16:17]
	v_mov_b32_e32 v88, v193
	v_mov_b32_e32 v89, v193
	v_pk_mul_f32 v[18:19], v[98:99], v[42:43]
	v_cvt_pk_bf16_f32 v24, v16, v17
	v_cndmask_b32_e64 v17, v107, v47, s[44:45]
	v_cndmask_b32_e64 v16, v44, v46, s[44:45]
	v_pk_mul_f32 v[42:43], v[96:97], v[12:13]
	v_mov_b32_dpp v88, v14 row_ror:15 row_mask:0xf bank_mask:0xf
	v_mov_b32_dpp v89, v15 row_ror:15 row_mask:0xf bank_mask:0xf
	v_cndmask_b32_e64 v21, v51, 0, s[42:43]
	v_cndmask_b32_e64 v20, v50, 0, s[42:43]
	v_pk_fma_f32 v[16:17], v[80:81], v[16:17], v[42:43]
	v_cndmask_b32_e64 v43, v49, v55, s[44:45]
	v_cndmask_b32_e64 v42, v48, v54, s[44:45]
	v_pk_fma_f32 v[16:17], v[84:85], v[20:21], v[16:17]
	v_cndmask_b32_e64 v21, v59, v89, s[42:43]
	v_cndmask_b32_e64 v20, v58, v88, s[42:43]
	v_pk_fma_f32 v[18:19], v[82:83], v[42:43], v[18:19]
	v_mov_b32_e32 v108, v193
	v_pk_fma_f32 v[18:19], v[86:87], v[20:21], v[18:19]
	v_mov_b32_e32 v109, v193
	v_pk_add_f32 v[18:19], v[94:95], v[18:19]
	v_mov_b32_e32 v90, v193
	v_mul_f32_e32 v20, 0xbfb8aa3b, v18
	v_mul_f32_e32 v21, 0xbfb8aa3b, v19
	v_exp_f32_e32 v20, v20
	v_exp_f32_e32 v21, v21
	v_mov_b32_e32 v91, v193
	v_mov_b32_dpp v108, v14 row_ror:1 row_mask:0xf bank_mask:0xf
	v_add_f32_e32 v20, 1.0, v20
	v_add_f32_e32 v21, 1.0, v21
	v_rcp_f32_e32 v20, v20
	v_rcp_f32_e32 v21, v21
	v_mov_b32_dpp v109, v15 row_ror:1 row_mask:0xf bank_mask:0xf
	v_mov_b32_dpp v90, v26 row_ror:1 row_mask:0xf bank_mask:0xf
	v_mov_b32_dpp v91, v27 row_ror:1 row_mask:0xf bank_mask:0xf
	v_pk_mul_f32 v[18:19], v[18:19], v[20:21]
	v_mov_b32_e32 v100, v193
	v_pk_mul_f32 v[18:19], v[22:23], v[18:19]
	v_mov_b32_e32 v101, v193
	v_pk_mul_f32 v[8:9], v[8:9], v[40:41] op_sel_hi:[1,0]
	v_mov_b32_e32 v102, v193
	v_mov_b32_e32 v103, v193
	v_pk_mul_f32 v[34:35], v[98:99], v[14:15]
	v_cvt_pk_bf16_f32 v25, v18, v19
	v_cndmask_b32_e64 v19, v109, v49, s[44:45]
	v_cndmask_b32_e64 v18, v108, v48, s[44:45]
	v_mov_b32_dpp v100, v32 row_ror:1 row_mask:0xf bank_mask:0xf
	v_mov_b32_dpp v101, v33 row_ror:1 row_mask:0xf bank_mask:0xf
	v_mov_b32_dpp v102, v8 row_ror:15 row_mask:0xf bank_mask:0xf
	v_mov_b32_dpp v103, v9 row_ror:15 row_mask:0xf bank_mask:0xf
	v_cndmask_b32_e64 v21, v89, 0, s[42:43]
	v_cndmask_b32_e64 v20, v88, 0, s[42:43]
	v_pk_fma_f32 v[18:19], v[82:83], v[18:19], v[34:35]
	v_pk_mul_f32 v[22:23], v[6:7], v[40:41] op_sel_hi:[1,0]
	v_pk_mul_f32 v[6:7], v[78:79], v[32:33]
	v_pk_mul_f32 v[26:27], v[76:77], v[26:27]
	v_cndmask_b32_e64 v33, v91, v52, s[44:45]
	v_cndmask_b32_e64 v32, v90, v39, s[44:45]
	v_pk_fma_f32 v[18:19], v[86:87], v[20:21], v[18:19]
	v_pk_mul_f32 v[20:21], v[4:5], v[40:41] op_sel_hi:[1,0]
	v_cndmask_b32_e64 v5, v61, v103, s[42:43]
	v_cndmask_b32_e64 v4, v60, v102, s[42:43]
	v_pk_fma_f32 v[26:27], v[64:65], v[32:33], v[26:27]
	v_mov_b32_e32 v34, v193
	v_pk_fma_f32 v[4:5], v[68:69], v[4:5], v[26:27]
	v_mov_b32_e32 v35, v193
	v_pk_add_f32 v[4:5], v[72:73], v[4:5]
; __device__ __forceinline__ unsigned cvt_pk_bf16(float lo, float hi) { typedef float f2 __attribute__((ext_vector_type(2))); typedef __bf16 b2 __attribute__((ext_vector_type(2))); f2 v = {lo, hi}; b2 b = __builtin_convertvector(v, b2); return __builtin_bit_cast(unsigned, b); }
;     __device__ __forceinline__ void operator()(const f32x4 (&acc)[2][2][4][2], const Unit& u, int wr, int wc, int fr, int fq) const {
;     ...
;             for (int m = 0; m < 4; ++m) { f32x4 ua[2], db[2], gnext[2]; u32x4 w4; f32x4 cvs[2], uus[2];
;                 const bool isF = (m == 0) && (fr == 0), isL = (m == 3) && (fr == 15);
; #pragma unroll
;                 for (int n = 0; n < 2; ++n) { db[n] = db_next[n];
; #pragma unroll
;                     for (int j = 0; j < 4; ++j) ua[n][j] = dpp_ror1(gcur[n][j]);
;                     if (m < 3) { gnext[n] = acc[ai][1][m < 3 ? m + 1 : 3][n] * rs8[ai][m < 3 ? m + 1 : 3];
; #pragma unroll
;                         for (int j = 0; j < 4; ++j) db_next[n][j] = dpp_ror15(gnext[n][j]); }
;                     else { gnext[n] = (f32x4){0.f, 0.f, 0.f, 0.f}; db_next[n] = gnext[n]; }
;                     const f32x4 w0 = cwv[n][0], w1 = cwv[n][1], w2 = cwv[n][2], bb = cwv[n][3]; const f32x4 uu = acc[ai][0][m][n] * rs8[ai][m]; f32x4 cv;
; #pragma unroll
;                     for (int j = 0; j < 4; ++j) { const float up = (fr > 0) ? ua[n][j] : ua_prev[n][j]; const float dn = (fr < 15) ? db[n][j] : db_next[n][j];
;                         cv[j] = w0[j] * up + w1[j] * gcur[n][j] + w2[j] * dn + bb[j]; }
;                     cvs[n] = cv; uus[n] = uu;
;                     f32x4 a4;
; #pragma unroll
;                     for (int j = 0; j < 4; ++j) a4[j] = cv[j] * sigm(cv[j]) * uu[j];
;                     w4[2 * n] = cvt_pk_bf16(a4[0], a4[1]); w4[2 * n + 1] = cvt_pk_bf16(a4[2], a4[3]); }
;                 if (isF || isL) { float* e = edge + ((size_t)blk * 2 + (isL ? 1 : 0)) * 2816 + ch0;
; #pragma unroll
;                     for (int n = 0; n < 2; ++n) { *(f32x4*)(e + 4 * n) = cvs[n]; *(f32x4*)(e + esz + 4 * n) = uus[n]; *(f32x4*)(e + 2 * esz + 4 * n) = gcur[n]; } }
;                 else *(u32x4*)(act + (size_t)(row0 + ai * HALF + m * 16) * 2816 + ch0) = w4;
; #pragma unroll
;                 for (int n = 0; n < 2; ++n) { ua_prev[n] = ua[n]; gcur[n] = gnext[n]; }
	v_mov_b32_dpp v34, v8 row_ror:1 row_mask:0xf bank_mask:0xf
	v_mul_f32_e32 v26, 0xbfb8aa3b, v4
	v_mul_f32_e32 v27, 0xbfb8aa3b, v5
	v_exp_f32_e32 v26, v26
	v_exp_f32_e32 v27, v27
	v_mov_b32_dpp v35, v9 row_ror:1 row_mask:0xf bank_mask:0xf
	v_pk_mul_f32 v[10:11], v[10:11], v[40:41] op_sel_hi:[1,0]
	v_add_f32_e32 v26, 1.0, v26
	v_add_f32_e32 v27, 1.0, v27
	v_rcp_f32_e32 v26, v26
	v_rcp_f32_e32 v27, v27
	v_mov_b32_e32 v104, v193
	v_mov_b32_e32 v105, v193
	v_cndmask_b32_e64 v33, v103, 0, s[42:43]
	v_pk_mul_f32 v[4:5], v[4:5], v[26:27]
	v_mov_b32_dpp v104, v10 row_ror:15 row_mask:0xf bank_mask:0xf
	v_pk_mul_f32 v[4:5], v[36:37], v[4:5]
	v_pk_mul_f32 v[36:37], v[76:77], v[8:9]
	v_cvt_pk_bf16_f32 v26, v4, v5
	v_cndmask_b32_e64 v5, v35, v91, s[44:45]
	v_cndmask_b32_e64 v4, v34, v90, s[44:45]
	v_mov_b32_dpp v105, v11 row_ror:15 row_mask:0xf bank_mask:0xf
	v_cndmask_b32_e64 v32, v102, 0, s[42:43]
	v_pk_fma_f32 v[4:5], v[64:65], v[4:5], v[36:37]
	v_cndmask_b32_e64 v37, v101, v53, s[44:45]
	v_cndmask_b32_e64 v36, v100, v38, s[44:45]
	v_pk_fma_f32 v[4:5], v[68:69], v[32:33], v[4:5]
	v_cndmask_b32_e64 v33, v63, v105, s[42:43]
	v_cndmask_b32_e64 v32, v62, v104, s[42:43]
	v_pk_fma_f32 v[6:7], v[66:67], v[36:37], v[6:7]
	v_mov_b32_e32 v41, v193
	v_pk_fma_f32 v[6:7], v[70:71], v[32:33], v[6:7]
	v_mov_b32_e32 v42, v193
	v_pk_add_f32 v[6:7], v[74:75], v[6:7]
	v_mov_b32_dpp v41, v10 row_ror:1 row_mask:0xf bank_mask:0xf
	v_mul_f32_e32 v27, 0xbfb8aa3b, v6
	v_exp_f32_e32 v27, v27
	v_mov_b32_dpp v42, v11 row_ror:1 row_mask:0xf bank_mask:0xf
	v_pk_mul_f32 v[34:35], v[78:79], v[10:11]
	v_pk_add_f32 v[16:17], v[92:93], v[16:17]
	v_add_f32_e32 v27, 1.0, v27
	v_rcp_f32_e32 v32, v27
	v_mul_f32_e32 v27, 0xbfb8aa3b, v7
	v_exp_f32_e32 v27, v27
	v_pk_add_f32 v[18:19], v[94:95], v[18:19]
	v_pk_add_f32 v[4:5], v[72:73], v[4:5]
	v_pk_mul_f32 v[2:3], v[2:3], v[40:41] op_sel_hi:[1,0]
	v_add_f32_e32 v27, 1.0, v27
	v_rcp_f32_e32 v33, v27
	v_pk_mul_f32 v[0:1], v[0:1], v[40:41] op_sel_hi:[1,0]
	v_pk_mul_f32 v[6:7], v[6:7], v[32:33]
	s_nop 0
	v_pk_mul_f32 v[6:7], v[30:31], v[6:7]
	s_nop 0
	v_cvt_pk_bf16_f32 v27, v6, v7
	v_cndmask_b32_e64 v7, v42, v101, s[44:45]
	v_cndmask_b32_e64 v6, v41, v100, s[44:45]
	global_store_dwordx4 v[28:29], v[24:27], off
	v_pk_fma_f32 v[6:7], v[66:67], v[6:7], v[34:35]
	s_nop 0
	v_cndmask_b32_e64 v25, v105, 0, s[42:43]
	v_cndmask_b32_e64 v24, v104, 0, s[42:43]
	v_pk_fma_f32 v[6:7], v[70:71], v[24:25], v[6:7]
	s_nop 0
	v_pk_add_f32 v[6:7], v[74:75], v[6:7]
	s_and_saveexec_b64 s[8:9], s[40:41]
	s_xor_b64 s[40:41], exec, s[8:9]
	s_cbranch_execz .LBB0_1113
	v_mul_f32_e32 v8, 0xbfb8aa3b, v16
	v_mul_f32_e32 v9, 0xbfb8aa3b, v17
	v_exp_f32_e32 v8, v8
	v_exp_f32_e32 v9, v9
	v_add_f32_e32 v8, 1.0, v8
	v_add_f32_e32 v9, 1.0, v9
	v_rcp_f32_e32 v8, v8
	v_rcp_f32_e32 v9, v9
	s_nop 0
	v_pk_mul_f32 v[8:9], v[16:17], v[8:9]
	s_nop 0
	v_pk_mul_f32 v[8:9], v[20:21], v[8:9]
	s_nop 0
	v_cvt_pk_bf16_f32 v8, v8, v9
	v_mul_f32_e32 v9, 0xbfb8aa3b, v18
	v_exp_f32_e32 v9, v9
	s_nop 0
	v_add_f32_e32 v9, 1.0, v9
	v_rcp_f32_e32 v10, v9
	v_mul_f32_e32 v9, 0xbfb8aa3b, v19
	v_exp_f32_e32 v9, v9
	s_nop 0
	v_add_f32_e32 v9, 1.0, v9
	v_rcp_f32_e32 v11, v9
	s_nop 0
	v_pk_mul_f32 v[10:11], v[18:19], v[10:11]
	s_nop 0
	v_pk_mul_f32 v[10:11], v[22:23], v[10:11]
	s_nop 0
	v_cvt_pk_bf16_f32 v9, v10, v11
	v_mul_f32_e32 v10, 0xbfb8aa3b, v4
	v_mul_f32_e32 v11, 0xbfb8aa3b, v5
	v_exp_f32_e32 v10, v10
	v_exp_f32_e32 v11, v11
	v_add_f32_e32 v10, 1.0, v10
	v_add_f32_e32 v11, 1.0, v11
	v_rcp_f32_e32 v10, v10
	v_rcp_f32_e32 v11, v11
	s_nop 0
	v_pk_mul_f32 v[4:5], v[4:5], v[10:11]
	s_nop 0
	v_pk_mul_f32 v[0:1], v[0:1], v[4:5]
	s_nop 0
	v_cvt_pk_bf16_f32 v10, v0, v1
	v_mul_f32_e32 v0, 0xbfb8aa3b, v6
	v_mul_f32_e32 v1, 0xbfb8aa3b, v7
	v_exp_f32_e32 v0, v0
	v_exp_f32_e32 v1, v1
	v_add_f32_e32 v0, 1.0, v0
	v_add_f32_e32 v1, 1.0, v1
	v_rcp_f32_e32 v0, v0
	v_rcp_f32_e32 v1, v1
	s_nop 0
	v_pk_mul_f32 v[0:1], v[6:7], v[0:1]
	s_nop 0
	v_pk_mul_f32 v[0:1], v[2:3], v[0:1]
	s_nop 0
	v_cvt_pk_bf16_f32 v11, v0, v1
	v_mov_b64_e32 v[0:1], s[36:37]
	v_mad_i64_i32 v[0:1], s[8:9], v174, s72, v[0:1]
	v_lshl_add_u64 v[0:1], v[172:173], 1, v[0:1]
	global_store_dwordx4 v[0:1], v[8:11], off
.LBB0_1113:
	s_andn2_saveexec_b64 s[40:41], s[40:41]
	s_cbranch_execz .LBB0_1115
	v_mov_b64_e32 v[24:25], s[6:7]
	v_mad_i64_i32 v[24:25], s[8:9], v106, s71, v[24:25]
	v_lshl_add_u64 v[24:25], v[172:173], 2, v[24:25]
	s_mov_b64 s[8:9], 0x2c00
	v_lshl_add_u64 v[26:27], v[24:25], 0, s[8:9]
	v_add_co_u32_e32 v24, vcc, 0x2000, v24
	v_lshl_add_u64 v[28:29], v[26:27], 0, s[66:67]
	s_nop 0
	v_addc_co_u32_e32 v25, vcc, 0, v25, vcc
	v_lshl_add_u64 v[30:31], v[28:29], 0, s[66:67]
	global_store_dwordx4 v[24:25], v[16:19], off offset:3072
	global_store_dwordx4 v[28:29], v[20:23], off
	global_store_dwordx4 v[30:31], v[12:15], off
	global_store_dwordx4 v[26:27], v[4:7], off offset:16
	global_store_dwordx4 v[28:29], v[0:3], off offset:16
	global_store_dwordx4 v[30:31], v[8:11], off offset:16

; __device__ __forceinline__ unsigned cvt_pk_bf16(float lo, float hi) { typedef float f2 __attribute__((ext_vector_type(2))); typedef __bf16 b2 __attribute__((ext_vector_type(2))); f2 v = {lo, hi}; b2 b = __builtin_convertvector(v, b2); return __builtin_bit_cast(unsigned, b); }
; __device__ __forceinline__ float sigm(float v) { return __builtin_amdgcn_rcpf(1.0f + __builtin_amdgcn_exp2f(-1.4426950408889634f * v)); }
; __device__ __forceinline__ void conv_fix_phase(const float* edge, bf16_t* ACT, const float* cw, int T, int gtid, int NT) {
;     constexpr int NCH = FF / 8; const int NBLK = T / 64; const size_t esz = (size_t)NBLK * 2 * FF;
; #pragma unroll 1
;     for (int idx = gtid; idx < NBLK * 2 * NCH; idx += NT) { const int ch = (idx % NCH) * 8, bw = idx / NCH, which = bw & 1, blk = bw >> 1;
;         const int row = blk * 64 + (which ? 63 : 0), pos = row & (SEQ - 1);
;         const bool nb_ok = which ? (pos < SEQ - 1) : (pos > 0);
;         const float* e = edge + (size_t)bw * FF + ch; const float* wv = cw + (which ? 2 * FF : 0) + ch;
;         const float* gn = edge + 2 * esz + (size_t)(which ? (blk + 1) * 2 : (blk - 1) * 2 + 1) * FF + ch;
;         u32x4 o;
; #pragma unroll
;         for (int q = 0; q < 2; ++q) { const f32x4 cv = ((const f32x4*)e)[q], uu = ((const f32x4*)(e + esz))[q], wq = ((const f32x4*)wv)[q]; f32x4 gq = {0.f, 0.f, 0.f, 0.f}; if (nb_ok) gq = ((const f32x4*)gn)[q];
;             float r[4];
; #pragma unroll
;             for (int j = 0; j < 4; ++j) { const float c = cv[j] + wq[j] * gq[j]; r[j] = c * pg8::sigm(c) * uu[j]; }
;             o[2 * q] = cvt_pk_bf16(r[0], r[1]); o[2 * q + 1] = cvt_pk_bf16(r[2], r[3]); }
;         *(u32x4*)(ACT + (size_t)row * FF + ch) = o; }
; }
.LBB0_1174:
	s_or_b64 exec, exec, s[8:9]
	s_waitcnt vmcnt(0) lgkmcnt(0)
	v_pk_fma_f32 v[20:21], v[24:25], v[28:29], v[20:21]
	v_pk_fma_f32 v[22:23], v[26:27], v[30:31], v[22:23]
	v_mul_f32_e32 v24, 0xbfb8aa3b, v20
	v_mul_f32_e32 v25, 0xbfb8aa3b, v21
	v_exp_f32_e32 v24, v24
	v_exp_f32_e32 v25, v25
	v_pk_fma_f32 v[8:9], v[16:17], v[8:9], v[12:13]
	v_bfi_b32 v34, 63, v38, v39
	v_add_f32_e32 v24, 1.0, v24
	v_add_f32_e32 v25, 1.0, v25
	v_rcp_f32_e32 v24, v24
	v_rcp_f32_e32 v25, v25
	v_add_u32_e32 v36, s54, v36
	v_cmp_le_i32_e32 vcc, s1, v36
	v_add_u32_e32 v37, s16, v37
	v_pk_mul_f32 v[20:21], v[20:21], v[24:25]
	s_or_b64 s[22:23], vcc, s[22:23]
	v_pk_mul_f32 v[4:5], v[4:5], v[20:21]
	v_mul_f32_e32 v20, 0xbfb8aa3b, v22
	v_mul_f32_e32 v21, 0xbfb8aa3b, v23
	v_exp_f32_e32 v20, v20
	v_exp_f32_e32 v21, v21
	v_cvt_pk_bf16_f32 v4, v4, v5
	v_add_f32_e32 v20, 1.0, v20
	v_add_f32_e32 v21, 1.0, v21
	v_rcp_f32_e32 v20, v20
	v_rcp_f32_e32 v21, v21
	s_nop 0
	v_pk_mul_f32 v[20:21], v[22:23], v[20:21]
	s_nop 0
	v_pk_mul_f32 v[6:7], v[6:7], v[20:21]
	s_nop 0
	v_cvt_pk_bf16_f32 v5, v6, v7
	v_pk_fma_f32 v[6:7], v[18:19], v[10:11], v[14:15]
	v_mul_f32_e32 v10, 0xbfb8aa3b, v8
	v_mul_f32_e32 v11, 0xbfb8aa3b, v9
	v_exp_f32_e32 v10, v10
	v_exp_f32_e32 v11, v11
	v_add_f32_e32 v10, 1.0, v10
	v_add_f32_e32 v11, 1.0, v11
	v_rcp_f32_e32 v10, v10
	v_rcp_f32_e32 v11, v11
	s_nop 0
	v_pk_mul_f32 v[8:9], v[8:9], v[10:11]
	s_nop 0
	v_pk_mul_f32 v[0:1], v[0:1], v[8:9]
	v_mul_f32_e32 v8, 0xbfb8aa3b, v6
	v_mul_f32_e32 v9, 0xbfb8aa3b, v7
	v_exp_f32_e32 v8, v8
	v_exp_f32_e32 v9, v9
	v_add_f32_e32 v8, 1.0, v8
	v_add_f32_e32 v9, 1.0, v9
	v_rcp_f32_e32 v8, v8
	v_rcp_f32_e32 v9, v9
	s_nop 0
	v_pk_mul_f32 v[6:7], v[6:7], v[8:9]
	s_nop 0
	v_pk_mul_f32 v[2:3], v[2:3], v[6:7]
	v_cvt_pk_bf16_f32 v6, v0, v1
	v_mov_b64_e32 v[0:1], s[12:13]
	v_mad_i64_i32 v[0:1], s[8:9], v34, s18, v[0:1]
	v_cvt_pk_bf16_f32 v7, v2, v3
	v_lshl_add_u64 v[0:1], v[32:33], 1, v[0:1]
	global_store_dwordx4 v[0:1], v[4:7], off
	s_andn2_b64 exec, exec, s[22:23]
	s_cbranch_execz .LBB0_1179
.LBB0_1175:
	s_mov_b32 s8, 0x2e8ba2e9
	v_mul_hi_i32 v0, v36, s8
	v_lshrrev_b32_e32 v1, 31, v0
	v_ashrrev_i32_e32 v0, 6, v0
	v_add_u32_e32 v12, v0, v1
	v_mul_i32_i24_e32 v0, 0x160, v12
	v_lshlrev_b32_e32 v0, 3, v0
	v_sub_u32_e32 v32, v37, v0
	v_bfe_i32 v38, v12, 0, 1
	v_mul_hi_i32_i24_e32 v1, 0x2c00, v12
	v_mul_i32_i24_e32 v0, 0x2c00, v12
	v_ashrrev_i32_e32 v33, 31, v32
	v_lshl_add_u64 v[0:1], s[10:11], 0, v[0:1]
	v_lshlrev_b64 v[8:9], 2, v[32:33]
	v_and_b32_e32 v192, 0x5800, v38
	v_lshl_add_u64 v[0:1], v[0:1], 0, v[8:9]
	v_lshl_add_u64 v[2:3], s[6:7], 0, v[192:193]
	v_lshl_add_u64 v[10:11], v[2:3], 0, v[8:9]
	v_lshl_add_u64 v[2:3], v[0:1], 0, s[66:67]
	global_load_dwordx4 v[20:23], v[0:1], off
	global_load_dwordx4 v[4:7], v[2:3], off
	global_load_dwordx4 v[24:27], v[10:11], off
	v_lshlrev_b32_e32 v39, 5, v12
	v_and_b32_e32 v14, 0xffffffc0, v39
	v_and_b32_e32 v15, 63, v38
	s_movk_i32 s8, 0x7ff
	v_bitop3_b32 v14, v15, s8, v14 bitop3:0xc8
	v_and_b32_e32 v15, 0x7ff, v38
	v_and_b32_e32 v13, 1, v12
	v_cmp_ne_u32_e32 vcc, v14, v15
	v_and_b32_e32 v14, -2, v12
	v_add_u32_e32 v14, 2, v14
	v_add_u32_e32 v12, -1, v12
	v_cmp_eq_u32_e64 s[38:39], 0, v13
	s_movk_i32 s8, 0x2c00
	v_mov_b32_e32 v28, 0
	v_cndmask_b32_e64 v14, v14, v12, s[38:39]
	v_mov_b64_e32 v[12:13], s[20:21]
	v_mad_i64_i32 v[12:13], s[8:9], v14, s8, v[12:13]
	v_lshl_add_u64 v[34:35], v[12:13], 0, v[8:9]
	v_mov_b32_e32 v8, 0
	v_mov_b32_e32 v29, 0
	v_mov_b32_e32 v30, 0
	v_mov_b32_e32 v31, 0
	s_and_saveexec_b64 s[8:9], vcc
	s_cbranch_execz .LBB0_1177
	global_load_dwordx4 v[28:31], v[34:35], off
.LBB0_1177:
	s_or_b64 exec, exec, s[8:9]
	global_load_dwordx4 v[12:15], v[0:1], off offset:16
	s_nop 0
	global_load_dwordx4 v[0:3], v[2:3], off offset:16
	s_nop 0
	global_load_dwordx4 v[16:19], v[10:11], off offset:16
	v_mov_b32_e32 v9, 0
	v_mov_b32_e32 v10, 0
	v_mov_b32_e32 v11, 0
	s_and_saveexec_b64 s[8:9], vcc
	s_cbranch_execz .LBB0_1174
	global_load_dwordx4 v[8:11], v[34:35], off offset:16
	s_branch .LBB0_1174

; __device__ __forceinline__ unsigned cvt_pk_bf16(float lo, float hi) { typedef float f2 __attribute__((ext_vector_type(2))); typedef __bf16 b2 __attribute__((ext_vector_type(2))); f2 v = {lo, hi}; b2 b = __builtin_convertvector(v, b2); return __builtin_bit_cast(unsigned, b); }
;     __device__ __forceinline__ void operator()(const f32x4 (&acc)[2][2][4][2], const Unit& u, int wr, int wc, int fr, int fq) const {
;         const int row0 = u.pm * BM + wr * 64 + fr; const int col0 = u.pn * BM + wc * 32 + 8 * fq;
;         u32x4 owv[2][4][2];
; #pragma unroll
;         for (int ai = 0; ai < 2; ++ai)
; #pragma unroll
;             for (int m = 0; m < 4; ++m) { const bf16_t* xp = xr + (size_t)(row0 + ai * HALF + m * 16) * 1024 + col0;
; #pragma unroll
;                 for (int bj = 0; bj < 2; ++bj) owv[ai][m][bj] = *(const u32x4*)(xp + bj * HALF); }
; #pragma unroll
;         for (int ai = 0; ai < 2; ++ai)
; #pragma unroll
;             for (int m = 0; m < 4; ++m) { const int row = row0 + ai * HALF + m * 16; bf16_t* xp = xr + (size_t)row * 1024 + col0; float sq = 0.f;
; #pragma unroll
;                 for (int bj = 0; bj < 2; ++bj) { const u32x4 ow = owv[ai][m][bj]; u32x4 w;
; #pragma unroll
;                     for (int n = 0; n < 2; ++n) { f32x4 v = acc[ai][bj][m][n]; const unsigned lo = ow[2 * n], hi_ = ow[2 * n + 1];
;                         v[0] += __uint_as_float(lo << 16); v[1] += __uint_as_float(lo & 0xffff0000u); v[2] += __uint_as_float(hi_ << 16); v[3] += __uint_as_float(hi_ & 0xffff0000u);
;                         sq += (v[0] * v[0] + v[1] * v[1]) + (v[2] * v[2] + v[3] * v[3]);
;                         w[2 * n] = cvt_pk_bf16(v[0], v[1]); w[2 * n + 1] = cvt_pk_bf16(v[2], v[3]); }
;                     *(u32x4*)(xp + bj * HALF) = w; }
;                 sq += __shfl_xor(sq, 16); sq += __shfl_xor(sq, 32);
;                 if (fq == 0) ssq[(size_t)row * 16 + u.pn * 4 + wc] = sq; }
.LBB0_1254:
	v_lshl_or_b32 v204, s16, 8, v241
	v_lshl_add_u32 v232, s65, 8, v249
	v_ashrrev_i32_e32 v205, 31, v204
	v_lshlrev_b64 v[236:237], 1, v[204:205]
	v_ashrrev_i32_e32 v233, 31, v232
	v_lshl_add_u64 v[100:101], s[12:13], 0, v[236:237]
	v_lshlrev_b64 v[238:239], 11, v[232:233]
	v_lshl_add_u64 v[102:103], v[100:101], 0, v[238:239]
	global_load_dwordx4 v[188:191], v[102:103], off
	global_load_dwordx4 v[184:187], v[102:103], off offset:256
	v_or_b32_e32 v228, 16, v232
	v_ashrrev_i32_e32 v229, 31, v228
	v_or_b32_e32 v224, 32, v232
	v_lshlrev_b64 v[234:235], 11, v[228:229]
	v_ashrrev_i32_e32 v225, 31, v224
	v_or_b32_e32 v220, 48, v232
	v_lshl_add_u64 v[102:103], v[100:101], 0, v[234:235]
	v_lshlrev_b64 v[230:231], 11, v[224:225]
	v_ashrrev_i32_e32 v221, 31, v220
	v_add_u32_e32 v216, 0x80, v232
	global_load_dwordx4 v[180:183], v[102:103], off
	global_load_dwordx4 v[176:179], v[102:103], off offset:256
	v_lshl_add_u64 v[102:103], v[100:101], 0, v[230:231]
	v_lshlrev_b64 v[226:227], 11, v[220:221]
	v_ashrrev_i32_e32 v217, 31, v216
	v_add_u32_e32 v212, 0x90, v232
	global_load_dwordx4 v[172:175], v[102:103], off
	global_load_dwordx4 v[168:171], v[102:103], off offset:256
	v_lshl_add_u64 v[102:103], v[100:101], 0, v[226:227]
	v_lshlrev_b64 v[222:223], 11, v[216:217]
	v_ashrrev_i32_e32 v213, 31, v212
	v_add_u32_e32 v208, 0xa0, v232
	v_add_u32_e32 v206, 0xb0, v232
	global_load_dwordx4 v[164:167], v[102:103], off
	global_load_dwordx4 v[160:163], v[102:103], off offset:256
	v_lshl_add_u64 v[102:103], v[100:101], 0, v[222:223]
	v_lshlrev_b64 v[218:219], 11, v[212:213]
	v_ashrrev_i32_e32 v209, 31, v208
	v_ashrrev_i32_e32 v207, 31, v206
	global_load_dwordx4 v[152:155], v[102:103], off
	global_load_dwordx4 v[144:147], v[102:103], off offset:256
	v_lshl_add_u64 v[102:103], v[100:101], 0, v[218:219]
	v_lshlrev_b64 v[214:215], 11, v[208:209]
	v_lshlrev_b64 v[210:211], 11, v[206:207]
	global_load_dwordx4 v[136:139], v[102:103], off
	global_load_dwordx4 v[128:131], v[102:103], off offset:256
	v_lshl_add_u64 v[102:103], v[100:101], 0, v[214:215]
	v_lshl_add_u64 v[100:101], v[100:101], 0, v[210:211]
	global_load_dwordx4 v[116:119], v[102:103], off
	global_load_dwordx4 v[108:111], v[102:103], off offset:256
	global_load_dwordx4 v[112:115], v[100:101], off
	s_nop 0
	global_load_dwordx4 v[100:103], v[100:101], off offset:256
	v_lshl_add_u64 v[238:239], s[12:13], 0, v[238:239]
	v_lshl_add_u64 v[236:237], v[238:239], 0, v[236:237]
	v_cmp_lt_i32_e32 vcc, v247, v245
	s_lshl_b32 s34, s16, 2
	s_ashr_i32 s35, s34, 31
	v_cndmask_b32_e32 v246, v244, v247, vcc
	v_cmp_lt_i32_e32 vcc, v250, v245
	v_lshlrev_b32_e32 v246, 2, v246
	s_waitcnt vmcnt(0) lgkmcnt(0)
	v_lshlrev_b32_e32 v238, 16, v188
	v_and_b32_e32 v239, 0xffff0000, v188
	v_lshlrev_b32_e32 v188, 16, v189
	v_and_b32_e32 v189, 0xffff0000, v189
	v_pk_add_f32 v[156:157], v[156:157], v[238:239]
	v_pk_add_f32 v[158:159], v[158:159], v[188:189]
	v_pk_mul_f32 v[188:189], v[156:157], v[156:157]
	v_pk_mul_f32 v[238:239], v[158:159], v[158:159]
	v_cvt_pk_bf16_f32 v156, v156, v157
	v_cvt_pk_bf16_f32 v157, v158, v159
	v_lshlrev_b32_e32 v158, 16, v190
	v_and_b32_e32 v159, 0xffff0000, v190
	v_pk_add_f32 v[148:149], v[148:149], v[158:159]
	v_lshlrev_b32_e32 v158, 16, v191
	v_and_b32_e32 v159, 0xffff0000, v191
	v_pk_add_f32 v[150:151], v[150:151], v[158:159]
	v_pk_mul_f32 v[190:191], v[148:149], v[148:149]
	v_cvt_pk_bf16_f32 v158, v148, v149
	v_lshlrev_b32_e32 v148, 16, v184
	v_and_b32_e32 v149, 0xffff0000, v184
	v_pk_add_f32 v[140:141], v[140:141], v[148:149]
	v_lshlrev_b32_e32 v148, 16, v185
	v_and_b32_e32 v149, 0xffff0000, v185
	v_pk_add_f32 v[142:143], v[142:143], v[148:149]
	v_cndmask_b32_e32 v248, v244, v250, vcc
	v_pk_mul_f32 v[250:251], v[150:151], v[150:151]
	v_cvt_pk_bf16_f32 v159, v150, v151
	v_pk_mul_f32 v[148:149], v[140:141], v[140:141]
	v_pk_mul_f32 v[150:151], v[142:143], v[142:143]
	v_cvt_pk_bf16_f32 v140, v140, v141
	v_cvt_pk_bf16_f32 v141, v142, v143
	v_lshlrev_b32_e32 v142, 16, v186
	v_and_b32_e32 v143, 0xffff0000, v186
	global_store_dwordx4 v[236:237], v[156:159], off
	v_pk_add_f32 v[132:133], v[132:133], v[142:143]
	v_lshlrev_b32_e32 v142, 16, v187
	v_and_b32_e32 v143, 0xffff0000, v187
	v_add_f32_e32 v158, v250, v251
	v_add_f32_e32 v159, v190, v191
	v_pk_add_f32 v[134:135], v[134:135], v[142:143]
	v_add_f32_e32 v158, v159, v158
	v_add_f32_e32 v159, v238, v239
	v_add_f32_e32 v184, v188, v189
	v_pk_mul_f32 v[142:143], v[132:133], v[132:133]
	v_pk_mul_f32 v[156:157], v[134:135], v[134:135]
	v_add_f32_e32 v159, v184, v159
	v_add_f32_e32 v150, v150, v151
	v_add_f32_e32 v148, v148, v149
	v_add_f32_e32 v158, v159, v158
	v_add_f32_e32 v148, v148, v150
	v_add_f32_e32 v149, v156, v157
	v_add_f32_e32 v142, v142, v143
	v_add_f32_e32 v148, v158, v148
	v_add_f32_e32 v142, v142, v149
	v_add_f32_e32 v148, v142, v148
	v_cvt_pk_bf16_f32 v142, v132, v133
	ds_bpermute_b32 v132, v246, v148
	v_lshlrev_b32_e32 v248, 2, v248
	v_cvt_pk_bf16_f32 v143, v134, v135
	global_store_dwordx4 v[236:237], v[140:143], off offset:256
	s_waitcnt lgkmcnt(0)
	v_add_f32_e32 v132, v148, v132
	ds_bpermute_b32 v133, v248, v132
	s_and_saveexec_b64 s[8:9], s[36:37]
	s_cbranch_execz .LBB0_1256
	s_waitcnt lgkmcnt(0)
	v_add_f32_e32 v134, v132, v133
	v_lshlrev_b64 v[132:133], 6, v[232:233]
	v_lshl_add_u64 v[132:133], s[18:19], 0, v[132:133]
	v_lshl_add_u64 v[132:133], s[34:35], 2, v[132:133]
	s_lshl_b32 s16, s48, 2
	v_lshl_add_u64 v[132:133], v[132:133], 0, s[16:17]
	global_store_dword v[132:133], v134, off
; __device__ __forceinline__ unsigned cvt_pk_bf16(float lo, float hi) { typedef float f2 __attribute__((ext_vector_type(2))); typedef __bf16 b2 __attribute__((ext_vector_type(2))); f2 v = {lo, hi}; b2 b = __builtin_convertvector(v, b2); return __builtin_bit_cast(unsigned, b); }
;     __device__ __forceinline__ void operator()(const f32x4 (&acc)[2][2][4][2], const Unit& u, int wr, int wc, int fr, int fq) const {
;     ...
;         for (int ai = 0; ai < 2; ++ai)
; #pragma unroll
;             for (int m = 0; m < 4; ++m) { const int row = row0 + ai * HALF + m * 16; bf16_t* xp = xr + (size_t)row * 1024 + col0; float sq = 0.f;
; #pragma unroll
;                 for (int bj = 0; bj < 2; ++bj) { const u32x4 ow = owv[ai][m][bj]; u32x4 w;
; #pragma unroll
;                     for (int n = 0; n < 2; ++n) { f32x4 v = acc[ai][bj][m][n]; const unsigned lo = ow[2 * n], hi_ = ow[2 * n + 1];
;                         v[0] += __uint_as_float(lo << 16); v[1] += __uint_as_float(lo & 0xffff0000u); v[2] += __uint_as_float(hi_ << 16); v[3] += __uint_as_float(hi_ & 0xffff0000u);
;                         sq += (v[0] * v[0] + v[1] * v[1]) + (v[2] * v[2] + v[3] * v[3]);
;                         w[2 * n] = cvt_pk_bf16(v[0], v[1]); w[2 * n + 1] = cvt_pk_bf16(v[2], v[3]); }
;                     *(u32x4*)(xp + bj * HALF) = w; }
;                 sq += __shfl_xor(sq, 16); sq += __shfl_xor(sq, 32);
;                 if (fq == 0) ssq[(size_t)row * 16 + u.pn * 4 + wc] = sq; }
.LBB0_1256:
	s_or_b64 exec, exec, s[8:9]
	v_lshlrev_b32_e32 v134, 16, v180
	v_and_b32_e32 v135, 0xffff0000, v180
	v_pk_add_f32 v[124:125], v[124:125], v[134:135]
	v_lshlrev_b32_e32 v134, 16, v181
	v_and_b32_e32 v135, 0xffff0000, v181
	v_pk_add_f32 v[126:127], v[126:127], v[134:135]
	v_pk_mul_f32 v[134:135], v[124:125], v[124:125]
	v_pk_mul_f32 v[140:141], v[126:127], v[126:127]
	v_cvt_pk_bf16_f32 v124, v124, v125
	v_cvt_pk_bf16_f32 v125, v126, v127
	v_lshlrev_b32_e32 v126, 16, v182
	v_and_b32_e32 v127, 0xffff0000, v182
	v_pk_add_f32 v[120:121], v[120:121], v[126:127]
	v_lshlrev_b32_e32 v126, 16, v183
	v_and_b32_e32 v127, 0xffff0000, v183
	v_pk_add_f32 v[122:123], v[122:123], v[126:127]
	v_pk_mul_f32 v[142:143], v[120:121], v[120:121]
	v_cvt_pk_bf16_f32 v126, v120, v121
	v_lshlrev_b32_e32 v120, 16, v176
	v_and_b32_e32 v121, 0xffff0000, v176
	v_pk_add_f32 v[104:105], v[104:105], v[120:121]
	v_lshlrev_b32_e32 v120, 16, v177
	v_and_b32_e32 v121, 0xffff0000, v177
	s_waitcnt lgkmcnt(0)
	v_lshl_add_u64 v[132:133], s[12:13], 0, v[234:235]
	v_pk_add_f32 v[106:107], v[106:107], v[120:121]
	v_lshl_add_u64 v[132:133], v[204:205], 1, v[132:133]
	v_pk_mul_f32 v[148:149], v[122:123], v[122:123]
	v_cvt_pk_bf16_f32 v127, v122, v123
	v_pk_mul_f32 v[120:121], v[104:105], v[104:105]
	v_pk_mul_f32 v[122:123], v[106:107], v[106:107]
	v_cvt_pk_bf16_f32 v104, v104, v105
	v_cvt_pk_bf16_f32 v105, v106, v107
	v_lshlrev_b32_e32 v106, 16, v178
	v_and_b32_e32 v107, 0xffff0000, v178
	global_store_dwordx4 v[132:133], v[124:127], off
	v_pk_add_f32 v[96:97], v[96:97], v[106:107]
	v_lshlrev_b32_e32 v106, 16, v179
	v_and_b32_e32 v107, 0xffff0000, v179
	v_add_f32_e32 v126, v148, v149
	v_add_f32_e32 v127, v142, v143
	v_pk_add_f32 v[98:99], v[98:99], v[106:107]
	v_add_f32_e32 v126, v127, v126
	v_add_f32_e32 v127, v140, v141
	v_add_f32_e32 v134, v134, v135
	v_pk_mul_f32 v[106:107], v[96:97], v[96:97]
	v_pk_mul_f32 v[124:125], v[98:99], v[98:99]
	v_add_f32_e32 v127, v134, v127
	v_add_f32_e32 v122, v122, v123
	v_add_f32_e32 v120, v120, v121
	v_add_f32_e32 v126, v127, v126
	v_add_f32_e32 v120, v120, v122
	v_add_f32_e32 v121, v124, v125
	v_add_f32_e32 v106, v106, v107
	v_add_f32_e32 v120, v126, v120
	v_add_f32_e32 v106, v106, v121
	v_add_f32_e32 v120, v106, v120
	v_cvt_pk_bf16_f32 v106, v96, v97
	ds_bpermute_b32 v96, v246, v120
	v_cvt_pk_bf16_f32 v107, v98, v99
	global_store_dwordx4 v[132:133], v[104:107], off offset:256
	s_waitcnt lgkmcnt(0)
	v_add_f32_e32 v96, v120, v96
	ds_bpermute_b32 v97, v248, v96
	s_and_saveexec_b64 s[8:9], s[36:37]
	s_cbranch_execz .LBB0_1258
	s_waitcnt lgkmcnt(0)
	v_add_f32_e32 v98, v96, v97
	v_lshlrev_b64 v[96:97], 6, v[228:229]
	v_lshl_add_u64 v[96:97], s[18:19], 0, v[96:97]
	v_lshl_add_u64 v[96:97], s[34:35], 2, v[96:97]
	s_lshl_b32 s16, s48, 2
	v_lshl_add_u64 v[96:97], v[96:97], 0, s[16:17]
	global_store_dword v[96:97], v98, off
.LBB0_1258:
	s_or_b64 exec, exec, s[8:9]
	v_lshlrev_b32_e32 v98, 16, v172
	v_and_b32_e32 v99, 0xffff0000, v172
	v_pk_add_f32 v[92:93], v[92:93], v[98:99]
	v_lshlrev_b32_e32 v98, 16, v173
	v_and_b32_e32 v99, 0xffff0000, v173
	v_pk_add_f32 v[94:95], v[94:95], v[98:99]
	v_pk_mul_f32 v[98:99], v[92:93], v[92:93]
	v_pk_mul_f32 v[104:105], v[94:95], v[94:95]
	v_cvt_pk_bf16_f32 v92, v92, v93
	v_cvt_pk_bf16_f32 v93, v94, v95
	v_lshlrev_b32_e32 v94, 16, v174
	v_and_b32_e32 v95, 0xffff0000, v174
	v_pk_add_f32 v[88:89], v[88:89], v[94:95]
	v_lshlrev_b32_e32 v94, 16, v175
	v_and_b32_e32 v95, 0xffff0000, v175
	v_pk_add_f32 v[90:91], v[90:91], v[94:95]
	v_pk_mul_f32 v[106:107], v[88:89], v[88:89]
	v_cvt_pk_bf16_f32 v94, v88, v89
	v_lshlrev_b32_e32 v88, 16, v168
	v_and_b32_e32 v89, 0xffff0000, v168
	v_pk_add_f32 v[84:85], v[84:85], v[88:89]
	v_lshlrev_b32_e32 v88, 16, v169
	v_and_b32_e32 v89, 0xffff0000, v169
	s_waitcnt lgkmcnt(0)
	v_lshl_add_u64 v[96:97], s[12:13], 0, v[230:231]
	v_pk_add_f32 v[86:87], v[86:87], v[88:89]
	v_lshl_add_u64 v[96:97], v[204:205], 1, v[96:97]
	v_pk_mul_f32 v[120:121], v[90:91], v[90:91]
	v_cvt_pk_bf16_f32 v95, v90, v91
	v_pk_mul_f32 v[88:89], v[84:85], v[84:85]
	v_pk_mul_f32 v[90:91], v[86:87], v[86:87]
	v_cvt_pk_bf16_f32 v84, v84, v85
	v_cvt_pk_bf16_f32 v85, v86, v87
	v_lshlrev_b32_e32 v86, 16, v170
	v_and_b32_e32 v87, 0xffff0000, v170
	global_store_dwordx4 v[96:97], v[92:95], off
	v_pk_add_f32 v[80:81], v[80:81], v[86:87]
	v_lshlrev_b32_e32 v86, 16, v171
	v_and_b32_e32 v87, 0xffff0000, v171
	v_add_f32_e32 v94, v120, v121
	v_add_f32_e32 v95, v106, v107
	v_pk_add_f32 v[82:83], v[82:83], v[86:87]
	v_add_f32_e32 v94, v95, v94
	v_add_f32_e32 v95, v104, v105
	v_add_f32_e32 v98, v98, v99
	v_pk_mul_f32 v[86:87], v[80:81], v[80:81]
	v_pk_mul_f32 v[92:93], v[82:83], v[82:83]
	v_add_f32_e32 v95, v98, v95
	v_add_f32_e32 v90, v90, v91
	v_add_f32_e32 v88, v88, v89
	v_add_f32_e32 v94, v95, v94
	v_add_f32_e32 v88, v88, v90
	v_add_f32_e32 v89, v92, v93
	v_add_f32_e32 v86, v86, v87
	v_add_f32_e32 v88, v94, v88
	v_add_f32_e32 v86, v86, v89
	v_add_f32_e32 v88, v86, v88
	v_cvt_pk_bf16_f32 v86, v80, v81
	ds_bpermute_b32 v80, v246, v88
	v_cvt_pk_bf16_f32 v87, v82, v83
	global_store_dwordx4 v[96:97], v[84:87], off offset:256
	s_waitcnt lgkmcnt(0)
	v_add_f32_e32 v80, v88, v80
	ds_bpermute_b32 v81, v248, v80
	s_mov_b64 s[8:9], exec
	s_and_b64 s[40:41], s[8:9], s[36:37]
	v_xor_b32_e32 v250, 32, v244
	s_mov_b64 exec, s[40:41]
	s_cbranch_execz .LBB0_1260
	s_waitcnt lgkmcnt(0)
	v_add_f32_e32 v82, v80, v81
	v_lshlrev_b64 v[80:81], 6, v[224:225]
	v_lshl_add_u64 v[80:81], s[18:19], 0, v[80:81]
	v_lshl_add_u64 v[80:81], s[34:35], 2, v[80:81]
	s_lshl_b32 s16, s48, 2
	v_lshl_add_u64 v[80:81], v[80:81], 0, s[16:17]
	global_store_dword v[80:81], v82, off
; __device__ __forceinline__ unsigned cvt_pk_bf16(float lo, float hi) { typedef float f2 __attribute__((ext_vector_type(2))); typedef __bf16 b2 __attribute__((ext_vector_type(2))); f2 v = {lo, hi}; b2 b = __builtin_convertvector(v, b2); return __builtin_bit_cast(unsigned, b); }
;     __device__ __forceinline__ void operator()(const f32x4 (&acc)[2][2][4][2], const Unit& u, int wr, int wc, int fr, int fq) const {
;     ...
;         for (int ai = 0; ai < 2; ++ai)
; #pragma unroll
;             for (int m = 0; m < 4; ++m) { const int row = row0 + ai * HALF + m * 16; bf16_t* xp = xr + (size_t)row * 1024 + col0; float sq = 0.f;
; #pragma unroll
;                 for (int bj = 0; bj < 2; ++bj) { const u32x4 ow = owv[ai][m][bj]; u32x4 w;
; #pragma unroll
;                     for (int n = 0; n < 2; ++n) { f32x4 v = acc[ai][bj][m][n]; const unsigned lo = ow[2 * n], hi_ = ow[2 * n + 1];
;                         v[0] += __uint_as_float(lo << 16); v[1] += __uint_as_float(lo & 0xffff0000u); v[2] += __uint_as_float(hi_ << 16); v[3] += __uint_as_float(hi_ & 0xffff0000u);
;                         sq += (v[0] * v[0] + v[1] * v[1]) + (v[2] * v[2] + v[3] * v[3]);
;                         w[2 * n] = cvt_pk_bf16(v[0], v[1]); w[2 * n + 1] = cvt_pk_bf16(v[2], v[3]); }
;                     *(u32x4*)(xp + bj * HALF) = w; }
;                 sq += __shfl_xor(sq, 16); sq += __shfl_xor(sq, 32);
;                 if (fq == 0) ssq[(size_t)row * 16 + u.pn * 4 + wc] = sq; }
.LBB0_1260:
	s_or_b64 exec, exec, s[8:9]
	v_lshlrev_b32_e32 v82, 16, v164
	v_and_b32_e32 v83, 0xffff0000, v164
	v_pk_add_f32 v[76:77], v[76:77], v[82:83]
	v_lshlrev_b32_e32 v82, 16, v165
	v_and_b32_e32 v83, 0xffff0000, v165
	v_pk_add_f32 v[78:79], v[78:79], v[82:83]
	v_pk_mul_f32 v[82:83], v[76:77], v[76:77]
	v_pk_mul_f32 v[84:85], v[78:79], v[78:79]
	v_cvt_pk_bf16_f32 v76, v76, v77
	v_cvt_pk_bf16_f32 v77, v78, v79
	v_lshlrev_b32_e32 v78, 16, v166
	v_and_b32_e32 v79, 0xffff0000, v166
	v_pk_add_f32 v[72:73], v[72:73], v[78:79]
	v_lshlrev_b32_e32 v78, 16, v167
	v_and_b32_e32 v79, 0xffff0000, v167
	v_pk_add_f32 v[74:75], v[74:75], v[78:79]
	v_pk_mul_f32 v[86:87], v[72:73], v[72:73]
	v_cvt_pk_bf16_f32 v78, v72, v73
	v_lshlrev_b32_e32 v72, 16, v160
	v_and_b32_e32 v73, 0xffff0000, v160
	v_pk_add_f32 v[68:69], v[68:69], v[72:73]
	v_lshlrev_b32_e32 v72, 16, v161
	v_and_b32_e32 v73, 0xffff0000, v161
	s_waitcnt lgkmcnt(0)
	v_lshl_add_u64 v[80:81], s[12:13], 0, v[226:227]
	v_pk_add_f32 v[70:71], v[70:71], v[72:73]
	v_lshl_add_u64 v[80:81], v[204:205], 1, v[80:81]
	v_pk_mul_f32 v[88:89], v[74:75], v[74:75]
	v_cvt_pk_bf16_f32 v79, v74, v75
	v_pk_mul_f32 v[72:73], v[68:69], v[68:69]
	v_pk_mul_f32 v[74:75], v[70:71], v[70:71]
	v_cvt_pk_bf16_f32 v68, v68, v69
	v_cvt_pk_bf16_f32 v69, v70, v71
	v_lshlrev_b32_e32 v70, 16, v162
	v_and_b32_e32 v71, 0xffff0000, v162
	global_store_dwordx4 v[80:81], v[76:79], off
	v_pk_add_f32 v[64:65], v[64:65], v[70:71]
	v_lshlrev_b32_e32 v70, 16, v163
	v_and_b32_e32 v71, 0xffff0000, v163
	v_add_f32_e32 v78, v88, v89
	v_add_f32_e32 v79, v86, v87
	v_pk_add_f32 v[66:67], v[66:67], v[70:71]
	v_add_f32_e32 v78, v79, v78
	v_add_f32_e32 v79, v84, v85
	v_add_f32_e32 v82, v82, v83
	v_pk_mul_f32 v[70:71], v[64:65], v[64:65]
	v_pk_mul_f32 v[76:77], v[66:67], v[66:67]
	v_add_f32_e32 v79, v82, v79
	v_add_f32_e32 v74, v74, v75
	v_add_f32_e32 v72, v72, v73
	v_add_f32_e32 v78, v79, v78
	v_add_f32_e32 v72, v72, v74
	v_add_f32_e32 v73, v76, v77
	v_add_f32_e32 v70, v70, v71
	v_add_f32_e32 v72, v78, v72
	v_add_f32_e32 v70, v70, v73
	v_add_f32_e32 v72, v70, v72
	v_cvt_pk_bf16_f32 v70, v64, v65
	ds_bpermute_b32 v64, v246, v72
	v_cvt_pk_bf16_f32 v71, v66, v67
	global_store_dwordx4 v[80:81], v[68:71], off offset:256
	s_waitcnt lgkmcnt(0)
	v_add_f32_e32 v64, v72, v64
	ds_bpermute_b32 v65, v248, v64
	s_and_saveexec_b64 s[8:9], s[36:37]
	s_cbranch_execz .LBB0_1262
	s_waitcnt lgkmcnt(0)
	v_add_f32_e32 v66, v64, v65
	v_lshlrev_b64 v[64:65], 6, v[220:221]
	v_lshl_add_u64 v[64:65], s[18:19], 0, v[64:65]
	v_lshl_add_u64 v[64:65], s[34:35], 2, v[64:65]
	s_lshl_b32 s16, s48, 2
	v_lshl_add_u64 v[64:65], v[64:65], 0, s[16:17]
	global_store_dword v[64:65], v66, off
.LBB0_1262:
	s_or_b64 exec, exec, s[8:9]
	v_lshlrev_b32_e32 v66, 16, v152
	v_and_b32_e32 v67, 0xffff0000, v152
	v_pk_add_f32 v[60:61], v[60:61], v[66:67]
	v_lshlrev_b32_e32 v66, 16, v153
	v_and_b32_e32 v67, 0xffff0000, v153
	v_pk_add_f32 v[62:63], v[62:63], v[66:67]
	v_pk_mul_f32 v[66:67], v[60:61], v[60:61]
	v_pk_mul_f32 v[68:69], v[62:63], v[62:63]
	v_cvt_pk_bf16_f32 v60, v60, v61
	v_cvt_pk_bf16_f32 v61, v62, v63
	v_lshlrev_b32_e32 v62, 16, v154
	v_and_b32_e32 v63, 0xffff0000, v154
	v_pk_add_f32 v[56:57], v[56:57], v[62:63]
	v_lshlrev_b32_e32 v62, 16, v155
	v_and_b32_e32 v63, 0xffff0000, v155
	v_pk_add_f32 v[58:59], v[58:59], v[62:63]
	v_pk_mul_f32 v[70:71], v[56:57], v[56:57]
	v_cvt_pk_bf16_f32 v62, v56, v57
	v_lshlrev_b32_e32 v56, 16, v144
	v_and_b32_e32 v57, 0xffff0000, v144
	v_pk_add_f32 v[52:53], v[52:53], v[56:57]
	v_lshlrev_b32_e32 v56, 16, v145
	v_and_b32_e32 v57, 0xffff0000, v145
	s_waitcnt lgkmcnt(0)
	v_lshl_add_u64 v[64:65], s[12:13], 0, v[222:223]
	v_pk_add_f32 v[54:55], v[54:55], v[56:57]
	v_lshl_add_u64 v[64:65], v[204:205], 1, v[64:65]
	v_pk_mul_f32 v[72:73], v[58:59], v[58:59]
	v_cvt_pk_bf16_f32 v63, v58, v59
	v_pk_mul_f32 v[56:57], v[52:53], v[52:53]
	v_pk_mul_f32 v[58:59], v[54:55], v[54:55]
	v_cvt_pk_bf16_f32 v52, v52, v53
	v_cvt_pk_bf16_f32 v53, v54, v55
	v_lshlrev_b32_e32 v54, 16, v146
	v_and_b32_e32 v55, 0xffff0000, v146
	global_store_dwordx4 v[64:65], v[60:63], off
	v_pk_add_f32 v[48:49], v[48:49], v[54:55]
	v_lshlrev_b32_e32 v54, 16, v147
	v_and_b32_e32 v55, 0xffff0000, v147
	v_add_f32_e32 v62, v72, v73
	v_add_f32_e32 v63, v70, v71
	v_pk_add_f32 v[50:51], v[50:51], v[54:55]
	v_add_f32_e32 v62, v63, v62
	v_add_f32_e32 v63, v68, v69
	v_add_f32_e32 v66, v66, v67
	v_pk_mul_f32 v[54:55], v[48:49], v[48:49]
	v_pk_mul_f32 v[60:61], v[50:51], v[50:51]
	v_add_f32_e32 v63, v66, v63
	v_add_f32_e32 v58, v58, v59
	v_add_f32_e32 v56, v56, v57
	v_add_f32_e32 v62, v63, v62
	v_add_f32_e32 v56, v56, v58
	v_add_f32_e32 v57, v60, v61
	v_add_f32_e32 v54, v54, v55
	v_add_f32_e32 v56, v62, v56
	v_add_f32_e32 v54, v54, v57
	v_add_f32_e32 v56, v54, v56
	v_cvt_pk_bf16_f32 v54, v48, v49
	ds_bpermute_b32 v48, v246, v56
	v_cvt_pk_bf16_f32 v55, v50, v51
	global_store_dwordx4 v[64:65], v[52:55], off offset:256
	s_waitcnt lgkmcnt(0)
	v_add_f32_e32 v48, v56, v48
	ds_bpermute_b32 v49, v248, v48
	s_and_saveexec_b64 s[8:9], s[36:37]
	s_cbranch_execz .LBB0_1264
	s_waitcnt lgkmcnt(0)
	v_add_f32_e32 v50, v48, v49
	v_lshlrev_b64 v[48:49], 6, v[216:217]
	v_lshl_add_u64 v[48:49], s[18:19], 0, v[48:49]
	v_lshl_add_u64 v[48:49], s[34:35], 2, v[48:49]
	s_lshl_b32 s16, s48, 2
	v_lshl_add_u64 v[48:49], v[48:49], 0, s[16:17]
	global_store_dword v[48:49], v50, off
; __device__ __forceinline__ unsigned cvt_pk_bf16(float lo, float hi) { typedef float f2 __attribute__((ext_vector_type(2))); typedef __bf16 b2 __attribute__((ext_vector_type(2))); f2 v = {lo, hi}; b2 b = __builtin_convertvector(v, b2); return __builtin_bit_cast(unsigned, b); }
;     __device__ __forceinline__ void operator()(const f32x4 (&acc)[2][2][4][2], const Unit& u, int wr, int wc, int fr, int fq) const {
;     ...
;         for (int ai = 0; ai < 2; ++ai)
; #pragma unroll
;             for (int m = 0; m < 4; ++m) { const int row = row0 + ai * HALF + m * 16; bf16_t* xp = xr + (size_t)row * 1024 + col0; float sq = 0.f;
; #pragma unroll
;                 for (int bj = 0; bj < 2; ++bj) { const u32x4 ow = owv[ai][m][bj]; u32x4 w;
; #pragma unroll
;                     for (int n = 0; n < 2; ++n) { f32x4 v = acc[ai][bj][m][n]; const unsigned lo = ow[2 * n], hi_ = ow[2 * n + 1];
;                         v[0] += __uint_as_float(lo << 16); v[1] += __uint_as_float(lo & 0xffff0000u); v[2] += __uint_as_float(hi_ << 16); v[3] += __uint_as_float(hi_ & 0xffff0000u);
;                         sq += (v[0] * v[0] + v[1] * v[1]) + (v[2] * v[2] + v[3] * v[3]);
;                         w[2 * n] = cvt_pk_bf16(v[0], v[1]); w[2 * n + 1] = cvt_pk_bf16(v[2], v[3]); }
;                     *(u32x4*)(xp + bj * HALF) = w; }
;                 sq += __shfl_xor(sq, 16); sq += __shfl_xor(sq, 32);
;                 if (fq == 0) ssq[(size_t)row * 16 + u.pn * 4 + wc] = sq; }
.LBB0_1264:
	s_or_b64 exec, exec, s[8:9]
	v_lshlrev_b32_e32 v50, 16, v136
	v_and_b32_e32 v51, 0xffff0000, v136
	v_pk_add_f32 v[44:45], v[44:45], v[50:51]
	v_lshlrev_b32_e32 v50, 16, v137
	v_and_b32_e32 v51, 0xffff0000, v137
	v_pk_add_f32 v[46:47], v[46:47], v[50:51]
	v_pk_mul_f32 v[50:51], v[44:45], v[44:45]
	v_pk_mul_f32 v[52:53], v[46:47], v[46:47]
	v_cvt_pk_bf16_f32 v44, v44, v45
	v_cvt_pk_bf16_f32 v45, v46, v47
	v_lshlrev_b32_e32 v46, 16, v138
	v_and_b32_e32 v47, 0xffff0000, v138
	v_pk_add_f32 v[40:41], v[40:41], v[46:47]
	v_lshlrev_b32_e32 v46, 16, v139
	v_and_b32_e32 v47, 0xffff0000, v139
	v_pk_add_f32 v[42:43], v[42:43], v[46:47]
	v_pk_mul_f32 v[54:55], v[40:41], v[40:41]
	v_cvt_pk_bf16_f32 v46, v40, v41
	v_lshlrev_b32_e32 v40, 16, v128
	v_and_b32_e32 v41, 0xffff0000, v128
	v_pk_add_f32 v[36:37], v[36:37], v[40:41]
	v_lshlrev_b32_e32 v40, 16, v129
	v_and_b32_e32 v41, 0xffff0000, v129
	s_waitcnt lgkmcnt(0)
	v_lshl_add_u64 v[48:49], s[12:13], 0, v[218:219]
	v_pk_add_f32 v[38:39], v[38:39], v[40:41]
	v_lshl_add_u64 v[48:49], v[204:205], 1, v[48:49]
	v_pk_mul_f32 v[56:57], v[42:43], v[42:43]
	v_cvt_pk_bf16_f32 v47, v42, v43
	v_pk_mul_f32 v[40:41], v[36:37], v[36:37]
	v_pk_mul_f32 v[42:43], v[38:39], v[38:39]
	v_cvt_pk_bf16_f32 v36, v36, v37
	v_cvt_pk_bf16_f32 v37, v38, v39
	v_lshlrev_b32_e32 v38, 16, v130
	v_and_b32_e32 v39, 0xffff0000, v130
	global_store_dwordx4 v[48:49], v[44:47], off
	v_pk_add_f32 v[32:33], v[32:33], v[38:39]
	v_lshlrev_b32_e32 v38, 16, v131
	v_and_b32_e32 v39, 0xffff0000, v131
	v_add_f32_e32 v46, v56, v57
	v_add_f32_e32 v47, v54, v55
	v_pk_add_f32 v[34:35], v[34:35], v[38:39]
	v_add_f32_e32 v46, v47, v46
	v_add_f32_e32 v47, v52, v53
	v_add_f32_e32 v50, v50, v51
	v_pk_mul_f32 v[38:39], v[32:33], v[32:33]
	v_pk_mul_f32 v[44:45], v[34:35], v[34:35]
	v_add_f32_e32 v47, v50, v47
	v_add_f32_e32 v42, v42, v43
	v_add_f32_e32 v40, v40, v41
	v_add_f32_e32 v46, v47, v46
	v_add_f32_e32 v40, v40, v42
	v_add_f32_e32 v41, v44, v45
	v_add_f32_e32 v38, v38, v39
	v_add_f32_e32 v40, v46, v40
	v_add_f32_e32 v38, v38, v41
	v_add_f32_e32 v40, v38, v40
	v_cvt_pk_bf16_f32 v38, v32, v33
	ds_bpermute_b32 v32, v246, v40
	v_cvt_pk_bf16_f32 v39, v34, v35
	global_store_dwordx4 v[48:49], v[36:39], off offset:256
	s_waitcnt lgkmcnt(0)
	v_add_f32_e32 v32, v40, v32
	ds_bpermute_b32 v33, v248, v32
	s_and_saveexec_b64 s[8:9], s[36:37]
	s_cbranch_execz .LBB0_1266
	s_waitcnt lgkmcnt(0)
	v_add_f32_e32 v34, v32, v33
	v_lshlrev_b64 v[32:33], 6, v[212:213]
	v_lshl_add_u64 v[32:33], s[18:19], 0, v[32:33]
	v_lshl_add_u64 v[32:33], s[34:35], 2, v[32:33]
	s_lshl_b32 s16, s48, 2
	v_lshl_add_u64 v[32:33], v[32:33], 0, s[16:17]
	global_store_dword v[32:33], v34, off
; __device__ __forceinline__ unsigned cvt_pk_bf16(float lo, float hi) { typedef float f2 __attribute__((ext_vector_type(2))); typedef __bf16 b2 __attribute__((ext_vector_type(2))); f2 v = {lo, hi}; b2 b = __builtin_convertvector(v, b2); return __builtin_bit_cast(unsigned, b); }
;     __device__ __forceinline__ void operator()(const f32x4 (&acc)[2][2][4][2], const Unit& u, int wr, int wc, int fr, int fq) const {
;     ...
;         for (int ai = 0; ai < 2; ++ai)
; #pragma unroll
;             for (int m = 0; m < 4; ++m) { const int row = row0 + ai * HALF + m * 16; bf16_t* xp = xr + (size_t)row * 1024 + col0; float sq = 0.f;
; #pragma unroll
;                 for (int bj = 0; bj < 2; ++bj) { const u32x4 ow = owv[ai][m][bj]; u32x4 w;
; #pragma unroll
;                     for (int n = 0; n < 2; ++n) { f32x4 v = acc[ai][bj][m][n]; const unsigned lo = ow[2 * n], hi_ = ow[2 * n + 1];
;                         v[0] += __uint_as_float(lo << 16); v[1] += __uint_as_float(lo & 0xffff0000u); v[2] += __uint_as_float(hi_ << 16); v[3] += __uint_as_float(hi_ & 0xffff0000u);
;                         sq += (v[0] * v[0] + v[1] * v[1]) + (v[2] * v[2] + v[3] * v[3]);
;                         w[2 * n] = cvt_pk_bf16(v[0], v[1]); w[2 * n + 1] = cvt_pk_bf16(v[2], v[3]); }
;                     *(u32x4*)(xp + bj * HALF) = w; }
;                 sq += __shfl_xor(sq, 16); sq += __shfl_xor(sq, 32);
;                 if (fq == 0) ssq[(size_t)row * 16 + u.pn * 4 + wc] = sq; }
.LBB0_1266:
	s_or_b64 exec, exec, s[8:9]
	v_lshlrev_b32_e32 v34, 16, v116
	v_and_b32_e32 v35, 0xffff0000, v116
	v_pk_add_f32 v[28:29], v[28:29], v[34:35]
	v_lshlrev_b32_e32 v34, 16, v117
	v_and_b32_e32 v35, 0xffff0000, v117
	v_pk_add_f32 v[30:31], v[30:31], v[34:35]
	v_pk_mul_f32 v[34:35], v[28:29], v[28:29]
	v_pk_mul_f32 v[36:37], v[30:31], v[30:31]
	v_cvt_pk_bf16_f32 v28, v28, v29
	v_cvt_pk_bf16_f32 v29, v30, v31
	v_lshlrev_b32_e32 v30, 16, v118
	v_and_b32_e32 v31, 0xffff0000, v118
	v_pk_add_f32 v[24:25], v[24:25], v[30:31]
	v_lshlrev_b32_e32 v30, 16, v119
	v_and_b32_e32 v31, 0xffff0000, v119
	v_pk_add_f32 v[26:27], v[26:27], v[30:31]
	v_pk_mul_f32 v[38:39], v[24:25], v[24:25]
	v_cvt_pk_bf16_f32 v30, v24, v25
	v_lshlrev_b32_e32 v24, 16, v108
	v_and_b32_e32 v25, 0xffff0000, v108
	v_pk_add_f32 v[20:21], v[20:21], v[24:25]
	v_lshlrev_b32_e32 v24, 16, v109
	v_and_b32_e32 v25, 0xffff0000, v109
	s_waitcnt lgkmcnt(0)
	v_lshl_add_u64 v[32:33], s[12:13], 0, v[214:215]
	v_pk_add_f32 v[22:23], v[22:23], v[24:25]
	v_lshl_add_u64 v[32:33], v[204:205], 1, v[32:33]
	v_pk_mul_f32 v[40:41], v[26:27], v[26:27]
	v_cvt_pk_bf16_f32 v31, v26, v27
	v_pk_mul_f32 v[24:25], v[20:21], v[20:21]
	v_pk_mul_f32 v[26:27], v[22:23], v[22:23]
	v_cvt_pk_bf16_f32 v20, v20, v21
	v_cvt_pk_bf16_f32 v21, v22, v23
	v_lshlrev_b32_e32 v22, 16, v110
	v_and_b32_e32 v23, 0xffff0000, v110
	global_store_dwordx4 v[32:33], v[28:31], off
	v_pk_add_f32 v[16:17], v[16:17], v[22:23]
	v_lshlrev_b32_e32 v22, 16, v111
	v_and_b32_e32 v23, 0xffff0000, v111
	v_add_f32_e32 v30, v40, v41
	v_add_f32_e32 v31, v38, v39
	v_pk_add_f32 v[18:19], v[18:19], v[22:23]
	v_add_f32_e32 v30, v31, v30
	v_add_f32_e32 v31, v36, v37
	v_add_f32_e32 v34, v34, v35
	v_pk_mul_f32 v[22:23], v[16:17], v[16:17]
	v_pk_mul_f32 v[28:29], v[18:19], v[18:19]
	v_add_f32_e32 v31, v34, v31
	v_add_f32_e32 v26, v26, v27
	v_add_f32_e32 v24, v24, v25
	v_add_f32_e32 v30, v31, v30
	v_add_f32_e32 v24, v24, v26
	v_add_f32_e32 v25, v28, v29
	v_add_f32_e32 v22, v22, v23
	v_add_f32_e32 v24, v30, v24
	v_add_f32_e32 v22, v22, v25
	v_add_f32_e32 v24, v22, v24
	v_cvt_pk_bf16_f32 v22, v16, v17
	ds_bpermute_b32 v16, v246, v24
	v_cvt_pk_bf16_f32 v23, v18, v19
	global_store_dwordx4 v[32:33], v[20:23], off offset:256
	s_waitcnt lgkmcnt(0)
	v_add_f32_e32 v16, v24, v16
	ds_bpermute_b32 v17, v248, v16
	s_and_saveexec_b64 s[8:9], s[36:37]
	s_cbranch_execz .LBB0_1268
	s_waitcnt lgkmcnt(0)
	v_add_f32_e32 v18, v16, v17
	v_lshlrev_b64 v[16:17], 6, v[208:209]
	v_lshl_add_u64 v[16:17], s[18:19], 0, v[16:17]
	v_lshl_add_u64 v[16:17], s[34:35], 2, v[16:17]
	s_lshl_b32 s16, s48, 2
	v_lshl_add_u64 v[16:17], v[16:17], 0, s[16:17]
	global_store_dword v[16:17], v18, off
.LBB0_1268:
	s_or_b64 exec, exec, s[8:9]
	v_lshlrev_b32_e32 v18, 16, v112
	v_and_b32_e32 v19, 0xffff0000, v112
	v_pk_add_f32 v[12:13], v[12:13], v[18:19]
	v_lshlrev_b32_e32 v18, 16, v113
	v_and_b32_e32 v19, 0xffff0000, v113
	v_pk_add_f32 v[14:15], v[14:15], v[18:19]
	v_pk_mul_f32 v[18:19], v[12:13], v[12:13]
	v_pk_mul_f32 v[20:21], v[14:15], v[14:15]
	v_cvt_pk_bf16_f32 v12, v12, v13
	v_cvt_pk_bf16_f32 v13, v14, v15
	v_lshlrev_b32_e32 v14, 16, v114
	v_and_b32_e32 v15, 0xffff0000, v114
	v_pk_add_f32 v[8:9], v[8:9], v[14:15]
	v_lshlrev_b32_e32 v14, 16, v115
	v_and_b32_e32 v15, 0xffff0000, v115
	v_pk_add_f32 v[10:11], v[10:11], v[14:15]
	v_pk_mul_f32 v[22:23], v[8:9], v[8:9]
	v_cvt_pk_bf16_f32 v14, v8, v9
	v_lshlrev_b32_e32 v8, 16, v100
	v_and_b32_e32 v9, 0xffff0000, v100
	v_pk_add_f32 v[4:5], v[4:5], v[8:9]
	v_lshlrev_b32_e32 v8, 16, v101
	v_and_b32_e32 v9, 0xffff0000, v101
	s_waitcnt lgkmcnt(0)
	v_lshl_add_u64 v[16:17], s[12:13], 0, v[210:211]
	v_pk_add_f32 v[6:7], v[6:7], v[8:9]
	v_lshl_add_u64 v[16:17], v[204:205], 1, v[16:17]
	v_pk_mul_f32 v[24:25], v[10:11], v[10:11]
	v_cvt_pk_bf16_f32 v15, v10, v11
	v_pk_mul_f32 v[8:9], v[4:5], v[4:5]
	v_pk_mul_f32 v[10:11], v[6:7], v[6:7]
	v_cvt_pk_bf16_f32 v4, v4, v5
	v_cvt_pk_bf16_f32 v5, v6, v7
	v_lshlrev_b32_e32 v6, 16, v102
	v_and_b32_e32 v7, 0xffff0000, v102
	global_store_dwordx4 v[16:17], v[12:15], off
	v_pk_add_f32 v[0:1], v[0:1], v[6:7]
	v_lshlrev_b32_e32 v6, 16, v103
	v_and_b32_e32 v7, 0xffff0000, v103
	v_add_f32_e32 v14, v24, v25
	v_add_f32_e32 v15, v22, v23
	v_pk_add_f32 v[2:3], v[2:3], v[6:7]
	v_add_f32_e32 v14, v15, v14
	v_add_f32_e32 v15, v20, v21
	v_add_f32_e32 v18, v18, v19
	v_pk_mul_f32 v[6:7], v[0:1], v[0:1]
	v_pk_mul_f32 v[12:13], v[2:3], v[2:3]
	v_add_f32_e32 v15, v18, v15
	v_add_f32_e32 v10, v10, v11
	v_add_f32_e32 v8, v8, v9
	v_add_f32_e32 v14, v15, v14
	v_add_f32_e32 v8, v8, v10
	v_add_f32_e32 v9, v12, v13
	v_add_f32_e32 v6, v6, v7
	v_add_f32_e32 v8, v14, v8
	v_add_f32_e32 v6, v6, v9
	v_add_f32_e32 v8, v6, v8
	v_cvt_pk_bf16_f32 v6, v0, v1
	ds_bpermute_b32 v0, v246, v8
	v_cvt_pk_bf16_f32 v7, v2, v3
	global_store_dwordx4 v[16:17], v[4:7], off offset:256
	s_waitcnt lgkmcnt(0)
	v_add_f32_e32 v0, v8, v0
	ds_bpermute_b32 v1, v248, v0
	s_and_saveexec_b64 s[8:9], s[36:37]
	s_cbranch_execz .LBB0_1270
	s_waitcnt lgkmcnt(0)
	v_add_f32_e32 v2, v0, v1
	v_lshlrev_b64 v[0:1], 6, v[206:207]
	v_lshl_add_u64 v[0:1], s[18:19], 0, v[0:1]
	v_lshl_add_u64 v[0:1], s[34:35], 2, v[0:1]
	s_lshl_b32 s16, s48, 2
	v_lshl_add_u64 v[0:1], v[0:1], 0, s[16:17]
	global_store_dword v[0:1], v2, off

; __device__ __forceinline__ void final_norm_phase(float* out, int row_g0, int T, const bf16_t* XR, const float* S0, const float* gain, int gw, int NGW, int lane) {
;     ...
;     for (int m0 = gw; m0 < T; m0 += 2 * NGW) { const int m1 = (m0 + NGW < T) ? m0 + NGW : m0;
;         u32x2 w[2][4]; f32x4 sp[2][4];
; #pragma unroll
;         for (int k = 0; k < 2; ++k) { const int m = k ? m1 : m0; const u32x2* x8 = (const u32x2*)(XR + (size_t)m * DM);
; #pragma unroll
;             for (int j = 0; j < 4; ++j) { w[k][j] = x8[lane + 64 * j]; sp[k][j] = ((const f32x4*)(S0 + (size_t)m * 16))[j]; } }
.LBB0_1330:
	s_add_i32 s9, s4, s25
	s_cmp_lt_i32 s9, s0
	s_cselect_b32 s6, s9, s4
	s_ashr_i32 s5, s4, 31
	s_lshl_b64 s[10:11], s[4:5], 11
	s_lshl_b64 s[12:13], s[4:5], 6
	s_add_u32 s12, s1, s12
	s_addc_u32 s13, s8, s13
	v_lshl_add_u64 v[16:17], v[34:35], 0, s[10:11]
	v_mov_b64_e32 v[18:19], s[12:13]
	global_load_dwordx2 v[60:61], v[16:17], off
	global_load_dwordx4 v[44:47], v[18:19], off
	global_load_dwordx2 v[62:63], v[16:17], off offset:512
	global_load_dwordx4 v[48:51], v[18:19], off offset:16
	global_load_dwordx2 v[64:65], v[16:17], off offset:1024
	global_load_dwordx4 v[52:55], v[18:19], off offset:32
	global_load_dwordx2 v[66:67], v[16:17], off offset:1536
	global_load_dwordx4 v[56:59], v[18:19], off offset:48
	s_ashr_i32 s7, s6, 31
	s_lshl_b64 s[10:11], s[6:7], 11
	s_lshl_b64 s[12:13], s[6:7], 6
	s_add_u32 s12, s1, s12
	s_addc_u32 s13, s8, s13
	v_lshl_add_u64 v[28:29], v[34:35], 0, s[10:11]
	v_mov_b64_e32 v[30:31], s[12:13]
	global_load_dwordx2 v[38:39], v[28:29], off
	global_load_dwordx4 v[16:19], v[30:31], off
	global_load_dwordx2 v[42:43], v[28:29], off offset:512
	global_load_dwordx4 v[20:23], v[30:31], off offset:16
	global_load_dwordx2 v[36:37], v[28:29], off offset:1024
	global_load_dwordx4 v[24:27], v[30:31], off offset:32
	global_load_dwordx2 v[40:41], v[28:29], off offset:1536
	s_nop 0
	global_load_dwordx4 v[28:31], v[30:31], off offset:48
	s_add_i32 s4, s94, s4
	s_ashr_i32 s5, s4, 31
	s_lshl_b64 s[4:5], s[4:5], 12
	s_waitcnt vmcnt(0) lgkmcnt(0)
; __device__ __forceinline__ void final_norm_phase(float* out, int row_g0, int T, const bf16_t* XR, const float* S0, const float* gain, int gw, int NGW, int lane) {
;     ...
;         for (int k = 0; k < 2; ++k) { const int m = k ? m1 : m0; float* orow = out + (size_t)(row_g0 + m) * DM;
;             const float sq_ = (((sp[k][0][0] + sp[k][0][1]) + (sp[k][0][2] + sp[k][0][3])) + ((sp[k][1][0] + sp[k][1][1]) + (sp[k][1][2] + sp[k][1][3]))) + (((sp[k][2][0] + sp[k][2][1]) + (sp[k][2][2] + sp[k][2][3])) + ((sp[k][3][0] + sp[k][3][1]) + (sp[k][3][2] + sp[k][3][3])));
;             const float rstd = 1.0f / sqrtf(sq_ * (1.f / DM) + EPS);
; #pragma unroll
;             for (int j = 0; j < 4; ++j) { f32x4 v; v.x = __uint_as_float(w[k][j].x << 16) * rstd * g[j].x; v.y = __uint_as_float(w[k][j].x & 0xffff0000u) * rstd * g[j].y; v.z = __uint_as_float(w[k][j].y << 16) * rstd * g[j].z; v.w = __uint_as_float(w[k][j].y & 0xffff0000u) * rstd * g[j].w;
;                 __builtin_nontemporal_store(v, ((f32x4*)orow) + lane + 64 * j); } }
	v_mov_b32_e32 v68, v44
	v_mov_b32_e32 v69, v52
	v_mov_b32_e32 v52, v45
	v_pk_add_f32 v[44:45], v[68:69], v[52:53]
	v_mov_b32_e32 v52, v46
	v_mov_b32_e32 v53, v54
	v_mov_b32_e32 v54, v47
	v_pk_add_f32 v[46:47], v[52:53], v[54:55]
	s_nop 0
	v_pk_add_f32 v[44:45], v[44:45], v[46:47]
	v_mov_b32_e32 v46, v48
	v_mov_b32_e32 v47, v56
	v_mov_b32_e32 v56, v49
	v_mov_b32_e32 v48, v50
	v_mov_b32_e32 v49, v58
	v_mov_b32_e32 v58, v51
	v_pk_add_f32 v[46:47], v[46:47], v[56:57]
	v_pk_add_f32 v[48:49], v[48:49], v[58:59]
	v_lshl_add_u64 v[50:51], v[32:33], 0, s[4:5]
	v_pk_add_f32 v[46:47], v[46:47], v[48:49]
	s_add_i32 s4, s6, s94
	v_pk_add_f32 v[44:45], v[44:45], v[46:47]
	s_ashr_i32 s5, s4, 31
	v_add_f32_e32 v44, v44, v45
	v_fmamk_f32 v44, v44, 0x3a800000, v242
	v_cmp_gt_f32_e32 vcc, s16, v44
	v_mul_f32_e32 v45, 0x4f800000, v44
	s_lshl_b64 s[4:5], s[4:5], 12
	v_cndmask_b32_e32 v44, v44, v45, vcc
	v_sqrt_f32_e32 v45, v44
	s_nop 0
	v_add_u32_e32 v46, -1, v45
	v_fma_f32 v47, -v46, v45, v44
	v_cmp_ge_f32_e64 s[36:37], 0, v47
	v_add_u32_e32 v47, 1, v45
	s_nop 0
	v_cndmask_b32_e64 v46, v45, v46, s[36:37]
	v_fma_f32 v45, -v47, v45, v44
	v_cmp_lt_f32_e64 s[36:37], 0, v45
	s_nop 1
	v_cndmask_b32_e64 v45, v46, v47, s[36:37]
	v_mul_f32_e32 v46, 0x37800000, v45
	v_cndmask_b32_e32 v45, v45, v46, vcc
	v_cmp_class_f32_e32 vcc, v44, v231
	s_nop 1
	v_cndmask_b32_e32 v44, v45, v44, vcc
	v_div_scale_f32 v45, s[10:11], v44, v44, 1.0
	v_rcp_f32_e32 v46, v45
	s_nop 0
	v_fma_f32 v47, -v45, v46, 1.0
	v_fmac_f32_e32 v46, v47, v46
	v_div_scale_f32 v47, vcc, 1.0, v44, 1.0
	v_mul_f32_e32 v48, v47, v46
	v_fma_f32 v49, -v45, v48, v47
	v_fmac_f32_e32 v48, v49, v46
	v_fma_f32 v45, -v45, v48, v47
	v_div_fmas_f32 v45, v45, v46, v48
	v_div_fixup_f32 v48, v45, v44, 1.0
	v_lshlrev_b32_e32 v44, 16, v60
	v_and_b32_e32 v45, 0xffff0000, v60
	v_lshlrev_b32_e32 v46, 16, v61
	v_and_b32_e32 v47, 0xffff0000, v61
	v_pk_mul_f32 v[44:45], v[48:49], v[44:45] op_sel_hi:[0,1]
	v_pk_mul_f32 v[46:47], v[48:49], v[46:47] op_sel_hi:[0,1]
	v_pk_mul_f32 v[44:45], v[12:13], v[44:45]
	v_pk_mul_f32 v[46:47], v[14:15], v[46:47]
	global_store_dwordx4 v[50:51], v[44:47], off nt
	s_nop 1
	v_lshlrev_b32_e32 v44, 16, v62
	v_and_b32_e32 v45, 0xffff0000, v62
	v_lshlrev_b32_e32 v46, 16, v63
	v_and_b32_e32 v47, 0xffff0000, v63
	v_pk_mul_f32 v[44:45], v[48:49], v[44:45] op_sel_hi:[0,1]
	v_pk_mul_f32 v[46:47], v[48:49], v[46:47] op_sel_hi:[0,1]
	v_pk_mul_f32 v[44:45], v[8:9], v[44:45]
	v_pk_mul_f32 v[46:47], v[10:11], v[46:47]
	global_store_dwordx4 v[50:51], v[44:47], off offset:1024 nt
	s_nop 1
	v_lshlrev_b32_e32 v44, 16, v64
	v_and_b32_e32 v45, 0xffff0000, v64
	v_lshlrev_b32_e32 v46, 16, v65
	v_and_b32_e32 v47, 0xffff0000, v65
	v_pk_mul_f32 v[44:45], v[48:49], v[44:45] op_sel_hi:[0,1]
	v_pk_mul_f32 v[46:47], v[48:49], v[46:47] op_sel_hi:[0,1]
	v_pk_mul_f32 v[44:45], v[4:5], v[44:45]
	v_pk_mul_f32 v[46:47], v[6:7], v[46:47]
	global_store_dwordx4 v[50:51], v[44:47], off offset:2048 nt
	s_nop 1
	v_lshlrev_b32_e32 v44, 16, v66
	v_and_b32_e32 v45, 0xffff0000, v66
	v_lshlrev_b32_e32 v46, 16, v67
	v_and_b32_e32 v47, 0xffff0000, v67
	v_pk_mul_f32 v[44:45], v[48:49], v[44:45] op_sel_hi:[0,1]
	v_pk_mul_f32 v[46:47], v[48:49], v[46:47] op_sel_hi:[0,1]
	v_pk_mul_f32 v[44:45], v[0:1], v[44:45]
	v_pk_mul_f32 v[46:47], v[2:3], v[46:47]
	global_store_dwordx4 v[50:51], v[44:47], off offset:3072 nt
	s_nop 1
	v_mov_b32_e32 v44, v16
	v_mov_b32_e32 v45, v24
	v_mov_b32_e32 v24, v17
	v_pk_add_f32 v[16:17], v[44:45], v[24:25]
	v_mov_b32_e32 v24, v18
	v_mov_b32_e32 v25, v26
	v_mov_b32_e32 v26, v19
	v_pk_add_f32 v[18:19], v[24:25], v[26:27]
	s_nop 0
	v_pk_add_f32 v[16:17], v[16:17], v[18:19]
	v_mov_b32_e32 v18, v20
	v_mov_b32_e32 v19, v28
	v_mov_b32_e32 v28, v21
	v_mov_b32_e32 v20, v22
	v_mov_b32_e32 v21, v30
	v_mov_b32_e32 v30, v23
	v_pk_add_f32 v[18:19], v[18:19], v[28:29]
	v_pk_add_f32 v[20:21], v[20:21], v[30:31]
	v_lshl_add_u64 v[22:23], v[32:33], 0, s[4:5]
	v_pk_add_f32 v[18:19], v[18:19], v[20:21]
	s_add_i32 s4, s9, s25
	v_pk_add_f32 v[16:17], v[16:17], v[18:19]
	s_cmp_lt_i32 s4, s0
	v_add_f32_e32 v16, v16, v17
	v_fmamk_f32 v16, v16, 0x3a800000, v242
	v_cmp_gt_f32_e32 vcc, s16, v16
	v_mul_f32_e32 v17, 0x4f800000, v16
	s_nop 0
	v_cndmask_b32_e32 v16, v16, v17, vcc
	v_sqrt_f32_e32 v17, v16
	s_nop 0
	v_add_u32_e32 v18, -1, v17
	v_fma_f32 v19, -v18, v17, v16
	v_cmp_ge_f32_e64 s[36:37], 0, v19
	v_add_u32_e32 v19, 1, v17
	s_nop 0
	v_cndmask_b32_e64 v18, v17, v18, s[36:37]
	v_fma_f32 v17, -v19, v17, v16
	v_cmp_lt_f32_e64 s[36:37], 0, v17
	s_nop 1
	v_cndmask_b32_e64 v17, v18, v19, s[36:37]
	v_mul_f32_e32 v18, 0x37800000, v17
	v_cndmask_b32_e32 v17, v17, v18, vcc
	v_cmp_class_f32_e32 vcc, v16, v231
	s_nop 1
	v_cndmask_b32_e32 v16, v17, v16, vcc
	v_div_scale_f32 v17, s[6:7], v16, v16, 1.0
	v_rcp_f32_e32 v18, v17
	s_nop 0
	v_fma_f32 v19, -v17, v18, 1.0
	v_fmac_f32_e32 v18, v19, v18
	v_div_scale_f32 v19, vcc, 1.0, v16, 1.0
	v_mul_f32_e32 v20, v19, v18
	v_fma_f32 v21, -v17, v20, v19
	v_fmac_f32_e32 v20, v21, v18
	v_fma_f32 v17, -v17, v20, v19
	v_div_fmas_f32 v17, v17, v18, v20
	v_div_fixup_f32 v20, v17, v16, 1.0
	v_lshlrev_b32_e32 v16, 16, v38
	v_and_b32_e32 v17, 0xffff0000, v38
	v_lshlrev_b32_e32 v18, 16, v39
	v_and_b32_e32 v19, 0xffff0000, v39
	v_pk_mul_f32 v[16:17], v[20:21], v[16:17] op_sel_hi:[0,1]
	v_pk_mul_f32 v[18:19], v[20:21], v[18:19] op_sel_hi:[0,1]
	v_pk_mul_f32 v[16:17], v[12:13], v[16:17]
	v_pk_mul_f32 v[18:19], v[14:15], v[18:19]
	global_store_dwordx4 v[22:23], v[16:19], off nt
	s_nop 1
	v_lshlrev_b32_e32 v16, 16, v42
	v_and_b32_e32 v17, 0xffff0000, v42
	v_lshlrev_b32_e32 v18, 16, v43
	v_and_b32_e32 v19, 0xffff0000, v43
	v_pk_mul_f32 v[16:17], v[20:21], v[16:17] op_sel_hi:[0,1]
	v_pk_mul_f32 v[18:19], v[20:21], v[18:19] op_sel_hi:[0,1]
	v_pk_mul_f32 v[16:17], v[8:9], v[16:17]
	v_pk_mul_f32 v[18:19], v[10:11], v[18:19]
	global_store_dwordx4 v[22:23], v[16:19], off offset:1024 nt
	s_nop 1
	v_lshlrev_b32_e32 v16, 16, v36
	v_and_b32_e32 v17, 0xffff0000, v36
	v_lshlrev_b32_e32 v18, 16, v37
	v_and_b32_e32 v19, 0xffff0000, v37
	v_pk_mul_f32 v[16:17], v[20:21], v[16:17] op_sel_hi:[0,1]
	v_pk_mul_f32 v[18:19], v[20:21], v[18:19] op_sel_hi:[0,1]
	v_pk_mul_f32 v[16:17], v[4:5], v[16:17]
	v_pk_mul_f32 v[18:19], v[6:7], v[18:19]
	global_store_dwordx4 v[22:23], v[16:19], off offset:2048 nt
	s_nop 1
	v_lshlrev_b32_e32 v16, 16, v40
	v_and_b32_e32 v17, 0xffff0000, v40
	v_lshlrev_b32_e32 v18, 16, v41
	v_and_b32_e32 v19, 0xffff0000, v41
	v_pk_mul_f32 v[16:17], v[20:21], v[16:17] op_sel_hi:[0,1]
	v_pk_mul_f32 v[18:19], v[20:21], v[18:19] op_sel_hi:[0,1]
	v_pk_mul_f32 v[16:17], v[0:1], v[16:17]
	v_pk_mul_f32 v[18:19], v[2:3], v[18:19]
	global_store_dwordx4 v[22:23], v[16:19], off offset:3072 nt
	s_cbranch_scc1 .LBB0_1330

; __global__ void __launch_bounds__(NTHR, 2) mega_fwd(Args a) {
	.amdhsa_kernel _Z8mega_fwd4Args
		.amdhsa_group_segment_fixed_size 0
		.amdhsa_private_segment_fixed_size 0
		.amdhsa_kernarg_size 464
		.amdhsa_user_sgpr_count 2
		.amdhsa_user_sgpr_dispatch_ptr 0
		.amdhsa_user_sgpr_queue_ptr 0
		.amdhsa_user_sgpr_kernarg_segment_ptr 1
		.amdhsa_user_sgpr_dispatch_id 0
		.amdhsa_user_sgpr_kernarg_preload_length 0
		.amdhsa_user_sgpr_kernarg_preload_offset 0
		.amdhsa_user_sgpr_private_segment_size 0
		.amdhsa_uses_dynamic_stack 0
		.amdhsa_enable_private_segment 0
		.amdhsa_system_sgpr_workgroup_id_x 1
		.amdhsa_system_sgpr_workgroup_id_y 0
		.amdhsa_system_sgpr_workgroup_id_z 0
		.amdhsa_system_sgpr_workgroup_info 0
		.amdhsa_system_vgpr_workitem_id 2
		.amdhsa_next_free_vgpr 256
		.amdhsa_next_free_sgpr 100
		.amdhsa_accum_offset 256
		.amdhsa_reserve_vcc 1
		.amdhsa_float_round_mode_32 0
		.amdhsa_float_round_mode_16_64 0
		.amdhsa_float_denorm_mode_32 3
		.amdhsa_float_denorm_mode_16_64 3
		.amdhsa_dx10_clamp 1
		.amdhsa_ieee_mode 1
		.amdhsa_fp16_overflow 0
		.amdhsa_tg_split 0
		.amdhsa_exception_fp_ieee_invalid_op 0
		.amdhsa_exception_fp_denorm_src 0
		.amdhsa_exception_fp_ieee_div_zero 0
		.amdhsa_exception_fp_ieee_overflow 0
		.amdhsa_exception_fp_ieee_underflow 0
		.amdhsa_exception_fp_ieee_inexact 0
		.amdhsa_exception_int_div_zero 0
	.end_amdhsa_kernel

; __global__ void __launch_bounds__(NTHR, 2) mega_fwd(Args a) {
;     extern __shared__ __attribute__((aligned(16))) unsigned char lds_raw[];
amdhsa.kernels:
  - .agpr_count:     0
    .args:
      - .offset:         0
        .size:           208
        .value_kind:     by_value
      - .offset:         208
        .size:           4
        .value_kind:     hidden_block_count_x
      - .offset:         212
        .size:           4
        .value_kind:     hidden_block_count_y
      - .offset:         216
        .size:           4
        .value_kind:     hidden_block_count_z
      - .offset:         220
        .size:           2
        .value_kind:     hidden_group_size_x
      - .offset:         222
        .size:           2
        .value_kind:     hidden_group_size_y
      - .offset:         224
        .size:           2
        .value_kind:     hidden_group_size_z
      - .offset:         226
        .size:           2
        .value_kind:     hidden_remainder_x
      - .offset:         228
        .size:           2
        .value_kind:     hidden_remainder_y
      - .offset:         230
        .size:           2
        .value_kind:     hidden_remainder_z
      - .offset:         248
        .size:           8
        .value_kind:     hidden_global_offset_x
      - .offset:         256
        .size:           8
        .value_kind:     hidden_global_offset_y
      - .offset:         264
        .size:           8
        .value_kind:     hidden_global_offset_z
      - .offset:         272
        .size:           2
        .value_kind:     hidden_grid_dims
      - .offset:         296
        .size:           8
        .value_kind:     hidden_multigrid_sync_arg
      - .offset:         328
        .size:           4
        .value_kind:     hidden_dynamic_lds_size
    .group_segment_fixed_size: 0
    .kernarg_segment_align: 8
    .kernarg_segment_size: 464
    .language:       OpenCL C
    .language_version:
      - 2
      - 0
    .max_flat_workgroup_size: 512
    .name:           _Z8mega_fwd4Args
    .private_segment_fixed_size: 0
    .sgpr_count:     106
    .sgpr_spill_count: 144
    .symbol:         _Z8mega_fwd4Args.kd
    .uniform_work_group_size: 1
    .uses_dynamic_stack: false
    .vgpr_count:     256
    .vgpr_spill_count: 0
    .wavefront_size: 64
